# w_in GEMM special-tile epilogue: forget biases loaded once per unit instead of 64 serialized load+store round trips
# speedup vs baseline: 1.0107x; 1.0107x over previous
; #define PG8_STAGE(bufoff, gbase, voff) do { _Pragma("unroll") for (int _i = 0; _i < 2; ++_i) \
;         __builtin_amdgcn_global_load_lds((const unsigned*)((const char*)(gbase) + (voff)[_i]), (LAS unsigned*)(lds + (bufoff) + ldsw + _i * 8192), 16, 0, 0); } while (0)
; #define PG8_LDA(dst, b, h) do { _Pragma("unroll") for (int m = 0; m < 4; ++m) _Pragma("unroll") for (int k = 0; k < 2; ++k) dst[m][k] = *(const LAS bf16x8*)(lds + PG8_SA(b, h) + aoff + m * 2048 + k * 1024); } while (0)
; #define PG8_WAIT_V(n) asm volatile("s_waitcnt vmcnt(" #n ")" ::: "memory")
; #define PG8_WAIT_L(n) asm volatile("s_waitcnt lgkmcnt(" #n ")" ::: "memory")
; template <class Epi, class Sched>
; __device__ __forceinline__ void gemm_phase(LAS unsigned char* lds, const Gemm g, const Sched& S, const Epi& E) {
;     ...
;         for (int t = 0; t < nt; t += 2) {
;             const bool last = (t == nt - 2);
;             const char* a1 = cA + (size_t)(t + 1) * kstep;
;             const char* a2 = last ? nA : cA + (size_t)(t + 2) * kstep; const char* b2 = last ? nB : cB + (size_t)(t + 2) * kstep;
;             const char* a3 = a2 + kstep; const char* b3 = b2 + kstep;
;             PG8_LDB(B0, 0, 0); PG8_SCHED; PG8_LDA(At, 0, 0); PG8_STAGE(PG8_SA(1, 1), a1 + hstepA, voffA);
;             PG8_WAIT_L(8); PG8_BAR; PG8_WAIT_L(0); PG8_MMA(0, 0, At, B0); PG8_BAR; PG8_SCHED;
;             PG8_LDB(B1, 0, 1); PG8_STAGE(PG8_SB(0, 0), b2, voffB);
;             PG8_BAR; PG8_WAIT_L(0); PG8_MMA(0, 1, At, B1); PG8_BAR;
;             PG8_LDA(At, 0, 1); PG8_STAGE(PG8_SA(0, 0), a2, voffA);
;             PG8_BAR; PG8_WAIT_L(0); PG8_MMA(1, 0, At, B0); PG8_BAR; PG8_SCHED;
;             PG8_STAGE(PG8_SB(0, 1), b2 + hstepB, voffB);
;             PG8_WAIT_V(6); PG8_BAR; PG8_MMA(1, 1, At, B1); PG8_BAR;
;             PG8_LDB(B0, 1, 0); PG8_SCHED; PG8_LDA(At, 1, 0); PG8_STAGE(PG8_SA(0, 1), a2 + hstepA, voffA);
;             PG8_WAIT_L(8); PG8_BAR; PG8_WAIT_L(0); PG8_MMA(0, 0, At, B0); PG8_BAR; PG8_SCHED;
;             PG8_LDB(B1, 1, 1); PG8_STAGE(PG8_SB(1, 0), b3, voffB);
;             PG8_BAR; PG8_WAIT_L(0); PG8_MMA(0, 1, At, B1); PG8_BAR;
;             PG8_LDA(At, 1, 1); PG8_STAGE(PG8_SA(1, 0), a3, voffA);
;             PG8_BAR; PG8_WAIT_L(0); PG8_MMA(1, 0, At, B0); PG8_BAR; PG8_SCHED;
;             PG8_STAGE(PG8_SB(1, 1), b3 + hstepB, voffB);
;             PG8_WAIT_V(6); PG8_BAR; PG8_MMA(1, 1, At, B1); PG8_BAR;
.LBB0_945:
	s_add_u32 s16, s10, 0xfff80080
	s_addc_u32 s17, s11, -1
	s_add_i32 s20, 0, 0x10000
	v_add_u32_e32 v0, s20, v156
	ds_read_b128 v[150:153], v0
	ds_read_b128 v[158:161], v0 offset:1024
	ds_read_b128 v[162:165], v0 offset:2048
	ds_read_b128 v[166:169], v0 offset:3072
	s_cmp_eq_u32 s14, 28
	s_cselect_b32 s19, s2, s17
	s_cselect_b32 s18, s3, s16
	s_cselect_b32 s17, s6, s12
	s_cselect_b32 s16, s7, s9
	v_lshl_add_u64 v[154:155], s[10:11], 0, v[148:149]
	s_add_i32 m0, s47, 0xc000
	ds_read_b128 v[170:173], v157
	ds_read_b128 v[174:177], v157 offset:1024
	ds_read_b128 v[178:181], v157 offset:2048
	ds_read_b128 v[182:185], v157 offset:3072
	ds_read_b128 v[186:189], v157 offset:4096
	ds_read_b128 v[190:193], v157 offset:5120
	ds_read_b128 v[198:201], v157 offset:6144
	ds_read_b128 v[202:205], v157 offset:7168
	global_load_lds_dwordx4 v[154:155], off
	v_lshl_add_u64 v[154:155], s[10:11], 0, v[146:147]
	s_add_i32 m0, s47, 0xe000
	s_nop 0
	global_load_lds_dwordx4 v[154:155], off
	s_waitcnt lgkmcnt(8)
	s_barrier
	s_waitcnt lgkmcnt(0)
	s_setprio 1
	s_waitcnt lgkmcnt(0)
	v_mfma_f32_16x16x32_bf16 v[126:129], v[150:153], v[170:173], v[126:129]
	v_mfma_f32_16x16x32_bf16 v[122:125], v[162:165], v[170:173], v[122:125]
	v_mfma_f32_16x16x32_bf16 v[110:113], v[150:153], v[178:181], v[110:113]
	v_mfma_f32_16x16x32_bf16 v[106:109], v[162:165], v[178:181], v[106:109]
	v_mfma_f32_16x16x32_bf16 v[94:97], v[150:153], v[186:189], v[94:97]
	v_mfma_f32_16x16x32_bf16 v[90:93], v[162:165], v[186:189], v[90:93]
	v_mfma_f32_16x16x32_bf16 v[78:81], v[150:153], v[198:201], v[78:81]
	v_mfma_f32_16x16x32_bf16 v[74:77], v[162:165], v[198:201], v[74:77]
	v_mfma_f32_16x16x32_bf16 v[126:129], v[158:161], v[174:177], v[126:129]
	v_mfma_f32_16x16x32_bf16 v[122:125], v[166:169], v[174:177], v[122:125]
	v_mfma_f32_16x16x32_bf16 v[110:113], v[158:161], v[182:185], v[110:113]
	v_mfma_f32_16x16x32_bf16 v[106:109], v[166:169], v[182:185], v[106:109]
	v_mfma_f32_16x16x32_bf16 v[94:97], v[158:161], v[190:193], v[94:97]
	v_mfma_f32_16x16x32_bf16 v[90:93], v[166:169], v[190:193], v[90:93]
	v_mfma_f32_16x16x32_bf16 v[78:81], v[158:161], v[202:205], v[78:81]
	v_mfma_f32_16x16x32_bf16 v[74:77], v[166:169], v[202:205], v[74:77]
	s_setprio 0
	s_barrier
	s_add_i32 s24, 0, 0x14000
	s_add_i32 s20, s20, s46
	v_add_u32_e32 v0, s24, v156
	v_lshl_add_u64 v[154:155], s[16:17], 0, v[132:133]
	s_mov_b32 m0, s20
	ds_read_b128 v[206:209], v0
	ds_read_b128 v[224:227], v0 offset:1024
	ds_read_b128 v[228:231], v0 offset:2048
	ds_read_b128 v[232:235], v0 offset:3072
	global_load_lds_dwordx4 v[154:155], off
	v_lshl_add_u64 v[194:195], s[16:17], 0, v[136:137]
	s_add_i32 m0, s20, 0x2000
	s_nop 0
	global_load_lds_dwordx4 v[194:195], off
	s_barrier
	s_waitcnt lgkmcnt(0)
	s_setprio 1
	s_waitcnt lgkmcnt(0)
	v_mfma_f32_16x16x32_bf16 v[118:121], v[206:209], v[170:173], v[118:121]
	v_mfma_f32_16x16x32_bf16 v[114:117], v[228:231], v[170:173], v[114:117]
	v_mfma_f32_16x16x32_bf16 v[102:105], v[206:209], v[178:181], v[102:105]
	v_mfma_f32_16x16x32_bf16 v[98:101], v[228:231], v[178:181], v[98:101]
	v_mfma_f32_16x16x32_bf16 v[86:89], v[206:209], v[186:189], v[86:89]
	v_mfma_f32_16x16x32_bf16 v[82:85], v[228:231], v[186:189], v[82:85]
	v_mfma_f32_16x16x32_bf16 v[70:73], v[206:209], v[198:201], v[70:73]
	v_mfma_f32_16x16x32_bf16 v[66:69], v[228:231], v[198:201], v[66:69]
	v_mfma_f32_16x16x32_bf16 v[118:121], v[224:227], v[174:177], v[118:121]
	v_mfma_f32_16x16x32_bf16 v[114:117], v[232:235], v[174:177], v[114:117]
	v_mfma_f32_16x16x32_bf16 v[102:105], v[224:227], v[182:185], v[102:105]
	v_mfma_f32_16x16x32_bf16 v[98:101], v[232:235], v[182:185], v[98:101]
	v_mfma_f32_16x16x32_bf16 v[86:89], v[224:227], v[190:193], v[86:89]
	v_mfma_f32_16x16x32_bf16 v[82:85], v[232:235], v[190:193], v[82:85]
	v_mfma_f32_16x16x32_bf16 v[70:73], v[224:227], v[202:205], v[70:73]
	v_mfma_f32_16x16x32_bf16 v[66:69], v[232:235], v[202:205], v[66:69]
	s_setprio 0
	s_mov_b32 m0, s47
	v_lshl_add_u64 v[196:197], s[18:19], 0, v[130:131]
	s_barrier
	ds_read_b128 v[170:173], v157 offset:16384
	ds_read_b128 v[174:177], v157 offset:17408
	ds_read_b128 v[178:181], v157 offset:18432
	ds_read_b128 v[182:185], v157 offset:19456
	ds_read_b128 v[186:189], v157 offset:20480
	ds_read_b128 v[190:193], v157 offset:21504
	ds_read_b128 v[198:201], v157 offset:22528
	ds_read_b128 v[202:205], v157 offset:23552
	global_load_lds_dwordx4 v[196:197], off
	v_lshl_add_u64 v[236:237], s[18:19], 0, v[134:135]
	s_mov_b32 m0, s72
	s_nop 0
	global_load_lds_dwordx4 v[236:237], off
	s_barrier
	s_waitcnt lgkmcnt(0)
	s_setprio 1
	s_waitcnt lgkmcnt(0)
	v_mfma_f32_16x16x32_bf16 v[62:65], v[150:153], v[170:173], v[62:65]
	v_mfma_f32_16x16x32_bf16 v[58:61], v[162:165], v[170:173], v[58:61]
	v_mfma_f32_16x16x32_bf16 v[46:49], v[150:153], v[178:181], v[46:49]
	v_mfma_f32_16x16x32_bf16 v[42:45], v[162:165], v[178:181], v[42:45]
	v_mfma_f32_16x16x32_bf16 v[30:33], v[150:153], v[186:189], v[30:33]
	v_mfma_f32_16x16x32_bf16 v[26:29], v[162:165], v[186:189], v[26:29]
	v_mfma_f32_16x16x32_bf16 v[14:17], v[150:153], v[198:201], v[14:17]
	v_mfma_f32_16x16x32_bf16 v[10:13], v[162:165], v[198:201], v[10:13]
	v_mfma_f32_16x16x32_bf16 v[62:65], v[158:161], v[174:177], v[62:65]
	v_mfma_f32_16x16x32_bf16 v[58:61], v[166:169], v[174:177], v[58:61]
	v_mfma_f32_16x16x32_bf16 v[46:49], v[158:161], v[182:185], v[46:49]
	v_mfma_f32_16x16x32_bf16 v[42:45], v[166:169], v[182:185], v[42:45]
	v_mfma_f32_16x16x32_bf16 v[30:33], v[158:161], v[190:193], v[30:33]
	v_mfma_f32_16x16x32_bf16 v[26:29], v[166:169], v[190:193], v[26:29]
	v_mfma_f32_16x16x32_bf16 v[14:17], v[158:161], v[202:205], v[14:17]
	v_mfma_f32_16x16x32_bf16 v[10:13], v[166:169], v[202:205], v[10:13]
	s_setprio 0
	s_barrier
; #define PG8_STAGE(bufoff, gbase, voff) do { _Pragma("unroll") for (int _i = 0; _i < 2; ++_i) \
;         __builtin_amdgcn_global_load_lds((const unsigned*)((const char*)(gbase) + (voff)[_i]), (LAS unsigned*)(lds + (bufoff) + ldsw + _i * 8192), 16, 0, 0); } while (0)
; #define PG8_LDA(dst, b, h) do { _Pragma("unroll") for (int m = 0; m < 4; ++m) _Pragma("unroll") for (int k = 0; k < 2; ++k) dst[m][k] = *(const LAS bf16x8*)(lds + PG8_SA(b, h) + aoff + m * 2048 + k * 1024); } while (0)
; #define PG8_WAIT_V(n) asm volatile("s_waitcnt vmcnt(" #n ")" ::: "memory")
; #define PG8_WAIT_L(n) asm volatile("s_waitcnt lgkmcnt(" #n ")" ::: "memory")
; template <class Epi, class Sched>
; __device__ __forceinline__ void gemm_phase(LAS unsigned char* lds, const Gemm g, const Sched& S, const Epi& E) {
;     ...
;         for (int t = 0; t < nt; t += 2) {
;             const bool last = (t == nt - 2);
;             const char* a1 = cA + (size_t)(t + 1) * kstep;
;             const char* a2 = last ? nA : cA + (size_t)(t + 2) * kstep; const char* b2 = last ? nB : cB + (size_t)(t + 2) * kstep;
;             const char* a3 = a2 + kstep; const char* b3 = b2 + kstep;
;             PG8_LDB(B0, 0, 0); PG8_SCHED; PG8_LDA(At, 0, 0); PG8_STAGE(PG8_SA(1, 1), a1 + hstepA, voffA);
;             PG8_WAIT_L(8); PG8_BAR; PG8_WAIT_L(0); PG8_MMA(0, 0, At, B0); PG8_BAR; PG8_SCHED;
;             PG8_LDB(B1, 0, 1); PG8_STAGE(PG8_SB(0, 0), b2, voffB);
;             PG8_BAR; PG8_WAIT_L(0); PG8_MMA(0, 1, At, B1); PG8_BAR;
;             PG8_LDA(At, 0, 1); PG8_STAGE(PG8_SA(0, 0), a2, voffA);
;             PG8_BAR; PG8_WAIT_L(0); PG8_MMA(1, 0, At, B0); PG8_BAR; PG8_SCHED;
;             PG8_STAGE(PG8_SB(0, 1), b2 + hstepB, voffB);
;             PG8_WAIT_V(6); PG8_BAR; PG8_MMA(1, 1, At, B1); PG8_BAR;
;             PG8_LDB(B0, 1, 0); PG8_SCHED; PG8_LDA(At, 1, 0); PG8_STAGE(PG8_SA(0, 1), a2 + hstepA, voffA);
;             PG8_WAIT_L(8); PG8_BAR; PG8_WAIT_L(0); PG8_MMA(0, 0, At, B0); PG8_BAR; PG8_SCHED;
;             PG8_LDB(B1, 1, 1); PG8_STAGE(PG8_SB(1, 0), b3, voffB);
;             PG8_BAR; PG8_WAIT_L(0); PG8_MMA(0, 1, At, B1); PG8_BAR;
;             PG8_LDA(At, 1, 1); PG8_STAGE(PG8_SA(1, 0), a3, voffA);
;             PG8_BAR; PG8_WAIT_L(0); PG8_MMA(1, 0, At, B0); PG8_BAR; PG8_SCHED;
;             PG8_STAGE(PG8_SB(1, 1), b3 + hstepB, voffB);
;             PG8_WAIT_V(6); PG8_BAR; PG8_MMA(1, 1, At, B1); PG8_BAR;
	s_add_u32 s20, s16, 0x80000
	s_addc_u32 s21, s17, 0
	s_add_i32 s24, s24, s46
	v_lshl_add_u64 v[150:151], s[20:21], 0, v[132:133]
	s_mov_b32 m0, s24
	s_nop 0
	global_load_lds_dwordx4 v[150:151], off
	v_lshl_add_u64 v[150:151], s[20:21], 0, v[136:137]
	s_add_i32 m0, s24, 0x2000
	s_nop 0
	global_load_lds_dwordx4 v[150:151], off
	s_waitcnt vmcnt(6)
	s_barrier
	s_setprio 1
	v_mfma_f32_16x16x32_bf16 v[54:57], v[206:209], v[170:173], v[54:57]
	v_mfma_f32_16x16x32_bf16 v[50:53], v[228:231], v[170:173], v[50:53]
	v_mfma_f32_16x16x32_bf16 v[38:41], v[206:209], v[178:181], v[38:41]
	v_mfma_f32_16x16x32_bf16 v[34:37], v[228:231], v[178:181], v[34:37]
	v_mfma_f32_16x16x32_bf16 v[22:25], v[206:209], v[186:189], v[22:25]
	v_mfma_f32_16x16x32_bf16 v[18:21], v[228:231], v[186:189], v[18:21]
	v_mfma_f32_16x16x32_bf16 v[6:9], v[206:209], v[198:201], v[6:9]
	v_mfma_f32_16x16x32_bf16 v[2:5], v[228:231], v[198:201], v[2:5]
	v_mfma_f32_16x16x32_bf16 v[54:57], v[224:227], v[174:177], v[54:57]
	v_mfma_f32_16x16x32_bf16 v[50:53], v[232:235], v[174:177], v[50:53]
	v_mfma_f32_16x16x32_bf16 v[38:41], v[224:227], v[182:185], v[38:41]
	v_mfma_f32_16x16x32_bf16 v[34:37], v[232:235], v[182:185], v[34:37]
	v_mfma_f32_16x16x32_bf16 v[22:25], v[224:227], v[190:193], v[22:25]
	v_mfma_f32_16x16x32_bf16 v[18:21], v[232:235], v[190:193], v[18:21]
	v_mfma_f32_16x16x32_bf16 v[6:9], v[224:227], v[202:205], v[6:9]
	v_mfma_f32_16x16x32_bf16 v[2:5], v[232:235], v[202:205], v[2:5]
	s_setprio 0
	s_add_i32 s20, 0, 0x18000
	v_add_u32_e32 v0, s20, v156
	s_barrier
	ds_read_b128 v[150:153], v0
	ds_read_b128 v[158:161], v0 offset:1024
	ds_read_b128 v[162:165], v0 offset:2048
	ds_read_b128 v[166:169], v0 offset:3072
	s_add_u32 s18, s18, 0x80000
	s_addc_u32 s19, s19, 0
	s_mov_b32 m0, s73
	v_lshl_add_u64 v[206:207], s[18:19], 0, v[130:131]
	ds_read_b128 v[170:173], v157 offset:32768
	ds_read_b128 v[174:177], v157 offset:33792
	ds_read_b128 v[178:181], v157 offset:34816
	ds_read_b128 v[182:185], v157 offset:35840
	ds_read_b128 v[186:189], v157 offset:36864
	ds_read_b128 v[190:193], v157 offset:37888
	ds_read_b128 v[198:201], v157 offset:38912
	ds_read_b128 v[202:205], v157 offset:39936
	global_load_lds_dwordx4 v[206:207], off
	v_lshl_add_u64 v[206:207], s[18:19], 0, v[134:135]
	s_mov_b32 m0, s74
	s_nop 0
	global_load_lds_dwordx4 v[206:207], off
	s_waitcnt lgkmcnt(8)
	s_barrier
	s_waitcnt lgkmcnt(0)
	s_setprio 1
	s_waitcnt lgkmcnt(0)
	v_mfma_f32_16x16x32_bf16 v[126:129], v[150:153], v[170:173], v[126:129]
	v_mfma_f32_16x16x32_bf16 v[122:125], v[162:165], v[170:173], v[122:125]
	v_mfma_f32_16x16x32_bf16 v[110:113], v[150:153], v[178:181], v[110:113]
	v_mfma_f32_16x16x32_bf16 v[106:109], v[162:165], v[178:181], v[106:109]
	v_mfma_f32_16x16x32_bf16 v[94:97], v[150:153], v[186:189], v[94:97]
	v_mfma_f32_16x16x32_bf16 v[90:93], v[162:165], v[186:189], v[90:93]
	v_mfma_f32_16x16x32_bf16 v[78:81], v[150:153], v[198:201], v[78:81]
	v_mfma_f32_16x16x32_bf16 v[74:77], v[162:165], v[198:201], v[74:77]
	v_mfma_f32_16x16x32_bf16 v[126:129], v[158:161], v[174:177], v[126:129]
	v_mfma_f32_16x16x32_bf16 v[122:125], v[166:169], v[174:177], v[122:125]
	v_mfma_f32_16x16x32_bf16 v[110:113], v[158:161], v[182:185], v[110:113]
	v_mfma_f32_16x16x32_bf16 v[106:109], v[166:169], v[182:185], v[106:109]
	v_mfma_f32_16x16x32_bf16 v[94:97], v[158:161], v[190:193], v[94:97]
	v_mfma_f32_16x16x32_bf16 v[90:93], v[166:169], v[190:193], v[90:93]
	v_mfma_f32_16x16x32_bf16 v[78:81], v[158:161], v[202:205], v[78:81]
	v_mfma_f32_16x16x32_bf16 v[74:77], v[166:169], v[202:205], v[74:77]
	s_setprio 0
	s_barrier
	s_add_i32 s18, 0, 0x1c000
	s_add_i32 s19, s20, s46
	v_add_u32_e32 v0, s18, v156
	v_lshl_add_u64 v[154:155], v[154:155], 0, s[26:27]
	s_mov_b32 m0, s19
	ds_read_b128 v[206:209], v0
	ds_read_b128 v[224:227], v0 offset:1024
	ds_read_b128 v[228:231], v0 offset:2048
	ds_read_b128 v[232:235], v0 offset:3072
	global_load_lds_dwordx4 v[154:155], off
	v_lshl_add_u64 v[154:155], v[194:195], 0, s[26:27]
	s_add_i32 m0, s19, 0x2000
	s_nop 0
	global_load_lds_dwordx4 v[154:155], off
	s_barrier
	s_waitcnt lgkmcnt(0)
	s_setprio 1
	s_waitcnt lgkmcnt(0)
	v_mfma_f32_16x16x32_bf16 v[118:121], v[206:209], v[170:173], v[118:121]
	v_mfma_f32_16x16x32_bf16 v[114:117], v[228:231], v[170:173], v[114:117]
	v_mfma_f32_16x16x32_bf16 v[102:105], v[206:209], v[178:181], v[102:105]
	v_mfma_f32_16x16x32_bf16 v[98:101], v[228:231], v[178:181], v[98:101]
	v_mfma_f32_16x16x32_bf16 v[86:89], v[206:209], v[186:189], v[86:89]
	v_mfma_f32_16x16x32_bf16 v[82:85], v[228:231], v[186:189], v[82:85]
	v_mfma_f32_16x16x32_bf16 v[70:73], v[206:209], v[198:201], v[70:73]
	v_mfma_f32_16x16x32_bf16 v[66:69], v[228:231], v[198:201], v[66:69]
	v_mfma_f32_16x16x32_bf16 v[118:121], v[224:227], v[174:177], v[118:121]
	v_mfma_f32_16x16x32_bf16 v[114:117], v[232:235], v[174:177], v[114:117]
	v_mfma_f32_16x16x32_bf16 v[102:105], v[224:227], v[182:185], v[102:105]
	v_mfma_f32_16x16x32_bf16 v[98:101], v[232:235], v[182:185], v[98:101]
	v_mfma_f32_16x16x32_bf16 v[86:89], v[224:227], v[190:193], v[86:89]
	v_mfma_f32_16x16x32_bf16 v[82:85], v[232:235], v[190:193], v[82:85]
	v_mfma_f32_16x16x32_bf16 v[70:73], v[224:227], v[202:205], v[70:73]
	v_mfma_f32_16x16x32_bf16 v[66:69], v[232:235], v[202:205], v[66:69]
	s_setprio 0
	s_mov_b32 m0, s77
	v_lshl_add_u64 v[154:155], v[196:197], 0, s[26:27]
	s_barrier
	ds_read_b128 v[170:173], v157 offset:49152
	ds_read_b128 v[174:177], v157 offset:50176
	ds_read_b128 v[178:181], v157 offset:51200
	ds_read_b128 v[182:185], v157 offset:52224
	ds_read_b128 v[186:189], v157 offset:53248
	ds_read_b128 v[190:193], v157 offset:54272
	ds_read_b128 v[198:201], v157 offset:55296
	ds_read_b128 v[202:205], v157 offset:56320
	global_load_lds_dwordx4 v[154:155], off
	v_lshl_add_u64 v[154:155], v[236:237], 0, s[26:27]
	s_mov_b32 m0, s78
	s_nop 0
	global_load_lds_dwordx4 v[154:155], off
	s_barrier
; #define PG8_STAGE(bufoff, gbase, voff) do { _Pragma("unroll") for (int _i = 0; _i < 2; ++_i) \
;         __builtin_amdgcn_global_load_lds((const unsigned*)((const char*)(gbase) + (voff)[_i]), (LAS unsigned*)(lds + (bufoff) + ldsw + _i * 8192), 16, 0, 0); } while (0)
; #define PG8_LDA(dst, b, h) do { _Pragma("unroll") for (int m = 0; m < 4; ++m) _Pragma("unroll") for (int k = 0; k < 2; ++k) dst[m][k] = *(const LAS bf16x8*)(lds + PG8_SA(b, h) + aoff + m * 2048 + k * 1024); } while (0)
; template <class Epi, class Sched>
; __device__ __forceinline__ void gemm_phase(LAS unsigned char* lds, const Gemm g, const Sched& S, const Epi& E) {
;     ...
;             PG8_WAIT_L(8); PG8_BAR; PG8_WAIT_L(0); PG8_MMA(0, 0, At, B0); PG8_BAR; PG8_SCHED;
;             PG8_LDB(B1, 0, 1); PG8_STAGE(PG8_SB(0, 0), b2, voffB);
;             PG8_BAR; PG8_WAIT_L(0); PG8_MMA(0, 1, At, B1); PG8_BAR;
;             PG8_LDA(At, 0, 1); PG8_STAGE(PG8_SA(0, 0), a2, voffA);
;             PG8_BAR; PG8_WAIT_L(0); PG8_MMA(1, 0, At, B0); PG8_BAR; PG8_SCHED;
;             PG8_STAGE(PG8_SB(0, 1), b2 + hstepB, voffB);
;             PG8_WAIT_V(6); PG8_BAR; PG8_MMA(1, 1, At, B1); PG8_BAR;
;             PG8_LDB(B0, 1, 0); PG8_SCHED; PG8_LDA(At, 1, 0); PG8_STAGE(PG8_SA(0, 1), a2 + hstepA, voffA);
;             PG8_WAIT_L(8); PG8_BAR; PG8_WAIT_L(0); PG8_MMA(0, 0, At, B0); PG8_BAR; PG8_SCHED;
;             PG8_LDB(B1, 1, 1); PG8_STAGE(PG8_SB(1, 0), b3, voffB);
;             PG8_BAR; PG8_WAIT_L(0); PG8_MMA(0, 1, At, B1); PG8_BAR;
;             PG8_LDA(At, 1, 1); PG8_STAGE(PG8_SA(1, 0), a3, voffA);
;             PG8_BAR; PG8_WAIT_L(0); PG8_MMA(1, 0, At, B0); PG8_BAR; PG8_SCHED;
;             PG8_STAGE(PG8_SB(1, 1), b3 + hstepB, voffB);
;             PG8_WAIT_V(6); PG8_BAR; PG8_MMA(1, 1, At, B1); PG8_BAR;
;         }
;         E(acc, cur, wr, wc, fr, fq);
;     __device__ __forceinline__ void operator()(const AccT& acc, const pg8::Unit& u, int wr, int wc, int fr, int fq) const {
;     ...
;                     } else if (wc == 1 && fq == 0) {
; #pragma unroll
;                         for (int n = 0; n < 2; ++n)
; #pragma unroll
;                             for (int j = 0; j < 4; ++j) {
;                                 const float x = acc[ai][0][m][n][j] * rs + bfg[4 * n + j];
;                                 lf[(4 * n + j) * MROWS + row] = fminf(x, 0.f) - log1pf(__expf(-fabsf(x)));
;                             }
	s_waitcnt lgkmcnt(0)
	s_setprio 1
	s_waitcnt lgkmcnt(0)
	v_mfma_f32_16x16x32_bf16 v[62:65], v[150:153], v[170:173], v[62:65]
	v_mfma_f32_16x16x32_bf16 v[58:61], v[162:165], v[170:173], v[58:61]
	v_mfma_f32_16x16x32_bf16 v[46:49], v[150:153], v[178:181], v[46:49]
	v_mfma_f32_16x16x32_bf16 v[42:45], v[162:165], v[178:181], v[42:45]
	v_mfma_f32_16x16x32_bf16 v[30:33], v[150:153], v[186:189], v[30:33]
	v_mfma_f32_16x16x32_bf16 v[26:29], v[162:165], v[186:189], v[26:29]
	v_mfma_f32_16x16x32_bf16 v[14:17], v[150:153], v[198:201], v[14:17]
	v_mfma_f32_16x16x32_bf16 v[10:13], v[162:165], v[198:201], v[10:13]
	v_mfma_f32_16x16x32_bf16 v[62:65], v[158:161], v[174:177], v[62:65]
	v_mfma_f32_16x16x32_bf16 v[58:61], v[166:169], v[174:177], v[58:61]
	v_mfma_f32_16x16x32_bf16 v[46:49], v[158:161], v[182:185], v[46:49]
	v_mfma_f32_16x16x32_bf16 v[42:45], v[166:169], v[182:185], v[42:45]
	v_mfma_f32_16x16x32_bf16 v[30:33], v[158:161], v[190:193], v[30:33]
	v_mfma_f32_16x16x32_bf16 v[26:29], v[166:169], v[190:193], v[26:29]
	v_mfma_f32_16x16x32_bf16 v[14:17], v[158:161], v[202:205], v[14:17]
	v_mfma_f32_16x16x32_bf16 v[10:13], v[166:169], v[202:205], v[10:13]
	s_setprio 0
	s_barrier
	s_add_u32 s16, s16, 0x80080
	s_addc_u32 s17, s17, 0
	s_add_i32 s18, s18, s46
	v_lshl_add_u64 v[150:151], s[16:17], 0, v[132:133]
	s_mov_b32 m0, s18
	s_nop 0
	global_load_lds_dwordx4 v[150:151], off
	v_lshl_add_u64 v[150:151], s[16:17], 0, v[136:137]
	s_add_i32 m0, s18, 0x2000
	s_nop 0
	global_load_lds_dwordx4 v[150:151], off
	s_waitcnt vmcnt(6)
	s_barrier
	s_setprio 1
	v_mfma_f32_16x16x32_bf16 v[54:57], v[206:209], v[170:173], v[54:57]
	v_mfma_f32_16x16x32_bf16 v[50:53], v[228:231], v[170:173], v[50:53]
	v_mfma_f32_16x16x32_bf16 v[38:41], v[206:209], v[178:181], v[38:41]
	v_mfma_f32_16x16x32_bf16 v[34:37], v[228:231], v[178:181], v[34:37]
	v_mfma_f32_16x16x32_bf16 v[22:25], v[206:209], v[186:189], v[22:25]
	v_mfma_f32_16x16x32_bf16 v[18:21], v[228:231], v[186:189], v[18:21]
	v_mfma_f32_16x16x32_bf16 v[6:9], v[206:209], v[198:201], v[6:9]
	v_mfma_f32_16x16x32_bf16 v[2:5], v[228:231], v[198:201], v[2:5]
	v_mfma_f32_16x16x32_bf16 v[54:57], v[224:227], v[174:177], v[54:57]
	v_mfma_f32_16x16x32_bf16 v[50:53], v[232:235], v[174:177], v[50:53]
	v_mfma_f32_16x16x32_bf16 v[38:41], v[224:227], v[182:185], v[38:41]
	v_mfma_f32_16x16x32_bf16 v[34:37], v[232:235], v[182:185], v[34:37]
	v_mfma_f32_16x16x32_bf16 v[22:25], v[224:227], v[190:193], v[22:25]
	v_mfma_f32_16x16x32_bf16 v[18:21], v[232:235], v[190:193], v[18:21]
	v_mfma_f32_16x16x32_bf16 v[6:9], v[224:227], v[202:205], v[6:9]
	v_mfma_f32_16x16x32_bf16 v[2:5], v[232:235], v[202:205], v[2:5]
	s_setprio 0
	s_add_i32 s14, s14, 2
	s_add_u32 s9, s9, 0x100
	s_addc_u32 s12, s12, 0
	s_add_u32 s10, s10, 0x100
	s_addc_u32 s11, s11, 0
	s_cmp_gt_u32 s14, 29
	s_barrier
	s_cbranch_scc0 .LBB0_945
	s_cmp_gt_i32 s40, 19
	s_cselect_b64 s[42:43], -1, 0
	s_cmp_lt_i32 s40, 4
	v_lshl_add_u32 v150, s8, 8, v139
	s_cselect_b64 s[44:45], -1, 0
	s_mov_b64 s[8:9], -1
	s_and_b64 vcc, exec, s[42:43]
	s_cbranch_vccz .LBB0_954
	s_and_b64 vcc, exec, s[56:57]
	s_cbranch_vccz .LBB0_951
	s_and_saveexec_b64 s[68:69], s[58:59]
	s_cbranch_execz .LBB0_950
	global_load_dword v240, v1, s[54:55]
	global_load_dword v241, v1, s[54:55] offset:4
	global_load_dword v242, v1, s[54:55] offset:8
	global_load_dword v243, v1, s[54:55] offset:12
	global_load_dword v244, v1, s[54:55] offset:16
	global_load_dword v245, v1, s[54:55] offset:20
	global_load_dword v246, v1, s[54:55] offset:24
	global_load_dword v247, v1, s[54:55] offset:28
	s_waitcnt vmcnt(0)
	s_mov_b32 s3, 0xbfb8aa3b
	s_mov_b32 s6, 0x3f2aaaab
	s_mov_b32 s7, 0x3f317218
	s_mov_b32 s8, 0x7f800000
	s_mov_b32 s9, 0x33800000
	s_mov_b32 s2, 0x8000
	v_add_f32_e32 v0, v126, v240
	v_min_f32_e32 v151, 0, v0
	v_mul_f32_e64 v0, |v0|, s3
	v_exp_f32_e32 v0, v0
	s_nop 0
	v_add_f32_e32 v154, 1.0, v0
	v_add_f32_e32 v152, -1.0, v154
	v_sub_f32_e32 v153, v152, v154
	v_add_f32_e32 v153, 1.0, v153
	v_sub_f32_e32 v152, v0, v152
	v_add_f32_e32 v155, v152, v153
	v_frexp_mant_f32_e32 v152, v154
	v_cmp_gt_f32_e32 vcc, s6, v152
	v_cvt_f64_f32_e32 v[152:153], v154
	v_frexp_exp_i32_f64_e32 v152, v[152:153]
	v_subbrev_co_u32_e32 v152, vcc, 0, v152, vcc
	v_sub_u32_e32 v153, 0, v152
	v_ldexp_f32 v154, v154, v153
	v_ldexp_f32 v153, v155, v153
	v_add_f32_e32 v155, -1.0, v154
	v_add_f32_e32 v158, 1.0, v155
	v_sub_f32_e32 v158, v154, v158
	v_add_f32_e32 v158, v153, v158
	v_add_f32_e32 v159, v155, v158
	v_sub_f32_e32 v155, v159, v155
	v_sub_f32_e32 v155, v158, v155
	v_add_f32_e32 v158, 1.0, v154
	v_add_f32_e32 v160, -1.0, v158
	v_sub_f32_e32 v154, v154, v160
	v_add_f32_e32 v153, v153, v154
	v_add_f32_e32 v154, v158, v153
	v_sub_f32_e32 v158, v154, v158
	v_sub_f32_e32 v153, v153, v158
	v_rcp_f32_e32 v158, v154
	v_cvt_f32_i32_e32 v152, v152
	v_cmp_neq_f32_e32 vcc, s8, v0
	v_mul_f32_e32 v160, v159, v158
	v_mul_f32_e32 v161, v154, v160
	v_fma_f32 v162, v160, v154, -v161
	v_fmac_f32_e32 v162, v160, v153
	v_add_f32_e32 v163, v161, v162
	v_sub_f32_e32 v164, v159, v163
	v_sub_f32_e32 v159, v159, v164
	v_sub_f32_e32 v161, v163, v161
	v_sub_f32_e32 v159, v159, v163
	v_add_f32_e32 v155, v155, v159
	v_sub_f32_e32 v159, v161, v162
	v_add_f32_e32 v155, v159, v155
	v_add_f32_e32 v159, v164, v155
	v_mul_f32_e32 v161, v158, v159
	v_mul_f32_e32 v162, v154, v161
	v_fma_f32 v154, v161, v154, -v162
	v_fmac_f32_e32 v154, v161, v153
	v_sub_f32_e32 v153, v164, v159
	v_add_f32_e32 v153, v155, v153
	v_add_f32_e32 v155, v162, v154
	v_sub_f32_e32 v163, v159, v155
	v_sub_f32_e32 v159, v159, v163
	v_sub_f32_e32 v162, v155, v162
	v_sub_f32_e32 v155, v159, v155
	v_add_f32_e32 v153, v153, v155
;     __device__ __forceinline__ void operator()(const AccT& acc, const pg8::Unit& u, int wr, int wc, int fr, int fq) const {
;     ...
;                     } else if (wc == 1 && fq == 0) {
; #pragma unroll
;                         for (int n = 0; n < 2; ++n)
; #pragma unroll
;                             for (int j = 0; j < 4; ++j) {
;                                 const float x = acc[ai][0][m][n][j] * rs + bfg[4 * n + j];
;                                 lf[(4 * n + j) * MROWS + row] = fminf(x, 0.f) - log1pf(__expf(-fabsf(x)));
;                             }
	v_sub_f32_e32 v154, v162, v154
	v_add_f32_e32 v153, v154, v153
	v_add_f32_e32 v154, v160, v161
	v_add_f32_e32 v153, v163, v153
	v_sub_f32_e32 v155, v154, v160
	v_mul_f32_e32 v153, v158, v153
	v_sub_f32_e32 v155, v161, v155
	v_add_f32_e32 v153, v155, v153
	v_mul_f32_e32 v160, 0x3f317218, v152
	v_add_f32_e32 v155, v154, v153
	v_fma_f32 v161, v152, s7, -v160
	v_mul_f32_e32 v158, v155, v155
	v_fmac_f32_e32 v161, 0xb102e308, v152
	v_sub_f32_e32 v152, v155, v154
	v_fmamk_f32 v159, v158, 0x3e9b6dac, v214
	v_sub_f32_e32 v152, v153, v152
	v_add_f32_e32 v153, v160, v161
	v_fmaak_f32 v159, v158, v159, 0x3f2aaada
	v_sub_f32_e32 v154, v153, v160
	v_ldexp_f32 v160, v155, 1
	v_mul_f32_e32 v155, v155, v158
	v_mul_f32_e32 v155, v155, v159
	v_add_f32_e32 v158, v160, v155
	v_sub_f32_e32 v159, v158, v160
	v_ldexp_f32 v152, v152, 1
	v_sub_f32_e32 v155, v155, v159
	v_add_f32_e32 v152, v152, v155
	v_add_f32_e32 v155, v158, v152
	v_sub_f32_e32 v158, v155, v158
	v_sub_f32_e32 v152, v152, v158
	v_add_f32_e32 v158, v153, v155
	v_sub_f32_e32 v159, v158, v153
	v_sub_f32_e32 v160, v158, v159
	v_sub_f32_e32 v154, v161, v154
	v_sub_f32_e32 v153, v153, v160
	v_sub_f32_e32 v155, v155, v159
	v_add_f32_e32 v153, v155, v153
	v_add_f32_e32 v155, v154, v152
	v_sub_f32_e32 v159, v155, v154
	v_sub_f32_e32 v160, v155, v159
	v_sub_f32_e32 v154, v154, v160
	v_sub_f32_e32 v152, v152, v159
	v_add_f32_e32 v153, v155, v153
	v_add_f32_e32 v152, v152, v154
	v_add_f32_e32 v154, v158, v153
	v_sub_f32_e32 v155, v154, v158
	v_sub_f32_e32 v153, v153, v155
	v_add_f32_e32 v152, v152, v153
	v_add_f32_e32 v152, v154, v152
	v_cndmask_b32_e32 v152, v221, v152, vcc
	v_cmp_ngt_f32_e32 vcc, -1.0, v0
	s_nop 1
	v_cndmask_b32_e32 v152, v222, v152, vcc
	v_cmp_neq_f32_e32 vcc, -1.0, v0
	s_nop 1
	v_cndmask_b32_e32 v152, v219, v152, vcc
	v_cmp_lt_f32_e64 vcc, |v0|, s9
	s_nop 1
	v_cndmask_b32_e32 v0, v152, v0, vcc
	v_sub_f32_e32 v0, v151, v0
	v_ashrrev_i32_e32 v151, 31, v150
	v_lshl_add_u64 v[152:153], v[150:151], 2, s[52:53]
	global_store_dword v[152:153], v0, off
	v_add_f32_e32 v0, v127, v241
	v_min_f32_e32 v151, 0, v0
	v_mul_f32_e64 v0, |v0|, s3
	v_exp_f32_e32 v0, v0
	s_nop 0
	v_add_f32_e32 v158, 1.0, v0
	v_add_f32_e32 v154, -1.0, v158
	v_sub_f32_e32 v155, v154, v158
	v_add_f32_e32 v155, 1.0, v155
	v_sub_f32_e32 v154, v0, v154
	v_add_f32_e32 v159, v154, v155
	v_frexp_mant_f32_e32 v154, v158
	v_cmp_gt_f32_e32 vcc, s6, v154
	v_cvt_f64_f32_e32 v[154:155], v158
	v_frexp_exp_i32_f64_e32 v154, v[154:155]
	v_subbrev_co_u32_e32 v154, vcc, 0, v154, vcc
	v_sub_u32_e32 v155, 0, v154
	v_ldexp_f32 v158, v158, v155
	v_ldexp_f32 v155, v159, v155
	v_add_f32_e32 v159, -1.0, v158
	v_add_f32_e32 v160, 1.0, v159
	v_sub_f32_e32 v160, v158, v160
	v_add_f32_e32 v160, v155, v160
	v_add_f32_e32 v161, v159, v160
	v_sub_f32_e32 v159, v161, v159
	v_sub_f32_e32 v159, v160, v159
	v_add_f32_e32 v160, 1.0, v158
	v_add_f32_e32 v162, -1.0, v160
	v_sub_f32_e32 v158, v158, v162
	v_add_f32_e32 v155, v155, v158
	v_add_f32_e32 v158, v160, v155
	v_sub_f32_e32 v160, v158, v160
	v_sub_f32_e32 v155, v155, v160
	v_rcp_f32_e32 v160, v158
	v_cvt_f32_i32_e32 v154, v154
	v_cmp_neq_f32_e32 vcc, s8, v0
	v_mul_f32_e32 v162, v161, v160
	v_mul_f32_e32 v163, v158, v162
	v_fma_f32 v164, v162, v158, -v163
	v_fmac_f32_e32 v164, v162, v155
	v_add_f32_e32 v165, v163, v164
	v_sub_f32_e32 v166, v161, v165
	v_sub_f32_e32 v161, v161, v166
	v_sub_f32_e32 v163, v165, v163
	v_sub_f32_e32 v161, v161, v165
	v_add_f32_e32 v159, v159, v161
	v_sub_f32_e32 v161, v163, v164
	v_add_f32_e32 v159, v161, v159
	v_add_f32_e32 v161, v166, v159
	v_mul_f32_e32 v163, v160, v161
	v_mul_f32_e32 v164, v158, v163
	v_fma_f32 v158, v163, v158, -v164
	v_fmac_f32_e32 v158, v163, v155
	v_sub_f32_e32 v155, v166, v161
	v_add_f32_e32 v155, v159, v155
	v_add_f32_e32 v159, v164, v158
	v_sub_f32_e32 v165, v161, v159
	v_sub_f32_e32 v161, v161, v165
	v_sub_f32_e32 v164, v159, v164
	v_sub_f32_e32 v159, v161, v159
	v_add_f32_e32 v155, v155, v159
	v_sub_f32_e32 v158, v164, v158
	v_add_f32_e32 v155, v158, v155
	v_add_f32_e32 v158, v162, v163
	v_add_f32_e32 v155, v165, v155
	v_sub_f32_e32 v159, v158, v162
	v_mul_f32_e32 v155, v160, v155
	v_sub_f32_e32 v159, v163, v159
	v_add_f32_e32 v155, v159, v155
	v_mul_f32_e32 v162, 0x3f317218, v154
	v_add_f32_e32 v159, v158, v155
	v_fma_f32 v163, v154, s7, -v162
	v_mul_f32_e32 v160, v159, v159
	v_fmac_f32_e32 v163, 0xb102e308, v154
	v_sub_f32_e32 v154, v159, v158
	v_fmamk_f32 v161, v160, 0x3e9b6dac, v214
	v_sub_f32_e32 v154, v155, v154
	v_add_f32_e32 v155, v162, v163
	v_fmaak_f32 v161, v160, v161, 0x3f2aaada
	v_sub_f32_e32 v158, v155, v162
	v_ldexp_f32 v162, v159, 1
	v_mul_f32_e32 v159, v159, v160
	v_mul_f32_e32 v159, v159, v161
	v_add_f32_e32 v160, v162, v159
	v_sub_f32_e32 v161, v160, v162
	v_ldexp_f32 v154, v154, 1
	v_sub_f32_e32 v159, v159, v161
	v_add_f32_e32 v154, v154, v159
	v_add_f32_e32 v159, v160, v154
	v_sub_f32_e32 v160, v159, v160
	v_sub_f32_e32 v154, v154, v160
	v_add_f32_e32 v160, v155, v159
	v_sub_f32_e32 v161, v160, v155
	v_sub_f32_e32 v162, v160, v161
	v_sub_f32_e32 v158, v163, v158
	v_sub_f32_e32 v155, v155, v162
	v_sub_f32_e32 v159, v159, v161
	v_add_f32_e32 v155, v159, v155
	v_add_f32_e32 v159, v158, v154
	v_sub_f32_e32 v161, v159, v158
	v_sub_f32_e32 v162, v159, v161
	v_sub_f32_e32 v158, v158, v162
	v_sub_f32_e32 v154, v154, v161
	v_add_f32_e32 v155, v159, v155
	v_add_f32_e32 v154, v154, v158
	v_add_f32_e32 v158, v160, v155
	v_sub_f32_e32 v159, v158, v160
	v_sub_f32_e32 v155, v155, v159
	v_add_f32_e32 v154, v154, v155
	v_add_f32_e32 v154, v158, v154
	v_cndmask_b32_e32 v154, v221, v154, vcc
	v_cmp_ngt_f32_e32 vcc, -1.0, v0
	s_nop 1
;     __device__ __forceinline__ void operator()(const AccT& acc, const pg8::Unit& u, int wr, int wc, int fr, int fq) const {
;     ...
;                     } else if (wc == 1 && fq == 0) {
; #pragma unroll
;                         for (int n = 0; n < 2; ++n)
; #pragma unroll
;                             for (int j = 0; j < 4; ++j) {
;                                 const float x = acc[ai][0][m][n][j] * rs + bfg[4 * n + j];
;                                 lf[(4 * n + j) * MROWS + row] = fminf(x, 0.f) - log1pf(__expf(-fabsf(x)));
;                             }
	v_cndmask_b32_e32 v154, v222, v154, vcc
	v_cmp_neq_f32_e32 vcc, -1.0, v0
	s_nop 1
	v_cndmask_b32_e32 v154, v219, v154, vcc
	v_cmp_lt_f32_e64 vcc, |v0|, s9
	s_nop 1
	v_cndmask_b32_e32 v0, v154, v0, vcc
	v_add_co_u32_e32 v154, vcc, s2, v152
	v_sub_f32_e32 v0, v151, v0
	s_nop 0
	v_addc_co_u32_e32 v155, vcc, 0, v153, vcc
	global_store_dword v[154:155], v0, off offset:1024
	s_mov_b32 s2, 0x10000
	v_add_f32_e32 v0, v128, v242
	v_min_f32_e32 v151, 0, v0
	v_mul_f32_e64 v0, |v0|, s3
	v_exp_f32_e32 v0, v0
	s_nop 0
	v_add_f32_e32 v158, 1.0, v0
	v_add_f32_e32 v154, -1.0, v158
	v_sub_f32_e32 v155, v154, v158
	v_add_f32_e32 v155, 1.0, v155
	v_sub_f32_e32 v154, v0, v154
	v_add_f32_e32 v159, v154, v155
	v_frexp_mant_f32_e32 v154, v158
	v_cmp_gt_f32_e32 vcc, s6, v154
	v_cvt_f64_f32_e32 v[154:155], v158
	v_frexp_exp_i32_f64_e32 v154, v[154:155]
	v_subbrev_co_u32_e32 v154, vcc, 0, v154, vcc
	v_sub_u32_e32 v155, 0, v154
	v_ldexp_f32 v158, v158, v155
	v_ldexp_f32 v155, v159, v155
	v_add_f32_e32 v159, -1.0, v158
	v_add_f32_e32 v160, 1.0, v159
	v_sub_f32_e32 v160, v158, v160
	v_add_f32_e32 v160, v155, v160
	v_add_f32_e32 v161, v159, v160
	v_sub_f32_e32 v159, v161, v159
	v_sub_f32_e32 v159, v160, v159
	v_add_f32_e32 v160, 1.0, v158
	v_add_f32_e32 v162, -1.0, v160
	v_sub_f32_e32 v158, v158, v162
	v_add_f32_e32 v155, v155, v158
	v_add_f32_e32 v158, v160, v155
	v_sub_f32_e32 v160, v158, v160
	v_sub_f32_e32 v155, v155, v160
	v_rcp_f32_e32 v160, v158
	v_cvt_f32_i32_e32 v154, v154
	v_cmp_neq_f32_e32 vcc, s8, v0
	v_mul_f32_e32 v162, v161, v160
	v_mul_f32_e32 v163, v158, v162
	v_fma_f32 v164, v162, v158, -v163
	v_fmac_f32_e32 v164, v162, v155
	v_add_f32_e32 v165, v163, v164
	v_sub_f32_e32 v166, v161, v165
	v_sub_f32_e32 v161, v161, v166
	v_sub_f32_e32 v163, v165, v163
	v_sub_f32_e32 v161, v161, v165
	v_add_f32_e32 v159, v159, v161
	v_sub_f32_e32 v161, v163, v164
	v_add_f32_e32 v159, v161, v159
	v_add_f32_e32 v161, v166, v159
	v_mul_f32_e32 v163, v160, v161
	v_mul_f32_e32 v164, v158, v163
	v_fma_f32 v158, v163, v158, -v164
	v_fmac_f32_e32 v158, v163, v155
	v_sub_f32_e32 v155, v166, v161
	v_add_f32_e32 v155, v159, v155
	v_add_f32_e32 v159, v164, v158
	v_sub_f32_e32 v165, v161, v159
	v_sub_f32_e32 v161, v161, v165
	v_sub_f32_e32 v164, v159, v164
	v_sub_f32_e32 v159, v161, v159
	v_add_f32_e32 v155, v155, v159
	v_sub_f32_e32 v158, v164, v158
	v_add_f32_e32 v155, v158, v155
	v_add_f32_e32 v158, v162, v163
	v_add_f32_e32 v155, v165, v155
	v_sub_f32_e32 v159, v158, v162
	v_mul_f32_e32 v155, v160, v155
	v_sub_f32_e32 v159, v163, v159
	v_add_f32_e32 v155, v159, v155
	v_mul_f32_e32 v162, 0x3f317218, v154
	v_add_f32_e32 v159, v158, v155
	v_fma_f32 v163, v154, s7, -v162
	v_mul_f32_e32 v160, v159, v159
	v_fmac_f32_e32 v163, 0xb102e308, v154
	v_sub_f32_e32 v154, v159, v158
	v_fmamk_f32 v161, v160, 0x3e9b6dac, v214
	v_sub_f32_e32 v154, v155, v154
	v_add_f32_e32 v155, v162, v163
	v_fmaak_f32 v161, v160, v161, 0x3f2aaada
	v_sub_f32_e32 v158, v155, v162
	v_ldexp_f32 v162, v159, 1
	v_mul_f32_e32 v159, v159, v160
	v_mul_f32_e32 v159, v159, v161
	v_add_f32_e32 v160, v162, v159
	v_sub_f32_e32 v161, v160, v162
	v_ldexp_f32 v154, v154, 1
	v_sub_f32_e32 v159, v159, v161
	v_add_f32_e32 v154, v154, v159
	v_add_f32_e32 v159, v160, v154
	v_sub_f32_e32 v160, v159, v160
	v_sub_f32_e32 v154, v154, v160
	v_add_f32_e32 v160, v155, v159
	v_sub_f32_e32 v161, v160, v155
	v_sub_f32_e32 v162, v160, v161
	v_sub_f32_e32 v158, v163, v158
	v_sub_f32_e32 v155, v155, v162
	v_sub_f32_e32 v159, v159, v161
	v_add_f32_e32 v155, v159, v155
	v_add_f32_e32 v159, v158, v154
	v_sub_f32_e32 v161, v159, v158
	v_sub_f32_e32 v162, v159, v161
	v_sub_f32_e32 v158, v158, v162
	v_sub_f32_e32 v154, v154, v161
	v_add_f32_e32 v155, v159, v155
	v_add_f32_e32 v154, v154, v158
	v_add_f32_e32 v158, v160, v155
	v_sub_f32_e32 v159, v158, v160
	v_sub_f32_e32 v155, v155, v159
	v_add_f32_e32 v154, v154, v155
	v_add_f32_e32 v154, v158, v154
	v_cndmask_b32_e32 v154, v221, v154, vcc
	v_cmp_ngt_f32_e32 vcc, -1.0, v0
	s_nop 1
	v_cndmask_b32_e32 v154, v222, v154, vcc
	v_cmp_neq_f32_e32 vcc, -1.0, v0
	s_nop 1
	v_cndmask_b32_e32 v154, v219, v154, vcc
	v_cmp_lt_f32_e64 vcc, |v0|, s9
	s_nop 1
	v_cndmask_b32_e32 v0, v154, v0, vcc
	v_add_co_u32_e32 v154, vcc, s2, v152
	v_sub_f32_e32 v0, v151, v0
	s_nop 0
	v_addc_co_u32_e32 v155, vcc, 0, v153, vcc
	global_store_dword v[154:155], v0, off offset:2048
	s_mov_b32 s2, 0x18000
	v_add_f32_e32 v0, v129, v243
	v_min_f32_e32 v151, 0, v0
	v_mul_f32_e64 v0, |v0|, s3
	v_exp_f32_e32 v0, v0
	s_nop 0
	v_add_f32_e32 v158, 1.0, v0
	v_add_f32_e32 v154, -1.0, v158
	v_sub_f32_e32 v155, v154, v158
	v_add_f32_e32 v155, 1.0, v155
	v_sub_f32_e32 v154, v0, v154
	v_add_f32_e32 v159, v154, v155
	v_frexp_mant_f32_e32 v154, v158
	v_cmp_gt_f32_e32 vcc, s6, v154
	v_cvt_f64_f32_e32 v[154:155], v158
	v_frexp_exp_i32_f64_e32 v154, v[154:155]
	v_subbrev_co_u32_e32 v154, vcc, 0, v154, vcc
	v_sub_u32_e32 v155, 0, v154
	v_ldexp_f32 v158, v158, v155
	v_ldexp_f32 v155, v159, v155
	v_add_f32_e32 v159, -1.0, v158
	v_add_f32_e32 v160, 1.0, v159
	v_sub_f32_e32 v160, v158, v160
	v_add_f32_e32 v160, v155, v160
	v_add_f32_e32 v161, v159, v160
	v_sub_f32_e32 v159, v161, v159
	v_sub_f32_e32 v159, v160, v159
	v_add_f32_e32 v160, 1.0, v158
	v_add_f32_e32 v162, -1.0, v160
	v_sub_f32_e32 v158, v158, v162
	v_add_f32_e32 v155, v155, v158
	v_add_f32_e32 v158, v160, v155
	v_sub_f32_e32 v160, v158, v160
	v_sub_f32_e32 v155, v155, v160
	v_rcp_f32_e32 v160, v158
	v_cvt_f32_i32_e32 v154, v154
	v_cmp_neq_f32_e32 vcc, s8, v0
	v_mul_f32_e32 v162, v161, v160
	v_mul_f32_e32 v163, v158, v162
	v_fma_f32 v164, v162, v158, -v163
	v_fmac_f32_e32 v164, v162, v155
;     __device__ __forceinline__ void operator()(const AccT& acc, const pg8::Unit& u, int wr, int wc, int fr, int fq) const {
;     ...
;                     } else if (wc == 1 && fq == 0) {
; #pragma unroll
;                         for (int n = 0; n < 2; ++n)
; #pragma unroll
;                             for (int j = 0; j < 4; ++j) {
;                                 const float x = acc[ai][0][m][n][j] * rs + bfg[4 * n + j];
;                                 lf[(4 * n + j) * MROWS + row] = fminf(x, 0.f) - log1pf(__expf(-fabsf(x)));
;                             }
	v_add_f32_e32 v165, v163, v164
	v_sub_f32_e32 v166, v161, v165
	v_sub_f32_e32 v161, v161, v166
	v_sub_f32_e32 v163, v165, v163
	v_sub_f32_e32 v161, v161, v165
	v_add_f32_e32 v159, v159, v161
	v_sub_f32_e32 v161, v163, v164
	v_add_f32_e32 v159, v161, v159
	v_add_f32_e32 v161, v166, v159
	v_mul_f32_e32 v163, v160, v161
	v_mul_f32_e32 v164, v158, v163
	v_fma_f32 v158, v163, v158, -v164
	v_fmac_f32_e32 v158, v163, v155
	v_sub_f32_e32 v155, v166, v161
	v_add_f32_e32 v155, v159, v155
	v_add_f32_e32 v159, v164, v158
	v_sub_f32_e32 v165, v161, v159
	v_sub_f32_e32 v161, v161, v165
	v_sub_f32_e32 v164, v159, v164
	v_sub_f32_e32 v159, v161, v159
	v_add_f32_e32 v155, v155, v159
	v_sub_f32_e32 v158, v164, v158
	v_add_f32_e32 v155, v158, v155
	v_add_f32_e32 v158, v162, v163
	v_add_f32_e32 v155, v165, v155
	v_sub_f32_e32 v159, v158, v162
	v_mul_f32_e32 v155, v160, v155
	v_sub_f32_e32 v159, v163, v159
	v_add_f32_e32 v155, v159, v155
	v_mul_f32_e32 v162, 0x3f317218, v154
	v_add_f32_e32 v159, v158, v155
	v_fma_f32 v163, v154, s7, -v162
	v_mul_f32_e32 v160, v159, v159
	v_fmac_f32_e32 v163, 0xb102e308, v154
	v_sub_f32_e32 v154, v159, v158
	v_fmamk_f32 v161, v160, 0x3e9b6dac, v214
	v_sub_f32_e32 v154, v155, v154
	v_add_f32_e32 v155, v162, v163
	v_fmaak_f32 v161, v160, v161, 0x3f2aaada
	v_sub_f32_e32 v158, v155, v162
	v_ldexp_f32 v162, v159, 1
	v_mul_f32_e32 v159, v159, v160
	v_mul_f32_e32 v159, v159, v161
	v_add_f32_e32 v160, v162, v159
	v_sub_f32_e32 v161, v160, v162
	v_ldexp_f32 v154, v154, 1
	v_sub_f32_e32 v159, v159, v161
	v_add_f32_e32 v154, v154, v159
	v_add_f32_e32 v159, v160, v154
	v_sub_f32_e32 v160, v159, v160
	v_sub_f32_e32 v154, v154, v160
	v_add_f32_e32 v160, v155, v159
	v_sub_f32_e32 v161, v160, v155
	v_sub_f32_e32 v162, v160, v161
	v_sub_f32_e32 v158, v163, v158
	v_sub_f32_e32 v155, v155, v162
	v_sub_f32_e32 v159, v159, v161
	v_add_f32_e32 v155, v159, v155
	v_add_f32_e32 v159, v158, v154
	v_sub_f32_e32 v161, v159, v158
	v_sub_f32_e32 v162, v159, v161
	v_sub_f32_e32 v158, v158, v162
	v_sub_f32_e32 v154, v154, v161
	v_add_f32_e32 v155, v159, v155
	v_add_f32_e32 v154, v154, v158
	v_add_f32_e32 v158, v160, v155
	v_sub_f32_e32 v159, v158, v160
	v_sub_f32_e32 v155, v155, v159
	v_add_f32_e32 v154, v154, v155
	v_add_f32_e32 v154, v158, v154
	v_cndmask_b32_e32 v154, v221, v154, vcc
	v_cmp_ngt_f32_e32 vcc, -1.0, v0
	s_nop 1
	v_cndmask_b32_e32 v154, v222, v154, vcc
	v_cmp_neq_f32_e32 vcc, -1.0, v0
	s_nop 1
	v_cndmask_b32_e32 v154, v219, v154, vcc
	v_cmp_lt_f32_e64 vcc, |v0|, s9
	s_nop 1
	v_cndmask_b32_e32 v0, v154, v0, vcc
	v_add_co_u32_e32 v154, vcc, s2, v152
	v_sub_f32_e32 v0, v151, v0
	s_nop 0
	v_addc_co_u32_e32 v155, vcc, 0, v153, vcc
	global_store_dword v[154:155], v0, off offset:3072
	s_mov_b32 s2, 0x21000
	v_add_f32_e32 v0, v122, v244
	v_min_f32_e32 v151, 0, v0
	v_mul_f32_e64 v0, |v0|, s3
	v_exp_f32_e32 v0, v0
	s_nop 0
	v_add_f32_e32 v158, 1.0, v0
	v_add_f32_e32 v154, -1.0, v158
	v_sub_f32_e32 v155, v154, v158
	v_add_f32_e32 v155, 1.0, v155
	v_sub_f32_e32 v154, v0, v154
	v_add_f32_e32 v159, v154, v155
	v_frexp_mant_f32_e32 v154, v158
	v_cmp_gt_f32_e32 vcc, s6, v154
	v_cvt_f64_f32_e32 v[154:155], v158
	v_frexp_exp_i32_f64_e32 v154, v[154:155]
	v_subbrev_co_u32_e32 v154, vcc, 0, v154, vcc
	v_sub_u32_e32 v155, 0, v154
	v_ldexp_f32 v158, v158, v155
	v_ldexp_f32 v155, v159, v155
	v_add_f32_e32 v159, -1.0, v158
	v_add_f32_e32 v160, 1.0, v159
	v_sub_f32_e32 v160, v158, v160
	v_add_f32_e32 v160, v155, v160
	v_add_f32_e32 v161, v159, v160
	v_sub_f32_e32 v159, v161, v159
	v_sub_f32_e32 v159, v160, v159
	v_add_f32_e32 v160, 1.0, v158
	v_add_f32_e32 v162, -1.0, v160
	v_sub_f32_e32 v158, v158, v162
	v_add_f32_e32 v155, v155, v158
	v_add_f32_e32 v158, v160, v155
	v_sub_f32_e32 v160, v158, v160
	v_sub_f32_e32 v155, v155, v160
	v_rcp_f32_e32 v160, v158
	v_cvt_f32_i32_e32 v154, v154
	v_cmp_neq_f32_e32 vcc, s8, v0
	v_mul_f32_e32 v162, v161, v160
	v_mul_f32_e32 v163, v158, v162
	v_fma_f32 v164, v162, v158, -v163
	v_fmac_f32_e32 v164, v162, v155
	v_add_f32_e32 v165, v163, v164
	v_sub_f32_e32 v166, v161, v165
	v_sub_f32_e32 v161, v161, v166
	v_sub_f32_e32 v163, v165, v163
	v_sub_f32_e32 v161, v161, v165
	v_add_f32_e32 v159, v159, v161
	v_sub_f32_e32 v161, v163, v164
	v_add_f32_e32 v159, v161, v159
	v_add_f32_e32 v161, v166, v159
	v_mul_f32_e32 v163, v160, v161
	v_mul_f32_e32 v164, v158, v163
	v_fma_f32 v158, v163, v158, -v164
	v_fmac_f32_e32 v158, v163, v155
	v_sub_f32_e32 v155, v166, v161
	v_add_f32_e32 v155, v159, v155
	v_add_f32_e32 v159, v164, v158
	v_sub_f32_e32 v165, v161, v159
	v_sub_f32_e32 v161, v161, v165
	v_sub_f32_e32 v164, v159, v164
	v_sub_f32_e32 v159, v161, v159
	v_add_f32_e32 v155, v155, v159
	v_sub_f32_e32 v158, v164, v158
	v_add_f32_e32 v155, v158, v155
	v_add_f32_e32 v158, v162, v163
	v_add_f32_e32 v155, v165, v155
	v_sub_f32_e32 v159, v158, v162
	v_mul_f32_e32 v155, v160, v155
	v_sub_f32_e32 v159, v163, v159
	v_add_f32_e32 v155, v159, v155
	v_mul_f32_e32 v162, 0x3f317218, v154
	v_add_f32_e32 v159, v158, v155
	v_fma_f32 v163, v154, s7, -v162
	v_mul_f32_e32 v160, v159, v159
	v_fmac_f32_e32 v163, 0xb102e308, v154
	v_sub_f32_e32 v154, v159, v158
	v_fmamk_f32 v161, v160, 0x3e9b6dac, v214
	v_sub_f32_e32 v154, v155, v154
	v_add_f32_e32 v155, v162, v163
	v_fmaak_f32 v161, v160, v161, 0x3f2aaada
	v_sub_f32_e32 v158, v155, v162
	v_ldexp_f32 v162, v159, 1
	v_mul_f32_e32 v159, v159, v160
	v_mul_f32_e32 v159, v159, v161
	v_add_f32_e32 v160, v162, v159
	v_sub_f32_e32 v161, v160, v162
	v_ldexp_f32 v154, v154, 1
	v_sub_f32_e32 v159, v159, v161
	v_add_f32_e32 v154, v154, v159
	v_add_f32_e32 v159, v160, v154
	v_sub_f32_e32 v160, v159, v160
	v_sub_f32_e32 v154, v154, v160
;     __device__ __forceinline__ void operator()(const AccT& acc, const pg8::Unit& u, int wr, int wc, int fr, int fq) const {
;     ...
;                     } else if (wc == 1 && fq == 0) {
; #pragma unroll
;                         for (int n = 0; n < 2; ++n)
; #pragma unroll
;                             for (int j = 0; j < 4; ++j) {
;                                 const float x = acc[ai][0][m][n][j] * rs + bfg[4 * n + j];
;                                 lf[(4 * n + j) * MROWS + row] = fminf(x, 0.f) - log1pf(__expf(-fabsf(x)));
;                             }
	v_add_f32_e32 v160, v155, v159
	v_sub_f32_e32 v161, v160, v155
	v_sub_f32_e32 v162, v160, v161
	v_sub_f32_e32 v158, v163, v158
	v_sub_f32_e32 v155, v155, v162
	v_sub_f32_e32 v159, v159, v161
	v_add_f32_e32 v155, v159, v155
	v_add_f32_e32 v159, v158, v154
	v_sub_f32_e32 v161, v159, v158
	v_sub_f32_e32 v162, v159, v161
	v_sub_f32_e32 v158, v158, v162
	v_sub_f32_e32 v154, v154, v161
	v_add_f32_e32 v155, v159, v155
	v_add_f32_e32 v154, v154, v158
	v_add_f32_e32 v158, v160, v155
	v_sub_f32_e32 v159, v158, v160
	v_sub_f32_e32 v155, v155, v159
	v_add_f32_e32 v154, v154, v155
	v_add_f32_e32 v154, v158, v154
	v_cndmask_b32_e32 v154, v221, v154, vcc
	v_cmp_ngt_f32_e32 vcc, -1.0, v0
	s_nop 1
	v_cndmask_b32_e32 v154, v222, v154, vcc
	v_cmp_neq_f32_e32 vcc, -1.0, v0
	s_nop 1
	v_cndmask_b32_e32 v154, v219, v154, vcc
	v_cmp_lt_f32_e64 vcc, |v0|, s9
	s_nop 1
	v_cndmask_b32_e32 v0, v154, v0, vcc
	v_add_co_u32_e32 v154, vcc, s2, v152
	v_sub_f32_e32 v0, v151, v0
	s_nop 0
	v_addc_co_u32_e32 v155, vcc, 0, v153, vcc
	global_store_dword v[154:155], v0, off
	s_mov_b32 s2, 0x29000
	v_add_f32_e32 v0, v123, v245
	v_min_f32_e32 v151, 0, v0
	v_mul_f32_e64 v0, |v0|, s3
	v_exp_f32_e32 v0, v0
	s_nop 0
	v_add_f32_e32 v158, 1.0, v0
	v_add_f32_e32 v154, -1.0, v158
	v_sub_f32_e32 v155, v154, v158
	v_add_f32_e32 v155, 1.0, v155
	v_sub_f32_e32 v154, v0, v154
	v_add_f32_e32 v159, v154, v155
	v_frexp_mant_f32_e32 v154, v158
	v_cmp_gt_f32_e32 vcc, s6, v154
	v_cvt_f64_f32_e32 v[154:155], v158
	v_frexp_exp_i32_f64_e32 v154, v[154:155]
	v_subbrev_co_u32_e32 v154, vcc, 0, v154, vcc
	v_sub_u32_e32 v155, 0, v154
	v_ldexp_f32 v158, v158, v155
	v_ldexp_f32 v155, v159, v155
	v_add_f32_e32 v159, -1.0, v158
	v_add_f32_e32 v160, 1.0, v159
	v_sub_f32_e32 v160, v158, v160
	v_add_f32_e32 v160, v155, v160
	v_add_f32_e32 v161, v159, v160
	v_sub_f32_e32 v159, v161, v159
	v_sub_f32_e32 v159, v160, v159
	v_add_f32_e32 v160, 1.0, v158
	v_add_f32_e32 v162, -1.0, v160
	v_sub_f32_e32 v158, v158, v162
	v_add_f32_e32 v155, v155, v158
	v_add_f32_e32 v158, v160, v155
	v_sub_f32_e32 v160, v158, v160
	v_sub_f32_e32 v155, v155, v160
	v_rcp_f32_e32 v160, v158
	v_cvt_f32_i32_e32 v154, v154
	v_cmp_neq_f32_e32 vcc, s8, v0
	v_mul_f32_e32 v162, v161, v160
	v_mul_f32_e32 v163, v158, v162
	v_fma_f32 v164, v162, v158, -v163
	v_fmac_f32_e32 v164, v162, v155
	v_add_f32_e32 v165, v163, v164
	v_sub_f32_e32 v166, v161, v165
	v_sub_f32_e32 v161, v161, v166
	v_sub_f32_e32 v163, v165, v163
	v_sub_f32_e32 v161, v161, v165
	v_add_f32_e32 v159, v159, v161
	v_sub_f32_e32 v161, v163, v164
	v_add_f32_e32 v159, v161, v159
	v_add_f32_e32 v161, v166, v159
	v_mul_f32_e32 v163, v160, v161
	v_mul_f32_e32 v164, v158, v163
	v_fma_f32 v158, v163, v158, -v164
	v_fmac_f32_e32 v158, v163, v155
	v_sub_f32_e32 v155, v166, v161
	v_add_f32_e32 v155, v159, v155
	v_add_f32_e32 v159, v164, v158
	v_sub_f32_e32 v165, v161, v159
	v_sub_f32_e32 v161, v161, v165
	v_sub_f32_e32 v164, v159, v164
	v_sub_f32_e32 v159, v161, v159
	v_add_f32_e32 v155, v155, v159
	v_sub_f32_e32 v158, v164, v158
	v_add_f32_e32 v155, v158, v155
	v_add_f32_e32 v158, v162, v163
	v_add_f32_e32 v155, v165, v155
	v_sub_f32_e32 v159, v158, v162
	v_mul_f32_e32 v155, v160, v155
	v_sub_f32_e32 v159, v163, v159
	v_add_f32_e32 v155, v159, v155
	v_mul_f32_e32 v162, 0x3f317218, v154
	v_add_f32_e32 v159, v158, v155
	v_fma_f32 v163, v154, s7, -v162
	v_mul_f32_e32 v160, v159, v159
	v_fmac_f32_e32 v163, 0xb102e308, v154
	v_sub_f32_e32 v154, v159, v158
	v_fmamk_f32 v161, v160, 0x3e9b6dac, v214
	v_sub_f32_e32 v154, v155, v154
	v_add_f32_e32 v155, v162, v163
	v_fmaak_f32 v161, v160, v161, 0x3f2aaada
	v_sub_f32_e32 v158, v155, v162
	v_ldexp_f32 v162, v159, 1
	v_mul_f32_e32 v159, v159, v160
	v_mul_f32_e32 v159, v159, v161
	v_add_f32_e32 v160, v162, v159
	v_sub_f32_e32 v161, v160, v162
	v_ldexp_f32 v154, v154, 1
	v_sub_f32_e32 v159, v159, v161
	v_add_f32_e32 v154, v154, v159
	v_add_f32_e32 v159, v160, v154
	v_sub_f32_e32 v160, v159, v160
	v_sub_f32_e32 v154, v154, v160
	v_add_f32_e32 v160, v155, v159
	v_sub_f32_e32 v161, v160, v155
	v_sub_f32_e32 v162, v160, v161
	v_sub_f32_e32 v158, v163, v158
	v_sub_f32_e32 v155, v155, v162
	v_sub_f32_e32 v159, v159, v161
	v_add_f32_e32 v155, v159, v155
	v_add_f32_e32 v159, v158, v154
	v_sub_f32_e32 v161, v159, v158
	v_sub_f32_e32 v162, v159, v161
	v_sub_f32_e32 v158, v158, v162
	v_sub_f32_e32 v154, v154, v161
	v_add_f32_e32 v155, v159, v155
	v_add_f32_e32 v154, v154, v158
	v_add_f32_e32 v158, v160, v155
	v_sub_f32_e32 v159, v158, v160
	v_sub_f32_e32 v155, v155, v159
	v_add_f32_e32 v154, v154, v155
	v_add_f32_e32 v154, v158, v154
	v_cndmask_b32_e32 v154, v221, v154, vcc
	v_cmp_ngt_f32_e32 vcc, -1.0, v0
	s_nop 1
	v_cndmask_b32_e32 v154, v222, v154, vcc
	v_cmp_neq_f32_e32 vcc, -1.0, v0
	s_nop 1
	v_cndmask_b32_e32 v154, v219, v154, vcc
	v_cmp_lt_f32_e64 vcc, |v0|, s9
	s_nop 1
	v_cndmask_b32_e32 v0, v154, v0, vcc
	v_add_co_u32_e32 v154, vcc, s2, v152
	v_sub_f32_e32 v0, v151, v0
	s_nop 0
	v_addc_co_u32_e32 v155, vcc, 0, v153, vcc
	global_store_dword v[154:155], v0, off offset:1024
	s_mov_b32 s2, 0x31000
	v_add_f32_e32 v0, v124, v246
	v_min_f32_e32 v151, 0, v0
	v_mul_f32_e64 v0, |v0|, s3
	v_exp_f32_e32 v0, v0
	s_nop 0
	v_add_f32_e32 v158, 1.0, v0
	v_add_f32_e32 v154, -1.0, v158
	v_sub_f32_e32 v155, v154, v158
	v_add_f32_e32 v155, 1.0, v155
	v_sub_f32_e32 v154, v0, v154
	v_add_f32_e32 v159, v154, v155
	v_frexp_mant_f32_e32 v154, v158
	v_cmp_gt_f32_e32 vcc, s6, v154
	v_cvt_f64_f32_e32 v[154:155], v158
	v_frexp_exp_i32_f64_e32 v154, v[154:155]
	v_subbrev_co_u32_e32 v154, vcc, 0, v154, vcc
	v_sub_u32_e32 v155, 0, v154
	v_ldexp_f32 v158, v158, v155
	v_ldexp_f32 v155, v159, v155
;     __device__ __forceinline__ void operator()(const AccT& acc, const pg8::Unit& u, int wr, int wc, int fr, int fq) const {
;     ...
;                     } else if (wc == 1 && fq == 0) {
; #pragma unroll
;                         for (int n = 0; n < 2; ++n)
; #pragma unroll
;                             for (int j = 0; j < 4; ++j) {
;                                 const float x = acc[ai][0][m][n][j] * rs + bfg[4 * n + j];
;                                 lf[(4 * n + j) * MROWS + row] = fminf(x, 0.f) - log1pf(__expf(-fabsf(x)));
;                             }
	v_add_f32_e32 v159, -1.0, v158
	v_add_f32_e32 v160, 1.0, v159
	v_sub_f32_e32 v160, v158, v160
	v_add_f32_e32 v160, v155, v160
	v_add_f32_e32 v161, v159, v160
	v_sub_f32_e32 v159, v161, v159
	v_sub_f32_e32 v159, v160, v159
	v_add_f32_e32 v160, 1.0, v158
	v_add_f32_e32 v162, -1.0, v160
	v_sub_f32_e32 v158, v158, v162
	v_add_f32_e32 v155, v155, v158
	v_add_f32_e32 v158, v160, v155
	v_sub_f32_e32 v160, v158, v160
	v_sub_f32_e32 v155, v155, v160
	v_rcp_f32_e32 v160, v158
	v_cvt_f32_i32_e32 v154, v154
	v_cmp_neq_f32_e32 vcc, s8, v0
	v_mul_f32_e32 v162, v161, v160
	v_mul_f32_e32 v163, v158, v162
	v_fma_f32 v164, v162, v158, -v163
	v_fmac_f32_e32 v164, v162, v155
	v_add_f32_e32 v165, v163, v164
	v_sub_f32_e32 v166, v161, v165
	v_sub_f32_e32 v161, v161, v166
	v_sub_f32_e32 v163, v165, v163
	v_sub_f32_e32 v161, v161, v165
	v_add_f32_e32 v159, v159, v161
	v_sub_f32_e32 v161, v163, v164
	v_add_f32_e32 v159, v161, v159
	v_add_f32_e32 v161, v166, v159
	v_mul_f32_e32 v163, v160, v161
	v_mul_f32_e32 v164, v158, v163
	v_fma_f32 v158, v163, v158, -v164
	v_fmac_f32_e32 v158, v163, v155
	v_sub_f32_e32 v155, v166, v161
	v_add_f32_e32 v155, v159, v155
	v_add_f32_e32 v159, v164, v158
	v_sub_f32_e32 v165, v161, v159
	v_sub_f32_e32 v161, v161, v165
	v_sub_f32_e32 v164, v159, v164
	v_sub_f32_e32 v159, v161, v159
	v_add_f32_e32 v155, v155, v159
	v_sub_f32_e32 v158, v164, v158
	v_add_f32_e32 v155, v158, v155
	v_add_f32_e32 v158, v162, v163
	v_add_f32_e32 v155, v165, v155
	v_sub_f32_e32 v159, v158, v162
	v_mul_f32_e32 v155, v160, v155
	v_sub_f32_e32 v159, v163, v159
	v_add_f32_e32 v155, v159, v155
	v_mul_f32_e32 v162, 0x3f317218, v154
	v_add_f32_e32 v159, v158, v155
	v_fma_f32 v163, v154, s7, -v162
	v_mul_f32_e32 v160, v159, v159
	v_fmac_f32_e32 v163, 0xb102e308, v154
	v_sub_f32_e32 v154, v159, v158
	v_fmamk_f32 v161, v160, 0x3e9b6dac, v214
	v_sub_f32_e32 v154, v155, v154
	v_add_f32_e32 v155, v162, v163
	v_fmaak_f32 v161, v160, v161, 0x3f2aaada
	v_sub_f32_e32 v158, v155, v162
	v_ldexp_f32 v162, v159, 1
	v_mul_f32_e32 v159, v159, v160
	v_mul_f32_e32 v159, v159, v161
	v_add_f32_e32 v160, v162, v159
	v_sub_f32_e32 v161, v160, v162
	v_ldexp_f32 v154, v154, 1
	v_sub_f32_e32 v159, v159, v161
	v_add_f32_e32 v154, v154, v159
	v_add_f32_e32 v159, v160, v154
	v_sub_f32_e32 v160, v159, v160
	v_sub_f32_e32 v154, v154, v160
	v_add_f32_e32 v160, v155, v159
	v_sub_f32_e32 v161, v160, v155
	v_sub_f32_e32 v162, v160, v161
	v_sub_f32_e32 v158, v163, v158
	v_sub_f32_e32 v155, v155, v162
	v_sub_f32_e32 v159, v159, v161
	v_add_f32_e32 v155, v159, v155
	v_add_f32_e32 v159, v158, v154
	v_sub_f32_e32 v161, v159, v158
	v_sub_f32_e32 v162, v159, v161
	v_sub_f32_e32 v158, v158, v162
	v_sub_f32_e32 v154, v154, v161
	v_add_f32_e32 v155, v159, v155
	v_add_f32_e32 v154, v154, v158
	v_add_f32_e32 v158, v160, v155
	v_sub_f32_e32 v159, v158, v160
	v_sub_f32_e32 v155, v155, v159
	v_add_f32_e32 v154, v154, v155
	v_add_f32_e32 v154, v158, v154
	v_cndmask_b32_e32 v154, v221, v154, vcc
	v_cmp_ngt_f32_e32 vcc, -1.0, v0
	s_nop 1
	v_cndmask_b32_e32 v154, v222, v154, vcc
	v_cmp_neq_f32_e32 vcc, -1.0, v0
	s_nop 1
	v_cndmask_b32_e32 v154, v219, v154, vcc
	v_cmp_lt_f32_e64 vcc, |v0|, s9
	s_nop 1
	v_cndmask_b32_e32 v0, v154, v0, vcc
	v_add_co_u32_e32 v154, vcc, s2, v152
	v_sub_f32_e32 v0, v151, v0
	s_nop 0
	v_addc_co_u32_e32 v155, vcc, 0, v153, vcc
	global_store_dword v[154:155], v0, off offset:2048
	v_add_f32_e32 v0, v125, v247
	v_min_f32_e32 v151, 0, v0
	v_mul_f32_e64 v0, |v0|, s3
	v_exp_f32_e32 v0, v0
	s_nop 0
	v_add_f32_e32 v158, 1.0, v0
	v_add_f32_e32 v154, -1.0, v158
	v_sub_f32_e32 v155, v154, v158
	v_add_f32_e32 v155, 1.0, v155
	v_sub_f32_e32 v154, v0, v154
	v_add_f32_e32 v159, v154, v155
;     __device__ __forceinline__ void operator()(const AccT& acc, const pg8::Unit& u, int wr, int wc, int fr, int fq) const {
;     ...
;                                 lf[(4 * n + j) * MROWS + row] = fminf(x, 0.f) - log1pf(__expf(-fabsf(x)));
	v_frexp_mant_f32_e32 v154, v158
	v_cmp_gt_f32_e32 vcc, s6, v154
	v_cvt_f64_f32_e32 v[154:155], v158
	v_frexp_exp_i32_f64_e32 v154, v[154:155]
	v_subbrev_co_u32_e32 v154, vcc, 0, v154, vcc
	v_sub_u32_e32 v155, 0, v154
	v_ldexp_f32 v158, v158, v155
	v_ldexp_f32 v155, v159, v155
	v_add_f32_e32 v159, -1.0, v158
	v_add_f32_e32 v160, 1.0, v159
	v_sub_f32_e32 v160, v158, v160
	v_add_f32_e32 v160, v155, v160
	v_add_f32_e32 v161, v159, v160
	v_sub_f32_e32 v159, v161, v159
	v_sub_f32_e32 v159, v160, v159
	v_add_f32_e32 v160, 1.0, v158
	v_add_f32_e32 v162, -1.0, v160
	v_sub_f32_e32 v158, v158, v162
	v_add_f32_e32 v155, v155, v158
	v_add_f32_e32 v158, v160, v155
	v_sub_f32_e32 v160, v158, v160
	v_sub_f32_e32 v155, v155, v160
	v_rcp_f32_e32 v160, v158
	v_cvt_f32_i32_e32 v154, v154
	v_cmp_neq_f32_e32 vcc, s8, v0
	v_mul_f32_e32 v162, v161, v160
	v_mul_f32_e32 v163, v158, v162
	v_fma_f32 v164, v162, v158, -v163
	v_fmac_f32_e32 v164, v162, v155
	v_add_f32_e32 v165, v163, v164
	v_sub_f32_e32 v166, v161, v165
	v_sub_f32_e32 v161, v161, v166
	v_sub_f32_e32 v163, v165, v163
	v_sub_f32_e32 v161, v161, v165
	v_add_f32_e32 v159, v159, v161
	v_sub_f32_e32 v161, v163, v164
	v_add_f32_e32 v159, v161, v159
	v_add_f32_e32 v161, v166, v159
	v_mul_f32_e32 v163, v160, v161
	v_mul_f32_e32 v164, v158, v163
	v_fma_f32 v158, v163, v158, -v164
	v_fmac_f32_e32 v158, v163, v155
	v_sub_f32_e32 v155, v166, v161
	v_add_f32_e32 v155, v159, v155
	v_add_f32_e32 v159, v164, v158
	v_sub_f32_e32 v165, v161, v159
	v_sub_f32_e32 v161, v161, v165
	v_sub_f32_e32 v164, v159, v164
	v_sub_f32_e32 v159, v161, v159
	v_add_f32_e32 v155, v155, v159
	v_sub_f32_e32 v158, v164, v158
	v_add_f32_e32 v155, v158, v155
	v_add_f32_e32 v158, v162, v163
	v_add_f32_e32 v155, v165, v155
	v_sub_f32_e32 v159, v158, v162
	v_mul_f32_e32 v155, v160, v155
	v_sub_f32_e32 v159, v163, v159
	v_add_f32_e32 v155, v159, v155
	v_mul_f32_e32 v162, 0x3f317218, v154
	v_add_f32_e32 v159, v158, v155
	v_fma_f32 v163, v154, s7, -v162
	v_mul_f32_e32 v160, v159, v159
	v_fmac_f32_e32 v163, 0xb102e308, v154
	v_sub_f32_e32 v154, v159, v158
	v_fmamk_f32 v161, v160, 0x3e9b6dac, v214
	v_sub_f32_e32 v154, v155, v154
	v_add_f32_e32 v155, v162, v163
	v_fmaak_f32 v161, v160, v161, 0x3f2aaada
	v_sub_f32_e32 v158, v155, v162
	v_ldexp_f32 v162, v159, 1
	v_mul_f32_e32 v159, v159, v160
	v_mul_f32_e32 v159, v159, v161
	v_add_f32_e32 v160, v162, v159
	v_sub_f32_e32 v161, v160, v162
	v_ldexp_f32 v154, v154, 1
	v_sub_f32_e32 v159, v159, v161
	v_add_f32_e32 v154, v154, v159
	v_add_f32_e32 v159, v160, v154
	v_sub_f32_e32 v160, v159, v160
	v_sub_f32_e32 v154, v154, v160
	v_add_f32_e32 v160, v155, v159
	v_sub_f32_e32 v161, v160, v155
	v_sub_f32_e32 v162, v160, v161
	v_sub_f32_e32 v158, v163, v158
	v_sub_f32_e32 v155, v155, v162
	v_sub_f32_e32 v159, v159, v161
	v_add_f32_e32 v155, v159, v155
	v_add_f32_e32 v159, v158, v154
	v_sub_f32_e32 v161, v159, v158
	v_sub_f32_e32 v162, v159, v161
	v_sub_f32_e32 v158, v158, v162
	v_sub_f32_e32 v154, v154, v161
	v_add_f32_e32 v155, v159, v155
	v_add_f32_e32 v154, v154, v158
	v_add_f32_e32 v158, v160, v155
	v_sub_f32_e32 v159, v158, v160
	v_sub_f32_e32 v155, v155, v159
	v_add_f32_e32 v154, v154, v155
	v_add_f32_e32 v154, v158, v154
	v_cndmask_b32_e32 v154, v221, v154, vcc
	v_cmp_ngt_f32_e32 vcc, -1.0, v0
	s_nop 1
	v_cndmask_b32_e32 v154, v222, v154, vcc
	v_cmp_neq_f32_e32 vcc, -1.0, v0
	s_nop 1
	v_cndmask_b32_e32 v154, v219, v154, vcc
	v_cmp_lt_f32_e64 vcc, |v0|, s9
	s_nop 1
	v_cndmask_b32_e32 v0, v154, v0, vcc
	v_add_co_u32_e32 v152, vcc, 0x39000, v152
	v_sub_f32_e32 v0, v151, v0
	s_nop 0
	v_addc_co_u32_e32 v153, vcc, 0, v153, vcc
	global_store_dword v[152:153], v0, off offset:3072

;     __device__ __forceinline__ void operator()(const AccT& acc, const pg8::Unit& u, int wr, int wc, int fr, int fq) const {
;     ...
;             for (int m = 0; m < 4; ++m) {
;                 const int row = row0 + ai * 128 + m * 16;
;                 const float rs = 1.0f;
;                 if (u.pn < 20) {
;     ...
;                     } else if (wc == 1 && fq == 0) {
; #pragma unroll
;                         for (int n = 0; n < 2; ++n)
; #pragma unroll
;                             for (int j = 0; j < 4; ++j) {
;                                 const float x = acc[ai][0][m][n][j] * rs + bfg[4 * n + j];
;                                 lf[(4 * n + j) * MROWS + row] = fminf(x, 0.f) - log1pf(__expf(-fabsf(x)));
;                             }
.LBB0_959:
	s_waitcnt lgkmcnt(0)
	v_cndmask_b32_e64 v115, 0, 1, s[42:43]
	v_cmp_ne_u32_e64 s[44:45], 1, v115
	v_cndmask_b32_e64 v115, 0, 1, s[56:57]
	v_or_b32_e32 v114, 16, v150
	s_mov_b64 s[8:9], -1
	s_andn2_b64 vcc, exec, s[42:43]
	v_cmp_ne_u32_e64 s[42:43], 1, v115
	s_cbranch_vccnz .LBB0_967
	s_and_b64 vcc, exec, s[42:43]
	s_cbranch_vccnz .LBB0_964
	s_and_saveexec_b64 s[70:71], s[58:59]
	s_cbranch_execz .LBB0_963
	s_mov_b32 s3, 0xbfb8aa3b
	s_mov_b32 s6, 0x3f2aaaab
	s_mov_b32 s7, 0x3f317218
	s_mov_b32 s8, 0x7f800000
	s_mov_b32 s9, 0x33800000
	v_ashrrev_i32_e32 v151, 31, v150
	s_mov_b32 s2, 0x8000
	v_add_f32_e32 v115, v110, v240
	v_min_f32_e32 v118, 0, v115
	v_mul_f32_e64 v115, |v115|, s3
	v_exp_f32_e32 v115, v115
	s_nop 0
	v_add_f32_e32 v119, 1.0, v115
	v_add_f32_e32 v116, -1.0, v119
	v_sub_f32_e32 v117, v116, v119
	v_add_f32_e32 v117, 1.0, v117
	v_sub_f32_e32 v116, v115, v116
	v_add_f32_e32 v120, v116, v117
	v_frexp_mant_f32_e32 v116, v119
	v_cmp_gt_f32_e32 vcc, s6, v116
	v_cvt_f64_f32_e32 v[116:117], v119
	v_frexp_exp_i32_f64_e32 v116, v[116:117]
	v_subbrev_co_u32_e32 v116, vcc, 0, v116, vcc
	v_sub_u32_e32 v117, 0, v116
	v_ldexp_f32 v119, v119, v117
	v_ldexp_f32 v117, v120, v117
	v_add_f32_e32 v120, -1.0, v119
	v_add_f32_e32 v121, 1.0, v120
	v_sub_f32_e32 v121, v119, v121
	v_add_f32_e32 v121, v117, v121
	v_add_f32_e32 v122, v120, v121
	v_sub_f32_e32 v120, v122, v120
	v_sub_f32_e32 v120, v121, v120
	v_add_f32_e32 v121, 1.0, v119
	v_add_f32_e32 v123, -1.0, v121
	v_sub_f32_e32 v119, v119, v123
	v_add_f32_e32 v117, v117, v119
	v_add_f32_e32 v119, v121, v117
	v_sub_f32_e32 v121, v119, v121
	v_sub_f32_e32 v117, v117, v121
	v_rcp_f32_e32 v121, v119
	v_cvt_f32_i32_e32 v116, v116
	v_cmp_neq_f32_e32 vcc, s8, v115
	v_mul_f32_e32 v123, v122, v121
	v_mul_f32_e32 v124, v119, v123
	v_fma_f32 v125, v123, v119, -v124
	v_fmac_f32_e32 v125, v123, v117
	v_add_f32_e32 v126, v124, v125
	v_sub_f32_e32 v127, v122, v126
	v_sub_f32_e32 v122, v122, v127
	v_sub_f32_e32 v124, v126, v124
	v_sub_f32_e32 v122, v122, v126
	v_add_f32_e32 v120, v120, v122
	v_sub_f32_e32 v122, v124, v125
	v_add_f32_e32 v120, v122, v120
	v_add_f32_e32 v122, v127, v120
	v_mul_f32_e32 v124, v121, v122
	v_mul_f32_e32 v125, v119, v124
	v_fma_f32 v119, v124, v119, -v125
	v_fmac_f32_e32 v119, v124, v117
	v_sub_f32_e32 v117, v127, v122
	v_add_f32_e32 v117, v120, v117
	v_add_f32_e32 v120, v125, v119
	v_sub_f32_e32 v126, v122, v120
	v_sub_f32_e32 v122, v122, v126
	v_sub_f32_e32 v125, v120, v125
	v_sub_f32_e32 v120, v122, v120
	v_add_f32_e32 v117, v117, v120
	v_sub_f32_e32 v119, v125, v119
	v_add_f32_e32 v117, v119, v117
	v_add_f32_e32 v119, v123, v124
	v_add_f32_e32 v117, v126, v117
	v_sub_f32_e32 v120, v119, v123
	v_mul_f32_e32 v117, v121, v117
	v_sub_f32_e32 v120, v124, v120
	v_add_f32_e32 v117, v120, v117
	v_mul_f32_e32 v123, 0x3f317218, v116
	v_add_f32_e32 v120, v119, v117
	v_fma_f32 v124, v116, s7, -v123
	v_mul_f32_e32 v121, v120, v120
	v_fmac_f32_e32 v124, 0xb102e308, v116
	v_sub_f32_e32 v116, v120, v119
	v_fmamk_f32 v122, v121, 0x3e9b6dac, v214
	v_sub_f32_e32 v116, v117, v116
	v_add_f32_e32 v117, v123, v124
	v_fmaak_f32 v122, v121, v122, 0x3f2aaada
	v_sub_f32_e32 v119, v117, v123
	v_ldexp_f32 v123, v120, 1
	v_mul_f32_e32 v120, v120, v121
	v_mul_f32_e32 v120, v120, v122
	v_add_f32_e32 v121, v123, v120
	v_sub_f32_e32 v122, v121, v123
	v_ldexp_f32 v116, v116, 1
	v_sub_f32_e32 v120, v120, v122
	v_add_f32_e32 v116, v116, v120
	v_add_f32_e32 v120, v121, v116
	v_sub_f32_e32 v121, v120, v121
	v_sub_f32_e32 v116, v116, v121
	v_add_f32_e32 v121, v117, v120
	v_sub_f32_e32 v122, v121, v117
	v_sub_f32_e32 v123, v121, v122
	v_sub_f32_e32 v119, v124, v119
	v_sub_f32_e32 v117, v117, v123
	v_sub_f32_e32 v120, v120, v122
	v_add_f32_e32 v117, v120, v117
	v_add_f32_e32 v120, v119, v116
	v_sub_f32_e32 v122, v120, v119
	v_sub_f32_e32 v123, v120, v122
	v_sub_f32_e32 v119, v119, v123
	v_sub_f32_e32 v116, v116, v122
	v_add_f32_e32 v117, v120, v117
	v_add_f32_e32 v116, v116, v119
	v_add_f32_e32 v119, v121, v117
	v_sub_f32_e32 v120, v119, v121
	v_sub_f32_e32 v117, v117, v120
	v_add_f32_e32 v116, v116, v117
	v_add_f32_e32 v116, v119, v116
	v_cndmask_b32_e32 v116, v221, v116, vcc
	v_cmp_ngt_f32_e32 vcc, -1.0, v115
	s_nop 1
	v_cndmask_b32_e32 v116, v222, v116, vcc
	v_cmp_neq_f32_e32 vcc, -1.0, v115
	s_nop 1
	v_cndmask_b32_e32 v116, v219, v116, vcc
	v_cmp_lt_f32_e64 vcc, |v115|, s9
	s_nop 1
	v_cndmask_b32_e32 v115, v116, v115, vcc
	v_sub_f32_e32 v118, v118, v115
	v_ashrrev_i32_e32 v115, 31, v114
	v_lshl_add_u64 v[116:117], v[114:115], 2, s[52:53]
	global_store_dword v[116:117], v118, off
	v_add_f32_e32 v115, v111, v241
	v_min_f32_e32 v118, 0, v115
	v_mul_f32_e64 v115, |v115|, s3
	v_exp_f32_e32 v115, v115
	s_nop 0
	v_add_f32_e32 v119, 1.0, v115
	v_add_f32_e32 v116, -1.0, v119
	v_sub_f32_e32 v117, v116, v119
	v_add_f32_e32 v117, 1.0, v117
	v_sub_f32_e32 v116, v115, v116
	v_add_f32_e32 v120, v116, v117
	v_frexp_mant_f32_e32 v116, v119
	v_cmp_gt_f32_e32 vcc, s6, v116
	v_cvt_f64_f32_e32 v[116:117], v119
	v_frexp_exp_i32_f64_e32 v116, v[116:117]
	v_subbrev_co_u32_e32 v116, vcc, 0, v116, vcc
	v_sub_u32_e32 v117, 0, v116
	v_ldexp_f32 v119, v119, v117
	v_ldexp_f32 v117, v120, v117
	v_add_f32_e32 v120, -1.0, v119
	v_add_f32_e32 v121, 1.0, v120
	v_sub_f32_e32 v121, v119, v121
	v_add_f32_e32 v121, v117, v121
	v_add_f32_e32 v122, v120, v121
	v_sub_f32_e32 v120, v122, v120
	v_sub_f32_e32 v120, v121, v120
	v_add_f32_e32 v121, 1.0, v119
	v_add_f32_e32 v123, -1.0, v121
	v_sub_f32_e32 v119, v119, v123
	v_add_f32_e32 v117, v117, v119
	v_add_f32_e32 v119, v121, v117
	v_sub_f32_e32 v121, v119, v121
	v_sub_f32_e32 v117, v117, v121
;     __device__ __forceinline__ void operator()(const AccT& acc, const pg8::Unit& u, int wr, int wc, int fr, int fq) const {
;     ...
;                                 lf[(4 * n + j) * MROWS + row] = fminf(x, 0.f) - log1pf(__expf(-fabsf(x)));
;                             }
	v_rcp_f32_e32 v121, v119
	v_cvt_f32_i32_e32 v116, v116
	v_cmp_neq_f32_e32 vcc, s8, v115
	v_mul_f32_e32 v123, v122, v121
	v_mul_f32_e32 v124, v119, v123
	v_fma_f32 v125, v123, v119, -v124
	v_fmac_f32_e32 v125, v123, v117
	v_add_f32_e32 v126, v124, v125
	v_sub_f32_e32 v127, v122, v126
	v_sub_f32_e32 v122, v122, v127
	v_sub_f32_e32 v124, v126, v124
	v_sub_f32_e32 v122, v122, v126
	v_add_f32_e32 v120, v120, v122
	v_sub_f32_e32 v122, v124, v125
	v_add_f32_e32 v120, v122, v120
	v_add_f32_e32 v122, v127, v120
	v_mul_f32_e32 v124, v121, v122
	v_mul_f32_e32 v125, v119, v124
	v_fma_f32 v119, v124, v119, -v125
	v_fmac_f32_e32 v119, v124, v117
	v_sub_f32_e32 v117, v127, v122
	v_add_f32_e32 v117, v120, v117
	v_add_f32_e32 v120, v125, v119
	v_sub_f32_e32 v126, v122, v120
	v_sub_f32_e32 v122, v122, v126
	v_sub_f32_e32 v125, v120, v125
	v_sub_f32_e32 v120, v122, v120
	v_add_f32_e32 v117, v117, v120
	v_sub_f32_e32 v119, v125, v119
	v_add_f32_e32 v117, v119, v117
	v_add_f32_e32 v119, v123, v124
	v_add_f32_e32 v117, v126, v117
	v_sub_f32_e32 v120, v119, v123
	v_mul_f32_e32 v117, v121, v117
	v_sub_f32_e32 v120, v124, v120
	v_add_f32_e32 v117, v120, v117
	v_mul_f32_e32 v123, 0x3f317218, v116
	v_add_f32_e32 v120, v119, v117
	v_fma_f32 v124, v116, s7, -v123
	v_mul_f32_e32 v121, v120, v120
	v_fmac_f32_e32 v124, 0xb102e308, v116
	v_sub_f32_e32 v116, v120, v119
	v_fmamk_f32 v122, v121, 0x3e9b6dac, v214
	v_sub_f32_e32 v116, v117, v116
	v_add_f32_e32 v117, v123, v124
	v_fmaak_f32 v122, v121, v122, 0x3f2aaada
	v_sub_f32_e32 v119, v117, v123
	v_ldexp_f32 v123, v120, 1
	v_mul_f32_e32 v120, v120, v121
	v_mul_f32_e32 v120, v120, v122
	v_add_f32_e32 v121, v123, v120
	v_sub_f32_e32 v122, v121, v123
	v_ldexp_f32 v116, v116, 1
	v_sub_f32_e32 v120, v120, v122
	v_add_f32_e32 v116, v116, v120
	v_add_f32_e32 v120, v121, v116
	v_sub_f32_e32 v121, v120, v121
	v_sub_f32_e32 v116, v116, v121
	v_add_f32_e32 v121, v117, v120
	v_sub_f32_e32 v122, v121, v117
	v_sub_f32_e32 v123, v121, v122
	v_sub_f32_e32 v119, v124, v119
	v_sub_f32_e32 v117, v117, v123
	v_sub_f32_e32 v120, v120, v122
	v_add_f32_e32 v117, v120, v117
	v_add_f32_e32 v120, v119, v116
	v_sub_f32_e32 v122, v120, v119
	v_sub_f32_e32 v123, v120, v122
	v_sub_f32_e32 v119, v119, v123
	v_sub_f32_e32 v116, v116, v122
	v_add_f32_e32 v117, v120, v117
	v_add_f32_e32 v116, v116, v119
	v_add_f32_e32 v119, v121, v117
	v_sub_f32_e32 v120, v119, v121
	v_sub_f32_e32 v117, v117, v120
	v_add_f32_e32 v116, v116, v117
	v_add_f32_e32 v116, v119, v116
	v_cndmask_b32_e32 v116, v221, v116, vcc
	v_cmp_ngt_f32_e32 vcc, -1.0, v115
	s_nop 1
	v_cndmask_b32_e32 v116, v222, v116, vcc
	v_cmp_neq_f32_e32 vcc, -1.0, v115
	s_nop 1
	v_cndmask_b32_e32 v116, v219, v116, vcc
	v_cmp_lt_f32_e64 vcc, |v115|, s9
	s_nop 1
	v_cndmask_b32_e32 v115, v116, v115, vcc
	v_lshl_add_u64 v[116:117], v[150:151], 2, s[52:53]
	v_sub_f32_e32 v115, v118, v115
	v_add_co_u32_e32 v118, vcc, s2, v116
	s_mov_b32 s2, 0x10000
	s_nop 0
	v_addc_co_u32_e32 v119, vcc, 0, v117, vcc
	global_store_dword v[118:119], v115, off offset:1088
	v_add_f32_e32 v115, v112, v242
	v_min_f32_e32 v120, 0, v115
	v_mul_f32_e64 v115, |v115|, s3
	v_exp_f32_e32 v115, v115
	s_nop 0
	v_add_f32_e32 v121, 1.0, v115
	v_add_f32_e32 v118, -1.0, v121
	v_sub_f32_e32 v119, v118, v121
	v_add_f32_e32 v119, 1.0, v119
	v_sub_f32_e32 v118, v115, v118
	v_add_f32_e32 v122, v118, v119
	v_frexp_mant_f32_e32 v118, v121
	v_cmp_gt_f32_e32 vcc, s6, v118
	v_cvt_f64_f32_e32 v[118:119], v121
	v_frexp_exp_i32_f64_e32 v118, v[118:119]
	v_subbrev_co_u32_e32 v118, vcc, 0, v118, vcc
	v_sub_u32_e32 v119, 0, v118
	v_ldexp_f32 v121, v121, v119
	v_ldexp_f32 v119, v122, v119
	v_add_f32_e32 v122, -1.0, v121
	v_add_f32_e32 v123, 1.0, v122
	v_sub_f32_e32 v123, v121, v123
	v_add_f32_e32 v123, v119, v123
	v_add_f32_e32 v124, v122, v123
	v_sub_f32_e32 v122, v124, v122
	v_sub_f32_e32 v122, v123, v122
	v_add_f32_e32 v123, 1.0, v121
	v_add_f32_e32 v125, -1.0, v123
	v_sub_f32_e32 v121, v121, v125
	v_add_f32_e32 v119, v119, v121
	v_add_f32_e32 v121, v123, v119
	v_sub_f32_e32 v123, v121, v123
	v_sub_f32_e32 v119, v119, v123
	v_rcp_f32_e32 v123, v121
	v_cvt_f32_i32_e32 v118, v118
	v_cmp_neq_f32_e32 vcc, s8, v115
	v_mul_f32_e32 v125, v124, v123
	v_mul_f32_e32 v126, v121, v125
	v_fma_f32 v127, v125, v121, -v126
	v_fmac_f32_e32 v127, v125, v119
	v_add_f32_e32 v128, v126, v127
	v_sub_f32_e32 v129, v124, v128
	v_sub_f32_e32 v124, v124, v129
	v_sub_f32_e32 v126, v128, v126
	v_sub_f32_e32 v124, v124, v128
	v_add_f32_e32 v122, v122, v124
	v_sub_f32_e32 v124, v126, v127
	v_add_f32_e32 v122, v124, v122
	v_add_f32_e32 v124, v129, v122
	v_mul_f32_e32 v126, v123, v124
	v_mul_f32_e32 v127, v121, v126
	v_fma_f32 v121, v126, v121, -v127
	v_fmac_f32_e32 v121, v126, v119
	v_sub_f32_e32 v119, v129, v124
	v_add_f32_e32 v119, v122, v119
	v_add_f32_e32 v122, v127, v121
	v_sub_f32_e32 v128, v124, v122
	v_sub_f32_e32 v124, v124, v128
	v_sub_f32_e32 v127, v122, v127
	v_sub_f32_e32 v122, v124, v122
	v_add_f32_e32 v119, v119, v122
	v_sub_f32_e32 v121, v127, v121
	v_add_f32_e32 v119, v121, v119
	v_add_f32_e32 v121, v125, v126
	v_add_f32_e32 v119, v128, v119
	v_sub_f32_e32 v122, v121, v125
	v_mul_f32_e32 v119, v123, v119
	v_sub_f32_e32 v122, v126, v122
	v_add_f32_e32 v119, v122, v119
	v_mul_f32_e32 v125, 0x3f317218, v118
	v_add_f32_e32 v122, v121, v119
	v_fma_f32 v126, v118, s7, -v125
	v_mul_f32_e32 v123, v122, v122
	v_fmac_f32_e32 v126, 0xb102e308, v118
	v_sub_f32_e32 v118, v122, v121
	v_fmamk_f32 v124, v123, 0x3e9b6dac, v214
	v_sub_f32_e32 v118, v119, v118
	v_add_f32_e32 v119, v125, v126
	v_fmaak_f32 v124, v123, v124, 0x3f2aaada
	v_sub_f32_e32 v121, v119, v125
	v_ldexp_f32 v125, v122, 1
;     __device__ __forceinline__ void operator()(const AccT& acc, const pg8::Unit& u, int wr, int wc, int fr, int fq) const {
;     ...
;                     } else if (wc == 1 && fq == 0) {
; #pragma unroll
;                         for (int n = 0; n < 2; ++n)
; #pragma unroll
;                             for (int j = 0; j < 4; ++j) {
;                                 const float x = acc[ai][0][m][n][j] * rs + bfg[4 * n + j];
;                                 lf[(4 * n + j) * MROWS + row] = fminf(x, 0.f) - log1pf(__expf(-fabsf(x)));
;                             }
	v_mul_f32_e32 v122, v122, v123
	v_mul_f32_e32 v122, v122, v124
	v_add_f32_e32 v123, v125, v122
	v_sub_f32_e32 v124, v123, v125
	v_ldexp_f32 v118, v118, 1
	v_sub_f32_e32 v122, v122, v124
	v_add_f32_e32 v118, v118, v122
	v_add_f32_e32 v122, v123, v118
	v_sub_f32_e32 v123, v122, v123
	v_sub_f32_e32 v118, v118, v123
	v_add_f32_e32 v123, v119, v122
	v_sub_f32_e32 v124, v123, v119
	v_sub_f32_e32 v125, v123, v124
	v_sub_f32_e32 v121, v126, v121
	v_sub_f32_e32 v119, v119, v125
	v_sub_f32_e32 v122, v122, v124
	v_add_f32_e32 v119, v122, v119
	v_add_f32_e32 v122, v121, v118
	v_sub_f32_e32 v124, v122, v121
	v_sub_f32_e32 v125, v122, v124
	v_sub_f32_e32 v121, v121, v125
	v_sub_f32_e32 v118, v118, v124
	v_add_f32_e32 v119, v122, v119
	v_add_f32_e32 v118, v118, v121
	v_add_f32_e32 v121, v123, v119
	v_sub_f32_e32 v122, v121, v123
	v_sub_f32_e32 v119, v119, v122
	v_add_f32_e32 v118, v118, v119
	v_add_f32_e32 v118, v121, v118
	v_cndmask_b32_e32 v118, v221, v118, vcc
	v_cmp_ngt_f32_e32 vcc, -1.0, v115
	s_nop 1
	v_cndmask_b32_e32 v118, v222, v118, vcc
	v_cmp_neq_f32_e32 vcc, -1.0, v115
	s_nop 1
	v_cndmask_b32_e32 v118, v219, v118, vcc
	v_cmp_lt_f32_e64 vcc, |v115|, s9
	s_nop 1
	v_cndmask_b32_e32 v115, v118, v115, vcc
	v_add_co_u32_e32 v118, vcc, s2, v116
	v_sub_f32_e32 v115, v120, v115
	s_nop 0
	v_addc_co_u32_e32 v119, vcc, 0, v117, vcc
	global_store_dword v[118:119], v115, off offset:2112
	s_mov_b32 s2, 0x18000
	v_add_f32_e32 v115, v113, v243
	v_min_f32_e32 v120, 0, v115
	v_mul_f32_e64 v115, |v115|, s3
	v_exp_f32_e32 v115, v115
	s_nop 0
	v_add_f32_e32 v121, 1.0, v115
	v_add_f32_e32 v118, -1.0, v121
	v_sub_f32_e32 v119, v118, v121
	v_add_f32_e32 v119, 1.0, v119
	v_sub_f32_e32 v118, v115, v118
	v_add_f32_e32 v122, v118, v119
	v_frexp_mant_f32_e32 v118, v121
	v_cmp_gt_f32_e32 vcc, s6, v118
	v_cvt_f64_f32_e32 v[118:119], v121
	v_frexp_exp_i32_f64_e32 v118, v[118:119]
	v_subbrev_co_u32_e32 v118, vcc, 0, v118, vcc
	v_sub_u32_e32 v119, 0, v118
	v_ldexp_f32 v121, v121, v119
	v_ldexp_f32 v119, v122, v119
	v_add_f32_e32 v122, -1.0, v121
	v_add_f32_e32 v123, 1.0, v122
	v_sub_f32_e32 v123, v121, v123
	v_add_f32_e32 v123, v119, v123
	v_add_f32_e32 v124, v122, v123
	v_sub_f32_e32 v122, v124, v122
	v_sub_f32_e32 v122, v123, v122
	v_add_f32_e32 v123, 1.0, v121
	v_add_f32_e32 v125, -1.0, v123
	v_sub_f32_e32 v121, v121, v125
	v_add_f32_e32 v119, v119, v121
	v_add_f32_e32 v121, v123, v119
	v_sub_f32_e32 v123, v121, v123
	v_sub_f32_e32 v119, v119, v123
	v_rcp_f32_e32 v123, v121
	v_cvt_f32_i32_e32 v118, v118
	v_cmp_neq_f32_e32 vcc, s8, v115
	v_mul_f32_e32 v125, v124, v123
	v_mul_f32_e32 v126, v121, v125
	v_fma_f32 v127, v125, v121, -v126
	v_fmac_f32_e32 v127, v125, v119
	v_add_f32_e32 v128, v126, v127
	v_sub_f32_e32 v129, v124, v128
	v_sub_f32_e32 v124, v124, v129
	v_sub_f32_e32 v126, v128, v126
	v_sub_f32_e32 v124, v124, v128
	v_add_f32_e32 v122, v122, v124
	v_sub_f32_e32 v124, v126, v127
	v_add_f32_e32 v122, v124, v122
	v_add_f32_e32 v124, v129, v122
	v_mul_f32_e32 v126, v123, v124
	v_mul_f32_e32 v127, v121, v126
	v_fma_f32 v121, v126, v121, -v127
	v_fmac_f32_e32 v121, v126, v119
	v_sub_f32_e32 v119, v129, v124
	v_add_f32_e32 v119, v122, v119
	v_add_f32_e32 v122, v127, v121
	v_sub_f32_e32 v128, v124, v122
	v_sub_f32_e32 v124, v124, v128
	v_sub_f32_e32 v127, v122, v127
	v_sub_f32_e32 v122, v124, v122
	v_add_f32_e32 v119, v119, v122
	v_sub_f32_e32 v121, v127, v121
	v_add_f32_e32 v119, v121, v119
	v_add_f32_e32 v121, v125, v126
	v_add_f32_e32 v119, v128, v119
	v_sub_f32_e32 v122, v121, v125
	v_mul_f32_e32 v119, v123, v119
	v_sub_f32_e32 v122, v126, v122
	v_add_f32_e32 v119, v122, v119
	v_mul_f32_e32 v125, 0x3f317218, v118
	v_add_f32_e32 v122, v121, v119
	v_fma_f32 v126, v118, s7, -v125
	v_mul_f32_e32 v123, v122, v122
	v_fmac_f32_e32 v126, 0xb102e308, v118
	v_sub_f32_e32 v118, v122, v121
	v_fmamk_f32 v124, v123, 0x3e9b6dac, v214
	v_sub_f32_e32 v118, v119, v118
	v_add_f32_e32 v119, v125, v126
	v_fmaak_f32 v124, v123, v124, 0x3f2aaada
	v_sub_f32_e32 v121, v119, v125
	v_ldexp_f32 v125, v122, 1
	v_mul_f32_e32 v122, v122, v123
	v_mul_f32_e32 v122, v122, v124
	v_add_f32_e32 v123, v125, v122
	v_sub_f32_e32 v124, v123, v125
	v_ldexp_f32 v118, v118, 1
	v_sub_f32_e32 v122, v122, v124
	v_add_f32_e32 v118, v118, v122
	v_add_f32_e32 v122, v123, v118
	v_sub_f32_e32 v123, v122, v123
	v_sub_f32_e32 v118, v118, v123
	v_add_f32_e32 v123, v119, v122
	v_sub_f32_e32 v124, v123, v119
	v_sub_f32_e32 v125, v123, v124
	v_sub_f32_e32 v121, v126, v121
	v_sub_f32_e32 v119, v119, v125
	v_sub_f32_e32 v122, v122, v124
	v_add_f32_e32 v119, v122, v119
	v_add_f32_e32 v122, v121, v118
	v_sub_f32_e32 v124, v122, v121
	v_sub_f32_e32 v125, v122, v124
	v_sub_f32_e32 v121, v121, v125
	v_sub_f32_e32 v118, v118, v124
	v_add_f32_e32 v119, v122, v119
	v_add_f32_e32 v118, v118, v121
	v_add_f32_e32 v121, v123, v119
	v_sub_f32_e32 v122, v121, v123
	v_sub_f32_e32 v119, v119, v122
	v_add_f32_e32 v118, v118, v119
	v_add_f32_e32 v118, v121, v118
	v_cndmask_b32_e32 v118, v221, v118, vcc
	v_cmp_ngt_f32_e32 vcc, -1.0, v115
	s_nop 1
	v_cndmask_b32_e32 v118, v222, v118, vcc
	v_cmp_neq_f32_e32 vcc, -1.0, v115
	s_nop 1
	v_cndmask_b32_e32 v118, v219, v118, vcc
	v_cmp_lt_f32_e64 vcc, |v115|, s9
	s_nop 1
	v_cndmask_b32_e32 v115, v118, v115, vcc
	v_add_co_u32_e32 v118, vcc, s2, v116
	v_sub_f32_e32 v115, v120, v115
	s_nop 0
	v_addc_co_u32_e32 v119, vcc, 0, v117, vcc
	global_store_dword v[118:119], v115, off offset:3136
	s_mov_b32 s2, 0x21000
	v_add_f32_e32 v115, v106, v244
	v_min_f32_e32 v120, 0, v115
	v_mul_f32_e64 v115, |v115|, s3
	v_exp_f32_e32 v115, v115
	s_nop 0
	v_add_f32_e32 v121, 1.0, v115
	v_add_f32_e32 v118, -1.0, v121
;     __device__ __forceinline__ void operator()(const AccT& acc, const pg8::Unit& u, int wr, int wc, int fr, int fq) const {
;     ...
;                     } else if (wc == 1 && fq == 0) {
; #pragma unroll
;                         for (int n = 0; n < 2; ++n)
; #pragma unroll
;                             for (int j = 0; j < 4; ++j) {
;                                 const float x = acc[ai][0][m][n][j] * rs + bfg[4 * n + j];
;                                 lf[(4 * n + j) * MROWS + row] = fminf(x, 0.f) - log1pf(__expf(-fabsf(x)));
;                             }
	v_sub_f32_e32 v119, v118, v121
	v_add_f32_e32 v119, 1.0, v119
	v_sub_f32_e32 v118, v115, v118
	v_add_f32_e32 v122, v118, v119
	v_frexp_mant_f32_e32 v118, v121
	v_cmp_gt_f32_e32 vcc, s6, v118
	v_cvt_f64_f32_e32 v[118:119], v121
	v_frexp_exp_i32_f64_e32 v118, v[118:119]
	v_subbrev_co_u32_e32 v118, vcc, 0, v118, vcc
	v_sub_u32_e32 v119, 0, v118
	v_ldexp_f32 v121, v121, v119
	v_ldexp_f32 v119, v122, v119
	v_add_f32_e32 v122, -1.0, v121
	v_add_f32_e32 v123, 1.0, v122
	v_sub_f32_e32 v123, v121, v123
	v_add_f32_e32 v123, v119, v123
	v_add_f32_e32 v124, v122, v123
	v_sub_f32_e32 v122, v124, v122
	v_sub_f32_e32 v122, v123, v122
	v_add_f32_e32 v123, 1.0, v121
	v_add_f32_e32 v125, -1.0, v123
	v_sub_f32_e32 v121, v121, v125
	v_add_f32_e32 v119, v119, v121
	v_add_f32_e32 v121, v123, v119
	v_sub_f32_e32 v123, v121, v123
	v_sub_f32_e32 v119, v119, v123
	v_rcp_f32_e32 v123, v121
	v_cvt_f32_i32_e32 v118, v118
	v_cmp_neq_f32_e32 vcc, s8, v115
	v_mul_f32_e32 v125, v124, v123
	v_mul_f32_e32 v126, v121, v125
	v_fma_f32 v127, v125, v121, -v126
	v_fmac_f32_e32 v127, v125, v119
	v_add_f32_e32 v128, v126, v127
	v_sub_f32_e32 v129, v124, v128
	v_sub_f32_e32 v124, v124, v129
	v_sub_f32_e32 v126, v128, v126
	v_sub_f32_e32 v124, v124, v128
	v_add_f32_e32 v122, v122, v124
	v_sub_f32_e32 v124, v126, v127
	v_add_f32_e32 v122, v124, v122
	v_add_f32_e32 v124, v129, v122
	v_mul_f32_e32 v126, v123, v124
	v_mul_f32_e32 v127, v121, v126
	v_fma_f32 v121, v126, v121, -v127
	v_fmac_f32_e32 v121, v126, v119
	v_sub_f32_e32 v119, v129, v124
	v_add_f32_e32 v119, v122, v119
	v_add_f32_e32 v122, v127, v121
	v_sub_f32_e32 v128, v124, v122
	v_sub_f32_e32 v124, v124, v128
	v_sub_f32_e32 v127, v122, v127
	v_sub_f32_e32 v122, v124, v122
	v_add_f32_e32 v119, v119, v122
	v_sub_f32_e32 v121, v127, v121
	v_add_f32_e32 v119, v121, v119
	v_add_f32_e32 v121, v125, v126
	v_add_f32_e32 v119, v128, v119
	v_sub_f32_e32 v122, v121, v125
	v_mul_f32_e32 v119, v123, v119
	v_sub_f32_e32 v122, v126, v122
	v_add_f32_e32 v119, v122, v119
	v_mul_f32_e32 v125, 0x3f317218, v118
	v_add_f32_e32 v122, v121, v119
	v_fma_f32 v126, v118, s7, -v125
	v_mul_f32_e32 v123, v122, v122
	v_fmac_f32_e32 v126, 0xb102e308, v118
	v_sub_f32_e32 v118, v122, v121
	v_fmamk_f32 v124, v123, 0x3e9b6dac, v214
	v_sub_f32_e32 v118, v119, v118
	v_add_f32_e32 v119, v125, v126
	v_fmaak_f32 v124, v123, v124, 0x3f2aaada
	v_sub_f32_e32 v121, v119, v125
	v_ldexp_f32 v125, v122, 1
	v_mul_f32_e32 v122, v122, v123
	v_mul_f32_e32 v122, v122, v124
	v_add_f32_e32 v123, v125, v122
	v_sub_f32_e32 v124, v123, v125
	v_ldexp_f32 v118, v118, 1
	v_sub_f32_e32 v122, v122, v124
	v_add_f32_e32 v118, v118, v122
	v_add_f32_e32 v122, v123, v118
	v_sub_f32_e32 v123, v122, v123
	v_sub_f32_e32 v118, v118, v123
	v_add_f32_e32 v123, v119, v122
	v_sub_f32_e32 v124, v123, v119
	v_sub_f32_e32 v125, v123, v124
	v_sub_f32_e32 v121, v126, v121
	v_sub_f32_e32 v119, v119, v125
	v_sub_f32_e32 v122, v122, v124
	v_add_f32_e32 v119, v122, v119
	v_add_f32_e32 v122, v121, v118
	v_sub_f32_e32 v124, v122, v121
	v_sub_f32_e32 v125, v122, v124
	v_sub_f32_e32 v121, v121, v125
	v_sub_f32_e32 v118, v118, v124
	v_add_f32_e32 v119, v122, v119
	v_add_f32_e32 v118, v118, v121
	v_add_f32_e32 v121, v123, v119
	v_sub_f32_e32 v122, v121, v123
	v_sub_f32_e32 v119, v119, v122
	v_add_f32_e32 v118, v118, v119
	v_add_f32_e32 v118, v121, v118
	v_cndmask_b32_e32 v118, v221, v118, vcc
	v_cmp_ngt_f32_e32 vcc, -1.0, v115
	s_nop 1
	v_cndmask_b32_e32 v118, v222, v118, vcc
	v_cmp_neq_f32_e32 vcc, -1.0, v115
	s_nop 1
	v_cndmask_b32_e32 v118, v219, v118, vcc
	v_cmp_lt_f32_e64 vcc, |v115|, s9
	s_nop 1
	v_cndmask_b32_e32 v115, v118, v115, vcc
	v_add_co_u32_e32 v118, vcc, s2, v116
	v_sub_f32_e32 v115, v120, v115
	s_nop 0
	v_addc_co_u32_e32 v119, vcc, 0, v117, vcc
	global_store_dword v[118:119], v115, off offset:64
	s_mov_b32 s2, 0x29000
	v_add_f32_e32 v115, v107, v245
	v_min_f32_e32 v120, 0, v115
	v_mul_f32_e64 v115, |v115|, s3
	v_exp_f32_e32 v115, v115
	s_nop 0
	v_add_f32_e32 v121, 1.0, v115
	v_add_f32_e32 v118, -1.0, v121
	v_sub_f32_e32 v119, v118, v121
	v_add_f32_e32 v119, 1.0, v119
	v_sub_f32_e32 v118, v115, v118
	v_add_f32_e32 v122, v118, v119
	v_frexp_mant_f32_e32 v118, v121
	v_cmp_gt_f32_e32 vcc, s6, v118
	v_cvt_f64_f32_e32 v[118:119], v121
	v_frexp_exp_i32_f64_e32 v118, v[118:119]
	v_subbrev_co_u32_e32 v118, vcc, 0, v118, vcc
	v_sub_u32_e32 v119, 0, v118
	v_ldexp_f32 v121, v121, v119
	v_ldexp_f32 v119, v122, v119
	v_add_f32_e32 v122, -1.0, v121
	v_add_f32_e32 v123, 1.0, v122
	v_sub_f32_e32 v123, v121, v123
	v_add_f32_e32 v123, v119, v123
	v_add_f32_e32 v124, v122, v123
	v_sub_f32_e32 v122, v124, v122
	v_sub_f32_e32 v122, v123, v122
	v_add_f32_e32 v123, 1.0, v121
	v_add_f32_e32 v125, -1.0, v123
	v_sub_f32_e32 v121, v121, v125
	v_add_f32_e32 v119, v119, v121
	v_add_f32_e32 v121, v123, v119
	v_sub_f32_e32 v123, v121, v123
	v_sub_f32_e32 v119, v119, v123
	v_rcp_f32_e32 v123, v121
	v_cvt_f32_i32_e32 v118, v118
	v_cmp_neq_f32_e32 vcc, s8, v115
	v_mul_f32_e32 v125, v124, v123
	v_mul_f32_e32 v126, v121, v125
	v_fma_f32 v127, v125, v121, -v126
	v_fmac_f32_e32 v127, v125, v119
	v_add_f32_e32 v128, v126, v127
	v_sub_f32_e32 v129, v124, v128
	v_sub_f32_e32 v124, v124, v129
	v_sub_f32_e32 v126, v128, v126
	v_sub_f32_e32 v124, v124, v128
	v_add_f32_e32 v122, v122, v124
	v_sub_f32_e32 v124, v126, v127
	v_add_f32_e32 v122, v124, v122
	v_add_f32_e32 v124, v129, v122
	v_mul_f32_e32 v126, v123, v124
	v_mul_f32_e32 v127, v121, v126
	v_fma_f32 v121, v126, v121, -v127
	v_fmac_f32_e32 v121, v126, v119
	v_sub_f32_e32 v119, v129, v124
	v_add_f32_e32 v119, v122, v119
	v_add_f32_e32 v122, v127, v121
	v_sub_f32_e32 v128, v124, v122
;     __device__ __forceinline__ void operator()(const AccT& acc, const pg8::Unit& u, int wr, int wc, int fr, int fq) const {
;     ...
;                     } else if (wc == 1 && fq == 0) {
; #pragma unroll
;                         for (int n = 0; n < 2; ++n)
; #pragma unroll
;                             for (int j = 0; j < 4; ++j) {
;                                 const float x = acc[ai][0][m][n][j] * rs + bfg[4 * n + j];
;                                 lf[(4 * n + j) * MROWS + row] = fminf(x, 0.f) - log1pf(__expf(-fabsf(x)));
;                             }
	v_sub_f32_e32 v124, v124, v128
	v_sub_f32_e32 v127, v122, v127
	v_sub_f32_e32 v122, v124, v122
	v_add_f32_e32 v119, v119, v122
	v_sub_f32_e32 v121, v127, v121
	v_add_f32_e32 v119, v121, v119
	v_add_f32_e32 v121, v125, v126
	v_add_f32_e32 v119, v128, v119
	v_sub_f32_e32 v122, v121, v125
	v_mul_f32_e32 v119, v123, v119
	v_sub_f32_e32 v122, v126, v122
	v_add_f32_e32 v119, v122, v119
	v_mul_f32_e32 v125, 0x3f317218, v118
	v_add_f32_e32 v122, v121, v119
	v_fma_f32 v126, v118, s7, -v125
	v_mul_f32_e32 v123, v122, v122
	v_fmac_f32_e32 v126, 0xb102e308, v118
	v_sub_f32_e32 v118, v122, v121
	v_fmamk_f32 v124, v123, 0x3e9b6dac, v214
	v_sub_f32_e32 v118, v119, v118
	v_add_f32_e32 v119, v125, v126
	v_fmaak_f32 v124, v123, v124, 0x3f2aaada
	v_sub_f32_e32 v121, v119, v125
	v_ldexp_f32 v125, v122, 1
	v_mul_f32_e32 v122, v122, v123
	v_mul_f32_e32 v122, v122, v124
	v_add_f32_e32 v123, v125, v122
	v_sub_f32_e32 v124, v123, v125
	v_ldexp_f32 v118, v118, 1
	v_sub_f32_e32 v122, v122, v124
	v_add_f32_e32 v118, v118, v122
	v_add_f32_e32 v122, v123, v118
	v_sub_f32_e32 v123, v122, v123
	v_sub_f32_e32 v118, v118, v123
	v_add_f32_e32 v123, v119, v122
	v_sub_f32_e32 v124, v123, v119
	v_sub_f32_e32 v125, v123, v124
	v_sub_f32_e32 v121, v126, v121
	v_sub_f32_e32 v119, v119, v125
	v_sub_f32_e32 v122, v122, v124
	v_add_f32_e32 v119, v122, v119
	v_add_f32_e32 v122, v121, v118
	v_sub_f32_e32 v124, v122, v121
	v_sub_f32_e32 v125, v122, v124
	v_sub_f32_e32 v121, v121, v125
	v_sub_f32_e32 v118, v118, v124
	v_add_f32_e32 v119, v122, v119
	v_add_f32_e32 v118, v118, v121
	v_add_f32_e32 v121, v123, v119
	v_sub_f32_e32 v122, v121, v123
	v_sub_f32_e32 v119, v119, v122
	v_add_f32_e32 v118, v118, v119
	v_add_f32_e32 v118, v121, v118
	v_cndmask_b32_e32 v118, v221, v118, vcc
	v_cmp_ngt_f32_e32 vcc, -1.0, v115
	s_nop 1
	v_cndmask_b32_e32 v118, v222, v118, vcc
	v_cmp_neq_f32_e32 vcc, -1.0, v115
	s_nop 1
	v_cndmask_b32_e32 v118, v219, v118, vcc
	v_cmp_lt_f32_e64 vcc, |v115|, s9
	s_nop 1
	v_cndmask_b32_e32 v115, v118, v115, vcc
	v_add_co_u32_e32 v118, vcc, s2, v116
	v_sub_f32_e32 v115, v120, v115
	s_nop 0
	v_addc_co_u32_e32 v119, vcc, 0, v117, vcc
	global_store_dword v[118:119], v115, off offset:1088
	s_mov_b32 s2, 0x31000
	v_add_f32_e32 v115, v108, v246
	v_min_f32_e32 v120, 0, v115
	v_mul_f32_e64 v115, |v115|, s3
	v_exp_f32_e32 v115, v115
	s_nop 0
	v_add_f32_e32 v121, 1.0, v115
	v_add_f32_e32 v118, -1.0, v121
	v_sub_f32_e32 v119, v118, v121
	v_add_f32_e32 v119, 1.0, v119
	v_sub_f32_e32 v118, v115, v118
	v_add_f32_e32 v122, v118, v119
	v_frexp_mant_f32_e32 v118, v121
	v_cmp_gt_f32_e32 vcc, s6, v118
	v_cvt_f64_f32_e32 v[118:119], v121
	v_frexp_exp_i32_f64_e32 v118, v[118:119]
	v_subbrev_co_u32_e32 v118, vcc, 0, v118, vcc
	v_sub_u32_e32 v119, 0, v118
	v_ldexp_f32 v121, v121, v119
	v_ldexp_f32 v119, v122, v119
	v_add_f32_e32 v122, -1.0, v121
	v_add_f32_e32 v123, 1.0, v122
	v_sub_f32_e32 v123, v121, v123
	v_add_f32_e32 v123, v119, v123
	v_add_f32_e32 v124, v122, v123
	v_sub_f32_e32 v122, v124, v122
	v_sub_f32_e32 v122, v123, v122
	v_add_f32_e32 v123, 1.0, v121
	v_add_f32_e32 v125, -1.0, v123
	v_sub_f32_e32 v121, v121, v125
	v_add_f32_e32 v119, v119, v121
	v_add_f32_e32 v121, v123, v119
	v_sub_f32_e32 v123, v121, v123
	v_sub_f32_e32 v119, v119, v123
	v_rcp_f32_e32 v123, v121
	v_cvt_f32_i32_e32 v118, v118
	v_cmp_neq_f32_e32 vcc, s8, v115
	v_mul_f32_e32 v125, v124, v123
	v_mul_f32_e32 v126, v121, v125
	v_fma_f32 v127, v125, v121, -v126
	v_fmac_f32_e32 v127, v125, v119
	v_add_f32_e32 v128, v126, v127
	v_sub_f32_e32 v129, v124, v128
	v_sub_f32_e32 v124, v124, v129
	v_sub_f32_e32 v126, v128, v126
	v_sub_f32_e32 v124, v124, v128
	v_add_f32_e32 v122, v122, v124
	v_sub_f32_e32 v124, v126, v127
	v_add_f32_e32 v122, v124, v122
	v_add_f32_e32 v124, v129, v122
	v_mul_f32_e32 v126, v123, v124
	v_mul_f32_e32 v127, v121, v126
	v_fma_f32 v121, v126, v121, -v127
	v_fmac_f32_e32 v121, v126, v119
	v_sub_f32_e32 v119, v129, v124
	v_add_f32_e32 v119, v122, v119
	v_add_f32_e32 v122, v127, v121
	v_sub_f32_e32 v128, v124, v122
	v_sub_f32_e32 v124, v124, v128
	v_sub_f32_e32 v127, v122, v127
	v_sub_f32_e32 v122, v124, v122
	v_add_f32_e32 v119, v119, v122
	v_sub_f32_e32 v121, v127, v121
	v_add_f32_e32 v119, v121, v119
	v_add_f32_e32 v121, v125, v126
	v_add_f32_e32 v119, v128, v119
	v_sub_f32_e32 v122, v121, v125
	v_mul_f32_e32 v119, v123, v119
	v_sub_f32_e32 v122, v126, v122
	v_add_f32_e32 v119, v122, v119
	v_mul_f32_e32 v125, 0x3f317218, v118
	v_add_f32_e32 v122, v121, v119
	v_fma_f32 v126, v118, s7, -v125
	v_mul_f32_e32 v123, v122, v122
	v_fmac_f32_e32 v126, 0xb102e308, v118
	v_sub_f32_e32 v118, v122, v121
	v_fmamk_f32 v124, v123, 0x3e9b6dac, v214
	v_sub_f32_e32 v118, v119, v118
	v_add_f32_e32 v119, v125, v126
	v_fmaak_f32 v124, v123, v124, 0x3f2aaada
	v_sub_f32_e32 v121, v119, v125
	v_ldexp_f32 v125, v122, 1
	v_mul_f32_e32 v122, v122, v123
	v_mul_f32_e32 v122, v122, v124
	v_add_f32_e32 v123, v125, v122
	v_sub_f32_e32 v124, v123, v125
	v_ldexp_f32 v118, v118, 1
	v_sub_f32_e32 v122, v122, v124
	v_add_f32_e32 v118, v118, v122
	v_add_f32_e32 v122, v123, v118
	v_sub_f32_e32 v123, v122, v123
;     __device__ __forceinline__ void operator()(const AccT& acc, const pg8::Unit& u, int wr, int wc, int fr, int fq) const {
;     ...
;                     } else if (wc == 1 && fq == 0) {
; #pragma unroll
;                         for (int n = 0; n < 2; ++n)
; #pragma unroll
;                             for (int j = 0; j < 4; ++j) {
;                                 const float x = acc[ai][0][m][n][j] * rs + bfg[4 * n + j];
;                                 lf[(4 * n + j) * MROWS + row] = fminf(x, 0.f) - log1pf(__expf(-fabsf(x)));
;                             }
	v_sub_f32_e32 v118, v118, v123
	v_add_f32_e32 v123, v119, v122
	v_sub_f32_e32 v124, v123, v119
	v_sub_f32_e32 v125, v123, v124
	v_sub_f32_e32 v121, v126, v121
	v_sub_f32_e32 v119, v119, v125
	v_sub_f32_e32 v122, v122, v124
	v_add_f32_e32 v119, v122, v119
	v_add_f32_e32 v122, v121, v118
	v_sub_f32_e32 v124, v122, v121
	v_sub_f32_e32 v125, v122, v124
	v_sub_f32_e32 v121, v121, v125
	v_sub_f32_e32 v118, v118, v124
	v_add_f32_e32 v119, v122, v119
	v_add_f32_e32 v118, v118, v121
	v_add_f32_e32 v121, v123, v119
	v_sub_f32_e32 v122, v121, v123
	v_sub_f32_e32 v119, v119, v122
	v_add_f32_e32 v118, v118, v119
	v_add_f32_e32 v118, v121, v118
	v_cndmask_b32_e32 v118, v221, v118, vcc
	v_cmp_ngt_f32_e32 vcc, -1.0, v115
	s_nop 1
	v_cndmask_b32_e32 v118, v222, v118, vcc
	v_cmp_neq_f32_e32 vcc, -1.0, v115
	s_nop 1
	v_cndmask_b32_e32 v118, v219, v118, vcc
	v_cmp_lt_f32_e64 vcc, |v115|, s9
	s_nop 1
	v_cndmask_b32_e32 v115, v118, v115, vcc
	v_add_co_u32_e32 v118, vcc, s2, v116
	v_sub_f32_e32 v115, v120, v115
	s_nop 0
	v_addc_co_u32_e32 v119, vcc, 0, v117, vcc
	global_store_dword v[118:119], v115, off offset:2112
	v_add_f32_e32 v115, v109, v247
	v_min_f32_e32 v120, 0, v115
	v_mul_f32_e64 v115, |v115|, s3
	v_exp_f32_e32 v115, v115
	s_nop 0
	v_add_f32_e32 v121, 1.0, v115
	v_add_f32_e32 v118, -1.0, v121
	v_sub_f32_e32 v119, v118, v121
	v_add_f32_e32 v119, 1.0, v119
	v_sub_f32_e32 v118, v115, v118
	v_add_f32_e32 v122, v118, v119
	v_frexp_mant_f32_e32 v118, v121
	v_cmp_gt_f32_e32 vcc, s6, v118
	v_cvt_f64_f32_e32 v[118:119], v121
	v_frexp_exp_i32_f64_e32 v118, v[118:119]
	v_subbrev_co_u32_e32 v118, vcc, 0, v118, vcc
	v_sub_u32_e32 v119, 0, v118
	v_ldexp_f32 v121, v121, v119
	v_ldexp_f32 v119, v122, v119
	v_add_f32_e32 v122, -1.0, v121
	v_add_f32_e32 v123, 1.0, v122
	v_sub_f32_e32 v123, v121, v123
	v_add_f32_e32 v123, v119, v123
	v_add_f32_e32 v124, v122, v123
	v_sub_f32_e32 v122, v124, v122
	v_sub_f32_e32 v122, v123, v122
	v_add_f32_e32 v123, 1.0, v121
	v_add_f32_e32 v125, -1.0, v123
	v_sub_f32_e32 v121, v121, v125
	v_add_f32_e32 v119, v119, v121
	v_add_f32_e32 v121, v123, v119
	v_sub_f32_e32 v123, v121, v123
	v_sub_f32_e32 v119, v119, v123
	v_rcp_f32_e32 v123, v121
	v_cvt_f32_i32_e32 v118, v118
	v_cmp_neq_f32_e32 vcc, s8, v115
	v_mul_f32_e32 v125, v124, v123
	v_mul_f32_e32 v126, v121, v125
	v_fma_f32 v127, v125, v121, -v126
	v_fmac_f32_e32 v127, v125, v119
	v_add_f32_e32 v128, v126, v127
	v_sub_f32_e32 v129, v124, v128
	v_sub_f32_e32 v124, v124, v129
	v_sub_f32_e32 v126, v128, v126
	v_sub_f32_e32 v124, v124, v128
	v_add_f32_e32 v122, v122, v124
	v_sub_f32_e32 v124, v126, v127
	v_add_f32_e32 v122, v124, v122
	v_add_f32_e32 v124, v129, v122
	v_mul_f32_e32 v126, v123, v124
	v_mul_f32_e32 v127, v121, v126
	v_fma_f32 v121, v126, v121, -v127
	v_fmac_f32_e32 v121, v126, v119
	v_sub_f32_e32 v119, v129, v124
	v_add_f32_e32 v119, v122, v119
	v_add_f32_e32 v122, v127, v121
	v_sub_f32_e32 v128, v124, v122
	v_sub_f32_e32 v124, v124, v128
	v_sub_f32_e32 v127, v122, v127
	v_sub_f32_e32 v122, v124, v122
	v_add_f32_e32 v119, v119, v122
	v_sub_f32_e32 v121, v127, v121
	v_add_f32_e32 v119, v121, v119
	v_add_f32_e32 v121, v125, v126
	v_add_f32_e32 v119, v128, v119
	v_sub_f32_e32 v122, v121, v125
	v_mul_f32_e32 v119, v123, v119
	v_sub_f32_e32 v122, v126, v122
	v_add_f32_e32 v119, v122, v119
	v_mul_f32_e32 v125, 0x3f317218, v118
	v_add_f32_e32 v122, v121, v119
	v_fma_f32 v126, v118, s7, -v125
	v_mul_f32_e32 v123, v122, v122
	v_fmac_f32_e32 v126, 0xb102e308, v118
	v_sub_f32_e32 v118, v122, v121
	v_fmamk_f32 v124, v123, 0x3e9b6dac, v214
	v_sub_f32_e32 v118, v119, v118
	v_add_f32_e32 v119, v125, v126
	v_fmaak_f32 v124, v123, v124, 0x3f2aaada
	v_sub_f32_e32 v121, v119, v125
	v_ldexp_f32 v125, v122, 1
	v_mul_f32_e32 v122, v122, v123
	v_mul_f32_e32 v122, v122, v124
	v_add_f32_e32 v123, v125, v122
	v_sub_f32_e32 v124, v123, v125
	v_ldexp_f32 v118, v118, 1
	v_sub_f32_e32 v122, v122, v124
	v_add_f32_e32 v118, v118, v122
	v_add_f32_e32 v122, v123, v118
	v_sub_f32_e32 v123, v122, v123
	v_sub_f32_e32 v118, v118, v123
	v_add_f32_e32 v123, v119, v122
	v_sub_f32_e32 v124, v123, v119
	v_sub_f32_e32 v125, v123, v124
	v_sub_f32_e32 v121, v126, v121
	v_sub_f32_e32 v119, v119, v125
	v_sub_f32_e32 v122, v122, v124
	v_add_f32_e32 v119, v122, v119
	v_add_f32_e32 v122, v121, v118
	v_sub_f32_e32 v124, v122, v121
	v_sub_f32_e32 v125, v122, v124
	v_sub_f32_e32 v121, v121, v125
	v_sub_f32_e32 v118, v118, v124
	v_add_f32_e32 v119, v122, v119
	v_add_f32_e32 v118, v118, v121
	v_add_f32_e32 v121, v123, v119
	v_sub_f32_e32 v122, v121, v123
	v_sub_f32_e32 v119, v119, v122
	v_add_f32_e32 v118, v118, v119
	v_add_f32_e32 v118, v121, v118
	v_cndmask_b32_e32 v118, v221, v118, vcc
	v_cmp_ngt_f32_e32 vcc, -1.0, v115
	s_nop 1
	v_cndmask_b32_e32 v118, v222, v118, vcc
	v_cmp_neq_f32_e32 vcc, -1.0, v115
	s_nop 1
	v_cndmask_b32_e32 v118, v219, v118, vcc
	v_cmp_lt_f32_e64 vcc, |v115|, s9
	s_nop 1
	v_cndmask_b32_e32 v115, v118, v115, vcc
	v_add_co_u32_e32 v116, vcc, 0x39000, v116
	v_sub_f32_e32 v115, v120, v115
	s_nop 0
	v_addc_co_u32_e32 v117, vcc, 0, v117, vcc
	global_store_dword v[116:117], v115, off offset:3136

;     __device__ __forceinline__ void operator()(const AccT& acc, const pg8::Unit& u, int wr, int wc, int fr, int fq) const {
;     ...
;             for (int m = 0; m < 4; ++m) {
;                 const int row = row0 + ai * 128 + m * 16;
;                 const float rs = 1.0f;
;                 if (u.pn < 20) {
;     ...
;                     } else if (wc == 1 && fq == 0) {
; #pragma unroll
;                         for (int n = 0; n < 2; ++n)
; #pragma unroll
;                             for (int j = 0; j < 4; ++j) {
;                                 const float x = acc[ai][0][m][n][j] * rs + bfg[4 * n + j];
;                                 lf[(4 * n + j) * MROWS + row] = fminf(x, 0.f) - log1pf(__expf(-fabsf(x)));
;                             }
.LBB0_972:
	v_or_b32_e32 v98, 32, v150
	s_and_b64 vcc, exec, s[44:45]
	s_mov_b64 s[8:9], -1
	s_cbranch_vccnz .LBB0_980
	s_and_b64 vcc, exec, s[42:43]
	s_cbranch_vccnz .LBB0_977
	s_and_saveexec_b64 s[70:71], s[58:59]
	s_cbranch_execz .LBB0_976
	s_waitcnt lgkmcnt(0)
	s_mov_b32 s3, 0xbfb8aa3b
	s_mov_b32 s6, 0x3f2aaaab
	s_mov_b32 s7, 0x3f317218
	s_mov_b32 s8, 0x7f800000
	s_mov_b32 s9, 0x33800000
	v_ashrrev_i32_e32 v151, 31, v150
	s_mov_b32 s2, 0x8000
	v_add_f32_e32 v99, v94, v240
	v_min_f32_e32 v102, 0, v99
	v_mul_f32_e64 v99, |v99|, s3
	v_exp_f32_e32 v99, v99
	s_nop 0
	v_add_f32_e32 v103, 1.0, v99
	v_add_f32_e32 v100, -1.0, v103
	v_sub_f32_e32 v101, v100, v103
	v_add_f32_e32 v101, 1.0, v101
	v_sub_f32_e32 v100, v99, v100
	v_add_f32_e32 v104, v100, v101
	v_frexp_mant_f32_e32 v100, v103
	v_cmp_gt_f32_e32 vcc, s6, v100
	v_cvt_f64_f32_e32 v[100:101], v103
	v_frexp_exp_i32_f64_e32 v100, v[100:101]
	v_subbrev_co_u32_e32 v100, vcc, 0, v100, vcc
	v_sub_u32_e32 v101, 0, v100
	v_ldexp_f32 v103, v103, v101
	v_ldexp_f32 v101, v104, v101
	v_add_f32_e32 v104, -1.0, v103
	v_add_f32_e32 v105, 1.0, v104
	v_sub_f32_e32 v105, v103, v105
	v_add_f32_e32 v105, v101, v105
	v_add_f32_e32 v106, v104, v105
	v_sub_f32_e32 v104, v106, v104
	v_sub_f32_e32 v104, v105, v104
	v_add_f32_e32 v105, 1.0, v103
	v_add_f32_e32 v107, -1.0, v105
	v_sub_f32_e32 v103, v103, v107
	v_add_f32_e32 v101, v101, v103
	v_add_f32_e32 v103, v105, v101
	v_sub_f32_e32 v105, v103, v105
	v_sub_f32_e32 v101, v101, v105
	v_rcp_f32_e32 v105, v103
	v_cvt_f32_i32_e32 v100, v100
	v_cmp_neq_f32_e32 vcc, s8, v99
	v_mul_f32_e32 v107, v106, v105
	v_mul_f32_e32 v108, v103, v107
	v_fma_f32 v109, v107, v103, -v108
	v_fmac_f32_e32 v109, v107, v101
	v_add_f32_e32 v110, v108, v109
	v_sub_f32_e32 v111, v106, v110
	v_sub_f32_e32 v106, v106, v111
	v_sub_f32_e32 v108, v110, v108
	v_sub_f32_e32 v106, v106, v110
	v_add_f32_e32 v104, v104, v106
	v_sub_f32_e32 v106, v108, v109
	v_add_f32_e32 v104, v106, v104
	v_add_f32_e32 v106, v111, v104
	v_mul_f32_e32 v108, v105, v106
	v_mul_f32_e32 v109, v103, v108
	v_fma_f32 v103, v108, v103, -v109
	v_fmac_f32_e32 v103, v108, v101
	v_sub_f32_e32 v101, v111, v106
	v_add_f32_e32 v101, v104, v101
	v_add_f32_e32 v104, v109, v103
	v_sub_f32_e32 v110, v106, v104
	v_sub_f32_e32 v106, v106, v110
	v_sub_f32_e32 v109, v104, v109
	v_sub_f32_e32 v104, v106, v104
	v_add_f32_e32 v101, v101, v104
	v_sub_f32_e32 v103, v109, v103
	v_add_f32_e32 v101, v103, v101
	v_add_f32_e32 v103, v107, v108
	v_add_f32_e32 v101, v110, v101
	v_sub_f32_e32 v104, v103, v107
	v_mul_f32_e32 v101, v105, v101
	v_sub_f32_e32 v104, v108, v104
	v_add_f32_e32 v101, v104, v101
	v_mul_f32_e32 v107, 0x3f317218, v100
	v_add_f32_e32 v104, v103, v101
	v_fma_f32 v108, v100, s7, -v107
	v_mul_f32_e32 v105, v104, v104
	v_fmac_f32_e32 v108, 0xb102e308, v100
	v_sub_f32_e32 v100, v104, v103
	v_fmamk_f32 v106, v105, 0x3e9b6dac, v214
	v_sub_f32_e32 v100, v101, v100
	v_add_f32_e32 v101, v107, v108
	v_fmaak_f32 v106, v105, v106, 0x3f2aaada
	v_sub_f32_e32 v103, v101, v107
	v_ldexp_f32 v107, v104, 1
	v_mul_f32_e32 v104, v104, v105
	v_mul_f32_e32 v104, v104, v106
	v_add_f32_e32 v105, v107, v104
	v_sub_f32_e32 v106, v105, v107
	v_ldexp_f32 v100, v100, 1
	v_sub_f32_e32 v104, v104, v106
	v_add_f32_e32 v100, v100, v104
	v_add_f32_e32 v104, v105, v100
	v_sub_f32_e32 v105, v104, v105
	v_sub_f32_e32 v100, v100, v105
	v_add_f32_e32 v105, v101, v104
	v_sub_f32_e32 v106, v105, v101
	v_sub_f32_e32 v107, v105, v106
	v_sub_f32_e32 v103, v108, v103
	v_sub_f32_e32 v101, v101, v107
	v_sub_f32_e32 v104, v104, v106
	v_add_f32_e32 v101, v104, v101
	v_add_f32_e32 v104, v103, v100
	v_sub_f32_e32 v106, v104, v103
	v_sub_f32_e32 v107, v104, v106
	v_sub_f32_e32 v103, v103, v107
	v_sub_f32_e32 v100, v100, v106
	v_add_f32_e32 v101, v104, v101
	v_add_f32_e32 v100, v100, v103
	v_add_f32_e32 v103, v105, v101
	v_sub_f32_e32 v104, v103, v105
	v_sub_f32_e32 v101, v101, v104
	v_add_f32_e32 v100, v100, v101
	v_add_f32_e32 v100, v103, v100
	v_cndmask_b32_e32 v100, v221, v100, vcc
	v_cmp_ngt_f32_e32 vcc, -1.0, v99
	s_nop 1
	v_cndmask_b32_e32 v100, v222, v100, vcc
	v_cmp_neq_f32_e32 vcc, -1.0, v99
	s_nop 1
	v_cndmask_b32_e32 v100, v219, v100, vcc
	v_cmp_lt_f32_e64 vcc, |v99|, s9
	s_nop 1
	v_cndmask_b32_e32 v99, v100, v99, vcc
	v_sub_f32_e32 v102, v102, v99
	v_ashrrev_i32_e32 v99, 31, v98
	v_lshl_add_u64 v[100:101], v[98:99], 2, s[52:53]
	global_store_dword v[100:101], v102, off
	v_add_f32_e32 v99, v95, v241
	v_min_f32_e32 v102, 0, v99
	v_mul_f32_e64 v99, |v99|, s3
	v_exp_f32_e32 v99, v99
	s_nop 0
	v_add_f32_e32 v103, 1.0, v99
	v_add_f32_e32 v100, -1.0, v103
	v_sub_f32_e32 v101, v100, v103
	v_add_f32_e32 v101, 1.0, v101
	v_sub_f32_e32 v100, v99, v100
	v_add_f32_e32 v104, v100, v101
	v_frexp_mant_f32_e32 v100, v103
	v_cmp_gt_f32_e32 vcc, s6, v100
	v_cvt_f64_f32_e32 v[100:101], v103
	v_frexp_exp_i32_f64_e32 v100, v[100:101]
	v_subbrev_co_u32_e32 v100, vcc, 0, v100, vcc
	v_sub_u32_e32 v101, 0, v100
	v_ldexp_f32 v103, v103, v101
	v_ldexp_f32 v101, v104, v101
	v_add_f32_e32 v104, -1.0, v103
	v_add_f32_e32 v105, 1.0, v104
	v_sub_f32_e32 v105, v103, v105
	v_add_f32_e32 v105, v101, v105
	v_add_f32_e32 v106, v104, v105
	v_sub_f32_e32 v104, v106, v104
	v_sub_f32_e32 v104, v105, v104
	v_add_f32_e32 v105, 1.0, v103
	v_add_f32_e32 v107, -1.0, v105
	v_sub_f32_e32 v103, v103, v107
	v_add_f32_e32 v101, v101, v103
	v_add_f32_e32 v103, v105, v101
	v_sub_f32_e32 v105, v103, v105
	v_sub_f32_e32 v101, v101, v105
	v_rcp_f32_e32 v105, v103
	v_cvt_f32_i32_e32 v100, v100
	v_cmp_neq_f32_e32 vcc, s8, v99
	v_mul_f32_e32 v107, v106, v105
	v_mul_f32_e32 v108, v103, v107
	v_fma_f32 v109, v107, v103, -v108
;     __device__ __forceinline__ void operator()(const AccT& acc, const pg8::Unit& u, int wr, int wc, int fr, int fq) const {
;     ...
;                                 lf[(4 * n + j) * MROWS + row] = fminf(x, 0.f) - log1pf(__expf(-fabsf(x)));
;                             }
	v_fmac_f32_e32 v109, v107, v101
	v_add_f32_e32 v110, v108, v109
	v_sub_f32_e32 v111, v106, v110
	v_sub_f32_e32 v106, v106, v111
	v_sub_f32_e32 v108, v110, v108
	v_sub_f32_e32 v106, v106, v110
	v_add_f32_e32 v104, v104, v106
	v_sub_f32_e32 v106, v108, v109
	v_add_f32_e32 v104, v106, v104
	v_add_f32_e32 v106, v111, v104
	v_mul_f32_e32 v108, v105, v106
	v_mul_f32_e32 v109, v103, v108
	v_fma_f32 v103, v108, v103, -v109
	v_fmac_f32_e32 v103, v108, v101
	v_sub_f32_e32 v101, v111, v106
	v_add_f32_e32 v101, v104, v101
	v_add_f32_e32 v104, v109, v103
	v_sub_f32_e32 v110, v106, v104
	v_sub_f32_e32 v106, v106, v110
	v_sub_f32_e32 v109, v104, v109
	v_sub_f32_e32 v104, v106, v104
	v_add_f32_e32 v101, v101, v104
	v_sub_f32_e32 v103, v109, v103
	v_add_f32_e32 v101, v103, v101
	v_add_f32_e32 v103, v107, v108
	v_add_f32_e32 v101, v110, v101
	v_sub_f32_e32 v104, v103, v107
	v_mul_f32_e32 v101, v105, v101
	v_sub_f32_e32 v104, v108, v104
	v_add_f32_e32 v101, v104, v101
	v_mul_f32_e32 v107, 0x3f317218, v100
	v_add_f32_e32 v104, v103, v101
	v_fma_f32 v108, v100, s7, -v107
	v_mul_f32_e32 v105, v104, v104
	v_fmac_f32_e32 v108, 0xb102e308, v100
	v_sub_f32_e32 v100, v104, v103
	v_fmamk_f32 v106, v105, 0x3e9b6dac, v214
	v_sub_f32_e32 v100, v101, v100
	v_add_f32_e32 v101, v107, v108
	v_fmaak_f32 v106, v105, v106, 0x3f2aaada
	v_sub_f32_e32 v103, v101, v107
	v_ldexp_f32 v107, v104, 1
	v_mul_f32_e32 v104, v104, v105
	v_mul_f32_e32 v104, v104, v106
	v_add_f32_e32 v105, v107, v104
	v_sub_f32_e32 v106, v105, v107
	v_ldexp_f32 v100, v100, 1
	v_sub_f32_e32 v104, v104, v106
	v_add_f32_e32 v100, v100, v104
	v_add_f32_e32 v104, v105, v100
	v_sub_f32_e32 v105, v104, v105
	v_sub_f32_e32 v100, v100, v105
	v_add_f32_e32 v105, v101, v104
	v_sub_f32_e32 v106, v105, v101
	v_sub_f32_e32 v107, v105, v106
	v_sub_f32_e32 v103, v108, v103
	v_sub_f32_e32 v101, v101, v107
	v_sub_f32_e32 v104, v104, v106
	v_add_f32_e32 v101, v104, v101
	v_add_f32_e32 v104, v103, v100
	v_sub_f32_e32 v106, v104, v103
	v_sub_f32_e32 v107, v104, v106
	v_sub_f32_e32 v103, v103, v107
	v_sub_f32_e32 v100, v100, v106
	v_add_f32_e32 v101, v104, v101
	v_add_f32_e32 v100, v100, v103
	v_add_f32_e32 v103, v105, v101
	v_sub_f32_e32 v104, v103, v105
	v_sub_f32_e32 v101, v101, v104
	v_add_f32_e32 v100, v100, v101
	v_add_f32_e32 v100, v103, v100
	v_cndmask_b32_e32 v100, v221, v100, vcc
	v_cmp_ngt_f32_e32 vcc, -1.0, v99
	s_nop 1
	v_cndmask_b32_e32 v100, v222, v100, vcc
	v_cmp_neq_f32_e32 vcc, -1.0, v99
	s_nop 1
	v_cndmask_b32_e32 v100, v219, v100, vcc
	v_cmp_lt_f32_e64 vcc, |v99|, s9
	s_nop 1
	v_cndmask_b32_e32 v99, v100, v99, vcc
	v_lshl_add_u64 v[100:101], v[150:151], 2, s[52:53]
	v_sub_f32_e32 v99, v102, v99
	v_add_co_u32_e32 v102, vcc, s2, v100
	s_mov_b32 s2, 0x10000
	s_nop 0
	v_addc_co_u32_e32 v103, vcc, 0, v101, vcc
	global_store_dword v[102:103], v99, off offset:1152
	v_add_f32_e32 v99, v96, v242
	v_min_f32_e32 v104, 0, v99
	v_mul_f32_e64 v99, |v99|, s3
	v_exp_f32_e32 v99, v99
	s_nop 0
	v_add_f32_e32 v105, 1.0, v99
	v_add_f32_e32 v102, -1.0, v105
	v_sub_f32_e32 v103, v102, v105
	v_add_f32_e32 v103, 1.0, v103
	v_sub_f32_e32 v102, v99, v102
	v_add_f32_e32 v106, v102, v103
	v_frexp_mant_f32_e32 v102, v105
	v_cmp_gt_f32_e32 vcc, s6, v102
	v_cvt_f64_f32_e32 v[102:103], v105
	v_frexp_exp_i32_f64_e32 v102, v[102:103]
	v_subbrev_co_u32_e32 v102, vcc, 0, v102, vcc
	v_sub_u32_e32 v103, 0, v102
	v_ldexp_f32 v105, v105, v103
	v_ldexp_f32 v103, v106, v103
	v_add_f32_e32 v106, -1.0, v105
	v_add_f32_e32 v107, 1.0, v106
	v_sub_f32_e32 v107, v105, v107
	v_add_f32_e32 v107, v103, v107
	v_add_f32_e32 v108, v106, v107
	v_sub_f32_e32 v106, v108, v106
	v_sub_f32_e32 v106, v107, v106
	v_add_f32_e32 v107, 1.0, v105
	v_add_f32_e32 v109, -1.0, v107
	v_sub_f32_e32 v105, v105, v109
	v_add_f32_e32 v103, v103, v105
	v_add_f32_e32 v105, v107, v103
	v_sub_f32_e32 v107, v105, v107
	v_sub_f32_e32 v103, v103, v107
	v_rcp_f32_e32 v107, v105
	v_cvt_f32_i32_e32 v102, v102
	v_cmp_neq_f32_e32 vcc, s8, v99
	v_mul_f32_e32 v109, v108, v107
	v_mul_f32_e32 v110, v105, v109
	v_fma_f32 v111, v109, v105, -v110
	v_fmac_f32_e32 v111, v109, v103
	v_add_f32_e32 v112, v110, v111
	v_sub_f32_e32 v113, v108, v112
	v_sub_f32_e32 v108, v108, v113
	v_sub_f32_e32 v110, v112, v110
	v_sub_f32_e32 v108, v108, v112
	v_add_f32_e32 v106, v106, v108
	v_sub_f32_e32 v108, v110, v111
	v_add_f32_e32 v106, v108, v106
	v_add_f32_e32 v108, v113, v106
	v_mul_f32_e32 v110, v107, v108
	v_mul_f32_e32 v111, v105, v110
	v_fma_f32 v105, v110, v105, -v111
	v_fmac_f32_e32 v105, v110, v103
	v_sub_f32_e32 v103, v113, v108
	v_add_f32_e32 v103, v106, v103
	v_add_f32_e32 v106, v111, v105
	v_sub_f32_e32 v112, v108, v106
	v_sub_f32_e32 v108, v108, v112
	v_sub_f32_e32 v111, v106, v111
	v_sub_f32_e32 v106, v108, v106
	v_add_f32_e32 v103, v103, v106
	v_sub_f32_e32 v105, v111, v105
	v_add_f32_e32 v103, v105, v103
	v_add_f32_e32 v105, v109, v110
	v_add_f32_e32 v103, v112, v103
	v_sub_f32_e32 v106, v105, v109
	v_mul_f32_e32 v103, v107, v103
	v_sub_f32_e32 v106, v110, v106
	v_add_f32_e32 v103, v106, v103
	v_mul_f32_e32 v109, 0x3f317218, v102
	v_add_f32_e32 v106, v105, v103
	v_fma_f32 v110, v102, s7, -v109
	v_mul_f32_e32 v107, v106, v106
	v_fmac_f32_e32 v110, 0xb102e308, v102
	v_sub_f32_e32 v102, v106, v105
	v_fmamk_f32 v108, v107, 0x3e9b6dac, v214
	v_sub_f32_e32 v102, v103, v102
	v_add_f32_e32 v103, v109, v110
	v_fmaak_f32 v108, v107, v108, 0x3f2aaada
	v_sub_f32_e32 v105, v103, v109
	v_ldexp_f32 v109, v106, 1
	v_mul_f32_e32 v106, v106, v107
	v_mul_f32_e32 v106, v106, v108
	v_add_f32_e32 v107, v109, v106
	v_sub_f32_e32 v108, v107, v109
	v_ldexp_f32 v102, v102, 1
	v_sub_f32_e32 v106, v106, v108
;     __device__ __forceinline__ void operator()(const AccT& acc, const pg8::Unit& u, int wr, int wc, int fr, int fq) const {
;     ...
;                     } else if (wc == 1 && fq == 0) {
; #pragma unroll
;                         for (int n = 0; n < 2; ++n)
; #pragma unroll
;                             for (int j = 0; j < 4; ++j) {
;                                 const float x = acc[ai][0][m][n][j] * rs + bfg[4 * n + j];
;                                 lf[(4 * n + j) * MROWS + row] = fminf(x, 0.f) - log1pf(__expf(-fabsf(x)));
;                             }
	v_add_f32_e32 v102, v102, v106
	v_add_f32_e32 v106, v107, v102
	v_sub_f32_e32 v107, v106, v107
	v_sub_f32_e32 v102, v102, v107
	v_add_f32_e32 v107, v103, v106
	v_sub_f32_e32 v108, v107, v103
	v_sub_f32_e32 v109, v107, v108
	v_sub_f32_e32 v105, v110, v105
	v_sub_f32_e32 v103, v103, v109
	v_sub_f32_e32 v106, v106, v108
	v_add_f32_e32 v103, v106, v103
	v_add_f32_e32 v106, v105, v102
	v_sub_f32_e32 v108, v106, v105
	v_sub_f32_e32 v109, v106, v108
	v_sub_f32_e32 v105, v105, v109
	v_sub_f32_e32 v102, v102, v108
	v_add_f32_e32 v103, v106, v103
	v_add_f32_e32 v102, v102, v105
	v_add_f32_e32 v105, v107, v103
	v_sub_f32_e32 v106, v105, v107
	v_sub_f32_e32 v103, v103, v106
	v_add_f32_e32 v102, v102, v103
	v_add_f32_e32 v102, v105, v102
	v_cndmask_b32_e32 v102, v221, v102, vcc
	v_cmp_ngt_f32_e32 vcc, -1.0, v99
	s_nop 1
	v_cndmask_b32_e32 v102, v222, v102, vcc
	v_cmp_neq_f32_e32 vcc, -1.0, v99
	s_nop 1
	v_cndmask_b32_e32 v102, v219, v102, vcc
	v_cmp_lt_f32_e64 vcc, |v99|, s9
	s_nop 1
	v_cndmask_b32_e32 v99, v102, v99, vcc
	v_add_co_u32_e32 v102, vcc, s2, v100
	v_sub_f32_e32 v99, v104, v99
	s_nop 0
	v_addc_co_u32_e32 v103, vcc, 0, v101, vcc
	global_store_dword v[102:103], v99, off offset:2176
	s_mov_b32 s2, 0x18000
	v_add_f32_e32 v99, v97, v243
	v_min_f32_e32 v104, 0, v99
	v_mul_f32_e64 v99, |v99|, s3
	v_exp_f32_e32 v99, v99
	s_nop 0
	v_add_f32_e32 v105, 1.0, v99
	v_add_f32_e32 v102, -1.0, v105
	v_sub_f32_e32 v103, v102, v105
	v_add_f32_e32 v103, 1.0, v103
	v_sub_f32_e32 v102, v99, v102
	v_add_f32_e32 v106, v102, v103
	v_frexp_mant_f32_e32 v102, v105
	v_cmp_gt_f32_e32 vcc, s6, v102
	v_cvt_f64_f32_e32 v[102:103], v105
	v_frexp_exp_i32_f64_e32 v102, v[102:103]
	v_subbrev_co_u32_e32 v102, vcc, 0, v102, vcc
	v_sub_u32_e32 v103, 0, v102
	v_ldexp_f32 v105, v105, v103
	v_ldexp_f32 v103, v106, v103
	v_add_f32_e32 v106, -1.0, v105
	v_add_f32_e32 v107, 1.0, v106
	v_sub_f32_e32 v107, v105, v107
	v_add_f32_e32 v107, v103, v107
	v_add_f32_e32 v108, v106, v107
	v_sub_f32_e32 v106, v108, v106
	v_sub_f32_e32 v106, v107, v106
	v_add_f32_e32 v107, 1.0, v105
	v_add_f32_e32 v109, -1.0, v107
	v_sub_f32_e32 v105, v105, v109
	v_add_f32_e32 v103, v103, v105
	v_add_f32_e32 v105, v107, v103
	v_sub_f32_e32 v107, v105, v107
	v_sub_f32_e32 v103, v103, v107
	v_rcp_f32_e32 v107, v105
	v_cvt_f32_i32_e32 v102, v102
	v_cmp_neq_f32_e32 vcc, s8, v99
	v_mul_f32_e32 v109, v108, v107
	v_mul_f32_e32 v110, v105, v109
	v_fma_f32 v111, v109, v105, -v110
	v_fmac_f32_e32 v111, v109, v103
	v_add_f32_e32 v112, v110, v111
	v_sub_f32_e32 v113, v108, v112
	v_sub_f32_e32 v108, v108, v113
	v_sub_f32_e32 v110, v112, v110
	v_sub_f32_e32 v108, v108, v112
	v_add_f32_e32 v106, v106, v108
	v_sub_f32_e32 v108, v110, v111
	v_add_f32_e32 v106, v108, v106
	v_add_f32_e32 v108, v113, v106
	v_mul_f32_e32 v110, v107, v108
	v_mul_f32_e32 v111, v105, v110
	v_fma_f32 v105, v110, v105, -v111
	v_fmac_f32_e32 v105, v110, v103
	v_sub_f32_e32 v103, v113, v108
	v_add_f32_e32 v103, v106, v103
	v_add_f32_e32 v106, v111, v105
	v_sub_f32_e32 v112, v108, v106
	v_sub_f32_e32 v108, v108, v112
	v_sub_f32_e32 v111, v106, v111
	v_sub_f32_e32 v106, v108, v106
	v_add_f32_e32 v103, v103, v106
	v_sub_f32_e32 v105, v111, v105
	v_add_f32_e32 v103, v105, v103
	v_add_f32_e32 v105, v109, v110
	v_add_f32_e32 v103, v112, v103
	v_sub_f32_e32 v106, v105, v109
	v_mul_f32_e32 v103, v107, v103
	v_sub_f32_e32 v106, v110, v106
	v_add_f32_e32 v103, v106, v103
	v_mul_f32_e32 v109, 0x3f317218, v102
	v_add_f32_e32 v106, v105, v103
	v_fma_f32 v110, v102, s7, -v109
	v_mul_f32_e32 v107, v106, v106
	v_fmac_f32_e32 v110, 0xb102e308, v102
	v_sub_f32_e32 v102, v106, v105
	v_fmamk_f32 v108, v107, 0x3e9b6dac, v214
	v_sub_f32_e32 v102, v103, v102
	v_add_f32_e32 v103, v109, v110
	v_fmaak_f32 v108, v107, v108, 0x3f2aaada
	v_sub_f32_e32 v105, v103, v109
	v_ldexp_f32 v109, v106, 1
	v_mul_f32_e32 v106, v106, v107
	v_mul_f32_e32 v106, v106, v108
	v_add_f32_e32 v107, v109, v106
	v_sub_f32_e32 v108, v107, v109
	v_ldexp_f32 v102, v102, 1
	v_sub_f32_e32 v106, v106, v108
	v_add_f32_e32 v102, v102, v106
	v_add_f32_e32 v106, v107, v102
	v_sub_f32_e32 v107, v106, v107
	v_sub_f32_e32 v102, v102, v107
	v_add_f32_e32 v107, v103, v106
	v_sub_f32_e32 v108, v107, v103
	v_sub_f32_e32 v109, v107, v108
	v_sub_f32_e32 v105, v110, v105
	v_sub_f32_e32 v103, v103, v109
	v_sub_f32_e32 v106, v106, v108
	v_add_f32_e32 v103, v106, v103
	v_add_f32_e32 v106, v105, v102
	v_sub_f32_e32 v108, v106, v105
	v_sub_f32_e32 v109, v106, v108
	v_sub_f32_e32 v105, v105, v109
	v_sub_f32_e32 v102, v102, v108
	v_add_f32_e32 v103, v106, v103
	v_add_f32_e32 v102, v102, v105
	v_add_f32_e32 v105, v107, v103
	v_sub_f32_e32 v106, v105, v107
	v_sub_f32_e32 v103, v103, v106
	v_add_f32_e32 v102, v102, v103
	v_add_f32_e32 v102, v105, v102
	v_cndmask_b32_e32 v102, v221, v102, vcc
	v_cmp_ngt_f32_e32 vcc, -1.0, v99
	s_nop 1
	v_cndmask_b32_e32 v102, v222, v102, vcc
	v_cmp_neq_f32_e32 vcc, -1.0, v99
	s_nop 1
	v_cndmask_b32_e32 v102, v219, v102, vcc
	v_cmp_lt_f32_e64 vcc, |v99|, s9
	s_nop 1
	v_cndmask_b32_e32 v99, v102, v99, vcc
	v_add_co_u32_e32 v102, vcc, s2, v100
	v_sub_f32_e32 v99, v104, v99
	s_nop 0
	v_addc_co_u32_e32 v103, vcc, 0, v101, vcc
	global_store_dword v[102:103], v99, off offset:3200
	s_mov_b32 s2, 0x21000
	v_add_f32_e32 v99, v90, v244
	v_min_f32_e32 v104, 0, v99
	v_mul_f32_e64 v99, |v99|, s3
	v_exp_f32_e32 v99, v99
	s_nop 0
	v_add_f32_e32 v105, 1.0, v99
	v_add_f32_e32 v102, -1.0, v105
	v_sub_f32_e32 v103, v102, v105
	v_add_f32_e32 v103, 1.0, v103
	v_sub_f32_e32 v102, v99, v102
	v_add_f32_e32 v106, v102, v103
	v_frexp_mant_f32_e32 v102, v105
	v_cmp_gt_f32_e32 vcc, s6, v102
	v_cvt_f64_f32_e32 v[102:103], v105
;     __device__ __forceinline__ void operator()(const AccT& acc, const pg8::Unit& u, int wr, int wc, int fr, int fq) const {
;     ...
;                     } else if (wc == 1 && fq == 0) {
; #pragma unroll
;                         for (int n = 0; n < 2; ++n)
; #pragma unroll
;                             for (int j = 0; j < 4; ++j) {
;                                 const float x = acc[ai][0][m][n][j] * rs + bfg[4 * n + j];
;                                 lf[(4 * n + j) * MROWS + row] = fminf(x, 0.f) - log1pf(__expf(-fabsf(x)));
;                             }
	v_frexp_exp_i32_f64_e32 v102, v[102:103]
	v_subbrev_co_u32_e32 v102, vcc, 0, v102, vcc
	v_sub_u32_e32 v103, 0, v102
	v_ldexp_f32 v105, v105, v103
	v_ldexp_f32 v103, v106, v103
	v_add_f32_e32 v106, -1.0, v105
	v_add_f32_e32 v107, 1.0, v106
	v_sub_f32_e32 v107, v105, v107
	v_add_f32_e32 v107, v103, v107
	v_add_f32_e32 v108, v106, v107
	v_sub_f32_e32 v106, v108, v106
	v_sub_f32_e32 v106, v107, v106
	v_add_f32_e32 v107, 1.0, v105
	v_add_f32_e32 v109, -1.0, v107
	v_sub_f32_e32 v105, v105, v109
	v_add_f32_e32 v103, v103, v105
	v_add_f32_e32 v105, v107, v103
	v_sub_f32_e32 v107, v105, v107
	v_sub_f32_e32 v103, v103, v107
	v_rcp_f32_e32 v107, v105
	v_cvt_f32_i32_e32 v102, v102
	v_cmp_neq_f32_e32 vcc, s8, v99
	v_mul_f32_e32 v109, v108, v107
	v_mul_f32_e32 v110, v105, v109
	v_fma_f32 v111, v109, v105, -v110
	v_fmac_f32_e32 v111, v109, v103
	v_add_f32_e32 v112, v110, v111
	v_sub_f32_e32 v113, v108, v112
	v_sub_f32_e32 v108, v108, v113
	v_sub_f32_e32 v110, v112, v110
	v_sub_f32_e32 v108, v108, v112
	v_add_f32_e32 v106, v106, v108
	v_sub_f32_e32 v108, v110, v111
	v_add_f32_e32 v106, v108, v106
	v_add_f32_e32 v108, v113, v106
	v_mul_f32_e32 v110, v107, v108
	v_mul_f32_e32 v111, v105, v110
	v_fma_f32 v105, v110, v105, -v111
	v_fmac_f32_e32 v105, v110, v103
	v_sub_f32_e32 v103, v113, v108
	v_add_f32_e32 v103, v106, v103
	v_add_f32_e32 v106, v111, v105
	v_sub_f32_e32 v112, v108, v106
	v_sub_f32_e32 v108, v108, v112
	v_sub_f32_e32 v111, v106, v111
	v_sub_f32_e32 v106, v108, v106
	v_add_f32_e32 v103, v103, v106
	v_sub_f32_e32 v105, v111, v105
	v_add_f32_e32 v103, v105, v103
	v_add_f32_e32 v105, v109, v110
	v_add_f32_e32 v103, v112, v103
	v_sub_f32_e32 v106, v105, v109
	v_mul_f32_e32 v103, v107, v103
	v_sub_f32_e32 v106, v110, v106
	v_add_f32_e32 v103, v106, v103
	v_mul_f32_e32 v109, 0x3f317218, v102
	v_add_f32_e32 v106, v105, v103
	v_fma_f32 v110, v102, s7, -v109
	v_mul_f32_e32 v107, v106, v106
	v_fmac_f32_e32 v110, 0xb102e308, v102
	v_sub_f32_e32 v102, v106, v105
	v_fmamk_f32 v108, v107, 0x3e9b6dac, v214
	v_sub_f32_e32 v102, v103, v102
	v_add_f32_e32 v103, v109, v110
	v_fmaak_f32 v108, v107, v108, 0x3f2aaada
	v_sub_f32_e32 v105, v103, v109
	v_ldexp_f32 v109, v106, 1
	v_mul_f32_e32 v106, v106, v107
	v_mul_f32_e32 v106, v106, v108
	v_add_f32_e32 v107, v109, v106
	v_sub_f32_e32 v108, v107, v109
	v_ldexp_f32 v102, v102, 1
	v_sub_f32_e32 v106, v106, v108
	v_add_f32_e32 v102, v102, v106
	v_add_f32_e32 v106, v107, v102
	v_sub_f32_e32 v107, v106, v107
	v_sub_f32_e32 v102, v102, v107
	v_add_f32_e32 v107, v103, v106
	v_sub_f32_e32 v108, v107, v103
	v_sub_f32_e32 v109, v107, v108
	v_sub_f32_e32 v105, v110, v105
	v_sub_f32_e32 v103, v103, v109
	v_sub_f32_e32 v106, v106, v108
	v_add_f32_e32 v103, v106, v103
	v_add_f32_e32 v106, v105, v102
	v_sub_f32_e32 v108, v106, v105
	v_sub_f32_e32 v109, v106, v108
	v_sub_f32_e32 v105, v105, v109
	v_sub_f32_e32 v102, v102, v108
	v_add_f32_e32 v103, v106, v103
	v_add_f32_e32 v102, v102, v105
	v_add_f32_e32 v105, v107, v103
	v_sub_f32_e32 v106, v105, v107
	v_sub_f32_e32 v103, v103, v106
	v_add_f32_e32 v102, v102, v103
	v_add_f32_e32 v102, v105, v102
	v_cndmask_b32_e32 v102, v221, v102, vcc
	v_cmp_ngt_f32_e32 vcc, -1.0, v99
	s_nop 1
	v_cndmask_b32_e32 v102, v222, v102, vcc
	v_cmp_neq_f32_e32 vcc, -1.0, v99
	s_nop 1
	v_cndmask_b32_e32 v102, v219, v102, vcc
	v_cmp_lt_f32_e64 vcc, |v99|, s9
	s_nop 1
	v_cndmask_b32_e32 v99, v102, v99, vcc
	v_add_co_u32_e32 v102, vcc, s2, v100
	v_sub_f32_e32 v99, v104, v99
	s_nop 0
	v_addc_co_u32_e32 v103, vcc, 0, v101, vcc
	global_store_dword v[102:103], v99, off offset:128
	s_mov_b32 s2, 0x29000
	v_add_f32_e32 v99, v91, v245
	v_min_f32_e32 v104, 0, v99
	v_mul_f32_e64 v99, |v99|, s3
	v_exp_f32_e32 v99, v99
	s_nop 0
	v_add_f32_e32 v105, 1.0, v99
	v_add_f32_e32 v102, -1.0, v105
	v_sub_f32_e32 v103, v102, v105
	v_add_f32_e32 v103, 1.0, v103
	v_sub_f32_e32 v102, v99, v102
	v_add_f32_e32 v106, v102, v103
	v_frexp_mant_f32_e32 v102, v105
	v_cmp_gt_f32_e32 vcc, s6, v102
	v_cvt_f64_f32_e32 v[102:103], v105
	v_frexp_exp_i32_f64_e32 v102, v[102:103]
	v_subbrev_co_u32_e32 v102, vcc, 0, v102, vcc
	v_sub_u32_e32 v103, 0, v102
	v_ldexp_f32 v105, v105, v103
	v_ldexp_f32 v103, v106, v103
	v_add_f32_e32 v106, -1.0, v105
	v_add_f32_e32 v107, 1.0, v106
	v_sub_f32_e32 v107, v105, v107
	v_add_f32_e32 v107, v103, v107
	v_add_f32_e32 v108, v106, v107
	v_sub_f32_e32 v106, v108, v106
	v_sub_f32_e32 v106, v107, v106
	v_add_f32_e32 v107, 1.0, v105
	v_add_f32_e32 v109, -1.0, v107
	v_sub_f32_e32 v105, v105, v109
	v_add_f32_e32 v103, v103, v105
	v_add_f32_e32 v105, v107, v103
	v_sub_f32_e32 v107, v105, v107
	v_sub_f32_e32 v103, v103, v107
	v_rcp_f32_e32 v107, v105
	v_cvt_f32_i32_e32 v102, v102
	v_cmp_neq_f32_e32 vcc, s8, v99
	v_mul_f32_e32 v109, v108, v107
	v_mul_f32_e32 v110, v105, v109
	v_fma_f32 v111, v109, v105, -v110
	v_fmac_f32_e32 v111, v109, v103
	v_add_f32_e32 v112, v110, v111
	v_sub_f32_e32 v113, v108, v112
	v_sub_f32_e32 v108, v108, v113
	v_sub_f32_e32 v110, v112, v110
	v_sub_f32_e32 v108, v108, v112
	v_add_f32_e32 v106, v106, v108
	v_sub_f32_e32 v108, v110, v111
	v_add_f32_e32 v106, v108, v106
	v_add_f32_e32 v108, v113, v106
	v_mul_f32_e32 v110, v107, v108
	v_mul_f32_e32 v111, v105, v110
	v_fma_f32 v105, v110, v105, -v111
	v_fmac_f32_e32 v105, v110, v103
	v_sub_f32_e32 v103, v113, v108
	v_add_f32_e32 v103, v106, v103
	v_add_f32_e32 v106, v111, v105
	v_sub_f32_e32 v112, v108, v106
	v_sub_f32_e32 v108, v108, v112
	v_sub_f32_e32 v111, v106, v111
	v_sub_f32_e32 v106, v108, v106
	v_add_f32_e32 v103, v103, v106
	v_sub_f32_e32 v105, v111, v105
	v_add_f32_e32 v103, v105, v103
	v_add_f32_e32 v105, v109, v110
	v_add_f32_e32 v103, v112, v103
;     __device__ __forceinline__ void operator()(const AccT& acc, const pg8::Unit& u, int wr, int wc, int fr, int fq) const {
;     ...
;                     } else if (wc == 1 && fq == 0) {
; #pragma unroll
;                         for (int n = 0; n < 2; ++n)
; #pragma unroll
;                             for (int j = 0; j < 4; ++j) {
;                                 const float x = acc[ai][0][m][n][j] * rs + bfg[4 * n + j];
;                                 lf[(4 * n + j) * MROWS + row] = fminf(x, 0.f) - log1pf(__expf(-fabsf(x)));
;                             }
	v_sub_f32_e32 v106, v105, v109
	v_mul_f32_e32 v103, v107, v103
	v_sub_f32_e32 v106, v110, v106
	v_add_f32_e32 v103, v106, v103
	v_mul_f32_e32 v109, 0x3f317218, v102
	v_add_f32_e32 v106, v105, v103
	v_fma_f32 v110, v102, s7, -v109
	v_mul_f32_e32 v107, v106, v106
	v_fmac_f32_e32 v110, 0xb102e308, v102
	v_sub_f32_e32 v102, v106, v105
	v_fmamk_f32 v108, v107, 0x3e9b6dac, v214
	v_sub_f32_e32 v102, v103, v102
	v_add_f32_e32 v103, v109, v110
	v_fmaak_f32 v108, v107, v108, 0x3f2aaada
	v_sub_f32_e32 v105, v103, v109
	v_ldexp_f32 v109, v106, 1
	v_mul_f32_e32 v106, v106, v107
	v_mul_f32_e32 v106, v106, v108
	v_add_f32_e32 v107, v109, v106
	v_sub_f32_e32 v108, v107, v109
	v_ldexp_f32 v102, v102, 1
	v_sub_f32_e32 v106, v106, v108
	v_add_f32_e32 v102, v102, v106
	v_add_f32_e32 v106, v107, v102
	v_sub_f32_e32 v107, v106, v107
	v_sub_f32_e32 v102, v102, v107
	v_add_f32_e32 v107, v103, v106
	v_sub_f32_e32 v108, v107, v103
	v_sub_f32_e32 v109, v107, v108
	v_sub_f32_e32 v105, v110, v105
	v_sub_f32_e32 v103, v103, v109
	v_sub_f32_e32 v106, v106, v108
	v_add_f32_e32 v103, v106, v103
	v_add_f32_e32 v106, v105, v102
	v_sub_f32_e32 v108, v106, v105
	v_sub_f32_e32 v109, v106, v108
	v_sub_f32_e32 v105, v105, v109
	v_sub_f32_e32 v102, v102, v108
	v_add_f32_e32 v103, v106, v103
	v_add_f32_e32 v102, v102, v105
	v_add_f32_e32 v105, v107, v103
	v_sub_f32_e32 v106, v105, v107
	v_sub_f32_e32 v103, v103, v106
	v_add_f32_e32 v102, v102, v103
	v_add_f32_e32 v102, v105, v102
	v_cndmask_b32_e32 v102, v221, v102, vcc
	v_cmp_ngt_f32_e32 vcc, -1.0, v99
	s_nop 1
	v_cndmask_b32_e32 v102, v222, v102, vcc
	v_cmp_neq_f32_e32 vcc, -1.0, v99
	s_nop 1
	v_cndmask_b32_e32 v102, v219, v102, vcc
	v_cmp_lt_f32_e64 vcc, |v99|, s9
	s_nop 1
	v_cndmask_b32_e32 v99, v102, v99, vcc
	v_add_co_u32_e32 v102, vcc, s2, v100
	v_sub_f32_e32 v99, v104, v99
	s_nop 0
	v_addc_co_u32_e32 v103, vcc, 0, v101, vcc
	global_store_dword v[102:103], v99, off offset:1152
	s_mov_b32 s2, 0x31000
	v_add_f32_e32 v99, v92, v246
	v_min_f32_e32 v104, 0, v99
	v_mul_f32_e64 v99, |v99|, s3
	v_exp_f32_e32 v99, v99
	s_nop 0
	v_add_f32_e32 v105, 1.0, v99
	v_add_f32_e32 v102, -1.0, v105
	v_sub_f32_e32 v103, v102, v105
	v_add_f32_e32 v103, 1.0, v103
	v_sub_f32_e32 v102, v99, v102
	v_add_f32_e32 v106, v102, v103
	v_frexp_mant_f32_e32 v102, v105
	v_cmp_gt_f32_e32 vcc, s6, v102
	v_cvt_f64_f32_e32 v[102:103], v105
	v_frexp_exp_i32_f64_e32 v102, v[102:103]
	v_subbrev_co_u32_e32 v102, vcc, 0, v102, vcc
	v_sub_u32_e32 v103, 0, v102
	v_ldexp_f32 v105, v105, v103
	v_ldexp_f32 v103, v106, v103
	v_add_f32_e32 v106, -1.0, v105
	v_add_f32_e32 v107, 1.0, v106
	v_sub_f32_e32 v107, v105, v107
	v_add_f32_e32 v107, v103, v107
	v_add_f32_e32 v108, v106, v107
	v_sub_f32_e32 v106, v108, v106
	v_sub_f32_e32 v106, v107, v106
	v_add_f32_e32 v107, 1.0, v105
	v_add_f32_e32 v109, -1.0, v107
	v_sub_f32_e32 v105, v105, v109
	v_add_f32_e32 v103, v103, v105
	v_add_f32_e32 v105, v107, v103
	v_sub_f32_e32 v107, v105, v107
	v_sub_f32_e32 v103, v103, v107
	v_rcp_f32_e32 v107, v105
	v_cvt_f32_i32_e32 v102, v102
	v_cmp_neq_f32_e32 vcc, s8, v99
	v_mul_f32_e32 v109, v108, v107
	v_mul_f32_e32 v110, v105, v109
	v_fma_f32 v111, v109, v105, -v110
	v_fmac_f32_e32 v111, v109, v103
	v_add_f32_e32 v112, v110, v111
	v_sub_f32_e32 v113, v108, v112
	v_sub_f32_e32 v108, v108, v113
	v_sub_f32_e32 v110, v112, v110
	v_sub_f32_e32 v108, v108, v112
	v_add_f32_e32 v106, v106, v108
	v_sub_f32_e32 v108, v110, v111
	v_add_f32_e32 v106, v108, v106
	v_add_f32_e32 v108, v113, v106
	v_mul_f32_e32 v110, v107, v108
	v_mul_f32_e32 v111, v105, v110
	v_fma_f32 v105, v110, v105, -v111
	v_fmac_f32_e32 v105, v110, v103
	v_sub_f32_e32 v103, v113, v108
	v_add_f32_e32 v103, v106, v103
	v_add_f32_e32 v106, v111, v105
	v_sub_f32_e32 v112, v108, v106
	v_sub_f32_e32 v108, v108, v112
	v_sub_f32_e32 v111, v106, v111
	v_sub_f32_e32 v106, v108, v106
	v_add_f32_e32 v103, v103, v106
	v_sub_f32_e32 v105, v111, v105
	v_add_f32_e32 v103, v105, v103
	v_add_f32_e32 v105, v109, v110
	v_add_f32_e32 v103, v112, v103
	v_sub_f32_e32 v106, v105, v109
	v_mul_f32_e32 v103, v107, v103
	v_sub_f32_e32 v106, v110, v106
	v_add_f32_e32 v103, v106, v103
	v_mul_f32_e32 v109, 0x3f317218, v102
	v_add_f32_e32 v106, v105, v103
	v_fma_f32 v110, v102, s7, -v109
	v_mul_f32_e32 v107, v106, v106
	v_fmac_f32_e32 v110, 0xb102e308, v102
	v_sub_f32_e32 v102, v106, v105
	v_fmamk_f32 v108, v107, 0x3e9b6dac, v214
	v_sub_f32_e32 v102, v103, v102
	v_add_f32_e32 v103, v109, v110
	v_fmaak_f32 v108, v107, v108, 0x3f2aaada
	v_sub_f32_e32 v105, v103, v109
	v_ldexp_f32 v109, v106, 1
	v_mul_f32_e32 v106, v106, v107
	v_mul_f32_e32 v106, v106, v108
	v_add_f32_e32 v107, v109, v106
	v_sub_f32_e32 v108, v107, v109
	v_ldexp_f32 v102, v102, 1
	v_sub_f32_e32 v106, v106, v108
	v_add_f32_e32 v102, v102, v106
	v_add_f32_e32 v106, v107, v102
	v_sub_f32_e32 v107, v106, v107
	v_sub_f32_e32 v102, v102, v107
	v_add_f32_e32 v107, v103, v106
	v_sub_f32_e32 v108, v107, v103
	v_sub_f32_e32 v109, v107, v108
;     __device__ __forceinline__ void operator()(const AccT& acc, const pg8::Unit& u, int wr, int wc, int fr, int fq) const {
;     ...
;                     } else if (wc == 1 && fq == 0) {
; #pragma unroll
;                         for (int n = 0; n < 2; ++n)
; #pragma unroll
;                             for (int j = 0; j < 4; ++j) {
;                                 const float x = acc[ai][0][m][n][j] * rs + bfg[4 * n + j];
;                                 lf[(4 * n + j) * MROWS + row] = fminf(x, 0.f) - log1pf(__expf(-fabsf(x)));
;                             }
	v_sub_f32_e32 v105, v110, v105
	v_sub_f32_e32 v103, v103, v109
	v_sub_f32_e32 v106, v106, v108
	v_add_f32_e32 v103, v106, v103
	v_add_f32_e32 v106, v105, v102
	v_sub_f32_e32 v108, v106, v105
	v_sub_f32_e32 v109, v106, v108
	v_sub_f32_e32 v105, v105, v109
	v_sub_f32_e32 v102, v102, v108
	v_add_f32_e32 v103, v106, v103
	v_add_f32_e32 v102, v102, v105
	v_add_f32_e32 v105, v107, v103
	v_sub_f32_e32 v106, v105, v107
	v_sub_f32_e32 v103, v103, v106
	v_add_f32_e32 v102, v102, v103
	v_add_f32_e32 v102, v105, v102
	v_cndmask_b32_e32 v102, v221, v102, vcc
	v_cmp_ngt_f32_e32 vcc, -1.0, v99
	s_nop 1
	v_cndmask_b32_e32 v102, v222, v102, vcc
	v_cmp_neq_f32_e32 vcc, -1.0, v99
	s_nop 1
	v_cndmask_b32_e32 v102, v219, v102, vcc
	v_cmp_lt_f32_e64 vcc, |v99|, s9
	s_nop 1
	v_cndmask_b32_e32 v99, v102, v99, vcc
	v_add_co_u32_e32 v102, vcc, s2, v100
	v_sub_f32_e32 v99, v104, v99
	s_nop 0
	v_addc_co_u32_e32 v103, vcc, 0, v101, vcc
	global_store_dword v[102:103], v99, off offset:2176
	v_add_f32_e32 v99, v93, v247
	v_min_f32_e32 v104, 0, v99
	v_mul_f32_e64 v99, |v99|, s3
	v_exp_f32_e32 v99, v99
	s_nop 0
	v_add_f32_e32 v105, 1.0, v99
	v_add_f32_e32 v102, -1.0, v105
	v_sub_f32_e32 v103, v102, v105
	v_add_f32_e32 v103, 1.0, v103
	v_sub_f32_e32 v102, v99, v102
	v_add_f32_e32 v106, v102, v103
	v_frexp_mant_f32_e32 v102, v105
	v_cmp_gt_f32_e32 vcc, s6, v102
	v_cvt_f64_f32_e32 v[102:103], v105
	v_frexp_exp_i32_f64_e32 v102, v[102:103]
	v_subbrev_co_u32_e32 v102, vcc, 0, v102, vcc
	v_sub_u32_e32 v103, 0, v102
	v_ldexp_f32 v105, v105, v103
	v_ldexp_f32 v103, v106, v103
	v_add_f32_e32 v106, -1.0, v105
	v_add_f32_e32 v107, 1.0, v106
	v_sub_f32_e32 v107, v105, v107
	v_add_f32_e32 v107, v103, v107
	v_add_f32_e32 v108, v106, v107
	v_sub_f32_e32 v106, v108, v106
	v_sub_f32_e32 v106, v107, v106
	v_add_f32_e32 v107, 1.0, v105
	v_add_f32_e32 v109, -1.0, v107
	v_sub_f32_e32 v105, v105, v109
	v_add_f32_e32 v103, v103, v105
	v_add_f32_e32 v105, v107, v103
	v_sub_f32_e32 v107, v105, v107
	v_sub_f32_e32 v103, v103, v107
	v_rcp_f32_e32 v107, v105
	v_cvt_f32_i32_e32 v102, v102
	v_cmp_neq_f32_e32 vcc, s8, v99
	v_mul_f32_e32 v109, v108, v107
	v_mul_f32_e32 v110, v105, v109
	v_fma_f32 v111, v109, v105, -v110
	v_fmac_f32_e32 v111, v109, v103
	v_add_f32_e32 v112, v110, v111
	v_sub_f32_e32 v113, v108, v112
	v_sub_f32_e32 v108, v108, v113
	v_sub_f32_e32 v110, v112, v110
	v_sub_f32_e32 v108, v108, v112
	v_add_f32_e32 v106, v106, v108
	v_sub_f32_e32 v108, v110, v111
	v_add_f32_e32 v106, v108, v106
	v_add_f32_e32 v108, v113, v106
	v_mul_f32_e32 v110, v107, v108
	v_mul_f32_e32 v111, v105, v110
	v_fma_f32 v105, v110, v105, -v111
	v_fmac_f32_e32 v105, v110, v103
	v_sub_f32_e32 v103, v113, v108
	v_add_f32_e32 v103, v106, v103
	v_add_f32_e32 v106, v111, v105
	v_sub_f32_e32 v112, v108, v106
	v_sub_f32_e32 v108, v108, v112
	v_sub_f32_e32 v111, v106, v111
	v_sub_f32_e32 v106, v108, v106
	v_add_f32_e32 v103, v103, v106
	v_sub_f32_e32 v105, v111, v105
	v_add_f32_e32 v103, v105, v103
	v_add_f32_e32 v105, v109, v110
	v_add_f32_e32 v103, v112, v103
	v_sub_f32_e32 v106, v105, v109
	v_mul_f32_e32 v103, v107, v103
	v_sub_f32_e32 v106, v110, v106
	v_add_f32_e32 v103, v106, v103
	v_mul_f32_e32 v109, 0x3f317218, v102
	v_add_f32_e32 v106, v105, v103
	v_fma_f32 v110, v102, s7, -v109
	v_mul_f32_e32 v107, v106, v106
	v_fmac_f32_e32 v110, 0xb102e308, v102
	v_sub_f32_e32 v102, v106, v105
	v_fmamk_f32 v108, v107, 0x3e9b6dac, v214
	v_sub_f32_e32 v102, v103, v102
	v_add_f32_e32 v103, v109, v110
	v_fmaak_f32 v108, v107, v108, 0x3f2aaada
	v_sub_f32_e32 v105, v103, v109
	v_ldexp_f32 v109, v106, 1
	v_mul_f32_e32 v106, v106, v107
	v_mul_f32_e32 v106, v106, v108
	v_add_f32_e32 v107, v109, v106
	v_sub_f32_e32 v108, v107, v109
	v_ldexp_f32 v102, v102, 1
	v_sub_f32_e32 v106, v106, v108
	v_add_f32_e32 v102, v102, v106
	v_add_f32_e32 v106, v107, v102
	v_sub_f32_e32 v107, v106, v107
	v_sub_f32_e32 v102, v102, v107
	v_add_f32_e32 v107, v103, v106
	v_sub_f32_e32 v108, v107, v103
	v_sub_f32_e32 v109, v107, v108
	v_sub_f32_e32 v105, v110, v105
	v_sub_f32_e32 v103, v103, v109
	v_sub_f32_e32 v106, v106, v108
	v_add_f32_e32 v103, v106, v103
	v_add_f32_e32 v106, v105, v102
	v_sub_f32_e32 v108, v106, v105
	v_sub_f32_e32 v109, v106, v108
	v_sub_f32_e32 v105, v105, v109
	v_sub_f32_e32 v102, v102, v108
	v_add_f32_e32 v103, v106, v103
	v_add_f32_e32 v102, v102, v105
	v_add_f32_e32 v105, v107, v103
	v_sub_f32_e32 v106, v105, v107
	v_sub_f32_e32 v103, v103, v106
	v_add_f32_e32 v102, v102, v103
	v_add_f32_e32 v102, v105, v102
	v_cndmask_b32_e32 v102, v221, v102, vcc
	v_cmp_ngt_f32_e32 vcc, -1.0, v99
	s_nop 1
	v_cndmask_b32_e32 v102, v222, v102, vcc
	v_cmp_neq_f32_e32 vcc, -1.0, v99
	s_nop 1
	v_cndmask_b32_e32 v102, v219, v102, vcc
	v_cmp_lt_f32_e64 vcc, |v99|, s9
	s_nop 1
	v_cndmask_b32_e32 v99, v102, v99, vcc
	v_add_co_u32_e32 v100, vcc, 0x39000, v100
	v_sub_f32_e32 v99, v104, v99
	s_nop 0
	v_addc_co_u32_e32 v101, vcc, 0, v101, vcc
	global_store_dword v[100:101], v99, off offset:3200

;     __device__ __forceinline__ void operator()(const AccT& acc, const pg8::Unit& u, int wr, int wc, int fr, int fq) const {
;     ...
;             for (int m = 0; m < 4; ++m) {
;                 const int row = row0 + ai * 128 + m * 16;
;                 const float rs = 1.0f;
;                 if (u.pn < 20) {
;     ...
;                     } else if (wc == 1 && fq == 0) {
; #pragma unroll
;                         for (int n = 0; n < 2; ++n)
; #pragma unroll
;                             for (int j = 0; j < 4; ++j) {
;                                 const float x = acc[ai][0][m][n][j] * rs + bfg[4 * n + j];
;                                 lf[(4 * n + j) * MROWS + row] = fminf(x, 0.f) - log1pf(__expf(-fabsf(x)));
;                             }
.LBB0_985:
	v_or_b32_e32 v82, 48, v150
	s_and_b64 vcc, exec, s[44:45]
	s_mov_b64 s[8:9], -1
	s_cbranch_vccnz .LBB0_993
	s_and_b64 vcc, exec, s[42:43]
	s_cbranch_vccnz .LBB0_990
	s_and_saveexec_b64 s[70:71], s[58:59]
	s_cbranch_execz .LBB0_989
	s_waitcnt lgkmcnt(0)
	s_mov_b32 s3, 0xbfb8aa3b
	s_mov_b32 s6, 0x3f2aaaab
	s_mov_b32 s7, 0x3f317218
	s_mov_b32 s8, 0x7f800000
	s_mov_b32 s9, 0x33800000
	v_ashrrev_i32_e32 v151, 31, v150
	s_mov_b32 s2, 0x8000
	v_add_f32_e32 v83, v78, v240
	v_min_f32_e32 v86, 0, v83
	v_mul_f32_e64 v83, |v83|, s3
	v_exp_f32_e32 v83, v83
	s_nop 0
	v_add_f32_e32 v87, 1.0, v83
	v_add_f32_e32 v84, -1.0, v87
	v_sub_f32_e32 v85, v84, v87
	v_add_f32_e32 v85, 1.0, v85
	v_sub_f32_e32 v84, v83, v84
	v_add_f32_e32 v88, v84, v85
	v_frexp_mant_f32_e32 v84, v87
	v_cmp_gt_f32_e32 vcc, s6, v84
	v_cvt_f64_f32_e32 v[84:85], v87
	v_frexp_exp_i32_f64_e32 v84, v[84:85]
	v_subbrev_co_u32_e32 v84, vcc, 0, v84, vcc
	v_sub_u32_e32 v85, 0, v84
	v_ldexp_f32 v87, v87, v85
	v_ldexp_f32 v85, v88, v85
	v_add_f32_e32 v88, -1.0, v87
	v_add_f32_e32 v89, 1.0, v88
	v_sub_f32_e32 v89, v87, v89
	v_add_f32_e32 v89, v85, v89
	v_add_f32_e32 v90, v88, v89
	v_sub_f32_e32 v88, v90, v88
	v_sub_f32_e32 v88, v89, v88
	v_add_f32_e32 v89, 1.0, v87
	v_add_f32_e32 v91, -1.0, v89
	v_sub_f32_e32 v87, v87, v91
	v_add_f32_e32 v85, v85, v87
	v_add_f32_e32 v87, v89, v85
	v_sub_f32_e32 v89, v87, v89
	v_sub_f32_e32 v85, v85, v89
	v_rcp_f32_e32 v89, v87
	v_cvt_f32_i32_e32 v84, v84
	v_cmp_neq_f32_e32 vcc, s8, v83
	v_mul_f32_e32 v91, v90, v89
	v_mul_f32_e32 v92, v87, v91
	v_fma_f32 v93, v91, v87, -v92
	v_fmac_f32_e32 v93, v91, v85
	v_add_f32_e32 v94, v92, v93
	v_sub_f32_e32 v95, v90, v94
	v_sub_f32_e32 v90, v90, v95
	v_sub_f32_e32 v92, v94, v92
	v_sub_f32_e32 v90, v90, v94
	v_add_f32_e32 v88, v88, v90
	v_sub_f32_e32 v90, v92, v93
	v_add_f32_e32 v88, v90, v88
	v_add_f32_e32 v90, v95, v88
	v_mul_f32_e32 v92, v89, v90
	v_mul_f32_e32 v93, v87, v92
	v_fma_f32 v87, v92, v87, -v93
	v_fmac_f32_e32 v87, v92, v85
	v_sub_f32_e32 v85, v95, v90
	v_add_f32_e32 v85, v88, v85
	v_add_f32_e32 v88, v93, v87
	v_sub_f32_e32 v94, v90, v88
	v_sub_f32_e32 v90, v90, v94
	v_sub_f32_e32 v93, v88, v93
	v_sub_f32_e32 v88, v90, v88
	v_add_f32_e32 v85, v85, v88
	v_sub_f32_e32 v87, v93, v87
	v_add_f32_e32 v85, v87, v85
	v_add_f32_e32 v87, v91, v92
	v_add_f32_e32 v85, v94, v85
	v_sub_f32_e32 v88, v87, v91
	v_mul_f32_e32 v85, v89, v85
	v_sub_f32_e32 v88, v92, v88
	v_add_f32_e32 v85, v88, v85
	v_mul_f32_e32 v91, 0x3f317218, v84
	v_add_f32_e32 v88, v87, v85
	v_fma_f32 v92, v84, s7, -v91
	v_mul_f32_e32 v89, v88, v88
	v_fmac_f32_e32 v92, 0xb102e308, v84
	v_sub_f32_e32 v84, v88, v87
	v_fmamk_f32 v90, v89, 0x3e9b6dac, v214
	v_sub_f32_e32 v84, v85, v84
	v_add_f32_e32 v85, v91, v92
	v_fmaak_f32 v90, v89, v90, 0x3f2aaada
	v_sub_f32_e32 v87, v85, v91
	v_ldexp_f32 v91, v88, 1
	v_mul_f32_e32 v88, v88, v89
	v_mul_f32_e32 v88, v88, v90
	v_add_f32_e32 v89, v91, v88
	v_sub_f32_e32 v90, v89, v91
	v_ldexp_f32 v84, v84, 1
	v_sub_f32_e32 v88, v88, v90
	v_add_f32_e32 v84, v84, v88
	v_add_f32_e32 v88, v89, v84
	v_sub_f32_e32 v89, v88, v89
	v_sub_f32_e32 v84, v84, v89
	v_add_f32_e32 v89, v85, v88
	v_sub_f32_e32 v90, v89, v85
	v_sub_f32_e32 v91, v89, v90
	v_sub_f32_e32 v87, v92, v87
	v_sub_f32_e32 v85, v85, v91
	v_sub_f32_e32 v88, v88, v90
	v_add_f32_e32 v85, v88, v85
	v_add_f32_e32 v88, v87, v84
	v_sub_f32_e32 v90, v88, v87
	v_sub_f32_e32 v91, v88, v90
	v_sub_f32_e32 v87, v87, v91
	v_sub_f32_e32 v84, v84, v90
	v_add_f32_e32 v85, v88, v85
	v_add_f32_e32 v84, v84, v87
	v_add_f32_e32 v87, v89, v85
	v_sub_f32_e32 v88, v87, v89
	v_sub_f32_e32 v85, v85, v88
	v_add_f32_e32 v84, v84, v85
	v_add_f32_e32 v84, v87, v84
	v_cndmask_b32_e32 v84, v221, v84, vcc
	v_cmp_ngt_f32_e32 vcc, -1.0, v83
	s_nop 1
	v_cndmask_b32_e32 v84, v222, v84, vcc
	v_cmp_neq_f32_e32 vcc, -1.0, v83
	s_nop 1
	v_cndmask_b32_e32 v84, v219, v84, vcc
	v_cmp_lt_f32_e64 vcc, |v83|, s9
	s_nop 1
	v_cndmask_b32_e32 v83, v84, v83, vcc
	v_sub_f32_e32 v86, v86, v83
	v_ashrrev_i32_e32 v83, 31, v82
	v_lshl_add_u64 v[84:85], v[82:83], 2, s[52:53]
	global_store_dword v[84:85], v86, off
	v_add_f32_e32 v83, v79, v241
	v_min_f32_e32 v86, 0, v83
	v_mul_f32_e64 v83, |v83|, s3
	v_exp_f32_e32 v83, v83
	s_nop 0
	v_add_f32_e32 v87, 1.0, v83
	v_add_f32_e32 v84, -1.0, v87
	v_sub_f32_e32 v85, v84, v87
	v_add_f32_e32 v85, 1.0, v85
	v_sub_f32_e32 v84, v83, v84
	v_add_f32_e32 v88, v84, v85
	v_frexp_mant_f32_e32 v84, v87
	v_cmp_gt_f32_e32 vcc, s6, v84
	v_cvt_f64_f32_e32 v[84:85], v87
	v_frexp_exp_i32_f64_e32 v84, v[84:85]
	v_subbrev_co_u32_e32 v84, vcc, 0, v84, vcc
	v_sub_u32_e32 v85, 0, v84
	v_ldexp_f32 v87, v87, v85
	v_ldexp_f32 v85, v88, v85
	v_add_f32_e32 v88, -1.0, v87
	v_add_f32_e32 v89, 1.0, v88
	v_sub_f32_e32 v89, v87, v89
	v_add_f32_e32 v89, v85, v89
	v_add_f32_e32 v90, v88, v89
	v_sub_f32_e32 v88, v90, v88
	v_sub_f32_e32 v88, v89, v88
	v_add_f32_e32 v89, 1.0, v87
	v_add_f32_e32 v91, -1.0, v89
	v_sub_f32_e32 v87, v87, v91
	v_add_f32_e32 v85, v85, v87
	v_add_f32_e32 v87, v89, v85
	v_sub_f32_e32 v89, v87, v89
	v_sub_f32_e32 v85, v85, v89
	v_rcp_f32_e32 v89, v87
	v_cvt_f32_i32_e32 v84, v84
	v_cmp_neq_f32_e32 vcc, s8, v83
	v_mul_f32_e32 v91, v90, v89
	v_mul_f32_e32 v92, v87, v91
	v_fma_f32 v93, v91, v87, -v92
	v_fmac_f32_e32 v93, v91, v85
	v_add_f32_e32 v94, v92, v93
	v_sub_f32_e32 v95, v90, v94
	v_sub_f32_e32 v90, v90, v95
	v_sub_f32_e32 v92, v94, v92
	v_sub_f32_e32 v90, v90, v94
	v_add_f32_e32 v88, v88, v90
	v_sub_f32_e32 v90, v92, v93
	v_add_f32_e32 v88, v90, v88
	v_add_f32_e32 v90, v95, v88
	v_mul_f32_e32 v92, v89, v90
	v_mul_f32_e32 v93, v87, v92
	v_fma_f32 v87, v92, v87, -v93
	v_fmac_f32_e32 v87, v92, v85
;     __device__ __forceinline__ void operator()(const AccT& acc, const pg8::Unit& u, int wr, int wc, int fr, int fq) const {
;     ...
;                                 lf[(4 * n + j) * MROWS + row] = fminf(x, 0.f) - log1pf(__expf(-fabsf(x)));
;                             }
	v_sub_f32_e32 v85, v95, v90
	v_add_f32_e32 v85, v88, v85
	v_add_f32_e32 v88, v93, v87
	v_sub_f32_e32 v94, v90, v88
	v_sub_f32_e32 v90, v90, v94
	v_sub_f32_e32 v93, v88, v93
	v_sub_f32_e32 v88, v90, v88
	v_add_f32_e32 v85, v85, v88
	v_sub_f32_e32 v87, v93, v87
	v_add_f32_e32 v85, v87, v85
	v_add_f32_e32 v87, v91, v92
	v_add_f32_e32 v85, v94, v85
	v_sub_f32_e32 v88, v87, v91
	v_mul_f32_e32 v85, v89, v85
	v_sub_f32_e32 v88, v92, v88
	v_add_f32_e32 v85, v88, v85
	v_mul_f32_e32 v91, 0x3f317218, v84
	v_add_f32_e32 v88, v87, v85
	v_fma_f32 v92, v84, s7, -v91
	v_mul_f32_e32 v89, v88, v88
	v_fmac_f32_e32 v92, 0xb102e308, v84
	v_sub_f32_e32 v84, v88, v87
	v_fmamk_f32 v90, v89, 0x3e9b6dac, v214
	v_sub_f32_e32 v84, v85, v84
	v_add_f32_e32 v85, v91, v92
	v_fmaak_f32 v90, v89, v90, 0x3f2aaada
	v_sub_f32_e32 v87, v85, v91
	v_ldexp_f32 v91, v88, 1
	v_mul_f32_e32 v88, v88, v89
	v_mul_f32_e32 v88, v88, v90
	v_add_f32_e32 v89, v91, v88
	v_sub_f32_e32 v90, v89, v91
	v_ldexp_f32 v84, v84, 1
	v_sub_f32_e32 v88, v88, v90
	v_add_f32_e32 v84, v84, v88
	v_add_f32_e32 v88, v89, v84
	v_sub_f32_e32 v89, v88, v89
	v_sub_f32_e32 v84, v84, v89
	v_add_f32_e32 v89, v85, v88
	v_sub_f32_e32 v90, v89, v85
	v_sub_f32_e32 v91, v89, v90
	v_sub_f32_e32 v87, v92, v87
	v_sub_f32_e32 v85, v85, v91
	v_sub_f32_e32 v88, v88, v90
	v_add_f32_e32 v85, v88, v85
	v_add_f32_e32 v88, v87, v84
	v_sub_f32_e32 v90, v88, v87
	v_sub_f32_e32 v91, v88, v90
	v_sub_f32_e32 v87, v87, v91
	v_sub_f32_e32 v84, v84, v90
	v_add_f32_e32 v85, v88, v85
	v_add_f32_e32 v84, v84, v87
	v_add_f32_e32 v87, v89, v85
	v_sub_f32_e32 v88, v87, v89
	v_sub_f32_e32 v85, v85, v88
	v_add_f32_e32 v84, v84, v85
	v_add_f32_e32 v84, v87, v84
	v_cndmask_b32_e32 v84, v221, v84, vcc
	v_cmp_ngt_f32_e32 vcc, -1.0, v83
	s_nop 1
	v_cndmask_b32_e32 v84, v222, v84, vcc
	v_cmp_neq_f32_e32 vcc, -1.0, v83
	s_nop 1
	v_cndmask_b32_e32 v84, v219, v84, vcc
	v_cmp_lt_f32_e64 vcc, |v83|, s9
	s_nop 1
	v_cndmask_b32_e32 v83, v84, v83, vcc
	v_lshl_add_u64 v[84:85], v[150:151], 2, s[52:53]
	v_sub_f32_e32 v83, v86, v83
	v_add_co_u32_e32 v86, vcc, s2, v84
	s_mov_b32 s2, 0x10000
	s_nop 0
	v_addc_co_u32_e32 v87, vcc, 0, v85, vcc
	global_store_dword v[86:87], v83, off offset:1216
	v_add_f32_e32 v83, v80, v242
	v_min_f32_e32 v88, 0, v83
	v_mul_f32_e64 v83, |v83|, s3
	v_exp_f32_e32 v83, v83
	s_nop 0
	v_add_f32_e32 v89, 1.0, v83
	v_add_f32_e32 v86, -1.0, v89
	v_sub_f32_e32 v87, v86, v89
	v_add_f32_e32 v87, 1.0, v87
	v_sub_f32_e32 v86, v83, v86
	v_add_f32_e32 v90, v86, v87
	v_frexp_mant_f32_e32 v86, v89
	v_cmp_gt_f32_e32 vcc, s6, v86
	v_cvt_f64_f32_e32 v[86:87], v89
	v_frexp_exp_i32_f64_e32 v86, v[86:87]
	v_subbrev_co_u32_e32 v86, vcc, 0, v86, vcc
	v_sub_u32_e32 v87, 0, v86
	v_ldexp_f32 v89, v89, v87
	v_ldexp_f32 v87, v90, v87
	v_add_f32_e32 v90, -1.0, v89
	v_add_f32_e32 v91, 1.0, v90
	v_sub_f32_e32 v91, v89, v91
	v_add_f32_e32 v91, v87, v91
	v_add_f32_e32 v92, v90, v91
	v_sub_f32_e32 v90, v92, v90
	v_sub_f32_e32 v90, v91, v90
	v_add_f32_e32 v91, 1.0, v89
	v_add_f32_e32 v93, -1.0, v91
	v_sub_f32_e32 v89, v89, v93
	v_add_f32_e32 v87, v87, v89
	v_add_f32_e32 v89, v91, v87
	v_sub_f32_e32 v91, v89, v91
	v_sub_f32_e32 v87, v87, v91
	v_rcp_f32_e32 v91, v89
	v_cvt_f32_i32_e32 v86, v86
	v_cmp_neq_f32_e32 vcc, s8, v83
	v_mul_f32_e32 v93, v92, v91
	v_mul_f32_e32 v94, v89, v93
	v_fma_f32 v95, v93, v89, -v94
	v_fmac_f32_e32 v95, v93, v87
	v_add_f32_e32 v96, v94, v95
	v_sub_f32_e32 v97, v92, v96
	v_sub_f32_e32 v92, v92, v97
	v_sub_f32_e32 v94, v96, v94
	v_sub_f32_e32 v92, v92, v96
	v_add_f32_e32 v90, v90, v92
	v_sub_f32_e32 v92, v94, v95
	v_add_f32_e32 v90, v92, v90
	v_add_f32_e32 v92, v97, v90
	v_mul_f32_e32 v94, v91, v92
	v_mul_f32_e32 v95, v89, v94
	v_fma_f32 v89, v94, v89, -v95
	v_fmac_f32_e32 v89, v94, v87
	v_sub_f32_e32 v87, v97, v92
	v_add_f32_e32 v87, v90, v87
	v_add_f32_e32 v90, v95, v89
	v_sub_f32_e32 v96, v92, v90
	v_sub_f32_e32 v92, v92, v96
	v_sub_f32_e32 v95, v90, v95
	v_sub_f32_e32 v90, v92, v90
	v_add_f32_e32 v87, v87, v90
	v_sub_f32_e32 v89, v95, v89
	v_add_f32_e32 v87, v89, v87
	v_add_f32_e32 v89, v93, v94
	v_add_f32_e32 v87, v96, v87
	v_sub_f32_e32 v90, v89, v93
	v_mul_f32_e32 v87, v91, v87
	v_sub_f32_e32 v90, v94, v90
	v_add_f32_e32 v87, v90, v87
	v_mul_f32_e32 v93, 0x3f317218, v86
	v_add_f32_e32 v90, v89, v87
	v_fma_f32 v94, v86, s7, -v93
	v_mul_f32_e32 v91, v90, v90
	v_fmac_f32_e32 v94, 0xb102e308, v86
	v_sub_f32_e32 v86, v90, v89
	v_fmamk_f32 v92, v91, 0x3e9b6dac, v214
	v_sub_f32_e32 v86, v87, v86
	v_add_f32_e32 v87, v93, v94
	v_fmaak_f32 v92, v91, v92, 0x3f2aaada
	v_sub_f32_e32 v89, v87, v93
	v_ldexp_f32 v93, v90, 1
	v_mul_f32_e32 v90, v90, v91
	v_mul_f32_e32 v90, v90, v92
	v_add_f32_e32 v91, v93, v90
	v_sub_f32_e32 v92, v91, v93
	v_ldexp_f32 v86, v86, 1
	v_sub_f32_e32 v90, v90, v92
	v_add_f32_e32 v86, v86, v90
	v_add_f32_e32 v90, v91, v86
	v_sub_f32_e32 v91, v90, v91
	v_sub_f32_e32 v86, v86, v91
	v_add_f32_e32 v91, v87, v90
	v_sub_f32_e32 v92, v91, v87
	v_sub_f32_e32 v93, v91, v92
	v_sub_f32_e32 v89, v94, v89
	v_sub_f32_e32 v87, v87, v93
	v_sub_f32_e32 v90, v90, v92
	v_add_f32_e32 v87, v90, v87
	v_add_f32_e32 v90, v89, v86
	v_sub_f32_e32 v92, v90, v89
	v_sub_f32_e32 v93, v90, v92
	v_sub_f32_e32 v89, v89, v93
	v_sub_f32_e32 v86, v86, v92
	v_add_f32_e32 v87, v90, v87
	v_add_f32_e32 v86, v86, v89
	v_add_f32_e32 v89, v91, v87
	v_sub_f32_e32 v90, v89, v91
	v_sub_f32_e32 v87, v87, v90
	v_add_f32_e32 v86, v86, v87
	v_add_f32_e32 v86, v89, v86
	v_cndmask_b32_e32 v86, v221, v86, vcc
	v_cmp_ngt_f32_e32 vcc, -1.0, v83
	s_nop 1
	v_cndmask_b32_e32 v86, v222, v86, vcc
	v_cmp_neq_f32_e32 vcc, -1.0, v83
	s_nop 1
	v_cndmask_b32_e32 v86, v219, v86, vcc
;     __device__ __forceinline__ void operator()(const AccT& acc, const pg8::Unit& u, int wr, int wc, int fr, int fq) const {
;     ...
;                     } else if (wc == 1 && fq == 0) {
; #pragma unroll
;                         for (int n = 0; n < 2; ++n)
; #pragma unroll
;                             for (int j = 0; j < 4; ++j) {
;                                 const float x = acc[ai][0][m][n][j] * rs + bfg[4 * n + j];
;                                 lf[(4 * n + j) * MROWS + row] = fminf(x, 0.f) - log1pf(__expf(-fabsf(x)));
;                             }
	v_cmp_lt_f32_e64 vcc, |v83|, s9
	s_nop 1
	v_cndmask_b32_e32 v83, v86, v83, vcc
	v_add_co_u32_e32 v86, vcc, s2, v84
	v_sub_f32_e32 v83, v88, v83
	s_nop 0
	v_addc_co_u32_e32 v87, vcc, 0, v85, vcc
	global_store_dword v[86:87], v83, off offset:2240
	s_mov_b32 s2, 0x18000
	v_add_f32_e32 v83, v81, v243
	v_min_f32_e32 v88, 0, v83
	v_mul_f32_e64 v83, |v83|, s3
	v_exp_f32_e32 v83, v83
	s_nop 0
	v_add_f32_e32 v89, 1.0, v83
	v_add_f32_e32 v86, -1.0, v89
	v_sub_f32_e32 v87, v86, v89
	v_add_f32_e32 v87, 1.0, v87
	v_sub_f32_e32 v86, v83, v86
	v_add_f32_e32 v90, v86, v87
	v_frexp_mant_f32_e32 v86, v89
	v_cmp_gt_f32_e32 vcc, s6, v86
	v_cvt_f64_f32_e32 v[86:87], v89
	v_frexp_exp_i32_f64_e32 v86, v[86:87]
	v_subbrev_co_u32_e32 v86, vcc, 0, v86, vcc
	v_sub_u32_e32 v87, 0, v86
	v_ldexp_f32 v89, v89, v87
	v_ldexp_f32 v87, v90, v87
	v_add_f32_e32 v90, -1.0, v89
	v_add_f32_e32 v91, 1.0, v90
	v_sub_f32_e32 v91, v89, v91
	v_add_f32_e32 v91, v87, v91
	v_add_f32_e32 v92, v90, v91
	v_sub_f32_e32 v90, v92, v90
	v_sub_f32_e32 v90, v91, v90
	v_add_f32_e32 v91, 1.0, v89
	v_add_f32_e32 v93, -1.0, v91
	v_sub_f32_e32 v89, v89, v93
	v_add_f32_e32 v87, v87, v89
	v_add_f32_e32 v89, v91, v87
	v_sub_f32_e32 v91, v89, v91
	v_sub_f32_e32 v87, v87, v91
	v_rcp_f32_e32 v91, v89
	v_cvt_f32_i32_e32 v86, v86
	v_cmp_neq_f32_e32 vcc, s8, v83
	v_mul_f32_e32 v93, v92, v91
	v_mul_f32_e32 v94, v89, v93
	v_fma_f32 v95, v93, v89, -v94
	v_fmac_f32_e32 v95, v93, v87
	v_add_f32_e32 v96, v94, v95
	v_sub_f32_e32 v97, v92, v96
	v_sub_f32_e32 v92, v92, v97
	v_sub_f32_e32 v94, v96, v94
	v_sub_f32_e32 v92, v92, v96
	v_add_f32_e32 v90, v90, v92
	v_sub_f32_e32 v92, v94, v95
	v_add_f32_e32 v90, v92, v90
	v_add_f32_e32 v92, v97, v90
	v_mul_f32_e32 v94, v91, v92
	v_mul_f32_e32 v95, v89, v94
	v_fma_f32 v89, v94, v89, -v95
	v_fmac_f32_e32 v89, v94, v87
	v_sub_f32_e32 v87, v97, v92
	v_add_f32_e32 v87, v90, v87
	v_add_f32_e32 v90, v95, v89
	v_sub_f32_e32 v96, v92, v90
	v_sub_f32_e32 v92, v92, v96
	v_sub_f32_e32 v95, v90, v95
	v_sub_f32_e32 v90, v92, v90
	v_add_f32_e32 v87, v87, v90
	v_sub_f32_e32 v89, v95, v89
	v_add_f32_e32 v87, v89, v87
	v_add_f32_e32 v89, v93, v94
	v_add_f32_e32 v87, v96, v87
	v_sub_f32_e32 v90, v89, v93
	v_mul_f32_e32 v87, v91, v87
	v_sub_f32_e32 v90, v94, v90
	v_add_f32_e32 v87, v90, v87
	v_mul_f32_e32 v93, 0x3f317218, v86
	v_add_f32_e32 v90, v89, v87
	v_fma_f32 v94, v86, s7, -v93
	v_mul_f32_e32 v91, v90, v90
	v_fmac_f32_e32 v94, 0xb102e308, v86
	v_sub_f32_e32 v86, v90, v89
	v_fmamk_f32 v92, v91, 0x3e9b6dac, v214
	v_sub_f32_e32 v86, v87, v86
	v_add_f32_e32 v87, v93, v94
	v_fmaak_f32 v92, v91, v92, 0x3f2aaada
	v_sub_f32_e32 v89, v87, v93
	v_ldexp_f32 v93, v90, 1
	v_mul_f32_e32 v90, v90, v91
	v_mul_f32_e32 v90, v90, v92
	v_add_f32_e32 v91, v93, v90
	v_sub_f32_e32 v92, v91, v93
	v_ldexp_f32 v86, v86, 1
	v_sub_f32_e32 v90, v90, v92
	v_add_f32_e32 v86, v86, v90
	v_add_f32_e32 v90, v91, v86
	v_sub_f32_e32 v91, v90, v91
	v_sub_f32_e32 v86, v86, v91
	v_add_f32_e32 v91, v87, v90
	v_sub_f32_e32 v92, v91, v87
	v_sub_f32_e32 v93, v91, v92
	v_sub_f32_e32 v89, v94, v89
	v_sub_f32_e32 v87, v87, v93
	v_sub_f32_e32 v90, v90, v92
	v_add_f32_e32 v87, v90, v87
	v_add_f32_e32 v90, v89, v86
	v_sub_f32_e32 v92, v90, v89
	v_sub_f32_e32 v93, v90, v92
	v_sub_f32_e32 v89, v89, v93
	v_sub_f32_e32 v86, v86, v92
	v_add_f32_e32 v87, v90, v87
	v_add_f32_e32 v86, v86, v89
	v_add_f32_e32 v89, v91, v87
	v_sub_f32_e32 v90, v89, v91
	v_sub_f32_e32 v87, v87, v90
	v_add_f32_e32 v86, v86, v87
	v_add_f32_e32 v86, v89, v86
	v_cndmask_b32_e32 v86, v221, v86, vcc
	v_cmp_ngt_f32_e32 vcc, -1.0, v83
	s_nop 1
	v_cndmask_b32_e32 v86, v222, v86, vcc
	v_cmp_neq_f32_e32 vcc, -1.0, v83
	s_nop 1
	v_cndmask_b32_e32 v86, v219, v86, vcc
	v_cmp_lt_f32_e64 vcc, |v83|, s9
	s_nop 1
	v_cndmask_b32_e32 v83, v86, v83, vcc
	v_add_co_u32_e32 v86, vcc, s2, v84
	v_sub_f32_e32 v83, v88, v83
	s_nop 0
	v_addc_co_u32_e32 v87, vcc, 0, v85, vcc
	global_store_dword v[86:87], v83, off offset:3264
	s_mov_b32 s2, 0x21000
	v_add_f32_e32 v83, v74, v244
	v_min_f32_e32 v88, 0, v83
	v_mul_f32_e64 v83, |v83|, s3
	v_exp_f32_e32 v83, v83
	s_nop 0
	v_add_f32_e32 v89, 1.0, v83
	v_add_f32_e32 v86, -1.0, v89
	v_sub_f32_e32 v87, v86, v89
	v_add_f32_e32 v87, 1.0, v87
	v_sub_f32_e32 v86, v83, v86
	v_add_f32_e32 v90, v86, v87
	v_frexp_mant_f32_e32 v86, v89
	v_cmp_gt_f32_e32 vcc, s6, v86
	v_cvt_f64_f32_e32 v[86:87], v89
	v_frexp_exp_i32_f64_e32 v86, v[86:87]
	v_subbrev_co_u32_e32 v86, vcc, 0, v86, vcc
	v_sub_u32_e32 v87, 0, v86
	v_ldexp_f32 v89, v89, v87
	v_ldexp_f32 v87, v90, v87
	v_add_f32_e32 v90, -1.0, v89
	v_add_f32_e32 v91, 1.0, v90
	v_sub_f32_e32 v91, v89, v91
	v_add_f32_e32 v91, v87, v91
	v_add_f32_e32 v92, v90, v91
	v_sub_f32_e32 v90, v92, v90
	v_sub_f32_e32 v90, v91, v90
	v_add_f32_e32 v91, 1.0, v89
	v_add_f32_e32 v93, -1.0, v91
	v_sub_f32_e32 v89, v89, v93
	v_add_f32_e32 v87, v87, v89
	v_add_f32_e32 v89, v91, v87
	v_sub_f32_e32 v91, v89, v91
	v_sub_f32_e32 v87, v87, v91
	v_rcp_f32_e32 v91, v89
	v_cvt_f32_i32_e32 v86, v86
	v_cmp_neq_f32_e32 vcc, s8, v83
	v_mul_f32_e32 v93, v92, v91
	v_mul_f32_e32 v94, v89, v93
	v_fma_f32 v95, v93, v89, -v94
	v_fmac_f32_e32 v95, v93, v87
	v_add_f32_e32 v96, v94, v95
	v_sub_f32_e32 v97, v92, v96
	v_sub_f32_e32 v92, v92, v97
	v_sub_f32_e32 v94, v96, v94
	v_sub_f32_e32 v92, v92, v96
	v_add_f32_e32 v90, v90, v92
	v_sub_f32_e32 v92, v94, v95
	v_add_f32_e32 v90, v92, v90
	v_add_f32_e32 v92, v97, v90
	v_mul_f32_e32 v94, v91, v92
	v_mul_f32_e32 v95, v89, v94
	v_fma_f32 v89, v94, v89, -v95
	v_fmac_f32_e32 v89, v94, v87
	v_sub_f32_e32 v87, v97, v92
	v_add_f32_e32 v87, v90, v87
	v_add_f32_e32 v90, v95, v89
	v_sub_f32_e32 v96, v92, v90
;     __device__ __forceinline__ void operator()(const AccT& acc, const pg8::Unit& u, int wr, int wc, int fr, int fq) const {
;     ...
;                     } else if (wc == 1 && fq == 0) {
; #pragma unroll
;                         for (int n = 0; n < 2; ++n)
; #pragma unroll
;                             for (int j = 0; j < 4; ++j) {
;                                 const float x = acc[ai][0][m][n][j] * rs + bfg[4 * n + j];
;                                 lf[(4 * n + j) * MROWS + row] = fminf(x, 0.f) - log1pf(__expf(-fabsf(x)));
;                             }
	v_sub_f32_e32 v92, v92, v96
	v_sub_f32_e32 v95, v90, v95
	v_sub_f32_e32 v90, v92, v90
	v_add_f32_e32 v87, v87, v90
	v_sub_f32_e32 v89, v95, v89
	v_add_f32_e32 v87, v89, v87
	v_add_f32_e32 v89, v93, v94
	v_add_f32_e32 v87, v96, v87
	v_sub_f32_e32 v90, v89, v93
	v_mul_f32_e32 v87, v91, v87
	v_sub_f32_e32 v90, v94, v90
	v_add_f32_e32 v87, v90, v87
	v_mul_f32_e32 v93, 0x3f317218, v86
	v_add_f32_e32 v90, v89, v87
	v_fma_f32 v94, v86, s7, -v93
	v_mul_f32_e32 v91, v90, v90
	v_fmac_f32_e32 v94, 0xb102e308, v86
	v_sub_f32_e32 v86, v90, v89
	v_fmamk_f32 v92, v91, 0x3e9b6dac, v214
	v_sub_f32_e32 v86, v87, v86
	v_add_f32_e32 v87, v93, v94
	v_fmaak_f32 v92, v91, v92, 0x3f2aaada
	v_sub_f32_e32 v89, v87, v93
	v_ldexp_f32 v93, v90, 1
	v_mul_f32_e32 v90, v90, v91
	v_mul_f32_e32 v90, v90, v92
	v_add_f32_e32 v91, v93, v90
	v_sub_f32_e32 v92, v91, v93
	v_ldexp_f32 v86, v86, 1
	v_sub_f32_e32 v90, v90, v92
	v_add_f32_e32 v86, v86, v90
	v_add_f32_e32 v90, v91, v86
	v_sub_f32_e32 v91, v90, v91
	v_sub_f32_e32 v86, v86, v91
	v_add_f32_e32 v91, v87, v90
	v_sub_f32_e32 v92, v91, v87
	v_sub_f32_e32 v93, v91, v92
	v_sub_f32_e32 v89, v94, v89
	v_sub_f32_e32 v87, v87, v93
	v_sub_f32_e32 v90, v90, v92
	v_add_f32_e32 v87, v90, v87
	v_add_f32_e32 v90, v89, v86
	v_sub_f32_e32 v92, v90, v89
	v_sub_f32_e32 v93, v90, v92
	v_sub_f32_e32 v89, v89, v93
	v_sub_f32_e32 v86, v86, v92
	v_add_f32_e32 v87, v90, v87
	v_add_f32_e32 v86, v86, v89
	v_add_f32_e32 v89, v91, v87
	v_sub_f32_e32 v90, v89, v91
	v_sub_f32_e32 v87, v87, v90
	v_add_f32_e32 v86, v86, v87
	v_add_f32_e32 v86, v89, v86
	v_cndmask_b32_e32 v86, v221, v86, vcc
	v_cmp_ngt_f32_e32 vcc, -1.0, v83
	s_nop 1
	v_cndmask_b32_e32 v86, v222, v86, vcc
	v_cmp_neq_f32_e32 vcc, -1.0, v83
	s_nop 1
	v_cndmask_b32_e32 v86, v219, v86, vcc
	v_cmp_lt_f32_e64 vcc, |v83|, s9
	s_nop 1
	v_cndmask_b32_e32 v83, v86, v83, vcc
	v_add_co_u32_e32 v86, vcc, s2, v84
	v_sub_f32_e32 v83, v88, v83
	s_nop 0
	v_addc_co_u32_e32 v87, vcc, 0, v85, vcc
	global_store_dword v[86:87], v83, off offset:192
	s_mov_b32 s2, 0x29000
	v_add_f32_e32 v83, v75, v245
	v_min_f32_e32 v88, 0, v83
	v_mul_f32_e64 v83, |v83|, s3
	v_exp_f32_e32 v83, v83
	s_nop 0
	v_add_f32_e32 v89, 1.0, v83
	v_add_f32_e32 v86, -1.0, v89
	v_sub_f32_e32 v87, v86, v89
	v_add_f32_e32 v87, 1.0, v87
	v_sub_f32_e32 v86, v83, v86
	v_add_f32_e32 v90, v86, v87
	v_frexp_mant_f32_e32 v86, v89
	v_cmp_gt_f32_e32 vcc, s6, v86
	v_cvt_f64_f32_e32 v[86:87], v89
	v_frexp_exp_i32_f64_e32 v86, v[86:87]
	v_subbrev_co_u32_e32 v86, vcc, 0, v86, vcc
	v_sub_u32_e32 v87, 0, v86
	v_ldexp_f32 v89, v89, v87
	v_ldexp_f32 v87, v90, v87
	v_add_f32_e32 v90, -1.0, v89
	v_add_f32_e32 v91, 1.0, v90
	v_sub_f32_e32 v91, v89, v91
	v_add_f32_e32 v91, v87, v91
	v_add_f32_e32 v92, v90, v91
	v_sub_f32_e32 v90, v92, v90
	v_sub_f32_e32 v90, v91, v90
	v_add_f32_e32 v91, 1.0, v89
	v_add_f32_e32 v93, -1.0, v91
	v_sub_f32_e32 v89, v89, v93
	v_add_f32_e32 v87, v87, v89
	v_add_f32_e32 v89, v91, v87
	v_sub_f32_e32 v91, v89, v91
	v_sub_f32_e32 v87, v87, v91
	v_rcp_f32_e32 v91, v89
	v_cvt_f32_i32_e32 v86, v86
	v_cmp_neq_f32_e32 vcc, s8, v83
	v_mul_f32_e32 v93, v92, v91
	v_mul_f32_e32 v94, v89, v93
	v_fma_f32 v95, v93, v89, -v94
	v_fmac_f32_e32 v95, v93, v87
	v_add_f32_e32 v96, v94, v95
	v_sub_f32_e32 v97, v92, v96
	v_sub_f32_e32 v92, v92, v97
	v_sub_f32_e32 v94, v96, v94
	v_sub_f32_e32 v92, v92, v96
	v_add_f32_e32 v90, v90, v92
	v_sub_f32_e32 v92, v94, v95
	v_add_f32_e32 v90, v92, v90
	v_add_f32_e32 v92, v97, v90
	v_mul_f32_e32 v94, v91, v92
	v_mul_f32_e32 v95, v89, v94
	v_fma_f32 v89, v94, v89, -v95
	v_fmac_f32_e32 v89, v94, v87
	v_sub_f32_e32 v87, v97, v92
	v_add_f32_e32 v87, v90, v87
	v_add_f32_e32 v90, v95, v89
	v_sub_f32_e32 v96, v92, v90
	v_sub_f32_e32 v92, v92, v96
	v_sub_f32_e32 v95, v90, v95
	v_sub_f32_e32 v90, v92, v90
	v_add_f32_e32 v87, v87, v90
	v_sub_f32_e32 v89, v95, v89
	v_add_f32_e32 v87, v89, v87
	v_add_f32_e32 v89, v93, v94
	v_add_f32_e32 v87, v96, v87
	v_sub_f32_e32 v90, v89, v93
	v_mul_f32_e32 v87, v91, v87
	v_sub_f32_e32 v90, v94, v90
	v_add_f32_e32 v87, v90, v87
	v_mul_f32_e32 v93, 0x3f317218, v86
	v_add_f32_e32 v90, v89, v87
	v_fma_f32 v94, v86, s7, -v93
	v_mul_f32_e32 v91, v90, v90
	v_fmac_f32_e32 v94, 0xb102e308, v86
	v_sub_f32_e32 v86, v90, v89
	v_fmamk_f32 v92, v91, 0x3e9b6dac, v214
	v_sub_f32_e32 v86, v87, v86
	v_add_f32_e32 v87, v93, v94
	v_fmaak_f32 v92, v91, v92, 0x3f2aaada
	v_sub_f32_e32 v89, v87, v93
	v_ldexp_f32 v93, v90, 1
	v_mul_f32_e32 v90, v90, v91
	v_mul_f32_e32 v90, v90, v92
	v_add_f32_e32 v91, v93, v90
	v_sub_f32_e32 v92, v91, v93
	v_ldexp_f32 v86, v86, 1
	v_sub_f32_e32 v90, v90, v92
	v_add_f32_e32 v86, v86, v90
	v_add_f32_e32 v90, v91, v86
	v_sub_f32_e32 v91, v90, v91
	v_sub_f32_e32 v86, v86, v91
	v_add_f32_e32 v91, v87, v90
	v_sub_f32_e32 v92, v91, v87
	v_sub_f32_e32 v93, v91, v92
	v_sub_f32_e32 v89, v94, v89
	v_sub_f32_e32 v87, v87, v93
	v_sub_f32_e32 v90, v90, v92
	v_add_f32_e32 v87, v90, v87
	v_add_f32_e32 v90, v89, v86
	v_sub_f32_e32 v92, v90, v89
	v_sub_f32_e32 v93, v90, v92
	v_sub_f32_e32 v89, v89, v93
	v_sub_f32_e32 v86, v86, v92
	v_add_f32_e32 v87, v90, v87
	v_add_f32_e32 v86, v86, v89
	v_add_f32_e32 v89, v91, v87
	v_sub_f32_e32 v90, v89, v91
	v_sub_f32_e32 v87, v87, v90
	v_add_f32_e32 v86, v86, v87
	v_add_f32_e32 v86, v89, v86
	v_cndmask_b32_e32 v86, v221, v86, vcc
	v_cmp_ngt_f32_e32 vcc, -1.0, v83
	s_nop 1
	v_cndmask_b32_e32 v86, v222, v86, vcc
	v_cmp_neq_f32_e32 vcc, -1.0, v83
	s_nop 1
	v_cndmask_b32_e32 v86, v219, v86, vcc
	v_cmp_lt_f32_e64 vcc, |v83|, s9
	s_nop 1
	v_cndmask_b32_e32 v83, v86, v83, vcc
	v_add_co_u32_e32 v86, vcc, s2, v84
	v_sub_f32_e32 v83, v88, v83
	s_nop 0
;     __device__ __forceinline__ void operator()(const AccT& acc, const pg8::Unit& u, int wr, int wc, int fr, int fq) const {
;     ...
;                     } else if (wc == 1 && fq == 0) {
; #pragma unroll
;                         for (int n = 0; n < 2; ++n)
; #pragma unroll
;                             for (int j = 0; j < 4; ++j) {
;                                 const float x = acc[ai][0][m][n][j] * rs + bfg[4 * n + j];
;                                 lf[(4 * n + j) * MROWS + row] = fminf(x, 0.f) - log1pf(__expf(-fabsf(x)));
;                             }
	v_addc_co_u32_e32 v87, vcc, 0, v85, vcc
	global_store_dword v[86:87], v83, off offset:1216
	s_mov_b32 s2, 0x31000
	v_add_f32_e32 v83, v76, v246
	v_min_f32_e32 v88, 0, v83
	v_mul_f32_e64 v83, |v83|, s3
	v_exp_f32_e32 v83, v83
	s_nop 0
	v_add_f32_e32 v89, 1.0, v83
	v_add_f32_e32 v86, -1.0, v89
	v_sub_f32_e32 v87, v86, v89
	v_add_f32_e32 v87, 1.0, v87
	v_sub_f32_e32 v86, v83, v86
	v_add_f32_e32 v90, v86, v87
	v_frexp_mant_f32_e32 v86, v89
	v_cmp_gt_f32_e32 vcc, s6, v86
	v_cvt_f64_f32_e32 v[86:87], v89
	v_frexp_exp_i32_f64_e32 v86, v[86:87]
	v_subbrev_co_u32_e32 v86, vcc, 0, v86, vcc
	v_sub_u32_e32 v87, 0, v86
	v_ldexp_f32 v89, v89, v87
	v_ldexp_f32 v87, v90, v87
	v_add_f32_e32 v90, -1.0, v89
	v_add_f32_e32 v91, 1.0, v90
	v_sub_f32_e32 v91, v89, v91
	v_add_f32_e32 v91, v87, v91
	v_add_f32_e32 v92, v90, v91
	v_sub_f32_e32 v90, v92, v90
	v_sub_f32_e32 v90, v91, v90
	v_add_f32_e32 v91, 1.0, v89
	v_add_f32_e32 v93, -1.0, v91
	v_sub_f32_e32 v89, v89, v93
	v_add_f32_e32 v87, v87, v89
	v_add_f32_e32 v89, v91, v87
	v_sub_f32_e32 v91, v89, v91
	v_sub_f32_e32 v87, v87, v91
	v_rcp_f32_e32 v91, v89
	v_cvt_f32_i32_e32 v86, v86
	v_cmp_neq_f32_e32 vcc, s8, v83
	v_mul_f32_e32 v93, v92, v91
	v_mul_f32_e32 v94, v89, v93
	v_fma_f32 v95, v93, v89, -v94
	v_fmac_f32_e32 v95, v93, v87
	v_add_f32_e32 v96, v94, v95
	v_sub_f32_e32 v97, v92, v96
	v_sub_f32_e32 v92, v92, v97
	v_sub_f32_e32 v94, v96, v94
	v_sub_f32_e32 v92, v92, v96
	v_add_f32_e32 v90, v90, v92
	v_sub_f32_e32 v92, v94, v95
	v_add_f32_e32 v90, v92, v90
	v_add_f32_e32 v92, v97, v90
	v_mul_f32_e32 v94, v91, v92
	v_mul_f32_e32 v95, v89, v94
	v_fma_f32 v89, v94, v89, -v95
	v_fmac_f32_e32 v89, v94, v87
	v_sub_f32_e32 v87, v97, v92
	v_add_f32_e32 v87, v90, v87
	v_add_f32_e32 v90, v95, v89
	v_sub_f32_e32 v96, v92, v90
	v_sub_f32_e32 v92, v92, v96
	v_sub_f32_e32 v95, v90, v95
	v_sub_f32_e32 v90, v92, v90
	v_add_f32_e32 v87, v87, v90
	v_sub_f32_e32 v89, v95, v89
	v_add_f32_e32 v87, v89, v87
	v_add_f32_e32 v89, v93, v94
	v_add_f32_e32 v87, v96, v87
	v_sub_f32_e32 v90, v89, v93
	v_mul_f32_e32 v87, v91, v87
	v_sub_f32_e32 v90, v94, v90
	v_add_f32_e32 v87, v90, v87
	v_mul_f32_e32 v93, 0x3f317218, v86
	v_add_f32_e32 v90, v89, v87
	v_fma_f32 v94, v86, s7, -v93
	v_mul_f32_e32 v91, v90, v90
	v_fmac_f32_e32 v94, 0xb102e308, v86
	v_sub_f32_e32 v86, v90, v89
	v_fmamk_f32 v92, v91, 0x3e9b6dac, v214
	v_sub_f32_e32 v86, v87, v86
	v_add_f32_e32 v87, v93, v94
	v_fmaak_f32 v92, v91, v92, 0x3f2aaada
	v_sub_f32_e32 v89, v87, v93
	v_ldexp_f32 v93, v90, 1
	v_mul_f32_e32 v90, v90, v91
	v_mul_f32_e32 v90, v90, v92
	v_add_f32_e32 v91, v93, v90
	v_sub_f32_e32 v92, v91, v93
	v_ldexp_f32 v86, v86, 1
	v_sub_f32_e32 v90, v90, v92
	v_add_f32_e32 v86, v86, v90
	v_add_f32_e32 v90, v91, v86
	v_sub_f32_e32 v91, v90, v91
	v_sub_f32_e32 v86, v86, v91
	v_add_f32_e32 v91, v87, v90
	v_sub_f32_e32 v92, v91, v87
	v_sub_f32_e32 v93, v91, v92
	v_sub_f32_e32 v89, v94, v89
	v_sub_f32_e32 v87, v87, v93
	v_sub_f32_e32 v90, v90, v92
	v_add_f32_e32 v87, v90, v87
	v_add_f32_e32 v90, v89, v86
	v_sub_f32_e32 v92, v90, v89
	v_sub_f32_e32 v93, v90, v92
	v_sub_f32_e32 v89, v89, v93
	v_sub_f32_e32 v86, v86, v92
	v_add_f32_e32 v87, v90, v87
	v_add_f32_e32 v86, v86, v89
	v_add_f32_e32 v89, v91, v87
	v_sub_f32_e32 v90, v89, v91
	v_sub_f32_e32 v87, v87, v90
	v_add_f32_e32 v86, v86, v87
	v_add_f32_e32 v86, v89, v86
	v_cndmask_b32_e32 v86, v221, v86, vcc
	v_cmp_ngt_f32_e32 vcc, -1.0, v83
	s_nop 1
	v_cndmask_b32_e32 v86, v222, v86, vcc
	v_cmp_neq_f32_e32 vcc, -1.0, v83
	s_nop 1
	v_cndmask_b32_e32 v86, v219, v86, vcc
	v_cmp_lt_f32_e64 vcc, |v83|, s9
	s_nop 1
	v_cndmask_b32_e32 v83, v86, v83, vcc
	v_add_co_u32_e32 v86, vcc, s2, v84
	v_sub_f32_e32 v83, v88, v83
	s_nop 0
	v_addc_co_u32_e32 v87, vcc, 0, v85, vcc
;     __device__ __forceinline__ void operator()(const AccT& acc, const pg8::Unit& u, int wr, int wc, int fr, int fq) const {
;     ...
;                     } else if (wc == 1 && fq == 0) {
; #pragma unroll
;                         for (int n = 0; n < 2; ++n)
; #pragma unroll
;                             for (int j = 0; j < 4; ++j) {
;                                 const float x = acc[ai][0][m][n][j] * rs + bfg[4 * n + j];
;                                 lf[(4 * n + j) * MROWS + row] = fminf(x, 0.f) - log1pf(__expf(-fabsf(x)));
;                             }
	global_store_dword v[86:87], v83, off offset:2240
	v_add_f32_e32 v83, v77, v247
	v_min_f32_e32 v88, 0, v83
	v_mul_f32_e64 v83, |v83|, s3
	v_exp_f32_e32 v83, v83
	s_nop 0
	v_add_f32_e32 v89, 1.0, v83
	v_add_f32_e32 v86, -1.0, v89
	v_sub_f32_e32 v87, v86, v89
	v_add_f32_e32 v87, 1.0, v87
	v_sub_f32_e32 v86, v83, v86
	v_add_f32_e32 v90, v86, v87
	v_frexp_mant_f32_e32 v86, v89
	v_cmp_gt_f32_e32 vcc, s6, v86
	v_cvt_f64_f32_e32 v[86:87], v89
	v_frexp_exp_i32_f64_e32 v86, v[86:87]
	v_subbrev_co_u32_e32 v86, vcc, 0, v86, vcc
	v_sub_u32_e32 v87, 0, v86
	v_ldexp_f32 v89, v89, v87
	v_ldexp_f32 v87, v90, v87
	v_add_f32_e32 v90, -1.0, v89
	v_add_f32_e32 v91, 1.0, v90
	v_sub_f32_e32 v91, v89, v91
	v_add_f32_e32 v91, v87, v91
	v_add_f32_e32 v92, v90, v91
	v_sub_f32_e32 v90, v92, v90
	v_sub_f32_e32 v90, v91, v90
	v_add_f32_e32 v91, 1.0, v89
	v_add_f32_e32 v93, -1.0, v91
	v_sub_f32_e32 v89, v89, v93
	v_add_f32_e32 v87, v87, v89
	v_add_f32_e32 v89, v91, v87
	v_sub_f32_e32 v91, v89, v91
	v_sub_f32_e32 v87, v87, v91
	v_rcp_f32_e32 v91, v89
	v_cvt_f32_i32_e32 v86, v86
	v_cmp_neq_f32_e32 vcc, s8, v83
	v_mul_f32_e32 v93, v92, v91
	v_mul_f32_e32 v94, v89, v93
	v_fma_f32 v95, v93, v89, -v94
	v_fmac_f32_e32 v95, v93, v87
	v_add_f32_e32 v96, v94, v95
	v_sub_f32_e32 v97, v92, v96
	v_sub_f32_e32 v92, v92, v97
	v_sub_f32_e32 v94, v96, v94
	v_sub_f32_e32 v92, v92, v96
	v_add_f32_e32 v90, v90, v92
	v_sub_f32_e32 v92, v94, v95
	v_add_f32_e32 v90, v92, v90
	v_add_f32_e32 v92, v97, v90
	v_mul_f32_e32 v94, v91, v92
	v_mul_f32_e32 v95, v89, v94
	v_fma_f32 v89, v94, v89, -v95
	v_fmac_f32_e32 v89, v94, v87
	v_sub_f32_e32 v87, v97, v92
	v_add_f32_e32 v87, v90, v87
	v_add_f32_e32 v90, v95, v89
	v_sub_f32_e32 v96, v92, v90
	v_sub_f32_e32 v92, v92, v96
	v_sub_f32_e32 v95, v90, v95
	v_sub_f32_e32 v90, v92, v90
	v_add_f32_e32 v87, v87, v90
	v_sub_f32_e32 v89, v95, v89
	v_add_f32_e32 v87, v89, v87
	v_add_f32_e32 v89, v93, v94
	v_add_f32_e32 v87, v96, v87
	v_sub_f32_e32 v90, v89, v93
	v_mul_f32_e32 v87, v91, v87
	v_sub_f32_e32 v90, v94, v90
	v_add_f32_e32 v87, v90, v87
	v_mul_f32_e32 v93, 0x3f317218, v86
	v_add_f32_e32 v90, v89, v87
	v_fma_f32 v94, v86, s7, -v93
	v_mul_f32_e32 v91, v90, v90
	v_fmac_f32_e32 v94, 0xb102e308, v86
	v_sub_f32_e32 v86, v90, v89
	v_fmamk_f32 v92, v91, 0x3e9b6dac, v214
	v_sub_f32_e32 v86, v87, v86
	v_add_f32_e32 v87, v93, v94
	v_fmaak_f32 v92, v91, v92, 0x3f2aaada
	v_sub_f32_e32 v89, v87, v93
	v_ldexp_f32 v93, v90, 1
	v_mul_f32_e32 v90, v90, v91
	v_mul_f32_e32 v90, v90, v92
	v_add_f32_e32 v91, v93, v90
	v_sub_f32_e32 v92, v91, v93
	v_ldexp_f32 v86, v86, 1
	v_sub_f32_e32 v90, v90, v92
	v_add_f32_e32 v86, v86, v90
	v_add_f32_e32 v90, v91, v86
	v_sub_f32_e32 v91, v90, v91
	v_sub_f32_e32 v86, v86, v91
	v_add_f32_e32 v91, v87, v90
	v_sub_f32_e32 v92, v91, v87
	v_sub_f32_e32 v93, v91, v92
	v_sub_f32_e32 v89, v94, v89
	v_sub_f32_e32 v87, v87, v93
	v_sub_f32_e32 v90, v90, v92
	v_add_f32_e32 v87, v90, v87
	v_add_f32_e32 v90, v89, v86
	v_sub_f32_e32 v92, v90, v89
	v_sub_f32_e32 v93, v90, v92
	v_sub_f32_e32 v89, v89, v93
	v_sub_f32_e32 v86, v86, v92
	v_add_f32_e32 v87, v90, v87
	v_add_f32_e32 v86, v86, v89
	v_add_f32_e32 v89, v91, v87
	v_sub_f32_e32 v90, v89, v91
	v_sub_f32_e32 v87, v87, v90
	v_add_f32_e32 v86, v86, v87
	v_add_f32_e32 v86, v89, v86
	v_cndmask_b32_e32 v86, v221, v86, vcc
	v_cmp_ngt_f32_e32 vcc, -1.0, v83
	s_nop 1
	v_cndmask_b32_e32 v86, v222, v86, vcc
	v_cmp_neq_f32_e32 vcc, -1.0, v83
	s_nop 1
	v_cndmask_b32_e32 v86, v219, v86, vcc
	v_cmp_lt_f32_e64 vcc, |v83|, s9
	s_nop 1
	v_cndmask_b32_e32 v83, v86, v83, vcc
	v_add_co_u32_e32 v84, vcc, 0x39000, v84
	v_sub_f32_e32 v83, v88, v83
	s_nop 0
	v_addc_co_u32_e32 v85, vcc, 0, v85, vcc
	global_store_dword v[84:85], v83, off offset:3264

;     __device__ __forceinline__ void operator()(const AccT& acc, const pg8::Unit& u, int wr, int wc, int fr, int fq) const {
;     ...
;             for (int m = 0; m < 4; ++m) {
;                 const int row = row0 + ai * 128 + m * 16;
;                 const float rs = 1.0f;
;                 if (u.pn < 20) {
;     ...
;                     } else if (wc == 1 && fq == 0) {
; #pragma unroll
;                         for (int n = 0; n < 2; ++n)
; #pragma unroll
;                             for (int j = 0; j < 4; ++j) {
;                                 const float x = acc[ai][0][m][n][j] * rs + bfg[4 * n + j];
;                                 lf[(4 * n + j) * MROWS + row] = fminf(x, 0.f) - log1pf(__expf(-fabsf(x)));
;                             }
.LBB0_998:
	v_add_u32_e32 v66, 0x80, v150
	s_and_b64 vcc, exec, s[44:45]
	s_mov_b64 s[8:9], -1
	s_cbranch_vccnz .LBB0_1006
	s_and_b64 vcc, exec, s[42:43]
	s_cbranch_vccnz .LBB0_1003
	s_and_saveexec_b64 s[70:71], s[58:59]
	s_cbranch_execz .LBB0_1002
	s_waitcnt lgkmcnt(0)
	s_mov_b32 s3, 0xbfb8aa3b
	s_mov_b32 s6, 0x3f2aaaab
	s_mov_b32 s7, 0x3f317218
	s_mov_b32 s8, 0x7f800000
	s_mov_b32 s9, 0x33800000
	v_ashrrev_i32_e32 v151, 31, v150
	s_mov_b32 s2, 0x8000
	v_add_f32_e32 v67, v62, v240
	v_min_f32_e32 v70, 0, v67
	v_mul_f32_e64 v67, |v67|, s3
	v_exp_f32_e32 v67, v67
	s_nop 0
	v_add_f32_e32 v71, 1.0, v67
	v_add_f32_e32 v68, -1.0, v71
	v_sub_f32_e32 v69, v68, v71
	v_add_f32_e32 v69, 1.0, v69
	v_sub_f32_e32 v68, v67, v68
	v_add_f32_e32 v72, v68, v69
	v_frexp_mant_f32_e32 v68, v71
	v_cmp_gt_f32_e32 vcc, s6, v68
	v_cvt_f64_f32_e32 v[68:69], v71
	v_frexp_exp_i32_f64_e32 v68, v[68:69]
	v_subbrev_co_u32_e32 v68, vcc, 0, v68, vcc
	v_sub_u32_e32 v69, 0, v68
	v_ldexp_f32 v71, v71, v69
	v_ldexp_f32 v69, v72, v69
	v_add_f32_e32 v72, -1.0, v71
	v_add_f32_e32 v73, 1.0, v72
	v_sub_f32_e32 v73, v71, v73
	v_add_f32_e32 v73, v69, v73
	v_add_f32_e32 v74, v72, v73
	v_sub_f32_e32 v72, v74, v72
	v_sub_f32_e32 v72, v73, v72
	v_add_f32_e32 v73, 1.0, v71
	v_add_f32_e32 v75, -1.0, v73
	v_sub_f32_e32 v71, v71, v75
	v_add_f32_e32 v69, v69, v71
	v_add_f32_e32 v71, v73, v69
	v_sub_f32_e32 v73, v71, v73
	v_sub_f32_e32 v69, v69, v73
	v_rcp_f32_e32 v73, v71
	v_cvt_f32_i32_e32 v68, v68
	v_cmp_neq_f32_e32 vcc, s8, v67
	v_mul_f32_e32 v75, v74, v73
	v_mul_f32_e32 v76, v71, v75
	v_fma_f32 v77, v75, v71, -v76
	v_fmac_f32_e32 v77, v75, v69
	v_add_f32_e32 v78, v76, v77
	v_sub_f32_e32 v79, v74, v78
	v_sub_f32_e32 v74, v74, v79
	v_sub_f32_e32 v76, v78, v76
	v_sub_f32_e32 v74, v74, v78
	v_add_f32_e32 v72, v72, v74
	v_sub_f32_e32 v74, v76, v77
	v_add_f32_e32 v72, v74, v72
	v_add_f32_e32 v74, v79, v72
	v_mul_f32_e32 v76, v73, v74
	v_mul_f32_e32 v77, v71, v76
	v_fma_f32 v71, v76, v71, -v77
	v_fmac_f32_e32 v71, v76, v69
	v_sub_f32_e32 v69, v79, v74
	v_add_f32_e32 v69, v72, v69
	v_add_f32_e32 v72, v77, v71
	v_sub_f32_e32 v78, v74, v72
	v_sub_f32_e32 v74, v74, v78
	v_sub_f32_e32 v77, v72, v77
	v_sub_f32_e32 v72, v74, v72
	v_add_f32_e32 v69, v69, v72
	v_sub_f32_e32 v71, v77, v71
	v_add_f32_e32 v69, v71, v69
	v_add_f32_e32 v71, v75, v76
	v_add_f32_e32 v69, v78, v69
	v_sub_f32_e32 v72, v71, v75
	v_mul_f32_e32 v69, v73, v69
	v_sub_f32_e32 v72, v76, v72
	v_add_f32_e32 v69, v72, v69
	v_mul_f32_e32 v75, 0x3f317218, v68
	v_add_f32_e32 v72, v71, v69
	v_fma_f32 v76, v68, s7, -v75
	v_mul_f32_e32 v73, v72, v72
	v_fmac_f32_e32 v76, 0xb102e308, v68
	v_sub_f32_e32 v68, v72, v71
	v_fmamk_f32 v74, v73, 0x3e9b6dac, v214
	v_sub_f32_e32 v68, v69, v68
	v_add_f32_e32 v69, v75, v76
	v_fmaak_f32 v74, v73, v74, 0x3f2aaada
	v_sub_f32_e32 v71, v69, v75
	v_ldexp_f32 v75, v72, 1
	v_mul_f32_e32 v72, v72, v73
	v_mul_f32_e32 v72, v72, v74
	v_add_f32_e32 v73, v75, v72
	v_sub_f32_e32 v74, v73, v75
	v_ldexp_f32 v68, v68, 1
	v_sub_f32_e32 v72, v72, v74
	v_add_f32_e32 v68, v68, v72
	v_add_f32_e32 v72, v73, v68
	v_sub_f32_e32 v73, v72, v73
	v_sub_f32_e32 v68, v68, v73
	v_add_f32_e32 v73, v69, v72
	v_sub_f32_e32 v74, v73, v69
	v_sub_f32_e32 v75, v73, v74
	v_sub_f32_e32 v71, v76, v71
	v_sub_f32_e32 v69, v69, v75
	v_sub_f32_e32 v72, v72, v74
	v_add_f32_e32 v69, v72, v69
	v_add_f32_e32 v72, v71, v68
	v_sub_f32_e32 v74, v72, v71
	v_sub_f32_e32 v75, v72, v74
	v_sub_f32_e32 v71, v71, v75
	v_sub_f32_e32 v68, v68, v74
	v_add_f32_e32 v69, v72, v69
	v_add_f32_e32 v68, v68, v71
	v_add_f32_e32 v71, v73, v69
	v_sub_f32_e32 v72, v71, v73
	v_sub_f32_e32 v69, v69, v72
	v_add_f32_e32 v68, v68, v69
	v_add_f32_e32 v68, v71, v68
	v_cndmask_b32_e32 v68, v221, v68, vcc
	v_cmp_ngt_f32_e32 vcc, -1.0, v67
	s_nop 1
	v_cndmask_b32_e32 v68, v222, v68, vcc
	v_cmp_neq_f32_e32 vcc, -1.0, v67
	s_nop 1
	v_cndmask_b32_e32 v68, v219, v68, vcc
	v_cmp_lt_f32_e64 vcc, |v67|, s9
	s_nop 1
	v_cndmask_b32_e32 v67, v68, v67, vcc
	v_sub_f32_e32 v70, v70, v67
	v_ashrrev_i32_e32 v67, 31, v66
	v_lshl_add_u64 v[68:69], v[66:67], 2, s[52:53]
	global_store_dword v[68:69], v70, off
	v_add_f32_e32 v67, v63, v241
	v_min_f32_e32 v70, 0, v67
	v_mul_f32_e64 v67, |v67|, s3
	v_exp_f32_e32 v67, v67
	s_nop 0
	v_add_f32_e32 v71, 1.0, v67
	v_add_f32_e32 v68, -1.0, v71
	v_sub_f32_e32 v69, v68, v71
	v_add_f32_e32 v69, 1.0, v69
	v_sub_f32_e32 v68, v67, v68
	v_add_f32_e32 v72, v68, v69
	v_frexp_mant_f32_e32 v68, v71
	v_cmp_gt_f32_e32 vcc, s6, v68
	v_cvt_f64_f32_e32 v[68:69], v71
	v_frexp_exp_i32_f64_e32 v68, v[68:69]
	v_subbrev_co_u32_e32 v68, vcc, 0, v68, vcc
	v_sub_u32_e32 v69, 0, v68
	v_ldexp_f32 v71, v71, v69
	v_ldexp_f32 v69, v72, v69
	v_add_f32_e32 v72, -1.0, v71
	v_add_f32_e32 v73, 1.0, v72
	v_sub_f32_e32 v73, v71, v73
	v_add_f32_e32 v73, v69, v73
	v_add_f32_e32 v74, v72, v73
	v_sub_f32_e32 v72, v74, v72
	v_sub_f32_e32 v72, v73, v72
	v_add_f32_e32 v73, 1.0, v71
	v_add_f32_e32 v75, -1.0, v73
	v_sub_f32_e32 v71, v71, v75
	v_add_f32_e32 v69, v69, v71
	v_add_f32_e32 v71, v73, v69
	v_sub_f32_e32 v73, v71, v73
	v_sub_f32_e32 v69, v69, v73
	v_rcp_f32_e32 v73, v71
	v_cvt_f32_i32_e32 v68, v68
	v_cmp_neq_f32_e32 vcc, s8, v67
	v_mul_f32_e32 v75, v74, v73
	v_mul_f32_e32 v76, v71, v75
	v_fma_f32 v77, v75, v71, -v76
	v_fmac_f32_e32 v77, v75, v69
	v_add_f32_e32 v78, v76, v77
	v_sub_f32_e32 v79, v74, v78
	v_sub_f32_e32 v74, v74, v79
	v_sub_f32_e32 v76, v78, v76
	v_sub_f32_e32 v74, v74, v78
	v_add_f32_e32 v72, v72, v74
	v_sub_f32_e32 v74, v76, v77
	v_add_f32_e32 v72, v74, v72
	v_add_f32_e32 v74, v79, v72
	v_mul_f32_e32 v76, v73, v74
	v_mul_f32_e32 v77, v71, v76
	v_fma_f32 v71, v76, v71, -v77
;     __device__ __forceinline__ void operator()(const AccT& acc, const pg8::Unit& u, int wr, int wc, int fr, int fq) const {
;     ...
;                                 lf[(4 * n + j) * MROWS + row] = fminf(x, 0.f) - log1pf(__expf(-fabsf(x)));
;                             }
	v_fmac_f32_e32 v71, v76, v69
	v_sub_f32_e32 v69, v79, v74
	v_add_f32_e32 v69, v72, v69
	v_add_f32_e32 v72, v77, v71
	v_sub_f32_e32 v78, v74, v72
	v_sub_f32_e32 v74, v74, v78
	v_sub_f32_e32 v77, v72, v77
	v_sub_f32_e32 v72, v74, v72
	v_add_f32_e32 v69, v69, v72
	v_sub_f32_e32 v71, v77, v71
	v_add_f32_e32 v69, v71, v69
	v_add_f32_e32 v71, v75, v76
	v_add_f32_e32 v69, v78, v69
	v_sub_f32_e32 v72, v71, v75
	v_mul_f32_e32 v69, v73, v69
	v_sub_f32_e32 v72, v76, v72
	v_add_f32_e32 v69, v72, v69
	v_mul_f32_e32 v75, 0x3f317218, v68
	v_add_f32_e32 v72, v71, v69
	v_fma_f32 v76, v68, s7, -v75
	v_mul_f32_e32 v73, v72, v72
	v_fmac_f32_e32 v76, 0xb102e308, v68
	v_sub_f32_e32 v68, v72, v71
	v_fmamk_f32 v74, v73, 0x3e9b6dac, v214
	v_sub_f32_e32 v68, v69, v68
	v_add_f32_e32 v69, v75, v76
	v_fmaak_f32 v74, v73, v74, 0x3f2aaada
	v_sub_f32_e32 v71, v69, v75
	v_ldexp_f32 v75, v72, 1
	v_mul_f32_e32 v72, v72, v73
	v_mul_f32_e32 v72, v72, v74
	v_add_f32_e32 v73, v75, v72
	v_sub_f32_e32 v74, v73, v75
	v_ldexp_f32 v68, v68, 1
	v_sub_f32_e32 v72, v72, v74
	v_add_f32_e32 v68, v68, v72
	v_add_f32_e32 v72, v73, v68
	v_sub_f32_e32 v73, v72, v73
	v_sub_f32_e32 v68, v68, v73
	v_add_f32_e32 v73, v69, v72
	v_sub_f32_e32 v74, v73, v69
	v_sub_f32_e32 v75, v73, v74
	v_sub_f32_e32 v71, v76, v71
	v_sub_f32_e32 v69, v69, v75
	v_sub_f32_e32 v72, v72, v74
	v_add_f32_e32 v69, v72, v69
	v_add_f32_e32 v72, v71, v68
	v_sub_f32_e32 v74, v72, v71
	v_sub_f32_e32 v75, v72, v74
	v_sub_f32_e32 v71, v71, v75
	v_sub_f32_e32 v68, v68, v74
	v_add_f32_e32 v69, v72, v69
	v_add_f32_e32 v68, v68, v71
	v_add_f32_e32 v71, v73, v69
	v_sub_f32_e32 v72, v71, v73
	v_sub_f32_e32 v69, v69, v72
	v_add_f32_e32 v68, v68, v69
	v_add_f32_e32 v68, v71, v68
	v_cndmask_b32_e32 v68, v221, v68, vcc
	v_cmp_ngt_f32_e32 vcc, -1.0, v67
	s_nop 1
	v_cndmask_b32_e32 v68, v222, v68, vcc
	v_cmp_neq_f32_e32 vcc, -1.0, v67
	s_nop 1
	v_cndmask_b32_e32 v68, v219, v68, vcc
	v_cmp_lt_f32_e64 vcc, |v67|, s9
	s_nop 1
	v_cndmask_b32_e32 v67, v68, v67, vcc
	v_lshl_add_u64 v[68:69], v[150:151], 2, s[52:53]
	v_sub_f32_e32 v67, v70, v67
	v_add_co_u32_e32 v70, vcc, s2, v68
	s_mov_b32 s2, 0x10000
	s_nop 0
	v_addc_co_u32_e32 v71, vcc, 0, v69, vcc
	global_store_dword v[70:71], v67, off offset:1536
	v_add_f32_e32 v67, v64, v242
	v_min_f32_e32 v72, 0, v67
	v_mul_f32_e64 v67, |v67|, s3
	v_exp_f32_e32 v67, v67
	s_nop 0
	v_add_f32_e32 v73, 1.0, v67
	v_add_f32_e32 v70, -1.0, v73
	v_sub_f32_e32 v71, v70, v73
	v_add_f32_e32 v71, 1.0, v71
	v_sub_f32_e32 v70, v67, v70
	v_add_f32_e32 v74, v70, v71
	v_frexp_mant_f32_e32 v70, v73
	v_cmp_gt_f32_e32 vcc, s6, v70
	v_cvt_f64_f32_e32 v[70:71], v73
	v_frexp_exp_i32_f64_e32 v70, v[70:71]
	v_subbrev_co_u32_e32 v70, vcc, 0, v70, vcc
	v_sub_u32_e32 v71, 0, v70
	v_ldexp_f32 v73, v73, v71
	v_ldexp_f32 v71, v74, v71
	v_add_f32_e32 v74, -1.0, v73
	v_add_f32_e32 v75, 1.0, v74
	v_sub_f32_e32 v75, v73, v75
	v_add_f32_e32 v75, v71, v75
	v_add_f32_e32 v76, v74, v75
	v_sub_f32_e32 v74, v76, v74
	v_sub_f32_e32 v74, v75, v74
	v_add_f32_e32 v75, 1.0, v73
	v_add_f32_e32 v77, -1.0, v75
	v_sub_f32_e32 v73, v73, v77
	v_add_f32_e32 v71, v71, v73
	v_add_f32_e32 v73, v75, v71
	v_sub_f32_e32 v75, v73, v75
	v_sub_f32_e32 v71, v71, v75
	v_rcp_f32_e32 v75, v73
	v_cvt_f32_i32_e32 v70, v70
	v_cmp_neq_f32_e32 vcc, s8, v67
	v_mul_f32_e32 v77, v76, v75
	v_mul_f32_e32 v78, v73, v77
	v_fma_f32 v79, v77, v73, -v78
	v_fmac_f32_e32 v79, v77, v71
	v_add_f32_e32 v80, v78, v79
	v_sub_f32_e32 v81, v76, v80
	v_sub_f32_e32 v76, v76, v81
	v_sub_f32_e32 v78, v80, v78
	v_sub_f32_e32 v76, v76, v80
	v_add_f32_e32 v74, v74, v76
	v_sub_f32_e32 v76, v78, v79
	v_add_f32_e32 v74, v76, v74
	v_add_f32_e32 v76, v81, v74
	v_mul_f32_e32 v78, v75, v76
	v_mul_f32_e32 v79, v73, v78
	v_fma_f32 v73, v78, v73, -v79
	v_fmac_f32_e32 v73, v78, v71
	v_sub_f32_e32 v71, v81, v76
	v_add_f32_e32 v71, v74, v71
	v_add_f32_e32 v74, v79, v73
	v_sub_f32_e32 v80, v76, v74
	v_sub_f32_e32 v76, v76, v80
	v_sub_f32_e32 v79, v74, v79
	v_sub_f32_e32 v74, v76, v74
	v_add_f32_e32 v71, v71, v74
	v_sub_f32_e32 v73, v79, v73
	v_add_f32_e32 v71, v73, v71
	v_add_f32_e32 v73, v77, v78
	v_add_f32_e32 v71, v80, v71
	v_sub_f32_e32 v74, v73, v77
	v_mul_f32_e32 v71, v75, v71
	v_sub_f32_e32 v74, v78, v74
	v_add_f32_e32 v71, v74, v71
	v_mul_f32_e32 v77, 0x3f317218, v70
	v_add_f32_e32 v74, v73, v71
	v_fma_f32 v78, v70, s7, -v77
	v_mul_f32_e32 v75, v74, v74
	v_fmac_f32_e32 v78, 0xb102e308, v70
	v_sub_f32_e32 v70, v74, v73
	v_fmamk_f32 v76, v75, 0x3e9b6dac, v214
	v_sub_f32_e32 v70, v71, v70
	v_add_f32_e32 v71, v77, v78
	v_fmaak_f32 v76, v75, v76, 0x3f2aaada
	v_sub_f32_e32 v73, v71, v77
	v_ldexp_f32 v77, v74, 1
	v_mul_f32_e32 v74, v74, v75
	v_mul_f32_e32 v74, v74, v76
	v_add_f32_e32 v75, v77, v74
	v_sub_f32_e32 v76, v75, v77
	v_ldexp_f32 v70, v70, 1
	v_sub_f32_e32 v74, v74, v76
	v_add_f32_e32 v70, v70, v74
	v_add_f32_e32 v74, v75, v70
	v_sub_f32_e32 v75, v74, v75
	v_sub_f32_e32 v70, v70, v75
	v_add_f32_e32 v75, v71, v74
	v_sub_f32_e32 v76, v75, v71
	v_sub_f32_e32 v77, v75, v76
	v_sub_f32_e32 v73, v78, v73
	v_sub_f32_e32 v71, v71, v77
	v_sub_f32_e32 v74, v74, v76
	v_add_f32_e32 v71, v74, v71
	v_add_f32_e32 v74, v73, v70
	v_sub_f32_e32 v76, v74, v73
	v_sub_f32_e32 v77, v74, v76
	v_sub_f32_e32 v73, v73, v77
	v_sub_f32_e32 v70, v70, v76
	v_add_f32_e32 v71, v74, v71
	v_add_f32_e32 v70, v70, v73
	v_add_f32_e32 v73, v75, v71
	v_sub_f32_e32 v74, v73, v75
	v_sub_f32_e32 v71, v71, v74
	v_add_f32_e32 v70, v70, v71
	v_add_f32_e32 v70, v73, v70
	v_cndmask_b32_e32 v70, v221, v70, vcc
	v_cmp_ngt_f32_e32 vcc, -1.0, v67
	s_nop 1
	v_cndmask_b32_e32 v70, v222, v70, vcc
	v_cmp_neq_f32_e32 vcc, -1.0, v67
	s_nop 1
;     __device__ __forceinline__ void operator()(const AccT& acc, const pg8::Unit& u, int wr, int wc, int fr, int fq) const {
;     ...
;                     } else if (wc == 1 && fq == 0) {
; #pragma unroll
;                         for (int n = 0; n < 2; ++n)
; #pragma unroll
;                             for (int j = 0; j < 4; ++j) {
;                                 const float x = acc[ai][0][m][n][j] * rs + bfg[4 * n + j];
;                                 lf[(4 * n + j) * MROWS + row] = fminf(x, 0.f) - log1pf(__expf(-fabsf(x)));
;                             }
	v_cndmask_b32_e32 v70, v219, v70, vcc
	v_cmp_lt_f32_e64 vcc, |v67|, s9
	s_nop 1
	v_cndmask_b32_e32 v67, v70, v67, vcc
	v_add_co_u32_e32 v70, vcc, s2, v68
	v_sub_f32_e32 v67, v72, v67
	s_nop 0
	v_addc_co_u32_e32 v71, vcc, 0, v69, vcc
	global_store_dword v[70:71], v67, off offset:2560
	s_mov_b32 s2, 0x18000
	v_add_f32_e32 v67, v65, v243
	v_min_f32_e32 v72, 0, v67
	v_mul_f32_e64 v67, |v67|, s3
	v_exp_f32_e32 v67, v67
	s_nop 0
	v_add_f32_e32 v73, 1.0, v67
	v_add_f32_e32 v70, -1.0, v73
	v_sub_f32_e32 v71, v70, v73
	v_add_f32_e32 v71, 1.0, v71
	v_sub_f32_e32 v70, v67, v70
	v_add_f32_e32 v74, v70, v71
	v_frexp_mant_f32_e32 v70, v73
	v_cmp_gt_f32_e32 vcc, s6, v70
	v_cvt_f64_f32_e32 v[70:71], v73
	v_frexp_exp_i32_f64_e32 v70, v[70:71]
	v_subbrev_co_u32_e32 v70, vcc, 0, v70, vcc
	v_sub_u32_e32 v71, 0, v70
	v_ldexp_f32 v73, v73, v71
	v_ldexp_f32 v71, v74, v71
	v_add_f32_e32 v74, -1.0, v73
	v_add_f32_e32 v75, 1.0, v74
	v_sub_f32_e32 v75, v73, v75
	v_add_f32_e32 v75, v71, v75
	v_add_f32_e32 v76, v74, v75
	v_sub_f32_e32 v74, v76, v74
	v_sub_f32_e32 v74, v75, v74
	v_add_f32_e32 v75, 1.0, v73
	v_add_f32_e32 v77, -1.0, v75
	v_sub_f32_e32 v73, v73, v77
	v_add_f32_e32 v71, v71, v73
	v_add_f32_e32 v73, v75, v71
	v_sub_f32_e32 v75, v73, v75
	v_sub_f32_e32 v71, v71, v75
	v_rcp_f32_e32 v75, v73
	v_cvt_f32_i32_e32 v70, v70
	v_cmp_neq_f32_e32 vcc, s8, v67
	v_mul_f32_e32 v77, v76, v75
	v_mul_f32_e32 v78, v73, v77
	v_fma_f32 v79, v77, v73, -v78
	v_fmac_f32_e32 v79, v77, v71
	v_add_f32_e32 v80, v78, v79
	v_sub_f32_e32 v81, v76, v80
	v_sub_f32_e32 v76, v76, v81
	v_sub_f32_e32 v78, v80, v78
	v_sub_f32_e32 v76, v76, v80
	v_add_f32_e32 v74, v74, v76
	v_sub_f32_e32 v76, v78, v79
	v_add_f32_e32 v74, v76, v74
	v_add_f32_e32 v76, v81, v74
	v_mul_f32_e32 v78, v75, v76
	v_mul_f32_e32 v79, v73, v78
	v_fma_f32 v73, v78, v73, -v79
	v_fmac_f32_e32 v73, v78, v71
	v_sub_f32_e32 v71, v81, v76
	v_add_f32_e32 v71, v74, v71
	v_add_f32_e32 v74, v79, v73
	v_sub_f32_e32 v80, v76, v74
	v_sub_f32_e32 v76, v76, v80
	v_sub_f32_e32 v79, v74, v79
	v_sub_f32_e32 v74, v76, v74
	v_add_f32_e32 v71, v71, v74
	v_sub_f32_e32 v73, v79, v73
	v_add_f32_e32 v71, v73, v71
	v_add_f32_e32 v73, v77, v78
	v_add_f32_e32 v71, v80, v71
	v_sub_f32_e32 v74, v73, v77
	v_mul_f32_e32 v71, v75, v71
	v_sub_f32_e32 v74, v78, v74
	v_add_f32_e32 v71, v74, v71
	v_mul_f32_e32 v77, 0x3f317218, v70
	v_add_f32_e32 v74, v73, v71
	v_fma_f32 v78, v70, s7, -v77
	v_mul_f32_e32 v75, v74, v74
	v_fmac_f32_e32 v78, 0xb102e308, v70
	v_sub_f32_e32 v70, v74, v73
	v_fmamk_f32 v76, v75, 0x3e9b6dac, v214
	v_sub_f32_e32 v70, v71, v70
	v_add_f32_e32 v71, v77, v78
	v_fmaak_f32 v76, v75, v76, 0x3f2aaada
	v_sub_f32_e32 v73, v71, v77
	v_ldexp_f32 v77, v74, 1
	v_mul_f32_e32 v74, v74, v75
	v_mul_f32_e32 v74, v74, v76
	v_add_f32_e32 v75, v77, v74
	v_sub_f32_e32 v76, v75, v77
	v_ldexp_f32 v70, v70, 1
	v_sub_f32_e32 v74, v74, v76
	v_add_f32_e32 v70, v70, v74
	v_add_f32_e32 v74, v75, v70
	v_sub_f32_e32 v75, v74, v75
	v_sub_f32_e32 v70, v70, v75
	v_add_f32_e32 v75, v71, v74
	v_sub_f32_e32 v76, v75, v71
	v_sub_f32_e32 v77, v75, v76
	v_sub_f32_e32 v73, v78, v73
	v_sub_f32_e32 v71, v71, v77
	v_sub_f32_e32 v74, v74, v76
	v_add_f32_e32 v71, v74, v71
	v_add_f32_e32 v74, v73, v70
	v_sub_f32_e32 v76, v74, v73
	v_sub_f32_e32 v77, v74, v76
	v_sub_f32_e32 v73, v73, v77
	v_sub_f32_e32 v70, v70, v76
	v_add_f32_e32 v71, v74, v71
	v_add_f32_e32 v70, v70, v73
	v_add_f32_e32 v73, v75, v71
	v_sub_f32_e32 v74, v73, v75
	v_sub_f32_e32 v71, v71, v74
	v_add_f32_e32 v70, v70, v71
	v_add_f32_e32 v70, v73, v70
	v_cndmask_b32_e32 v70, v221, v70, vcc
	v_cmp_ngt_f32_e32 vcc, -1.0, v67
	s_nop 1
	v_cndmask_b32_e32 v70, v222, v70, vcc
	v_cmp_neq_f32_e32 vcc, -1.0, v67
	s_nop 1
	v_cndmask_b32_e32 v70, v219, v70, vcc
	v_cmp_lt_f32_e64 vcc, |v67|, s9
	s_nop 1
	v_cndmask_b32_e32 v67, v70, v67, vcc
	v_add_co_u32_e32 v70, vcc, s2, v68
	v_sub_f32_e32 v67, v72, v67
	s_nop 0
	v_addc_co_u32_e32 v71, vcc, 0, v69, vcc
	global_store_dword v[70:71], v67, off offset:3584
	s_mov_b32 s2, 0x21000
	v_add_f32_e32 v67, v58, v244
	v_min_f32_e32 v72, 0, v67
	v_mul_f32_e64 v67, |v67|, s3
	v_exp_f32_e32 v67, v67
	s_nop 0
	v_add_f32_e32 v73, 1.0, v67
	v_add_f32_e32 v70, -1.0, v73
	v_sub_f32_e32 v71, v70, v73
	v_add_f32_e32 v71, 1.0, v71
	v_sub_f32_e32 v70, v67, v70
	v_add_f32_e32 v74, v70, v71
	v_frexp_mant_f32_e32 v70, v73
	v_cmp_gt_f32_e32 vcc, s6, v70
	v_cvt_f64_f32_e32 v[70:71], v73
	v_frexp_exp_i32_f64_e32 v70, v[70:71]
	v_subbrev_co_u32_e32 v70, vcc, 0, v70, vcc
	v_sub_u32_e32 v71, 0, v70
	v_ldexp_f32 v73, v73, v71
	v_ldexp_f32 v71, v74, v71
	v_add_f32_e32 v74, -1.0, v73
	v_add_f32_e32 v75, 1.0, v74
	v_sub_f32_e32 v75, v73, v75
	v_add_f32_e32 v75, v71, v75
	v_add_f32_e32 v76, v74, v75
	v_sub_f32_e32 v74, v76, v74
	v_sub_f32_e32 v74, v75, v74
	v_add_f32_e32 v75, 1.0, v73
	v_add_f32_e32 v77, -1.0, v75
	v_sub_f32_e32 v73, v73, v77
	v_add_f32_e32 v71, v71, v73
	v_add_f32_e32 v73, v75, v71
	v_sub_f32_e32 v75, v73, v75
	v_sub_f32_e32 v71, v71, v75
	v_rcp_f32_e32 v75, v73
	v_cvt_f32_i32_e32 v70, v70
	v_cmp_neq_f32_e32 vcc, s8, v67
	v_mul_f32_e32 v77, v76, v75
	v_mul_f32_e32 v78, v73, v77
	v_fma_f32 v79, v77, v73, -v78
	v_fmac_f32_e32 v79, v77, v71
	v_add_f32_e32 v80, v78, v79
	v_sub_f32_e32 v81, v76, v80
	v_sub_f32_e32 v76, v76, v81
	v_sub_f32_e32 v78, v80, v78
	v_sub_f32_e32 v76, v76, v80
	v_add_f32_e32 v74, v74, v76
	v_sub_f32_e32 v76, v78, v79
	v_add_f32_e32 v74, v76, v74
	v_add_f32_e32 v76, v81, v74
	v_mul_f32_e32 v78, v75, v76
	v_mul_f32_e32 v79, v73, v78
	v_fma_f32 v73, v78, v73, -v79
	v_fmac_f32_e32 v73, v78, v71
	v_sub_f32_e32 v71, v81, v76
	v_add_f32_e32 v71, v74, v71
	v_add_f32_e32 v74, v79, v73
;     __device__ __forceinline__ void operator()(const AccT& acc, const pg8::Unit& u, int wr, int wc, int fr, int fq) const {
;     ...
;                     } else if (wc == 1 && fq == 0) {
; #pragma unroll
;                         for (int n = 0; n < 2; ++n)
; #pragma unroll
;                             for (int j = 0; j < 4; ++j) {
;                                 const float x = acc[ai][0][m][n][j] * rs + bfg[4 * n + j];
;                                 lf[(4 * n + j) * MROWS + row] = fminf(x, 0.f) - log1pf(__expf(-fabsf(x)));
;                             }
	v_sub_f32_e32 v80, v76, v74
	v_sub_f32_e32 v76, v76, v80
	v_sub_f32_e32 v79, v74, v79
	v_sub_f32_e32 v74, v76, v74
	v_add_f32_e32 v71, v71, v74
	v_sub_f32_e32 v73, v79, v73
	v_add_f32_e32 v71, v73, v71
	v_add_f32_e32 v73, v77, v78
	v_add_f32_e32 v71, v80, v71
	v_sub_f32_e32 v74, v73, v77
	v_mul_f32_e32 v71, v75, v71
	v_sub_f32_e32 v74, v78, v74
	v_add_f32_e32 v71, v74, v71
	v_mul_f32_e32 v77, 0x3f317218, v70
	v_add_f32_e32 v74, v73, v71
	v_fma_f32 v78, v70, s7, -v77
	v_mul_f32_e32 v75, v74, v74
	v_fmac_f32_e32 v78, 0xb102e308, v70
	v_sub_f32_e32 v70, v74, v73
	v_fmamk_f32 v76, v75, 0x3e9b6dac, v214
	v_sub_f32_e32 v70, v71, v70
	v_add_f32_e32 v71, v77, v78
	v_fmaak_f32 v76, v75, v76, 0x3f2aaada
	v_sub_f32_e32 v73, v71, v77
	v_ldexp_f32 v77, v74, 1
	v_mul_f32_e32 v74, v74, v75
	v_mul_f32_e32 v74, v74, v76
	v_add_f32_e32 v75, v77, v74
	v_sub_f32_e32 v76, v75, v77
	v_ldexp_f32 v70, v70, 1
	v_sub_f32_e32 v74, v74, v76
	v_add_f32_e32 v70, v70, v74
	v_add_f32_e32 v74, v75, v70
	v_sub_f32_e32 v75, v74, v75
	v_sub_f32_e32 v70, v70, v75
	v_add_f32_e32 v75, v71, v74
	v_sub_f32_e32 v76, v75, v71
	v_sub_f32_e32 v77, v75, v76
	v_sub_f32_e32 v73, v78, v73
	v_sub_f32_e32 v71, v71, v77
	v_sub_f32_e32 v74, v74, v76
	v_add_f32_e32 v71, v74, v71
	v_add_f32_e32 v74, v73, v70
	v_sub_f32_e32 v76, v74, v73
	v_sub_f32_e32 v77, v74, v76
	v_sub_f32_e32 v73, v73, v77
	v_sub_f32_e32 v70, v70, v76
	v_add_f32_e32 v71, v74, v71
	v_add_f32_e32 v70, v70, v73
	v_add_f32_e32 v73, v75, v71
	v_sub_f32_e32 v74, v73, v75
	v_sub_f32_e32 v71, v71, v74
	v_add_f32_e32 v70, v70, v71
	v_add_f32_e32 v70, v73, v70
	v_cndmask_b32_e32 v70, v221, v70, vcc
	v_cmp_ngt_f32_e32 vcc, -1.0, v67
	s_nop 1
	v_cndmask_b32_e32 v70, v222, v70, vcc
	v_cmp_neq_f32_e32 vcc, -1.0, v67
	s_nop 1
	v_cndmask_b32_e32 v70, v219, v70, vcc
	v_cmp_lt_f32_e64 vcc, |v67|, s9
	s_nop 1
	v_cndmask_b32_e32 v67, v70, v67, vcc
	v_add_co_u32_e32 v70, vcc, s2, v68
	v_sub_f32_e32 v67, v72, v67
	s_nop 0
	v_addc_co_u32_e32 v71, vcc, 0, v69, vcc
	global_store_dword v[70:71], v67, off offset:512
	s_mov_b32 s2, 0x29000
	v_add_f32_e32 v67, v59, v245
	v_min_f32_e32 v72, 0, v67
	v_mul_f32_e64 v67, |v67|, s3
	v_exp_f32_e32 v67, v67
	s_nop 0
	v_add_f32_e32 v73, 1.0, v67
	v_add_f32_e32 v70, -1.0, v73
	v_sub_f32_e32 v71, v70, v73
	v_add_f32_e32 v71, 1.0, v71
	v_sub_f32_e32 v70, v67, v70
	v_add_f32_e32 v74, v70, v71
	v_frexp_mant_f32_e32 v70, v73
	v_cmp_gt_f32_e32 vcc, s6, v70
	v_cvt_f64_f32_e32 v[70:71], v73
	v_frexp_exp_i32_f64_e32 v70, v[70:71]
	v_subbrev_co_u32_e32 v70, vcc, 0, v70, vcc
	v_sub_u32_e32 v71, 0, v70
	v_ldexp_f32 v73, v73, v71
	v_ldexp_f32 v71, v74, v71
	v_add_f32_e32 v74, -1.0, v73
	v_add_f32_e32 v75, 1.0, v74
	v_sub_f32_e32 v75, v73, v75
	v_add_f32_e32 v75, v71, v75
	v_add_f32_e32 v76, v74, v75
	v_sub_f32_e32 v74, v76, v74
	v_sub_f32_e32 v74, v75, v74
	v_add_f32_e32 v75, 1.0, v73
	v_add_f32_e32 v77, -1.0, v75
	v_sub_f32_e32 v73, v73, v77
	v_add_f32_e32 v71, v71, v73
	v_add_f32_e32 v73, v75, v71
	v_sub_f32_e32 v75, v73, v75
	v_sub_f32_e32 v71, v71, v75
	v_rcp_f32_e32 v75, v73
	v_cvt_f32_i32_e32 v70, v70
	v_cmp_neq_f32_e32 vcc, s8, v67
	v_mul_f32_e32 v77, v76, v75
	v_mul_f32_e32 v78, v73, v77
	v_fma_f32 v79, v77, v73, -v78
	v_fmac_f32_e32 v79, v77, v71
	v_add_f32_e32 v80, v78, v79
	v_sub_f32_e32 v81, v76, v80
	v_sub_f32_e32 v76, v76, v81
	v_sub_f32_e32 v78, v80, v78
	v_sub_f32_e32 v76, v76, v80
	v_add_f32_e32 v74, v74, v76
	v_sub_f32_e32 v76, v78, v79
	v_add_f32_e32 v74, v76, v74
	v_add_f32_e32 v76, v81, v74
	v_mul_f32_e32 v78, v75, v76
	v_mul_f32_e32 v79, v73, v78
	v_fma_f32 v73, v78, v73, -v79
	v_fmac_f32_e32 v73, v78, v71
	v_sub_f32_e32 v71, v81, v76
	v_add_f32_e32 v71, v74, v71
	v_add_f32_e32 v74, v79, v73
	v_sub_f32_e32 v80, v76, v74
	v_sub_f32_e32 v76, v76, v80
	v_sub_f32_e32 v79, v74, v79
	v_sub_f32_e32 v74, v76, v74
	v_add_f32_e32 v71, v71, v74
	v_sub_f32_e32 v73, v79, v73
	v_add_f32_e32 v71, v73, v71
	v_add_f32_e32 v73, v77, v78
	v_add_f32_e32 v71, v80, v71
	v_sub_f32_e32 v74, v73, v77
	v_mul_f32_e32 v71, v75, v71
	v_sub_f32_e32 v74, v78, v74
	v_add_f32_e32 v71, v74, v71
	v_mul_f32_e32 v77, 0x3f317218, v70
	v_add_f32_e32 v74, v73, v71
	v_fma_f32 v78, v70, s7, -v77
	v_mul_f32_e32 v75, v74, v74
	v_fmac_f32_e32 v78, 0xb102e308, v70
	v_sub_f32_e32 v70, v74, v73
	v_fmamk_f32 v76, v75, 0x3e9b6dac, v214
	v_sub_f32_e32 v70, v71, v70
	v_add_f32_e32 v71, v77, v78
	v_fmaak_f32 v76, v75, v76, 0x3f2aaada
	v_sub_f32_e32 v73, v71, v77
	v_ldexp_f32 v77, v74, 1
	v_mul_f32_e32 v74, v74, v75
	v_mul_f32_e32 v74, v74, v76
	v_add_f32_e32 v75, v77, v74
	v_sub_f32_e32 v76, v75, v77
	v_ldexp_f32 v70, v70, 1
	v_sub_f32_e32 v74, v74, v76
	v_add_f32_e32 v70, v70, v74
	v_add_f32_e32 v74, v75, v70
	v_sub_f32_e32 v75, v74, v75
	v_sub_f32_e32 v70, v70, v75
	v_add_f32_e32 v75, v71, v74
	v_sub_f32_e32 v76, v75, v71
	v_sub_f32_e32 v77, v75, v76
	v_sub_f32_e32 v73, v78, v73
	v_sub_f32_e32 v71, v71, v77
	v_sub_f32_e32 v74, v74, v76
	v_add_f32_e32 v71, v74, v71
	v_add_f32_e32 v74, v73, v70
	v_sub_f32_e32 v76, v74, v73
	v_sub_f32_e32 v77, v74, v76
	v_sub_f32_e32 v73, v73, v77
	v_sub_f32_e32 v70, v70, v76
	v_add_f32_e32 v71, v74, v71
	v_add_f32_e32 v70, v70, v73
	v_add_f32_e32 v73, v75, v71
	v_sub_f32_e32 v74, v73, v75
	v_sub_f32_e32 v71, v71, v74
	v_add_f32_e32 v70, v70, v71
	v_add_f32_e32 v70, v73, v70
	v_cndmask_b32_e32 v70, v221, v70, vcc
	v_cmp_ngt_f32_e32 vcc, -1.0, v67
	s_nop 1
	v_cndmask_b32_e32 v70, v222, v70, vcc
	v_cmp_neq_f32_e32 vcc, -1.0, v67
	s_nop 1
	v_cndmask_b32_e32 v70, v219, v70, vcc
	v_cmp_lt_f32_e64 vcc, |v67|, s9
	s_nop 1
	v_cndmask_b32_e32 v67, v70, v67, vcc
	v_add_co_u32_e32 v70, vcc, s2, v68
	v_sub_f32_e32 v67, v72, v67
;     __device__ __forceinline__ void operator()(const AccT& acc, const pg8::Unit& u, int wr, int wc, int fr, int fq) const {
;     ...
;                     } else if (wc == 1 && fq == 0) {
; #pragma unroll
;                         for (int n = 0; n < 2; ++n)
; #pragma unroll
;                             for (int j = 0; j < 4; ++j) {
;                                 const float x = acc[ai][0][m][n][j] * rs + bfg[4 * n + j];
;                                 lf[(4 * n + j) * MROWS + row] = fminf(x, 0.f) - log1pf(__expf(-fabsf(x)));
;                             }
	s_nop 0
	v_addc_co_u32_e32 v71, vcc, 0, v69, vcc
	global_store_dword v[70:71], v67, off offset:1536
	s_mov_b32 s2, 0x31000
	v_add_f32_e32 v67, v60, v246
	v_min_f32_e32 v72, 0, v67
	v_mul_f32_e64 v67, |v67|, s3
	v_exp_f32_e32 v67, v67
	s_nop 0
	v_add_f32_e32 v73, 1.0, v67
	v_add_f32_e32 v70, -1.0, v73
	v_sub_f32_e32 v71, v70, v73
	v_add_f32_e32 v71, 1.0, v71
	v_sub_f32_e32 v70, v67, v70
	v_add_f32_e32 v74, v70, v71
	v_frexp_mant_f32_e32 v70, v73
	v_cmp_gt_f32_e32 vcc, s6, v70
	v_cvt_f64_f32_e32 v[70:71], v73
	v_frexp_exp_i32_f64_e32 v70, v[70:71]
	v_subbrev_co_u32_e32 v70, vcc, 0, v70, vcc
	v_sub_u32_e32 v71, 0, v70
	v_ldexp_f32 v73, v73, v71
	v_ldexp_f32 v71, v74, v71
	v_add_f32_e32 v74, -1.0, v73
	v_add_f32_e32 v75, 1.0, v74
	v_sub_f32_e32 v75, v73, v75
	v_add_f32_e32 v75, v71, v75
	v_add_f32_e32 v76, v74, v75
	v_sub_f32_e32 v74, v76, v74
	v_sub_f32_e32 v74, v75, v74
	v_add_f32_e32 v75, 1.0, v73
	v_add_f32_e32 v77, -1.0, v75
	v_sub_f32_e32 v73, v73, v77
	v_add_f32_e32 v71, v71, v73
	v_add_f32_e32 v73, v75, v71
	v_sub_f32_e32 v75, v73, v75
	v_sub_f32_e32 v71, v71, v75
	v_rcp_f32_e32 v75, v73
	v_cvt_f32_i32_e32 v70, v70
	v_cmp_neq_f32_e32 vcc, s8, v67
	v_mul_f32_e32 v77, v76, v75
	v_mul_f32_e32 v78, v73, v77
	v_fma_f32 v79, v77, v73, -v78
	v_fmac_f32_e32 v79, v77, v71
	v_add_f32_e32 v80, v78, v79
	v_sub_f32_e32 v81, v76, v80
	v_sub_f32_e32 v76, v76, v81
	v_sub_f32_e32 v78, v80, v78
	v_sub_f32_e32 v76, v76, v80
	v_add_f32_e32 v74, v74, v76
	v_sub_f32_e32 v76, v78, v79
	v_add_f32_e32 v74, v76, v74
	v_add_f32_e32 v76, v81, v74
	v_mul_f32_e32 v78, v75, v76
	v_mul_f32_e32 v79, v73, v78
	v_fma_f32 v73, v78, v73, -v79
	v_fmac_f32_e32 v73, v78, v71
	v_sub_f32_e32 v71, v81, v76
	v_add_f32_e32 v71, v74, v71
	v_add_f32_e32 v74, v79, v73
	v_sub_f32_e32 v80, v76, v74
	v_sub_f32_e32 v76, v76, v80
	v_sub_f32_e32 v79, v74, v79
	v_sub_f32_e32 v74, v76, v74
	v_add_f32_e32 v71, v71, v74
	v_sub_f32_e32 v73, v79, v73
	v_add_f32_e32 v71, v73, v71
	v_add_f32_e32 v73, v77, v78
	v_add_f32_e32 v71, v80, v71
	v_sub_f32_e32 v74, v73, v77
	v_mul_f32_e32 v71, v75, v71
	v_sub_f32_e32 v74, v78, v74
	v_add_f32_e32 v71, v74, v71
	v_mul_f32_e32 v77, 0x3f317218, v70
	v_add_f32_e32 v74, v73, v71
	v_fma_f32 v78, v70, s7, -v77
	v_mul_f32_e32 v75, v74, v74
	v_fmac_f32_e32 v78, 0xb102e308, v70
	v_sub_f32_e32 v70, v74, v73
	v_fmamk_f32 v76, v75, 0x3e9b6dac, v214
	v_sub_f32_e32 v70, v71, v70
	v_add_f32_e32 v71, v77, v78
	v_fmaak_f32 v76, v75, v76, 0x3f2aaada
	v_sub_f32_e32 v73, v71, v77
	v_ldexp_f32 v77, v74, 1
	v_mul_f32_e32 v74, v74, v75
	v_mul_f32_e32 v74, v74, v76
	v_add_f32_e32 v75, v77, v74
	v_sub_f32_e32 v76, v75, v77
	v_ldexp_f32 v70, v70, 1
	v_sub_f32_e32 v74, v74, v76
	v_add_f32_e32 v70, v70, v74
	v_add_f32_e32 v74, v75, v70
	v_sub_f32_e32 v75, v74, v75
	v_sub_f32_e32 v70, v70, v75
	v_add_f32_e32 v75, v71, v74
	v_sub_f32_e32 v76, v75, v71
	v_sub_f32_e32 v77, v75, v76
	v_sub_f32_e32 v73, v78, v73
	v_sub_f32_e32 v71, v71, v77
	v_sub_f32_e32 v74, v74, v76
	v_add_f32_e32 v71, v74, v71
	v_add_f32_e32 v74, v73, v70
	v_sub_f32_e32 v76, v74, v73
	v_sub_f32_e32 v77, v74, v76
	v_sub_f32_e32 v73, v73, v77
	v_sub_f32_e32 v70, v70, v76
	v_add_f32_e32 v71, v74, v71
	v_add_f32_e32 v70, v70, v73
	v_add_f32_e32 v73, v75, v71
	v_sub_f32_e32 v74, v73, v75
	v_sub_f32_e32 v71, v71, v74
	v_add_f32_e32 v70, v70, v71
	v_add_f32_e32 v70, v73, v70
	v_cndmask_b32_e32 v70, v221, v70, vcc
	v_cmp_ngt_f32_e32 vcc, -1.0, v67
	s_nop 1
	v_cndmask_b32_e32 v70, v222, v70, vcc
	v_cmp_neq_f32_e32 vcc, -1.0, v67
	s_nop 1
	v_cndmask_b32_e32 v70, v219, v70, vcc
	v_cmp_lt_f32_e64 vcc, |v67|, s9
	s_nop 1
	v_cndmask_b32_e32 v67, v70, v67, vcc
	v_add_co_u32_e32 v70, vcc, s2, v68
	v_sub_f32_e32 v67, v72, v67
	s_nop 0
	v_addc_co_u32_e32 v71, vcc, 0, v69, vcc
;     __device__ __forceinline__ void operator()(const AccT& acc, const pg8::Unit& u, int wr, int wc, int fr, int fq) const {
;     ...
;                     } else if (wc == 1 && fq == 0) {
; #pragma unroll
;                         for (int n = 0; n < 2; ++n)
; #pragma unroll
;                             for (int j = 0; j < 4; ++j) {
;                                 const float x = acc[ai][0][m][n][j] * rs + bfg[4 * n + j];
;                                 lf[(4 * n + j) * MROWS + row] = fminf(x, 0.f) - log1pf(__expf(-fabsf(x)));
;                             }
	global_store_dword v[70:71], v67, off offset:2560
	v_add_f32_e32 v67, v61, v247
	v_min_f32_e32 v72, 0, v67
	v_mul_f32_e64 v67, |v67|, s3
	v_exp_f32_e32 v67, v67
	s_nop 0
	v_add_f32_e32 v73, 1.0, v67
	v_add_f32_e32 v70, -1.0, v73
	v_sub_f32_e32 v71, v70, v73
	v_add_f32_e32 v71, 1.0, v71
	v_sub_f32_e32 v70, v67, v70
	v_add_f32_e32 v74, v70, v71
	v_frexp_mant_f32_e32 v70, v73
	v_cmp_gt_f32_e32 vcc, s6, v70
	v_cvt_f64_f32_e32 v[70:71], v73
	v_frexp_exp_i32_f64_e32 v70, v[70:71]
	v_subbrev_co_u32_e32 v70, vcc, 0, v70, vcc
	v_sub_u32_e32 v71, 0, v70
	v_ldexp_f32 v73, v73, v71
	v_ldexp_f32 v71, v74, v71
	v_add_f32_e32 v74, -1.0, v73
	v_add_f32_e32 v75, 1.0, v74
	v_sub_f32_e32 v75, v73, v75
	v_add_f32_e32 v75, v71, v75
	v_add_f32_e32 v76, v74, v75
	v_sub_f32_e32 v74, v76, v74
	v_sub_f32_e32 v74, v75, v74
	v_add_f32_e32 v75, 1.0, v73
	v_add_f32_e32 v77, -1.0, v75
	v_sub_f32_e32 v73, v73, v77
	v_add_f32_e32 v71, v71, v73
	v_add_f32_e32 v73, v75, v71
	v_sub_f32_e32 v75, v73, v75
	v_sub_f32_e32 v71, v71, v75
	v_rcp_f32_e32 v75, v73
	v_cvt_f32_i32_e32 v70, v70
	v_cmp_neq_f32_e32 vcc, s8, v67
	v_mul_f32_e32 v77, v76, v75
	v_mul_f32_e32 v78, v73, v77
	v_fma_f32 v79, v77, v73, -v78
	v_fmac_f32_e32 v79, v77, v71
	v_add_f32_e32 v80, v78, v79
	v_sub_f32_e32 v81, v76, v80
	v_sub_f32_e32 v76, v76, v81
	v_sub_f32_e32 v78, v80, v78
	v_sub_f32_e32 v76, v76, v80
	v_add_f32_e32 v74, v74, v76
	v_sub_f32_e32 v76, v78, v79
	v_add_f32_e32 v74, v76, v74
	v_add_f32_e32 v76, v81, v74
	v_mul_f32_e32 v78, v75, v76
	v_mul_f32_e32 v79, v73, v78
	v_fma_f32 v73, v78, v73, -v79
	v_fmac_f32_e32 v73, v78, v71
	v_sub_f32_e32 v71, v81, v76
	v_add_f32_e32 v71, v74, v71
	v_add_f32_e32 v74, v79, v73
	v_sub_f32_e32 v80, v76, v74
	v_sub_f32_e32 v76, v76, v80
	v_sub_f32_e32 v79, v74, v79
	v_sub_f32_e32 v74, v76, v74
	v_add_f32_e32 v71, v71, v74
	v_sub_f32_e32 v73, v79, v73
	v_add_f32_e32 v71, v73, v71
	v_add_f32_e32 v73, v77, v78
	v_add_f32_e32 v71, v80, v71
	v_sub_f32_e32 v74, v73, v77
	v_mul_f32_e32 v71, v75, v71
	v_sub_f32_e32 v74, v78, v74
	v_add_f32_e32 v71, v74, v71
	v_mul_f32_e32 v77, 0x3f317218, v70
	v_add_f32_e32 v74, v73, v71
	v_fma_f32 v78, v70, s7, -v77
	v_mul_f32_e32 v75, v74, v74
	v_fmac_f32_e32 v78, 0xb102e308, v70
	v_sub_f32_e32 v70, v74, v73
	v_fmamk_f32 v76, v75, 0x3e9b6dac, v214
	v_sub_f32_e32 v70, v71, v70
	v_add_f32_e32 v71, v77, v78
	v_fmaak_f32 v76, v75, v76, 0x3f2aaada
	v_sub_f32_e32 v73, v71, v77
	v_ldexp_f32 v77, v74, 1
	v_mul_f32_e32 v74, v74, v75
	v_mul_f32_e32 v74, v74, v76
	v_add_f32_e32 v75, v77, v74
	v_sub_f32_e32 v76, v75, v77
	v_ldexp_f32 v70, v70, 1
	v_sub_f32_e32 v74, v74, v76
	v_add_f32_e32 v70, v70, v74
	v_add_f32_e32 v74, v75, v70
	v_sub_f32_e32 v75, v74, v75
	v_sub_f32_e32 v70, v70, v75
	v_add_f32_e32 v75, v71, v74
	v_sub_f32_e32 v76, v75, v71
	v_sub_f32_e32 v77, v75, v76
	v_sub_f32_e32 v73, v78, v73
	v_sub_f32_e32 v71, v71, v77
	v_sub_f32_e32 v74, v74, v76
	v_add_f32_e32 v71, v74, v71
	v_add_f32_e32 v74, v73, v70
	v_sub_f32_e32 v76, v74, v73
	v_sub_f32_e32 v77, v74, v76
	v_sub_f32_e32 v73, v73, v77
	v_sub_f32_e32 v70, v70, v76
	v_add_f32_e32 v71, v74, v71
	v_add_f32_e32 v70, v70, v73
	v_add_f32_e32 v73, v75, v71
	v_sub_f32_e32 v74, v73, v75
	v_sub_f32_e32 v71, v71, v74
	v_add_f32_e32 v70, v70, v71
	v_add_f32_e32 v70, v73, v70
	v_cndmask_b32_e32 v70, v221, v70, vcc
	v_cmp_ngt_f32_e32 vcc, -1.0, v67
	s_nop 1
	v_cndmask_b32_e32 v70, v222, v70, vcc
	v_cmp_neq_f32_e32 vcc, -1.0, v67
	s_nop 1
	v_cndmask_b32_e32 v70, v219, v70, vcc
	v_cmp_lt_f32_e64 vcc, |v67|, s9
	s_nop 1
	v_cndmask_b32_e32 v67, v70, v67, vcc
	v_add_co_u32_e32 v68, vcc, 0x39000, v68
	v_sub_f32_e32 v67, v72, v67
	s_nop 0
	v_addc_co_u32_e32 v69, vcc, 0, v69, vcc
	global_store_dword v[68:69], v67, off offset:3584

;     __device__ __forceinline__ void operator()(const AccT& acc, const pg8::Unit& u, int wr, int wc, int fr, int fq) const {
;     ...
;                 const int row = row0 + ai * 128 + m * 16;
;                 const float rs = 1.0f;
;                 if (u.pn < 20) {
;                     float ss = 0.f;
; #pragma unroll
;                     for (int bj = 0; bj < 2; ++bj) {
;                         const f32x4 a = acc[ai][bj][m][0], b = acc[ai][bj][m][1];
;                         *(u32x4*)(Z + (size_t)row * ZLD + u.pn * 256 + bj * 128 + wc * 32 + 8 * fq) = pack8s(a, b, rs);
; #pragma unroll
;                         for (int j = 0; j < 4; ++j) ss += a[j] * a[j] + b[j] * b[j];
;                     }
;                     if (u.pn < 4) {
;                         ss *= rs * rs;
;                         ss += __shfl_xor(ss, 16); ss += __shfl_xor(ss, 32);
;                         if (fq == 0) ssqp[row * 16 + u.pn * 4 + wc] = ss;
;                     }
;                 } else {
;                     if (wc == 0) {
;                         const f32x4 c0 = *(const f32x4*)(cosT + row * 32 + 8 * fq), c1 = *(const f32x4*)(cosT + row * 32 + 8 * fq + 4);
;                         const f32x4 s0 = *(const f32x4*)(sinT + row * 32 + 8 * fq), s1 = *(const f32x4*)(sinT + row * 32 + 8 * fq + 4);
;                         const f32x4 x1a = acc[ai][0][m][0] * rs, x1b = acc[ai][0][m][1] * rs, x2a = acc[ai][1][m][0] * rs, x2b = acc[ai][1][m][1] * rs;
;                         const f32x4 y1a = x1a * c0 - x2a * s0, y1b = x1b * c1 - x2b * s1, y2a = x2a * c0 + x1a * s0, y2b = x2b * c1 + x1b * s1;
;                         *(u32x4*)(Kr + (size_t)row * 64 + 8 * fq) = pack8s(y1a, y1b, 1.0f);
;                         *(u32x4*)(Kr + (size_t)row * 64 + 32 + 8 * fq) = pack8s(y2a, y2b, 1.0f);
;                     } else if (wc == 1 && fq == 0) {
; #pragma unroll
;                         for (int n = 0; n < 2; ++n)
; #pragma unroll
;                             for (int j = 0; j < 4; ++j) {
;                                 const float x = acc[ai][0][m][n][j] * rs + bfg[4 * n + j];
;                                 lf[(4 * n + j) * MROWS + row] = fminf(x, 0.f) - log1pf(__expf(-fabsf(x)));
;                             }
.LBB0_1011:
	v_add_u32_e32 v50, 0x90, v150
	s_and_b64 vcc, exec, s[44:45]
	s_mov_b64 s[8:9], -1
	s_cbranch_vccnz .LBB0_1019
	s_and_b64 vcc, exec, s[42:43]
	s_cbranch_vccnz .LBB0_1016
	s_and_saveexec_b64 s[70:71], s[58:59]
	s_cbranch_execz .LBB0_1015
	s_waitcnt lgkmcnt(0)
	s_mov_b32 s3, 0xbfb8aa3b
	s_mov_b32 s6, 0x3f2aaaab
	s_mov_b32 s7, 0x3f317218
	s_mov_b32 s8, 0x7f800000
	s_mov_b32 s9, 0x33800000
	v_ashrrev_i32_e32 v151, 31, v150
	s_mov_b32 s2, 0x8000
	v_add_f32_e32 v51, v46, v240
	v_min_f32_e32 v54, 0, v51
	v_mul_f32_e64 v51, |v51|, s3
	v_exp_f32_e32 v51, v51
	s_nop 0
	v_add_f32_e32 v55, 1.0, v51
	v_add_f32_e32 v52, -1.0, v55
	v_sub_f32_e32 v53, v52, v55
	v_add_f32_e32 v53, 1.0, v53
	v_sub_f32_e32 v52, v51, v52
	v_add_f32_e32 v56, v52, v53
	v_frexp_mant_f32_e32 v52, v55
	v_cmp_gt_f32_e32 vcc, s6, v52
	v_cvt_f64_f32_e32 v[52:53], v55
	v_frexp_exp_i32_f64_e32 v52, v[52:53]
	v_subbrev_co_u32_e32 v52, vcc, 0, v52, vcc
	v_sub_u32_e32 v53, 0, v52
	v_ldexp_f32 v55, v55, v53
	v_ldexp_f32 v53, v56, v53
	v_add_f32_e32 v56, -1.0, v55
	v_add_f32_e32 v57, 1.0, v56
	v_sub_f32_e32 v57, v55, v57
	v_add_f32_e32 v57, v53, v57
	v_add_f32_e32 v58, v56, v57
	v_sub_f32_e32 v56, v58, v56
	v_sub_f32_e32 v56, v57, v56
	v_add_f32_e32 v57, 1.0, v55
	v_add_f32_e32 v59, -1.0, v57
	v_sub_f32_e32 v55, v55, v59
	v_add_f32_e32 v53, v53, v55
	v_add_f32_e32 v55, v57, v53
	v_sub_f32_e32 v57, v55, v57
	v_sub_f32_e32 v53, v53, v57
	v_rcp_f32_e32 v57, v55
	v_cvt_f32_i32_e32 v52, v52
	v_cmp_neq_f32_e32 vcc, s8, v51
	v_mul_f32_e32 v59, v58, v57
	v_mul_f32_e32 v60, v55, v59
	v_fma_f32 v61, v59, v55, -v60
	v_fmac_f32_e32 v61, v59, v53
	v_add_f32_e32 v62, v60, v61
	v_sub_f32_e32 v63, v58, v62
	v_sub_f32_e32 v58, v58, v63
	v_sub_f32_e32 v60, v62, v60
	v_sub_f32_e32 v58, v58, v62
	v_add_f32_e32 v56, v56, v58
	v_sub_f32_e32 v58, v60, v61
	v_add_f32_e32 v56, v58, v56
	v_add_f32_e32 v58, v63, v56
	v_mul_f32_e32 v60, v57, v58
	v_mul_f32_e32 v61, v55, v60
	v_fma_f32 v55, v60, v55, -v61
	v_fmac_f32_e32 v55, v60, v53
	v_sub_f32_e32 v53, v63, v58
	v_add_f32_e32 v53, v56, v53
	v_add_f32_e32 v56, v61, v55
	v_sub_f32_e32 v62, v58, v56
	v_sub_f32_e32 v58, v58, v62
	v_sub_f32_e32 v61, v56, v61
	v_sub_f32_e32 v56, v58, v56
	v_add_f32_e32 v53, v53, v56
	v_sub_f32_e32 v55, v61, v55
	v_add_f32_e32 v53, v55, v53
	v_add_f32_e32 v55, v59, v60
	v_add_f32_e32 v53, v62, v53
	v_sub_f32_e32 v56, v55, v59
	v_mul_f32_e32 v53, v57, v53
	v_sub_f32_e32 v56, v60, v56
	v_add_f32_e32 v53, v56, v53
	v_mul_f32_e32 v59, 0x3f317218, v52
	v_add_f32_e32 v56, v55, v53
	v_fma_f32 v60, v52, s7, -v59
	v_mul_f32_e32 v57, v56, v56
	v_fmac_f32_e32 v60, 0xb102e308, v52
	v_sub_f32_e32 v52, v56, v55
	v_fmamk_f32 v58, v57, 0x3e9b6dac, v214
	v_sub_f32_e32 v52, v53, v52
	v_add_f32_e32 v53, v59, v60
	v_fmaak_f32 v58, v57, v58, 0x3f2aaada
	v_sub_f32_e32 v55, v53, v59
	v_ldexp_f32 v59, v56, 1
	v_mul_f32_e32 v56, v56, v57
	v_mul_f32_e32 v56, v56, v58
	v_add_f32_e32 v57, v59, v56
	v_sub_f32_e32 v58, v57, v59
	v_ldexp_f32 v52, v52, 1
	v_sub_f32_e32 v56, v56, v58
	v_add_f32_e32 v52, v52, v56
	v_add_f32_e32 v56, v57, v52
	v_sub_f32_e32 v57, v56, v57
	v_sub_f32_e32 v52, v52, v57
	v_add_f32_e32 v57, v53, v56
	v_sub_f32_e32 v58, v57, v53
	v_sub_f32_e32 v59, v57, v58
	v_sub_f32_e32 v55, v60, v55
	v_sub_f32_e32 v53, v53, v59
	v_sub_f32_e32 v56, v56, v58
	v_add_f32_e32 v53, v56, v53
	v_add_f32_e32 v56, v55, v52
	v_sub_f32_e32 v58, v56, v55
	v_sub_f32_e32 v59, v56, v58
	v_sub_f32_e32 v55, v55, v59
	v_sub_f32_e32 v52, v52, v58
	v_add_f32_e32 v53, v56, v53
	v_add_f32_e32 v52, v52, v55
	v_add_f32_e32 v55, v57, v53
	v_sub_f32_e32 v56, v55, v57
	v_sub_f32_e32 v53, v53, v56
	v_add_f32_e32 v52, v52, v53
	v_add_f32_e32 v52, v55, v52
	v_cndmask_b32_e32 v52, v221, v52, vcc
	v_cmp_ngt_f32_e32 vcc, -1.0, v51
	s_nop 1
	v_cndmask_b32_e32 v52, v222, v52, vcc
	v_cmp_neq_f32_e32 vcc, -1.0, v51
	s_nop 1
	v_cndmask_b32_e32 v52, v219, v52, vcc
	v_cmp_lt_f32_e64 vcc, |v51|, s9
	s_nop 1
	v_cndmask_b32_e32 v51, v52, v51, vcc
	v_sub_f32_e32 v54, v54, v51
	v_ashrrev_i32_e32 v51, 31, v50
	v_lshl_add_u64 v[52:53], v[50:51], 2, s[52:53]
	global_store_dword v[52:53], v54, off
	v_add_f32_e32 v51, v47, v241
	v_min_f32_e32 v54, 0, v51
	v_mul_f32_e64 v51, |v51|, s3
	v_exp_f32_e32 v51, v51
	s_nop 0
	v_add_f32_e32 v55, 1.0, v51
	v_add_f32_e32 v52, -1.0, v55
	v_sub_f32_e32 v53, v52, v55
	v_add_f32_e32 v53, 1.0, v53
	v_sub_f32_e32 v52, v51, v52
	v_add_f32_e32 v56, v52, v53
	v_frexp_mant_f32_e32 v52, v55
	v_cmp_gt_f32_e32 vcc, s6, v52
	v_cvt_f64_f32_e32 v[52:53], v55
	v_frexp_exp_i32_f64_e32 v52, v[52:53]
	v_subbrev_co_u32_e32 v52, vcc, 0, v52, vcc
	v_sub_u32_e32 v53, 0, v52
	v_ldexp_f32 v55, v55, v53
	v_ldexp_f32 v53, v56, v53
	v_add_f32_e32 v56, -1.0, v55
	v_add_f32_e32 v57, 1.0, v56
	v_sub_f32_e32 v57, v55, v57
	v_add_f32_e32 v57, v53, v57
	v_add_f32_e32 v58, v56, v57
	v_sub_f32_e32 v56, v58, v56
	v_sub_f32_e32 v56, v57, v56
	v_add_f32_e32 v57, 1.0, v55
	v_add_f32_e32 v59, -1.0, v57
	v_sub_f32_e32 v55, v55, v59
	v_add_f32_e32 v53, v53, v55
	v_add_f32_e32 v55, v57, v53
	v_sub_f32_e32 v57, v55, v57
	v_sub_f32_e32 v53, v53, v57
	v_rcp_f32_e32 v57, v55
	v_cvt_f32_i32_e32 v52, v52
	v_cmp_neq_f32_e32 vcc, s8, v51
	v_mul_f32_e32 v59, v58, v57
	v_mul_f32_e32 v60, v55, v59
	v_fma_f32 v61, v59, v55, -v60
	v_fmac_f32_e32 v61, v59, v53
	v_add_f32_e32 v62, v60, v61
	v_sub_f32_e32 v63, v58, v62
	v_sub_f32_e32 v58, v58, v63
	v_sub_f32_e32 v60, v62, v60
	v_sub_f32_e32 v58, v58, v62
	v_add_f32_e32 v56, v56, v58
	v_sub_f32_e32 v58, v60, v61
	v_add_f32_e32 v56, v58, v56
	v_add_f32_e32 v58, v63, v56
	v_mul_f32_e32 v60, v57, v58
	v_mul_f32_e32 v61, v55, v60
	v_fma_f32 v55, v60, v55, -v61
;     __device__ __forceinline__ void operator()(const AccT& acc, const pg8::Unit& u, int wr, int wc, int fr, int fq) const {
;     ...
;                     } else if (wc == 1 && fq == 0) {
; #pragma unroll
;                         for (int n = 0; n < 2; ++n)
; #pragma unroll
;                             for (int j = 0; j < 4; ++j) {
;                                 const float x = acc[ai][0][m][n][j] * rs + bfg[4 * n + j];
;                                 lf[(4 * n + j) * MROWS + row] = fminf(x, 0.f) - log1pf(__expf(-fabsf(x)));
;                             }
	v_fmac_f32_e32 v55, v60, v53
	v_sub_f32_e32 v53, v63, v58
	v_add_f32_e32 v53, v56, v53
	v_add_f32_e32 v56, v61, v55
	v_sub_f32_e32 v62, v58, v56
	v_sub_f32_e32 v58, v58, v62
	v_sub_f32_e32 v61, v56, v61
	v_sub_f32_e32 v56, v58, v56
	v_add_f32_e32 v53, v53, v56
	v_sub_f32_e32 v55, v61, v55
	v_add_f32_e32 v53, v55, v53
	v_add_f32_e32 v55, v59, v60
	v_add_f32_e32 v53, v62, v53
	v_sub_f32_e32 v56, v55, v59
	v_mul_f32_e32 v53, v57, v53
	v_sub_f32_e32 v56, v60, v56
	v_add_f32_e32 v53, v56, v53
	v_mul_f32_e32 v59, 0x3f317218, v52
	v_add_f32_e32 v56, v55, v53
	v_fma_f32 v60, v52, s7, -v59
	v_mul_f32_e32 v57, v56, v56
	v_fmac_f32_e32 v60, 0xb102e308, v52
	v_sub_f32_e32 v52, v56, v55
	v_fmamk_f32 v58, v57, 0x3e9b6dac, v214
	v_sub_f32_e32 v52, v53, v52
	v_add_f32_e32 v53, v59, v60
	v_fmaak_f32 v58, v57, v58, 0x3f2aaada
	v_sub_f32_e32 v55, v53, v59
	v_ldexp_f32 v59, v56, 1
	v_mul_f32_e32 v56, v56, v57
	v_mul_f32_e32 v56, v56, v58
	v_add_f32_e32 v57, v59, v56
	v_sub_f32_e32 v58, v57, v59
	v_ldexp_f32 v52, v52, 1
	v_sub_f32_e32 v56, v56, v58
	v_add_f32_e32 v52, v52, v56
	v_add_f32_e32 v56, v57, v52
	v_sub_f32_e32 v57, v56, v57
	v_sub_f32_e32 v52, v52, v57
	v_add_f32_e32 v57, v53, v56
	v_sub_f32_e32 v58, v57, v53
	v_sub_f32_e32 v59, v57, v58
	v_sub_f32_e32 v55, v60, v55
	v_sub_f32_e32 v53, v53, v59
	v_sub_f32_e32 v56, v56, v58
	v_add_f32_e32 v53, v56, v53
	v_add_f32_e32 v56, v55, v52
	v_sub_f32_e32 v58, v56, v55
	v_sub_f32_e32 v59, v56, v58
	v_sub_f32_e32 v55, v55, v59
	v_sub_f32_e32 v52, v52, v58
	v_add_f32_e32 v53, v56, v53
	v_add_f32_e32 v52, v52, v55
	v_add_f32_e32 v55, v57, v53
	v_sub_f32_e32 v56, v55, v57
	v_sub_f32_e32 v53, v53, v56
	v_add_f32_e32 v52, v52, v53
	v_add_f32_e32 v52, v55, v52
	v_cndmask_b32_e32 v52, v221, v52, vcc
	v_cmp_ngt_f32_e32 vcc, -1.0, v51
	s_nop 1
	v_cndmask_b32_e32 v52, v222, v52, vcc
	v_cmp_neq_f32_e32 vcc, -1.0, v51
	s_nop 1
	v_cndmask_b32_e32 v52, v219, v52, vcc
	v_cmp_lt_f32_e64 vcc, |v51|, s9
	s_nop 1
	v_cndmask_b32_e32 v51, v52, v51, vcc
	v_lshl_add_u64 v[52:53], v[150:151], 2, s[52:53]
	v_sub_f32_e32 v51, v54, v51
	v_add_co_u32_e32 v54, vcc, s2, v52
	s_mov_b32 s2, 0x10000
	s_nop 0
	v_addc_co_u32_e32 v55, vcc, 0, v53, vcc
	global_store_dword v[54:55], v51, off offset:1600
	v_add_f32_e32 v51, v48, v242
	v_min_f32_e32 v56, 0, v51
	v_mul_f32_e64 v51, |v51|, s3
	v_exp_f32_e32 v51, v51
	s_nop 0
	v_add_f32_e32 v57, 1.0, v51
	v_add_f32_e32 v54, -1.0, v57
	v_sub_f32_e32 v55, v54, v57
	v_add_f32_e32 v55, 1.0, v55
	v_sub_f32_e32 v54, v51, v54
	v_add_f32_e32 v58, v54, v55
	v_frexp_mant_f32_e32 v54, v57
	v_cmp_gt_f32_e32 vcc, s6, v54
	v_cvt_f64_f32_e32 v[54:55], v57
	v_frexp_exp_i32_f64_e32 v54, v[54:55]
	v_subbrev_co_u32_e32 v54, vcc, 0, v54, vcc
	v_sub_u32_e32 v55, 0, v54
	v_ldexp_f32 v57, v57, v55
	v_ldexp_f32 v55, v58, v55
	v_add_f32_e32 v58, -1.0, v57
	v_add_f32_e32 v59, 1.0, v58
	v_sub_f32_e32 v59, v57, v59
	v_add_f32_e32 v59, v55, v59
	v_add_f32_e32 v60, v58, v59
	v_sub_f32_e32 v58, v60, v58
	v_sub_f32_e32 v58, v59, v58
	v_add_f32_e32 v59, 1.0, v57
	v_add_f32_e32 v61, -1.0, v59
	v_sub_f32_e32 v57, v57, v61
	v_add_f32_e32 v55, v55, v57
	v_add_f32_e32 v57, v59, v55
	v_sub_f32_e32 v59, v57, v59
	v_sub_f32_e32 v55, v55, v59
	v_rcp_f32_e32 v59, v57
	v_cvt_f32_i32_e32 v54, v54
	v_cmp_neq_f32_e32 vcc, s8, v51
	v_mul_f32_e32 v61, v60, v59
	v_mul_f32_e32 v62, v57, v61
	v_fma_f32 v63, v61, v57, -v62
	v_fmac_f32_e32 v63, v61, v55
	v_add_f32_e32 v64, v62, v63
	v_sub_f32_e32 v65, v60, v64
	v_sub_f32_e32 v60, v60, v65
	v_sub_f32_e32 v62, v64, v62
	v_sub_f32_e32 v60, v60, v64
	v_add_f32_e32 v58, v58, v60
	v_sub_f32_e32 v60, v62, v63
	v_add_f32_e32 v58, v60, v58
	v_add_f32_e32 v60, v65, v58
	v_mul_f32_e32 v62, v59, v60
	v_mul_f32_e32 v63, v57, v62
	v_fma_f32 v57, v62, v57, -v63
	v_fmac_f32_e32 v57, v62, v55
	v_sub_f32_e32 v55, v65, v60
	v_add_f32_e32 v55, v58, v55
	v_add_f32_e32 v58, v63, v57
	v_sub_f32_e32 v64, v60, v58
	v_sub_f32_e32 v60, v60, v64
	v_sub_f32_e32 v63, v58, v63
	v_sub_f32_e32 v58, v60, v58
	v_add_f32_e32 v55, v55, v58
	v_sub_f32_e32 v57, v63, v57
	v_add_f32_e32 v55, v57, v55
	v_add_f32_e32 v57, v61, v62
	v_add_f32_e32 v55, v64, v55
	v_sub_f32_e32 v58, v57, v61
	v_mul_f32_e32 v55, v59, v55
	v_sub_f32_e32 v58, v62, v58
	v_add_f32_e32 v55, v58, v55
	v_mul_f32_e32 v61, 0x3f317218, v54
	v_add_f32_e32 v58, v57, v55
	v_fma_f32 v62, v54, s7, -v61
	v_mul_f32_e32 v59, v58, v58
	v_fmac_f32_e32 v62, 0xb102e308, v54
	v_sub_f32_e32 v54, v58, v57
	v_fmamk_f32 v60, v59, 0x3e9b6dac, v214
	v_sub_f32_e32 v54, v55, v54
	v_add_f32_e32 v55, v61, v62
	v_fmaak_f32 v60, v59, v60, 0x3f2aaada
	v_sub_f32_e32 v57, v55, v61
	v_ldexp_f32 v61, v58, 1
	v_mul_f32_e32 v58, v58, v59
	v_mul_f32_e32 v58, v58, v60
	v_add_f32_e32 v59, v61, v58
	v_sub_f32_e32 v60, v59, v61
	v_ldexp_f32 v54, v54, 1
	v_sub_f32_e32 v58, v58, v60
	v_add_f32_e32 v54, v54, v58
	v_add_f32_e32 v58, v59, v54
	v_sub_f32_e32 v59, v58, v59
	v_sub_f32_e32 v54, v54, v59
	v_add_f32_e32 v59, v55, v58
	v_sub_f32_e32 v60, v59, v55
	v_sub_f32_e32 v61, v59, v60
	v_sub_f32_e32 v57, v62, v57
	v_sub_f32_e32 v55, v55, v61
	v_sub_f32_e32 v58, v58, v60
	v_add_f32_e32 v55, v58, v55
	v_add_f32_e32 v58, v57, v54
	v_sub_f32_e32 v60, v58, v57
	v_sub_f32_e32 v61, v58, v60
	v_sub_f32_e32 v57, v57, v61
	v_sub_f32_e32 v54, v54, v60
	v_add_f32_e32 v55, v58, v55
	v_add_f32_e32 v54, v54, v57
	v_add_f32_e32 v57, v59, v55
	v_sub_f32_e32 v58, v57, v59
	v_sub_f32_e32 v55, v55, v58
	v_add_f32_e32 v54, v54, v55
	v_add_f32_e32 v54, v57, v54
	v_cndmask_b32_e32 v54, v221, v54, vcc
	v_cmp_ngt_f32_e32 vcc, -1.0, v51
	s_nop 1
	v_cndmask_b32_e32 v54, v222, v54, vcc
	v_cmp_neq_f32_e32 vcc, -1.0, v51
	s_nop 1
;     __device__ __forceinline__ void operator()(const AccT& acc, const pg8::Unit& u, int wr, int wc, int fr, int fq) const {
;     ...
;                     } else if (wc == 1 && fq == 0) {
; #pragma unroll
;                         for (int n = 0; n < 2; ++n)
; #pragma unroll
;                             for (int j = 0; j < 4; ++j) {
;                                 const float x = acc[ai][0][m][n][j] * rs + bfg[4 * n + j];
;                                 lf[(4 * n + j) * MROWS + row] = fminf(x, 0.f) - log1pf(__expf(-fabsf(x)));
;                             }
	v_cndmask_b32_e32 v54, v219, v54, vcc
	v_cmp_lt_f32_e64 vcc, |v51|, s9
	s_nop 1
	v_cndmask_b32_e32 v51, v54, v51, vcc
	v_add_co_u32_e32 v54, vcc, s2, v52
	v_sub_f32_e32 v51, v56, v51
	s_nop 0
	v_addc_co_u32_e32 v55, vcc, 0, v53, vcc
	global_store_dword v[54:55], v51, off offset:2624
	s_mov_b32 s2, 0x18000
	v_add_f32_e32 v51, v49, v243
	v_min_f32_e32 v56, 0, v51
	v_mul_f32_e64 v51, |v51|, s3
	v_exp_f32_e32 v51, v51
	s_nop 0
	v_add_f32_e32 v57, 1.0, v51
	v_add_f32_e32 v54, -1.0, v57
	v_sub_f32_e32 v55, v54, v57
	v_add_f32_e32 v55, 1.0, v55
	v_sub_f32_e32 v54, v51, v54
	v_add_f32_e32 v58, v54, v55
	v_frexp_mant_f32_e32 v54, v57
	v_cmp_gt_f32_e32 vcc, s6, v54
	v_cvt_f64_f32_e32 v[54:55], v57
	v_frexp_exp_i32_f64_e32 v54, v[54:55]
	v_subbrev_co_u32_e32 v54, vcc, 0, v54, vcc
	v_sub_u32_e32 v55, 0, v54
	v_ldexp_f32 v57, v57, v55
	v_ldexp_f32 v55, v58, v55
	v_add_f32_e32 v58, -1.0, v57
	v_add_f32_e32 v59, 1.0, v58
	v_sub_f32_e32 v59, v57, v59
	v_add_f32_e32 v59, v55, v59
	v_add_f32_e32 v60, v58, v59
	v_sub_f32_e32 v58, v60, v58
	v_sub_f32_e32 v58, v59, v58
	v_add_f32_e32 v59, 1.0, v57
	v_add_f32_e32 v61, -1.0, v59
	v_sub_f32_e32 v57, v57, v61
	v_add_f32_e32 v55, v55, v57
	v_add_f32_e32 v57, v59, v55
	v_sub_f32_e32 v59, v57, v59
	v_sub_f32_e32 v55, v55, v59
	v_rcp_f32_e32 v59, v57
	v_cvt_f32_i32_e32 v54, v54
	v_cmp_neq_f32_e32 vcc, s8, v51
	v_mul_f32_e32 v61, v60, v59
	v_mul_f32_e32 v62, v57, v61
	v_fma_f32 v63, v61, v57, -v62
	v_fmac_f32_e32 v63, v61, v55
	v_add_f32_e32 v64, v62, v63
	v_sub_f32_e32 v65, v60, v64
	v_sub_f32_e32 v60, v60, v65
	v_sub_f32_e32 v62, v64, v62
	v_sub_f32_e32 v60, v60, v64
	v_add_f32_e32 v58, v58, v60
	v_sub_f32_e32 v60, v62, v63
	v_add_f32_e32 v58, v60, v58
	v_add_f32_e32 v60, v65, v58
	v_mul_f32_e32 v62, v59, v60
	v_mul_f32_e32 v63, v57, v62
	v_fma_f32 v57, v62, v57, -v63
	v_fmac_f32_e32 v57, v62, v55
	v_sub_f32_e32 v55, v65, v60
	v_add_f32_e32 v55, v58, v55
	v_add_f32_e32 v58, v63, v57
	v_sub_f32_e32 v64, v60, v58
	v_sub_f32_e32 v60, v60, v64
	v_sub_f32_e32 v63, v58, v63
	v_sub_f32_e32 v58, v60, v58
	v_add_f32_e32 v55, v55, v58
	v_sub_f32_e32 v57, v63, v57
	v_add_f32_e32 v55, v57, v55
	v_add_f32_e32 v57, v61, v62
	v_add_f32_e32 v55, v64, v55
	v_sub_f32_e32 v58, v57, v61
	v_mul_f32_e32 v55, v59, v55
	v_sub_f32_e32 v58, v62, v58
	v_add_f32_e32 v55, v58, v55
	v_mul_f32_e32 v61, 0x3f317218, v54
	v_add_f32_e32 v58, v57, v55
	v_fma_f32 v62, v54, s7, -v61
	v_mul_f32_e32 v59, v58, v58
	v_fmac_f32_e32 v62, 0xb102e308, v54
	v_sub_f32_e32 v54, v58, v57
	v_fmamk_f32 v60, v59, 0x3e9b6dac, v214
	v_sub_f32_e32 v54, v55, v54
	v_add_f32_e32 v55, v61, v62
	v_fmaak_f32 v60, v59, v60, 0x3f2aaada
	v_sub_f32_e32 v57, v55, v61
	v_ldexp_f32 v61, v58, 1
	v_mul_f32_e32 v58, v58, v59
	v_mul_f32_e32 v58, v58, v60
	v_add_f32_e32 v59, v61, v58
	v_sub_f32_e32 v60, v59, v61
	v_ldexp_f32 v54, v54, 1
	v_sub_f32_e32 v58, v58, v60
	v_add_f32_e32 v54, v54, v58
	v_add_f32_e32 v58, v59, v54
	v_sub_f32_e32 v59, v58, v59
	v_sub_f32_e32 v54, v54, v59
	v_add_f32_e32 v59, v55, v58
	v_sub_f32_e32 v60, v59, v55
	v_sub_f32_e32 v61, v59, v60
	v_sub_f32_e32 v57, v62, v57
	v_sub_f32_e32 v55, v55, v61
	v_sub_f32_e32 v58, v58, v60
	v_add_f32_e32 v55, v58, v55
	v_add_f32_e32 v58, v57, v54
	v_sub_f32_e32 v60, v58, v57
	v_sub_f32_e32 v61, v58, v60
	v_sub_f32_e32 v57, v57, v61
	v_sub_f32_e32 v54, v54, v60
	v_add_f32_e32 v55, v58, v55
	v_add_f32_e32 v54, v54, v57
	v_add_f32_e32 v57, v59, v55
	v_sub_f32_e32 v58, v57, v59
	v_sub_f32_e32 v55, v55, v58
	v_add_f32_e32 v54, v54, v55
	v_add_f32_e32 v54, v57, v54
	v_cndmask_b32_e32 v54, v221, v54, vcc
	v_cmp_ngt_f32_e32 vcc, -1.0, v51
	s_nop 1
	v_cndmask_b32_e32 v54, v222, v54, vcc
	v_cmp_neq_f32_e32 vcc, -1.0, v51
	s_nop 1
	v_cndmask_b32_e32 v54, v219, v54, vcc
	v_cmp_lt_f32_e64 vcc, |v51|, s9
	s_nop 1
	v_cndmask_b32_e32 v51, v54, v51, vcc
	v_add_co_u32_e32 v54, vcc, s2, v52
	v_sub_f32_e32 v51, v56, v51
	s_nop 0
	v_addc_co_u32_e32 v55, vcc, 0, v53, vcc
	global_store_dword v[54:55], v51, off offset:3648
	s_mov_b32 s2, 0x21000
	v_add_f32_e32 v51, v42, v244
	v_min_f32_e32 v56, 0, v51
	v_mul_f32_e64 v51, |v51|, s3
	v_exp_f32_e32 v51, v51
	s_nop 0
	v_add_f32_e32 v57, 1.0, v51
	v_add_f32_e32 v54, -1.0, v57
	v_sub_f32_e32 v55, v54, v57
	v_add_f32_e32 v55, 1.0, v55
	v_sub_f32_e32 v54, v51, v54
	v_add_f32_e32 v58, v54, v55
	v_frexp_mant_f32_e32 v54, v57
	v_cmp_gt_f32_e32 vcc, s6, v54
	v_cvt_f64_f32_e32 v[54:55], v57
	v_frexp_exp_i32_f64_e32 v54, v[54:55]
	v_subbrev_co_u32_e32 v54, vcc, 0, v54, vcc
	v_sub_u32_e32 v55, 0, v54
	v_ldexp_f32 v57, v57, v55
	v_ldexp_f32 v55, v58, v55
	v_add_f32_e32 v58, -1.0, v57
	v_add_f32_e32 v59, 1.0, v58
	v_sub_f32_e32 v59, v57, v59
	v_add_f32_e32 v59, v55, v59
	v_add_f32_e32 v60, v58, v59
	v_sub_f32_e32 v58, v60, v58
	v_sub_f32_e32 v58, v59, v58
	v_add_f32_e32 v59, 1.0, v57
	v_add_f32_e32 v61, -1.0, v59
	v_sub_f32_e32 v57, v57, v61
	v_add_f32_e32 v55, v55, v57
	v_add_f32_e32 v57, v59, v55
	v_sub_f32_e32 v59, v57, v59
	v_sub_f32_e32 v55, v55, v59
	v_rcp_f32_e32 v59, v57
	v_cvt_f32_i32_e32 v54, v54
	v_cmp_neq_f32_e32 vcc, s8, v51
	v_mul_f32_e32 v61, v60, v59
	v_mul_f32_e32 v62, v57, v61
	v_fma_f32 v63, v61, v57, -v62
	v_fmac_f32_e32 v63, v61, v55
	v_add_f32_e32 v64, v62, v63
	v_sub_f32_e32 v65, v60, v64
	v_sub_f32_e32 v60, v60, v65
	v_sub_f32_e32 v62, v64, v62
	v_sub_f32_e32 v60, v60, v64
	v_add_f32_e32 v58, v58, v60
	v_sub_f32_e32 v60, v62, v63
	v_add_f32_e32 v58, v60, v58
	v_add_f32_e32 v60, v65, v58
	v_mul_f32_e32 v62, v59, v60
	v_mul_f32_e32 v63, v57, v62
	v_fma_f32 v57, v62, v57, -v63
	v_fmac_f32_e32 v57, v62, v55
	v_sub_f32_e32 v55, v65, v60
	v_add_f32_e32 v55, v58, v55
	v_add_f32_e32 v58, v63, v57
;     __device__ __forceinline__ void operator()(const AccT& acc, const pg8::Unit& u, int wr, int wc, int fr, int fq) const {
;     ...
;                     } else if (wc == 1 && fq == 0) {
; #pragma unroll
;                         for (int n = 0; n < 2; ++n)
; #pragma unroll
;                             for (int j = 0; j < 4; ++j) {
;                                 const float x = acc[ai][0][m][n][j] * rs + bfg[4 * n + j];
;                                 lf[(4 * n + j) * MROWS + row] = fminf(x, 0.f) - log1pf(__expf(-fabsf(x)));
;                             }
	v_sub_f32_e32 v64, v60, v58
	v_sub_f32_e32 v60, v60, v64
	v_sub_f32_e32 v63, v58, v63
	v_sub_f32_e32 v58, v60, v58
	v_add_f32_e32 v55, v55, v58
	v_sub_f32_e32 v57, v63, v57
	v_add_f32_e32 v55, v57, v55
	v_add_f32_e32 v57, v61, v62
	v_add_f32_e32 v55, v64, v55
	v_sub_f32_e32 v58, v57, v61
	v_mul_f32_e32 v55, v59, v55
	v_sub_f32_e32 v58, v62, v58
	v_add_f32_e32 v55, v58, v55
	v_mul_f32_e32 v61, 0x3f317218, v54
	v_add_f32_e32 v58, v57, v55
	v_fma_f32 v62, v54, s7, -v61
	v_mul_f32_e32 v59, v58, v58
	v_fmac_f32_e32 v62, 0xb102e308, v54
	v_sub_f32_e32 v54, v58, v57
	v_fmamk_f32 v60, v59, 0x3e9b6dac, v214
	v_sub_f32_e32 v54, v55, v54
	v_add_f32_e32 v55, v61, v62
	v_fmaak_f32 v60, v59, v60, 0x3f2aaada
	v_sub_f32_e32 v57, v55, v61
	v_ldexp_f32 v61, v58, 1
	v_mul_f32_e32 v58, v58, v59
	v_mul_f32_e32 v58, v58, v60
	v_add_f32_e32 v59, v61, v58
	v_sub_f32_e32 v60, v59, v61
	v_ldexp_f32 v54, v54, 1
	v_sub_f32_e32 v58, v58, v60
	v_add_f32_e32 v54, v54, v58
	v_add_f32_e32 v58, v59, v54
	v_sub_f32_e32 v59, v58, v59
	v_sub_f32_e32 v54, v54, v59
	v_add_f32_e32 v59, v55, v58
	v_sub_f32_e32 v60, v59, v55
	v_sub_f32_e32 v61, v59, v60
	v_sub_f32_e32 v57, v62, v57
	v_sub_f32_e32 v55, v55, v61
	v_sub_f32_e32 v58, v58, v60
	v_add_f32_e32 v55, v58, v55
	v_add_f32_e32 v58, v57, v54
	v_sub_f32_e32 v60, v58, v57
	v_sub_f32_e32 v61, v58, v60
	v_sub_f32_e32 v57, v57, v61
	v_sub_f32_e32 v54, v54, v60
	v_add_f32_e32 v55, v58, v55
	v_add_f32_e32 v54, v54, v57
	v_add_f32_e32 v57, v59, v55
	v_sub_f32_e32 v58, v57, v59
	v_sub_f32_e32 v55, v55, v58
	v_add_f32_e32 v54, v54, v55
	v_add_f32_e32 v54, v57, v54
	v_cndmask_b32_e32 v54, v221, v54, vcc
	v_cmp_ngt_f32_e32 vcc, -1.0, v51
	s_nop 1
	v_cndmask_b32_e32 v54, v222, v54, vcc
	v_cmp_neq_f32_e32 vcc, -1.0, v51
	s_nop 1
	v_cndmask_b32_e32 v54, v219, v54, vcc
	v_cmp_lt_f32_e64 vcc, |v51|, s9
	s_nop 1
	v_cndmask_b32_e32 v51, v54, v51, vcc
	v_add_co_u32_e32 v54, vcc, s2, v52
	v_sub_f32_e32 v51, v56, v51
	s_nop 0
	v_addc_co_u32_e32 v55, vcc, 0, v53, vcc
	global_store_dword v[54:55], v51, off offset:576
	s_mov_b32 s2, 0x29000
	v_add_f32_e32 v51, v43, v245
	v_min_f32_e32 v56, 0, v51
	v_mul_f32_e64 v51, |v51|, s3
	v_exp_f32_e32 v51, v51
	s_nop 0
	v_add_f32_e32 v57, 1.0, v51
	v_add_f32_e32 v54, -1.0, v57
	v_sub_f32_e32 v55, v54, v57
	v_add_f32_e32 v55, 1.0, v55
	v_sub_f32_e32 v54, v51, v54
	v_add_f32_e32 v58, v54, v55
	v_frexp_mant_f32_e32 v54, v57
	v_cmp_gt_f32_e32 vcc, s6, v54
	v_cvt_f64_f32_e32 v[54:55], v57
	v_frexp_exp_i32_f64_e32 v54, v[54:55]
	v_subbrev_co_u32_e32 v54, vcc, 0, v54, vcc
	v_sub_u32_e32 v55, 0, v54
	v_ldexp_f32 v57, v57, v55
	v_ldexp_f32 v55, v58, v55
	v_add_f32_e32 v58, -1.0, v57
	v_add_f32_e32 v59, 1.0, v58
	v_sub_f32_e32 v59, v57, v59
	v_add_f32_e32 v59, v55, v59
	v_add_f32_e32 v60, v58, v59
	v_sub_f32_e32 v58, v60, v58
	v_sub_f32_e32 v58, v59, v58
	v_add_f32_e32 v59, 1.0, v57
	v_add_f32_e32 v61, -1.0, v59
	v_sub_f32_e32 v57, v57, v61
	v_add_f32_e32 v55, v55, v57
	v_add_f32_e32 v57, v59, v55
	v_sub_f32_e32 v59, v57, v59
	v_sub_f32_e32 v55, v55, v59
	v_rcp_f32_e32 v59, v57
	v_cvt_f32_i32_e32 v54, v54
	v_cmp_neq_f32_e32 vcc, s8, v51
	v_mul_f32_e32 v61, v60, v59
	v_mul_f32_e32 v62, v57, v61
	v_fma_f32 v63, v61, v57, -v62
	v_fmac_f32_e32 v63, v61, v55
	v_add_f32_e32 v64, v62, v63
	v_sub_f32_e32 v65, v60, v64
	v_sub_f32_e32 v60, v60, v65
	v_sub_f32_e32 v62, v64, v62
	v_sub_f32_e32 v60, v60, v64
	v_add_f32_e32 v58, v58, v60
	v_sub_f32_e32 v60, v62, v63
	v_add_f32_e32 v58, v60, v58
	v_add_f32_e32 v60, v65, v58
	v_mul_f32_e32 v62, v59, v60
	v_mul_f32_e32 v63, v57, v62
	v_fma_f32 v57, v62, v57, -v63
	v_fmac_f32_e32 v57, v62, v55
	v_sub_f32_e32 v55, v65, v60
	v_add_f32_e32 v55, v58, v55
	v_add_f32_e32 v58, v63, v57
	v_sub_f32_e32 v64, v60, v58
	v_sub_f32_e32 v60, v60, v64
	v_sub_f32_e32 v63, v58, v63
	v_sub_f32_e32 v58, v60, v58
	v_add_f32_e32 v55, v55, v58
	v_sub_f32_e32 v57, v63, v57
	v_add_f32_e32 v55, v57, v55
	v_add_f32_e32 v57, v61, v62
	v_add_f32_e32 v55, v64, v55
	v_sub_f32_e32 v58, v57, v61
	v_mul_f32_e32 v55, v59, v55
	v_sub_f32_e32 v58, v62, v58
	v_add_f32_e32 v55, v58, v55
	v_mul_f32_e32 v61, 0x3f317218, v54
	v_add_f32_e32 v58, v57, v55
	v_fma_f32 v62, v54, s7, -v61
	v_mul_f32_e32 v59, v58, v58
	v_fmac_f32_e32 v62, 0xb102e308, v54
	v_sub_f32_e32 v54, v58, v57
	v_fmamk_f32 v60, v59, 0x3e9b6dac, v214
	v_sub_f32_e32 v54, v55, v54
	v_add_f32_e32 v55, v61, v62
	v_fmaak_f32 v60, v59, v60, 0x3f2aaada
	v_sub_f32_e32 v57, v55, v61
	v_ldexp_f32 v61, v58, 1
	v_mul_f32_e32 v58, v58, v59
	v_mul_f32_e32 v58, v58, v60
	v_add_f32_e32 v59, v61, v58
	v_sub_f32_e32 v60, v59, v61
	v_ldexp_f32 v54, v54, 1
	v_sub_f32_e32 v58, v58, v60
	v_add_f32_e32 v54, v54, v58
	v_add_f32_e32 v58, v59, v54
	v_sub_f32_e32 v59, v58, v59
	v_sub_f32_e32 v54, v54, v59
	v_add_f32_e32 v59, v55, v58
	v_sub_f32_e32 v60, v59, v55
	v_sub_f32_e32 v61, v59, v60
	v_sub_f32_e32 v57, v62, v57
	v_sub_f32_e32 v55, v55, v61
	v_sub_f32_e32 v58, v58, v60
	v_add_f32_e32 v55, v58, v55
	v_add_f32_e32 v58, v57, v54
	v_sub_f32_e32 v60, v58, v57
	v_sub_f32_e32 v61, v58, v60
	v_sub_f32_e32 v57, v57, v61
	v_sub_f32_e32 v54, v54, v60
	v_add_f32_e32 v55, v58, v55
	v_add_f32_e32 v54, v54, v57
	v_add_f32_e32 v57, v59, v55
	v_sub_f32_e32 v58, v57, v59
	v_sub_f32_e32 v55, v55, v58
	v_add_f32_e32 v54, v54, v55
	v_add_f32_e32 v54, v57, v54
	v_cndmask_b32_e32 v54, v221, v54, vcc
	v_cmp_ngt_f32_e32 vcc, -1.0, v51
	s_nop 1
	v_cndmask_b32_e32 v54, v222, v54, vcc
	v_cmp_neq_f32_e32 vcc, -1.0, v51
	s_nop 1
	v_cndmask_b32_e32 v54, v219, v54, vcc
	v_cmp_lt_f32_e64 vcc, |v51|, s9
	s_nop 1
	v_cndmask_b32_e32 v51, v54, v51, vcc
	v_add_co_u32_e32 v54, vcc, s2, v52
	v_sub_f32_e32 v51, v56, v51
;     __device__ __forceinline__ void operator()(const AccT& acc, const pg8::Unit& u, int wr, int wc, int fr, int fq) const {
;     ...
;                     } else if (wc == 1 && fq == 0) {
; #pragma unroll
;                         for (int n = 0; n < 2; ++n)
; #pragma unroll
;                             for (int j = 0; j < 4; ++j) {
;                                 const float x = acc[ai][0][m][n][j] * rs + bfg[4 * n + j];
;                                 lf[(4 * n + j) * MROWS + row] = fminf(x, 0.f) - log1pf(__expf(-fabsf(x)));
;                             }
	s_nop 0
	v_addc_co_u32_e32 v55, vcc, 0, v53, vcc
	global_store_dword v[54:55], v51, off offset:1600
	s_mov_b32 s2, 0x31000
	v_add_f32_e32 v51, v44, v246
	v_min_f32_e32 v56, 0, v51
	v_mul_f32_e64 v51, |v51|, s3
	v_exp_f32_e32 v51, v51
	s_nop 0
	v_add_f32_e32 v57, 1.0, v51
	v_add_f32_e32 v54, -1.0, v57
	v_sub_f32_e32 v55, v54, v57
	v_add_f32_e32 v55, 1.0, v55
	v_sub_f32_e32 v54, v51, v54
	v_add_f32_e32 v58, v54, v55
	v_frexp_mant_f32_e32 v54, v57
	v_cmp_gt_f32_e32 vcc, s6, v54
	v_cvt_f64_f32_e32 v[54:55], v57
	v_frexp_exp_i32_f64_e32 v54, v[54:55]
	v_subbrev_co_u32_e32 v54, vcc, 0, v54, vcc
	v_sub_u32_e32 v55, 0, v54
	v_ldexp_f32 v57, v57, v55
	v_ldexp_f32 v55, v58, v55
	v_add_f32_e32 v58, -1.0, v57
	v_add_f32_e32 v59, 1.0, v58
	v_sub_f32_e32 v59, v57, v59
	v_add_f32_e32 v59, v55, v59
	v_add_f32_e32 v60, v58, v59
	v_sub_f32_e32 v58, v60, v58
	v_sub_f32_e32 v58, v59, v58
	v_add_f32_e32 v59, 1.0, v57
	v_add_f32_e32 v61, -1.0, v59
	v_sub_f32_e32 v57, v57, v61
	v_add_f32_e32 v55, v55, v57
	v_add_f32_e32 v57, v59, v55
	v_sub_f32_e32 v59, v57, v59
	v_sub_f32_e32 v55, v55, v59
	v_rcp_f32_e32 v59, v57
	v_cvt_f32_i32_e32 v54, v54
	v_cmp_neq_f32_e32 vcc, s8, v51
	v_mul_f32_e32 v61, v60, v59
	v_mul_f32_e32 v62, v57, v61
	v_fma_f32 v63, v61, v57, -v62
	v_fmac_f32_e32 v63, v61, v55
	v_add_f32_e32 v64, v62, v63
	v_sub_f32_e32 v65, v60, v64
	v_sub_f32_e32 v60, v60, v65
	v_sub_f32_e32 v62, v64, v62
	v_sub_f32_e32 v60, v60, v64
	v_add_f32_e32 v58, v58, v60
	v_sub_f32_e32 v60, v62, v63
	v_add_f32_e32 v58, v60, v58
	v_add_f32_e32 v60, v65, v58
	v_mul_f32_e32 v62, v59, v60
	v_mul_f32_e32 v63, v57, v62
	v_fma_f32 v57, v62, v57, -v63
	v_fmac_f32_e32 v57, v62, v55
	v_sub_f32_e32 v55, v65, v60
	v_add_f32_e32 v55, v58, v55
	v_add_f32_e32 v58, v63, v57
	v_sub_f32_e32 v64, v60, v58
	v_sub_f32_e32 v60, v60, v64
	v_sub_f32_e32 v63, v58, v63
	v_sub_f32_e32 v58, v60, v58
	v_add_f32_e32 v55, v55, v58
	v_sub_f32_e32 v57, v63, v57
	v_add_f32_e32 v55, v57, v55
	v_add_f32_e32 v57, v61, v62
	v_add_f32_e32 v55, v64, v55
	v_sub_f32_e32 v58, v57, v61
	v_mul_f32_e32 v55, v59, v55
	v_sub_f32_e32 v58, v62, v58
	v_add_f32_e32 v55, v58, v55
	v_mul_f32_e32 v61, 0x3f317218, v54
	v_add_f32_e32 v58, v57, v55
	v_fma_f32 v62, v54, s7, -v61
	v_mul_f32_e32 v59, v58, v58
	v_fmac_f32_e32 v62, 0xb102e308, v54
	v_sub_f32_e32 v54, v58, v57
	v_fmamk_f32 v60, v59, 0x3e9b6dac, v214
	v_sub_f32_e32 v54, v55, v54
	v_add_f32_e32 v55, v61, v62
	v_fmaak_f32 v60, v59, v60, 0x3f2aaada
	v_sub_f32_e32 v57, v55, v61
	v_ldexp_f32 v61, v58, 1
	v_mul_f32_e32 v58, v58, v59
	v_mul_f32_e32 v58, v58, v60
	v_add_f32_e32 v59, v61, v58
	v_sub_f32_e32 v60, v59, v61
	v_ldexp_f32 v54, v54, 1
	v_sub_f32_e32 v58, v58, v60
	v_add_f32_e32 v54, v54, v58
	v_add_f32_e32 v58, v59, v54
	v_sub_f32_e32 v59, v58, v59
	v_sub_f32_e32 v54, v54, v59
	v_add_f32_e32 v59, v55, v58
	v_sub_f32_e32 v60, v59, v55
	v_sub_f32_e32 v61, v59, v60
	v_sub_f32_e32 v57, v62, v57
	v_sub_f32_e32 v55, v55, v61
	v_sub_f32_e32 v58, v58, v60
	v_add_f32_e32 v55, v58, v55
	v_add_f32_e32 v58, v57, v54
	v_sub_f32_e32 v60, v58, v57
	v_sub_f32_e32 v61, v58, v60
	v_sub_f32_e32 v57, v57, v61
	v_sub_f32_e32 v54, v54, v60
	v_add_f32_e32 v55, v58, v55
	v_add_f32_e32 v54, v54, v57
	v_add_f32_e32 v57, v59, v55
	v_sub_f32_e32 v58, v57, v59
	v_sub_f32_e32 v55, v55, v58
	v_add_f32_e32 v54, v54, v55
	v_add_f32_e32 v54, v57, v54
	v_cndmask_b32_e32 v54, v221, v54, vcc
	v_cmp_ngt_f32_e32 vcc, -1.0, v51
	s_nop 1
	v_cndmask_b32_e32 v54, v222, v54, vcc
	v_cmp_neq_f32_e32 vcc, -1.0, v51
	s_nop 1
	v_cndmask_b32_e32 v54, v219, v54, vcc
	v_cmp_lt_f32_e64 vcc, |v51|, s9
	s_nop 1
	v_cndmask_b32_e32 v51, v54, v51, vcc
	v_add_co_u32_e32 v54, vcc, s2, v52
	v_sub_f32_e32 v51, v56, v51
	s_nop 0
	v_addc_co_u32_e32 v55, vcc, 0, v53, vcc
;     __device__ __forceinline__ void operator()(const AccT& acc, const pg8::Unit& u, int wr, int wc, int fr, int fq) const {
;     ...
;                     } else if (wc == 1 && fq == 0) {
; #pragma unroll
;                         for (int n = 0; n < 2; ++n)
; #pragma unroll
;                             for (int j = 0; j < 4; ++j) {
;                                 const float x = acc[ai][0][m][n][j] * rs + bfg[4 * n + j];
;                                 lf[(4 * n + j) * MROWS + row] = fminf(x, 0.f) - log1pf(__expf(-fabsf(x)));
;                             }
	global_store_dword v[54:55], v51, off offset:2624
	v_add_f32_e32 v51, v45, v247
	v_min_f32_e32 v56, 0, v51
	v_mul_f32_e64 v51, |v51|, s3
	v_exp_f32_e32 v51, v51
	s_nop 0
	v_add_f32_e32 v57, 1.0, v51
	v_add_f32_e32 v54, -1.0, v57
	v_sub_f32_e32 v55, v54, v57
	v_add_f32_e32 v55, 1.0, v55
	v_sub_f32_e32 v54, v51, v54
	v_add_f32_e32 v58, v54, v55
	v_frexp_mant_f32_e32 v54, v57
	v_cmp_gt_f32_e32 vcc, s6, v54
	v_cvt_f64_f32_e32 v[54:55], v57
	v_frexp_exp_i32_f64_e32 v54, v[54:55]
	v_subbrev_co_u32_e32 v54, vcc, 0, v54, vcc
	v_sub_u32_e32 v55, 0, v54
	v_ldexp_f32 v57, v57, v55
	v_ldexp_f32 v55, v58, v55
	v_add_f32_e32 v58, -1.0, v57
	v_add_f32_e32 v59, 1.0, v58
	v_sub_f32_e32 v59, v57, v59
	v_add_f32_e32 v59, v55, v59
	v_add_f32_e32 v60, v58, v59
	v_sub_f32_e32 v58, v60, v58
	v_sub_f32_e32 v58, v59, v58
	v_add_f32_e32 v59, 1.0, v57
	v_add_f32_e32 v61, -1.0, v59
	v_sub_f32_e32 v57, v57, v61
	v_add_f32_e32 v55, v55, v57
	v_add_f32_e32 v57, v59, v55
	v_sub_f32_e32 v59, v57, v59
	v_sub_f32_e32 v55, v55, v59
	v_rcp_f32_e32 v59, v57
	v_cvt_f32_i32_e32 v54, v54
	v_cmp_neq_f32_e32 vcc, s8, v51
	v_mul_f32_e32 v61, v60, v59
	v_mul_f32_e32 v62, v57, v61
	v_fma_f32 v63, v61, v57, -v62
	v_fmac_f32_e32 v63, v61, v55
	v_add_f32_e32 v64, v62, v63
	v_sub_f32_e32 v65, v60, v64
	v_sub_f32_e32 v60, v60, v65
	v_sub_f32_e32 v62, v64, v62
	v_sub_f32_e32 v60, v60, v64
	v_add_f32_e32 v58, v58, v60
	v_sub_f32_e32 v60, v62, v63
	v_add_f32_e32 v58, v60, v58
	v_add_f32_e32 v60, v65, v58
	v_mul_f32_e32 v62, v59, v60
	v_mul_f32_e32 v63, v57, v62
	v_fma_f32 v57, v62, v57, -v63
	v_fmac_f32_e32 v57, v62, v55
	v_sub_f32_e32 v55, v65, v60
	v_add_f32_e32 v55, v58, v55
	v_add_f32_e32 v58, v63, v57
	v_sub_f32_e32 v64, v60, v58
	v_sub_f32_e32 v60, v60, v64
	v_sub_f32_e32 v63, v58, v63
	v_sub_f32_e32 v58, v60, v58
	v_add_f32_e32 v55, v55, v58
	v_sub_f32_e32 v57, v63, v57
	v_add_f32_e32 v55, v57, v55
	v_add_f32_e32 v57, v61, v62
	v_add_f32_e32 v55, v64, v55
	v_sub_f32_e32 v58, v57, v61
	v_mul_f32_e32 v55, v59, v55
	v_sub_f32_e32 v58, v62, v58
	v_add_f32_e32 v55, v58, v55
	v_mul_f32_e32 v61, 0x3f317218, v54
	v_add_f32_e32 v58, v57, v55
	v_fma_f32 v62, v54, s7, -v61
	v_mul_f32_e32 v59, v58, v58
	v_fmac_f32_e32 v62, 0xb102e308, v54
	v_sub_f32_e32 v54, v58, v57
	v_fmamk_f32 v60, v59, 0x3e9b6dac, v214
	v_sub_f32_e32 v54, v55, v54
	v_add_f32_e32 v55, v61, v62
	v_fmaak_f32 v60, v59, v60, 0x3f2aaada
	v_sub_f32_e32 v57, v55, v61
	v_ldexp_f32 v61, v58, 1
	v_mul_f32_e32 v58, v58, v59
	v_mul_f32_e32 v58, v58, v60
	v_add_f32_e32 v59, v61, v58
	v_sub_f32_e32 v60, v59, v61
	v_ldexp_f32 v54, v54, 1
	v_sub_f32_e32 v58, v58, v60
	v_add_f32_e32 v54, v54, v58
	v_add_f32_e32 v58, v59, v54
	v_sub_f32_e32 v59, v58, v59
	v_sub_f32_e32 v54, v54, v59
	v_add_f32_e32 v59, v55, v58
	v_sub_f32_e32 v60, v59, v55
	v_sub_f32_e32 v61, v59, v60
	v_sub_f32_e32 v57, v62, v57
	v_sub_f32_e32 v55, v55, v61
	v_sub_f32_e32 v58, v58, v60
	v_add_f32_e32 v55, v58, v55
	v_add_f32_e32 v58, v57, v54
	v_sub_f32_e32 v60, v58, v57
	v_sub_f32_e32 v61, v58, v60
	v_sub_f32_e32 v57, v57, v61
	v_sub_f32_e32 v54, v54, v60
	v_add_f32_e32 v55, v58, v55
	v_add_f32_e32 v54, v54, v57
	v_add_f32_e32 v57, v59, v55
	v_sub_f32_e32 v58, v57, v59
	v_sub_f32_e32 v55, v55, v58
	v_add_f32_e32 v54, v54, v55
	v_add_f32_e32 v54, v57, v54
	v_cndmask_b32_e32 v54, v221, v54, vcc
	v_cmp_ngt_f32_e32 vcc, -1.0, v51
	s_nop 1
	v_cndmask_b32_e32 v54, v222, v54, vcc
	v_cmp_neq_f32_e32 vcc, -1.0, v51
	s_nop 1
	v_cndmask_b32_e32 v54, v219, v54, vcc
	v_cmp_lt_f32_e64 vcc, |v51|, s9
	s_nop 1
	v_cndmask_b32_e32 v51, v54, v51, vcc
	v_add_co_u32_e32 v52, vcc, 0x39000, v52
	v_sub_f32_e32 v51, v56, v51
	s_nop 0
	v_addc_co_u32_e32 v53, vcc, 0, v53, vcc
	global_store_dword v[52:53], v51, off offset:3648

;     __device__ __forceinline__ void operator()(const AccT& acc, const pg8::Unit& u, int wr, int wc, int fr, int fq) const {
;     ...
;                 const int row = row0 + ai * 128 + m * 16;
;                 const float rs = 1.0f;
;                 if (u.pn < 20) {
;                     float ss = 0.f;
; #pragma unroll
;                     for (int bj = 0; bj < 2; ++bj) {
;                         const f32x4 a = acc[ai][bj][m][0], b = acc[ai][bj][m][1];
;                         *(u32x4*)(Z + (size_t)row * ZLD + u.pn * 256 + bj * 128 + wc * 32 + 8 * fq) = pack8s(a, b, rs);
; #pragma unroll
;                         for (int j = 0; j < 4; ++j) ss += a[j] * a[j] + b[j] * b[j];
;                     }
;                     if (u.pn < 4) {
;                         ss *= rs * rs;
;                         ss += __shfl_xor(ss, 16); ss += __shfl_xor(ss, 32);
;                         if (fq == 0) ssqp[row * 16 + u.pn * 4 + wc] = ss;
;                     }
;                 } else {
;                     if (wc == 0) {
;                         const f32x4 c0 = *(const f32x4*)(cosT + row * 32 + 8 * fq), c1 = *(const f32x4*)(cosT + row * 32 + 8 * fq + 4);
;                         const f32x4 s0 = *(const f32x4*)(sinT + row * 32 + 8 * fq), s1 = *(const f32x4*)(sinT + row * 32 + 8 * fq + 4);
;                         const f32x4 x1a = acc[ai][0][m][0] * rs, x1b = acc[ai][0][m][1] * rs, x2a = acc[ai][1][m][0] * rs, x2b = acc[ai][1][m][1] * rs;
;                         const f32x4 y1a = x1a * c0 - x2a * s0, y1b = x1b * c1 - x2b * s1, y2a = x2a * c0 + x1a * s0, y2b = x2b * c1 + x1b * s1;
;                         *(u32x4*)(Kr + (size_t)row * 64 + 8 * fq) = pack8s(y1a, y1b, 1.0f);
;                         *(u32x4*)(Kr + (size_t)row * 64 + 32 + 8 * fq) = pack8s(y2a, y2b, 1.0f);
;                     } else if (wc == 1 && fq == 0) {
; #pragma unroll
;                         for (int n = 0; n < 2; ++n)
; #pragma unroll
;                             for (int j = 0; j < 4; ++j) {
;                                 const float x = acc[ai][0][m][n][j] * rs + bfg[4 * n + j];
;                                 lf[(4 * n + j) * MROWS + row] = fminf(x, 0.f) - log1pf(__expf(-fabsf(x)));
;                             }
.LBB0_1024:
	v_add_u32_e32 v34, 0xa0, v150
	s_and_b64 vcc, exec, s[44:45]
	s_mov_b64 s[8:9], -1
	s_cbranch_vccnz .LBB0_1032
	s_and_b64 vcc, exec, s[42:43]
	s_cbranch_vccnz .LBB0_1029
	s_and_saveexec_b64 s[70:71], s[58:59]
	s_cbranch_execz .LBB0_1028
	s_waitcnt lgkmcnt(0)
	s_mov_b32 s3, 0xbfb8aa3b
	s_mov_b32 s6, 0x3f2aaaab
	s_mov_b32 s7, 0x3f317218
	s_mov_b32 s8, 0x7f800000
	s_mov_b32 s9, 0x33800000
	v_ashrrev_i32_e32 v151, 31, v150
	s_mov_b32 s2, 0x8000
	v_add_f32_e32 v35, v30, v240
	v_min_f32_e32 v38, 0, v35
	v_mul_f32_e64 v35, |v35|, s3
	v_exp_f32_e32 v35, v35
	s_nop 0
	v_add_f32_e32 v39, 1.0, v35
	v_add_f32_e32 v36, -1.0, v39
	v_sub_f32_e32 v37, v36, v39
	v_add_f32_e32 v37, 1.0, v37
	v_sub_f32_e32 v36, v35, v36
	v_add_f32_e32 v40, v36, v37
	v_frexp_mant_f32_e32 v36, v39
	v_cmp_gt_f32_e32 vcc, s6, v36
	v_cvt_f64_f32_e32 v[36:37], v39
	v_frexp_exp_i32_f64_e32 v36, v[36:37]
	v_subbrev_co_u32_e32 v36, vcc, 0, v36, vcc
	v_sub_u32_e32 v37, 0, v36
	v_ldexp_f32 v39, v39, v37
	v_ldexp_f32 v37, v40, v37
	v_add_f32_e32 v40, -1.0, v39
	v_add_f32_e32 v41, 1.0, v40
	v_sub_f32_e32 v41, v39, v41
	v_add_f32_e32 v41, v37, v41
	v_add_f32_e32 v42, v40, v41
	v_sub_f32_e32 v40, v42, v40
	v_sub_f32_e32 v40, v41, v40
	v_add_f32_e32 v41, 1.0, v39
	v_add_f32_e32 v43, -1.0, v41
	v_sub_f32_e32 v39, v39, v43
	v_add_f32_e32 v37, v37, v39
	v_add_f32_e32 v39, v41, v37
	v_sub_f32_e32 v41, v39, v41
	v_sub_f32_e32 v37, v37, v41
	v_rcp_f32_e32 v41, v39
	v_cvt_f32_i32_e32 v36, v36
	v_cmp_neq_f32_e32 vcc, s8, v35
	v_mul_f32_e32 v43, v42, v41
	v_mul_f32_e32 v44, v39, v43
	v_fma_f32 v45, v43, v39, -v44
	v_fmac_f32_e32 v45, v43, v37
	v_add_f32_e32 v46, v44, v45
	v_sub_f32_e32 v47, v42, v46
	v_sub_f32_e32 v42, v42, v47
	v_sub_f32_e32 v44, v46, v44
	v_sub_f32_e32 v42, v42, v46
	v_add_f32_e32 v40, v40, v42
	v_sub_f32_e32 v42, v44, v45
	v_add_f32_e32 v40, v42, v40
	v_add_f32_e32 v42, v47, v40
	v_mul_f32_e32 v44, v41, v42
	v_mul_f32_e32 v45, v39, v44
	v_fma_f32 v39, v44, v39, -v45
	v_fmac_f32_e32 v39, v44, v37
	v_sub_f32_e32 v37, v47, v42
	v_add_f32_e32 v37, v40, v37
	v_add_f32_e32 v40, v45, v39
	v_sub_f32_e32 v46, v42, v40
	v_sub_f32_e32 v42, v42, v46
	v_sub_f32_e32 v45, v40, v45
	v_sub_f32_e32 v40, v42, v40
	v_add_f32_e32 v37, v37, v40
	v_sub_f32_e32 v39, v45, v39
	v_add_f32_e32 v37, v39, v37
	v_add_f32_e32 v39, v43, v44
	v_add_f32_e32 v37, v46, v37
	v_sub_f32_e32 v40, v39, v43
	v_mul_f32_e32 v37, v41, v37
	v_sub_f32_e32 v40, v44, v40
	v_add_f32_e32 v37, v40, v37
	v_mul_f32_e32 v43, 0x3f317218, v36
	v_add_f32_e32 v40, v39, v37
	v_fma_f32 v44, v36, s7, -v43
	v_mul_f32_e32 v41, v40, v40
	v_fmac_f32_e32 v44, 0xb102e308, v36
	v_sub_f32_e32 v36, v40, v39
	v_fmamk_f32 v42, v41, 0x3e9b6dac, v214
	v_sub_f32_e32 v36, v37, v36
	v_add_f32_e32 v37, v43, v44
	v_fmaak_f32 v42, v41, v42, 0x3f2aaada
	v_sub_f32_e32 v39, v37, v43
	v_ldexp_f32 v43, v40, 1
	v_mul_f32_e32 v40, v40, v41
	v_mul_f32_e32 v40, v40, v42
	v_add_f32_e32 v41, v43, v40
	v_sub_f32_e32 v42, v41, v43
	v_ldexp_f32 v36, v36, 1
	v_sub_f32_e32 v40, v40, v42
	v_add_f32_e32 v36, v36, v40
	v_add_f32_e32 v40, v41, v36
	v_sub_f32_e32 v41, v40, v41
	v_sub_f32_e32 v36, v36, v41
	v_add_f32_e32 v41, v37, v40
	v_sub_f32_e32 v42, v41, v37
	v_sub_f32_e32 v43, v41, v42
	v_sub_f32_e32 v39, v44, v39
	v_sub_f32_e32 v37, v37, v43
	v_sub_f32_e32 v40, v40, v42
	v_add_f32_e32 v37, v40, v37
	v_add_f32_e32 v40, v39, v36
	v_sub_f32_e32 v42, v40, v39
	v_sub_f32_e32 v43, v40, v42
	v_sub_f32_e32 v39, v39, v43
	v_sub_f32_e32 v36, v36, v42
	v_add_f32_e32 v37, v40, v37
	v_add_f32_e32 v36, v36, v39
	v_add_f32_e32 v39, v41, v37
	v_sub_f32_e32 v40, v39, v41
	v_sub_f32_e32 v37, v37, v40
	v_add_f32_e32 v36, v36, v37
	v_add_f32_e32 v36, v39, v36
	v_cndmask_b32_e32 v36, v221, v36, vcc
	v_cmp_ngt_f32_e32 vcc, -1.0, v35
	s_nop 1
	v_cndmask_b32_e32 v36, v222, v36, vcc
	v_cmp_neq_f32_e32 vcc, -1.0, v35
	s_nop 1
	v_cndmask_b32_e32 v36, v219, v36, vcc
	v_cmp_lt_f32_e64 vcc, |v35|, s9
	s_nop 1
	v_cndmask_b32_e32 v35, v36, v35, vcc
	v_sub_f32_e32 v38, v38, v35
	v_ashrrev_i32_e32 v35, 31, v34
	v_lshl_add_u64 v[36:37], v[34:35], 2, s[52:53]
	global_store_dword v[36:37], v38, off
	v_add_f32_e32 v35, v31, v241
	v_min_f32_e32 v38, 0, v35
	v_mul_f32_e64 v35, |v35|, s3
	v_exp_f32_e32 v35, v35
	s_nop 0
	v_add_f32_e32 v39, 1.0, v35
	v_add_f32_e32 v36, -1.0, v39
	v_sub_f32_e32 v37, v36, v39
	v_add_f32_e32 v37, 1.0, v37
	v_sub_f32_e32 v36, v35, v36
	v_add_f32_e32 v40, v36, v37
	v_frexp_mant_f32_e32 v36, v39
	v_cmp_gt_f32_e32 vcc, s6, v36
	v_cvt_f64_f32_e32 v[36:37], v39
	v_frexp_exp_i32_f64_e32 v36, v[36:37]
	v_subbrev_co_u32_e32 v36, vcc, 0, v36, vcc
	v_sub_u32_e32 v37, 0, v36
	v_ldexp_f32 v39, v39, v37
	v_ldexp_f32 v37, v40, v37
	v_add_f32_e32 v40, -1.0, v39
	v_add_f32_e32 v41, 1.0, v40
	v_sub_f32_e32 v41, v39, v41
	v_add_f32_e32 v41, v37, v41
	v_add_f32_e32 v42, v40, v41
	v_sub_f32_e32 v40, v42, v40
	v_sub_f32_e32 v40, v41, v40
	v_add_f32_e32 v41, 1.0, v39
	v_add_f32_e32 v43, -1.0, v41
	v_sub_f32_e32 v39, v39, v43
	v_add_f32_e32 v37, v37, v39
	v_add_f32_e32 v39, v41, v37
	v_sub_f32_e32 v41, v39, v41
	v_sub_f32_e32 v37, v37, v41
	v_rcp_f32_e32 v41, v39
	v_cvt_f32_i32_e32 v36, v36
	v_cmp_neq_f32_e32 vcc, s8, v35
	v_mul_f32_e32 v43, v42, v41
	v_mul_f32_e32 v44, v39, v43
	v_fma_f32 v45, v43, v39, -v44
	v_fmac_f32_e32 v45, v43, v37
	v_add_f32_e32 v46, v44, v45
	v_sub_f32_e32 v47, v42, v46
	v_sub_f32_e32 v42, v42, v47
	v_sub_f32_e32 v44, v46, v44
	v_sub_f32_e32 v42, v42, v46
	v_add_f32_e32 v40, v40, v42
	v_sub_f32_e32 v42, v44, v45
	v_add_f32_e32 v40, v42, v40
	v_add_f32_e32 v42, v47, v40
	v_mul_f32_e32 v44, v41, v42
	v_mul_f32_e32 v45, v39, v44
	v_fma_f32 v39, v44, v39, -v45
;     __device__ __forceinline__ void operator()(const AccT& acc, const pg8::Unit& u, int wr, int wc, int fr, int fq) const {
;     ...
;                     } else if (wc == 1 && fq == 0) {
; #pragma unroll
;                         for (int n = 0; n < 2; ++n)
; #pragma unroll
;                             for (int j = 0; j < 4; ++j) {
;                                 const float x = acc[ai][0][m][n][j] * rs + bfg[4 * n + j];
;                                 lf[(4 * n + j) * MROWS + row] = fminf(x, 0.f) - log1pf(__expf(-fabsf(x)));
;                             }
	v_fmac_f32_e32 v39, v44, v37
	v_sub_f32_e32 v37, v47, v42
	v_add_f32_e32 v37, v40, v37
	v_add_f32_e32 v40, v45, v39
	v_sub_f32_e32 v46, v42, v40
	v_sub_f32_e32 v42, v42, v46
	v_sub_f32_e32 v45, v40, v45
	v_sub_f32_e32 v40, v42, v40
	v_add_f32_e32 v37, v37, v40
	v_sub_f32_e32 v39, v45, v39
	v_add_f32_e32 v37, v39, v37
	v_add_f32_e32 v39, v43, v44
	v_add_f32_e32 v37, v46, v37
	v_sub_f32_e32 v40, v39, v43
	v_mul_f32_e32 v37, v41, v37
	v_sub_f32_e32 v40, v44, v40
	v_add_f32_e32 v37, v40, v37
	v_mul_f32_e32 v43, 0x3f317218, v36
	v_add_f32_e32 v40, v39, v37
	v_fma_f32 v44, v36, s7, -v43
	v_mul_f32_e32 v41, v40, v40
	v_fmac_f32_e32 v44, 0xb102e308, v36
	v_sub_f32_e32 v36, v40, v39
	v_fmamk_f32 v42, v41, 0x3e9b6dac, v214
	v_sub_f32_e32 v36, v37, v36
	v_add_f32_e32 v37, v43, v44
	v_fmaak_f32 v42, v41, v42, 0x3f2aaada
	v_sub_f32_e32 v39, v37, v43
	v_ldexp_f32 v43, v40, 1
	v_mul_f32_e32 v40, v40, v41
	v_mul_f32_e32 v40, v40, v42
	v_add_f32_e32 v41, v43, v40
	v_sub_f32_e32 v42, v41, v43
	v_ldexp_f32 v36, v36, 1
	v_sub_f32_e32 v40, v40, v42
	v_add_f32_e32 v36, v36, v40
	v_add_f32_e32 v40, v41, v36
	v_sub_f32_e32 v41, v40, v41
	v_sub_f32_e32 v36, v36, v41
	v_add_f32_e32 v41, v37, v40
	v_sub_f32_e32 v42, v41, v37
	v_sub_f32_e32 v43, v41, v42
	v_sub_f32_e32 v39, v44, v39
	v_sub_f32_e32 v37, v37, v43
	v_sub_f32_e32 v40, v40, v42
	v_add_f32_e32 v37, v40, v37
	v_add_f32_e32 v40, v39, v36
	v_sub_f32_e32 v42, v40, v39
	v_sub_f32_e32 v43, v40, v42
	v_sub_f32_e32 v39, v39, v43
	v_sub_f32_e32 v36, v36, v42
	v_add_f32_e32 v37, v40, v37
	v_add_f32_e32 v36, v36, v39
	v_add_f32_e32 v39, v41, v37
	v_sub_f32_e32 v40, v39, v41
	v_sub_f32_e32 v37, v37, v40
	v_add_f32_e32 v36, v36, v37
	v_add_f32_e32 v36, v39, v36
	v_cndmask_b32_e32 v36, v221, v36, vcc
	v_cmp_ngt_f32_e32 vcc, -1.0, v35
	s_nop 1
	v_cndmask_b32_e32 v36, v222, v36, vcc
	v_cmp_neq_f32_e32 vcc, -1.0, v35
	s_nop 1
	v_cndmask_b32_e32 v36, v219, v36, vcc
	v_cmp_lt_f32_e64 vcc, |v35|, s9
	s_nop 1
	v_cndmask_b32_e32 v35, v36, v35, vcc
	v_lshl_add_u64 v[36:37], v[150:151], 2, s[52:53]
	v_sub_f32_e32 v35, v38, v35
	v_add_co_u32_e32 v38, vcc, s2, v36
	s_mov_b32 s2, 0x10000
	s_nop 0
	v_addc_co_u32_e32 v39, vcc, 0, v37, vcc
	global_store_dword v[38:39], v35, off offset:1664
	v_add_f32_e32 v35, v32, v242
	v_min_f32_e32 v40, 0, v35
	v_mul_f32_e64 v35, |v35|, s3
	v_exp_f32_e32 v35, v35
	s_nop 0
	v_add_f32_e32 v41, 1.0, v35
	v_add_f32_e32 v38, -1.0, v41
	v_sub_f32_e32 v39, v38, v41
	v_add_f32_e32 v39, 1.0, v39
	v_sub_f32_e32 v38, v35, v38
	v_add_f32_e32 v42, v38, v39
	v_frexp_mant_f32_e32 v38, v41
	v_cmp_gt_f32_e32 vcc, s6, v38
	v_cvt_f64_f32_e32 v[38:39], v41
	v_frexp_exp_i32_f64_e32 v38, v[38:39]
	v_subbrev_co_u32_e32 v38, vcc, 0, v38, vcc
	v_sub_u32_e32 v39, 0, v38
	v_ldexp_f32 v41, v41, v39
	v_ldexp_f32 v39, v42, v39
	v_add_f32_e32 v42, -1.0, v41
	v_add_f32_e32 v43, 1.0, v42
	v_sub_f32_e32 v43, v41, v43
	v_add_f32_e32 v43, v39, v43
	v_add_f32_e32 v44, v42, v43
	v_sub_f32_e32 v42, v44, v42
	v_sub_f32_e32 v42, v43, v42
	v_add_f32_e32 v43, 1.0, v41
	v_add_f32_e32 v45, -1.0, v43
	v_sub_f32_e32 v41, v41, v45
	v_add_f32_e32 v39, v39, v41
	v_add_f32_e32 v41, v43, v39
	v_sub_f32_e32 v43, v41, v43
	v_sub_f32_e32 v39, v39, v43
	v_rcp_f32_e32 v43, v41
	v_cvt_f32_i32_e32 v38, v38
	v_cmp_neq_f32_e32 vcc, s8, v35
	v_mul_f32_e32 v45, v44, v43
	v_mul_f32_e32 v46, v41, v45
	v_fma_f32 v47, v45, v41, -v46
	v_fmac_f32_e32 v47, v45, v39
	v_add_f32_e32 v48, v46, v47
	v_sub_f32_e32 v49, v44, v48
	v_sub_f32_e32 v44, v44, v49
	v_sub_f32_e32 v46, v48, v46
	v_sub_f32_e32 v44, v44, v48
	v_add_f32_e32 v42, v42, v44
	v_sub_f32_e32 v44, v46, v47
	v_add_f32_e32 v42, v44, v42
	v_add_f32_e32 v44, v49, v42
	v_mul_f32_e32 v46, v43, v44
	v_mul_f32_e32 v47, v41, v46
	v_fma_f32 v41, v46, v41, -v47
	v_fmac_f32_e32 v41, v46, v39
	v_sub_f32_e32 v39, v49, v44
	v_add_f32_e32 v39, v42, v39
	v_add_f32_e32 v42, v47, v41
	v_sub_f32_e32 v48, v44, v42
	v_sub_f32_e32 v44, v44, v48
	v_sub_f32_e32 v47, v42, v47
	v_sub_f32_e32 v42, v44, v42
	v_add_f32_e32 v39, v39, v42
	v_sub_f32_e32 v41, v47, v41
	v_add_f32_e32 v39, v41, v39
	v_add_f32_e32 v41, v45, v46
	v_add_f32_e32 v39, v48, v39
	v_sub_f32_e32 v42, v41, v45
	v_mul_f32_e32 v39, v43, v39
	v_sub_f32_e32 v42, v46, v42
	v_add_f32_e32 v39, v42, v39
	v_mul_f32_e32 v45, 0x3f317218, v38
	v_add_f32_e32 v42, v41, v39
	v_fma_f32 v46, v38, s7, -v45
	v_mul_f32_e32 v43, v42, v42
	v_fmac_f32_e32 v46, 0xb102e308, v38
	v_sub_f32_e32 v38, v42, v41
	v_fmamk_f32 v44, v43, 0x3e9b6dac, v214
	v_sub_f32_e32 v38, v39, v38
	v_add_f32_e32 v39, v45, v46
	v_fmaak_f32 v44, v43, v44, 0x3f2aaada
	v_sub_f32_e32 v41, v39, v45
	v_ldexp_f32 v45, v42, 1
	v_mul_f32_e32 v42, v42, v43
	v_mul_f32_e32 v42, v42, v44
	v_add_f32_e32 v43, v45, v42
	v_sub_f32_e32 v44, v43, v45
	v_ldexp_f32 v38, v38, 1
	v_sub_f32_e32 v42, v42, v44
	v_add_f32_e32 v38, v38, v42
	v_add_f32_e32 v42, v43, v38
	v_sub_f32_e32 v43, v42, v43
	v_sub_f32_e32 v38, v38, v43
	v_add_f32_e32 v43, v39, v42
	v_sub_f32_e32 v44, v43, v39
	v_sub_f32_e32 v45, v43, v44
	v_sub_f32_e32 v41, v46, v41
	v_sub_f32_e32 v39, v39, v45
	v_sub_f32_e32 v42, v42, v44
	v_add_f32_e32 v39, v42, v39
	v_add_f32_e32 v42, v41, v38
	v_sub_f32_e32 v44, v42, v41
	v_sub_f32_e32 v45, v42, v44
	v_sub_f32_e32 v41, v41, v45
	v_sub_f32_e32 v38, v38, v44
	v_add_f32_e32 v39, v42, v39
	v_add_f32_e32 v38, v38, v41
	v_add_f32_e32 v41, v43, v39
	v_sub_f32_e32 v42, v41, v43
	v_sub_f32_e32 v39, v39, v42
	v_add_f32_e32 v38, v38, v39
	v_add_f32_e32 v38, v41, v38
	v_cndmask_b32_e32 v38, v221, v38, vcc
	v_cmp_ngt_f32_e32 vcc, -1.0, v35
	s_nop 1
	v_cndmask_b32_e32 v38, v222, v38, vcc
	v_cmp_neq_f32_e32 vcc, -1.0, v35
	s_nop 1
;     __device__ __forceinline__ void operator()(const AccT& acc, const pg8::Unit& u, int wr, int wc, int fr, int fq) const {
;     ...
;                     } else if (wc == 1 && fq == 0) {
; #pragma unroll
;                         for (int n = 0; n < 2; ++n)
; #pragma unroll
;                             for (int j = 0; j < 4; ++j) {
;                                 const float x = acc[ai][0][m][n][j] * rs + bfg[4 * n + j];
;                                 lf[(4 * n + j) * MROWS + row] = fminf(x, 0.f) - log1pf(__expf(-fabsf(x)));
;                             }
	v_cndmask_b32_e32 v38, v219, v38, vcc
	v_cmp_lt_f32_e64 vcc, |v35|, s9
	s_nop 1
	v_cndmask_b32_e32 v35, v38, v35, vcc
	v_add_co_u32_e32 v38, vcc, s2, v36
	v_sub_f32_e32 v35, v40, v35
	s_nop 0
	v_addc_co_u32_e32 v39, vcc, 0, v37, vcc
	global_store_dword v[38:39], v35, off offset:2688
	s_mov_b32 s2, 0x18000
	v_add_f32_e32 v35, v33, v243
	v_min_f32_e32 v40, 0, v35
	v_mul_f32_e64 v35, |v35|, s3
	v_exp_f32_e32 v35, v35
	s_nop 0
	v_add_f32_e32 v41, 1.0, v35
	v_add_f32_e32 v38, -1.0, v41
	v_sub_f32_e32 v39, v38, v41
	v_add_f32_e32 v39, 1.0, v39
	v_sub_f32_e32 v38, v35, v38
	v_add_f32_e32 v42, v38, v39
	v_frexp_mant_f32_e32 v38, v41
	v_cmp_gt_f32_e32 vcc, s6, v38
	v_cvt_f64_f32_e32 v[38:39], v41
	v_frexp_exp_i32_f64_e32 v38, v[38:39]
	v_subbrev_co_u32_e32 v38, vcc, 0, v38, vcc
	v_sub_u32_e32 v39, 0, v38
	v_ldexp_f32 v41, v41, v39
	v_ldexp_f32 v39, v42, v39
	v_add_f32_e32 v42, -1.0, v41
	v_add_f32_e32 v43, 1.0, v42
	v_sub_f32_e32 v43, v41, v43
	v_add_f32_e32 v43, v39, v43
	v_add_f32_e32 v44, v42, v43
	v_sub_f32_e32 v42, v44, v42
	v_sub_f32_e32 v42, v43, v42
	v_add_f32_e32 v43, 1.0, v41
	v_add_f32_e32 v45, -1.0, v43
	v_sub_f32_e32 v41, v41, v45
	v_add_f32_e32 v39, v39, v41
	v_add_f32_e32 v41, v43, v39
	v_sub_f32_e32 v43, v41, v43
	v_sub_f32_e32 v39, v39, v43
	v_rcp_f32_e32 v43, v41
	v_cvt_f32_i32_e32 v38, v38
	v_cmp_neq_f32_e32 vcc, s8, v35
	v_mul_f32_e32 v45, v44, v43
	v_mul_f32_e32 v46, v41, v45
	v_fma_f32 v47, v45, v41, -v46
	v_fmac_f32_e32 v47, v45, v39
	v_add_f32_e32 v48, v46, v47
	v_sub_f32_e32 v49, v44, v48
	v_sub_f32_e32 v44, v44, v49
	v_sub_f32_e32 v46, v48, v46
	v_sub_f32_e32 v44, v44, v48
	v_add_f32_e32 v42, v42, v44
	v_sub_f32_e32 v44, v46, v47
	v_add_f32_e32 v42, v44, v42
	v_add_f32_e32 v44, v49, v42
	v_mul_f32_e32 v46, v43, v44
	v_mul_f32_e32 v47, v41, v46
	v_fma_f32 v41, v46, v41, -v47
	v_fmac_f32_e32 v41, v46, v39
	v_sub_f32_e32 v39, v49, v44
	v_add_f32_e32 v39, v42, v39
	v_add_f32_e32 v42, v47, v41
	v_sub_f32_e32 v48, v44, v42
	v_sub_f32_e32 v44, v44, v48
	v_sub_f32_e32 v47, v42, v47
	v_sub_f32_e32 v42, v44, v42
	v_add_f32_e32 v39, v39, v42
	v_sub_f32_e32 v41, v47, v41
	v_add_f32_e32 v39, v41, v39
	v_add_f32_e32 v41, v45, v46
	v_add_f32_e32 v39, v48, v39
	v_sub_f32_e32 v42, v41, v45
	v_mul_f32_e32 v39, v43, v39
	v_sub_f32_e32 v42, v46, v42
	v_add_f32_e32 v39, v42, v39
	v_mul_f32_e32 v45, 0x3f317218, v38
	v_add_f32_e32 v42, v41, v39
	v_fma_f32 v46, v38, s7, -v45
	v_mul_f32_e32 v43, v42, v42
	v_fmac_f32_e32 v46, 0xb102e308, v38
	v_sub_f32_e32 v38, v42, v41
	v_fmamk_f32 v44, v43, 0x3e9b6dac, v214
	v_sub_f32_e32 v38, v39, v38
	v_add_f32_e32 v39, v45, v46
	v_fmaak_f32 v44, v43, v44, 0x3f2aaada
	v_sub_f32_e32 v41, v39, v45
	v_ldexp_f32 v45, v42, 1
	v_mul_f32_e32 v42, v42, v43
	v_mul_f32_e32 v42, v42, v44
	v_add_f32_e32 v43, v45, v42
	v_sub_f32_e32 v44, v43, v45
	v_ldexp_f32 v38, v38, 1
	v_sub_f32_e32 v42, v42, v44
	v_add_f32_e32 v38, v38, v42
	v_add_f32_e32 v42, v43, v38
	v_sub_f32_e32 v43, v42, v43
	v_sub_f32_e32 v38, v38, v43
	v_add_f32_e32 v43, v39, v42
	v_sub_f32_e32 v44, v43, v39
	v_sub_f32_e32 v45, v43, v44
	v_sub_f32_e32 v41, v46, v41
	v_sub_f32_e32 v39, v39, v45
	v_sub_f32_e32 v42, v42, v44
	v_add_f32_e32 v39, v42, v39
	v_add_f32_e32 v42, v41, v38
	v_sub_f32_e32 v44, v42, v41
	v_sub_f32_e32 v45, v42, v44
	v_sub_f32_e32 v41, v41, v45
	v_sub_f32_e32 v38, v38, v44
	v_add_f32_e32 v39, v42, v39
	v_add_f32_e32 v38, v38, v41
	v_add_f32_e32 v41, v43, v39
	v_sub_f32_e32 v42, v41, v43
	v_sub_f32_e32 v39, v39, v42
	v_add_f32_e32 v38, v38, v39
	v_add_f32_e32 v38, v41, v38
	v_cndmask_b32_e32 v38, v221, v38, vcc
	v_cmp_ngt_f32_e32 vcc, -1.0, v35
	s_nop 1
	v_cndmask_b32_e32 v38, v222, v38, vcc
	v_cmp_neq_f32_e32 vcc, -1.0, v35
	s_nop 1
	v_cndmask_b32_e32 v38, v219, v38, vcc
	v_cmp_lt_f32_e64 vcc, |v35|, s9
	s_nop 1
	v_cndmask_b32_e32 v35, v38, v35, vcc
	v_add_co_u32_e32 v38, vcc, s2, v36
	v_sub_f32_e32 v35, v40, v35
	s_nop 0
	v_addc_co_u32_e32 v39, vcc, 0, v37, vcc
	global_store_dword v[38:39], v35, off offset:3712
	s_mov_b32 s2, 0x21000
	v_add_f32_e32 v35, v26, v244
	v_min_f32_e32 v40, 0, v35
	v_mul_f32_e64 v35, |v35|, s3
	v_exp_f32_e32 v35, v35
	s_nop 0
	v_add_f32_e32 v41, 1.0, v35
	v_add_f32_e32 v38, -1.0, v41
	v_sub_f32_e32 v39, v38, v41
	v_add_f32_e32 v39, 1.0, v39
	v_sub_f32_e32 v38, v35, v38
	v_add_f32_e32 v42, v38, v39
	v_frexp_mant_f32_e32 v38, v41
	v_cmp_gt_f32_e32 vcc, s6, v38
	v_cvt_f64_f32_e32 v[38:39], v41
	v_frexp_exp_i32_f64_e32 v38, v[38:39]
	v_subbrev_co_u32_e32 v38, vcc, 0, v38, vcc
	v_sub_u32_e32 v39, 0, v38
	v_ldexp_f32 v41, v41, v39
	v_ldexp_f32 v39, v42, v39
	v_add_f32_e32 v42, -1.0, v41
	v_add_f32_e32 v43, 1.0, v42
	v_sub_f32_e32 v43, v41, v43
	v_add_f32_e32 v43, v39, v43
	v_add_f32_e32 v44, v42, v43
	v_sub_f32_e32 v42, v44, v42
	v_sub_f32_e32 v42, v43, v42
	v_add_f32_e32 v43, 1.0, v41
	v_add_f32_e32 v45, -1.0, v43
	v_sub_f32_e32 v41, v41, v45
	v_add_f32_e32 v39, v39, v41
	v_add_f32_e32 v41, v43, v39
	v_sub_f32_e32 v43, v41, v43
	v_sub_f32_e32 v39, v39, v43
	v_rcp_f32_e32 v43, v41
	v_cvt_f32_i32_e32 v38, v38
	v_cmp_neq_f32_e32 vcc, s8, v35
	v_mul_f32_e32 v45, v44, v43
	v_mul_f32_e32 v46, v41, v45
	v_fma_f32 v47, v45, v41, -v46
	v_fmac_f32_e32 v47, v45, v39
	v_add_f32_e32 v48, v46, v47
	v_sub_f32_e32 v49, v44, v48
	v_sub_f32_e32 v44, v44, v49
	v_sub_f32_e32 v46, v48, v46
	v_sub_f32_e32 v44, v44, v48
	v_add_f32_e32 v42, v42, v44
	v_sub_f32_e32 v44, v46, v47
	v_add_f32_e32 v42, v44, v42
	v_add_f32_e32 v44, v49, v42
	v_mul_f32_e32 v46, v43, v44
	v_mul_f32_e32 v47, v41, v46
	v_fma_f32 v41, v46, v41, -v47
	v_fmac_f32_e32 v41, v46, v39
	v_sub_f32_e32 v39, v49, v44
	v_add_f32_e32 v39, v42, v39
	v_add_f32_e32 v42, v47, v41
;     __device__ __forceinline__ void operator()(const AccT& acc, const pg8::Unit& u, int wr, int wc, int fr, int fq) const {
;     ...
;                     } else if (wc == 1 && fq == 0) {
; #pragma unroll
;                         for (int n = 0; n < 2; ++n)
; #pragma unroll
;                             for (int j = 0; j < 4; ++j) {
;                                 const float x = acc[ai][0][m][n][j] * rs + bfg[4 * n + j];
;                                 lf[(4 * n + j) * MROWS + row] = fminf(x, 0.f) - log1pf(__expf(-fabsf(x)));
;                             }
	v_sub_f32_e32 v48, v44, v42
	v_sub_f32_e32 v44, v44, v48
	v_sub_f32_e32 v47, v42, v47
	v_sub_f32_e32 v42, v44, v42
	v_add_f32_e32 v39, v39, v42
	v_sub_f32_e32 v41, v47, v41
	v_add_f32_e32 v39, v41, v39
	v_add_f32_e32 v41, v45, v46
	v_add_f32_e32 v39, v48, v39
	v_sub_f32_e32 v42, v41, v45
	v_mul_f32_e32 v39, v43, v39
	v_sub_f32_e32 v42, v46, v42
	v_add_f32_e32 v39, v42, v39
	v_mul_f32_e32 v45, 0x3f317218, v38
	v_add_f32_e32 v42, v41, v39
	v_fma_f32 v46, v38, s7, -v45
	v_mul_f32_e32 v43, v42, v42
	v_fmac_f32_e32 v46, 0xb102e308, v38
	v_sub_f32_e32 v38, v42, v41
	v_fmamk_f32 v44, v43, 0x3e9b6dac, v214
	v_sub_f32_e32 v38, v39, v38
	v_add_f32_e32 v39, v45, v46
	v_fmaak_f32 v44, v43, v44, 0x3f2aaada
	v_sub_f32_e32 v41, v39, v45
	v_ldexp_f32 v45, v42, 1
	v_mul_f32_e32 v42, v42, v43
	v_mul_f32_e32 v42, v42, v44
	v_add_f32_e32 v43, v45, v42
	v_sub_f32_e32 v44, v43, v45
	v_ldexp_f32 v38, v38, 1
	v_sub_f32_e32 v42, v42, v44
	v_add_f32_e32 v38, v38, v42
	v_add_f32_e32 v42, v43, v38
	v_sub_f32_e32 v43, v42, v43
	v_sub_f32_e32 v38, v38, v43
	v_add_f32_e32 v43, v39, v42
	v_sub_f32_e32 v44, v43, v39
	v_sub_f32_e32 v45, v43, v44
	v_sub_f32_e32 v41, v46, v41
	v_sub_f32_e32 v39, v39, v45
	v_sub_f32_e32 v42, v42, v44
	v_add_f32_e32 v39, v42, v39
	v_add_f32_e32 v42, v41, v38
	v_sub_f32_e32 v44, v42, v41
	v_sub_f32_e32 v45, v42, v44
	v_sub_f32_e32 v41, v41, v45
	v_sub_f32_e32 v38, v38, v44
	v_add_f32_e32 v39, v42, v39
	v_add_f32_e32 v38, v38, v41
	v_add_f32_e32 v41, v43, v39
	v_sub_f32_e32 v42, v41, v43
	v_sub_f32_e32 v39, v39, v42
	v_add_f32_e32 v38, v38, v39
	v_add_f32_e32 v38, v41, v38
	v_cndmask_b32_e32 v38, v221, v38, vcc
	v_cmp_ngt_f32_e32 vcc, -1.0, v35
	s_nop 1
	v_cndmask_b32_e32 v38, v222, v38, vcc
	v_cmp_neq_f32_e32 vcc, -1.0, v35
	s_nop 1
	v_cndmask_b32_e32 v38, v219, v38, vcc
	v_cmp_lt_f32_e64 vcc, |v35|, s9
	s_nop 1
	v_cndmask_b32_e32 v35, v38, v35, vcc
	v_add_co_u32_e32 v38, vcc, s2, v36
	v_sub_f32_e32 v35, v40, v35
	s_nop 0
	v_addc_co_u32_e32 v39, vcc, 0, v37, vcc
	global_store_dword v[38:39], v35, off offset:640
	s_mov_b32 s2, 0x29000
	v_add_f32_e32 v35, v27, v245
	v_min_f32_e32 v40, 0, v35
	v_mul_f32_e64 v35, |v35|, s3
	v_exp_f32_e32 v35, v35
	s_nop 0
	v_add_f32_e32 v41, 1.0, v35
	v_add_f32_e32 v38, -1.0, v41
	v_sub_f32_e32 v39, v38, v41
	v_add_f32_e32 v39, 1.0, v39
	v_sub_f32_e32 v38, v35, v38
	v_add_f32_e32 v42, v38, v39
	v_frexp_mant_f32_e32 v38, v41
	v_cmp_gt_f32_e32 vcc, s6, v38
	v_cvt_f64_f32_e32 v[38:39], v41
	v_frexp_exp_i32_f64_e32 v38, v[38:39]
	v_subbrev_co_u32_e32 v38, vcc, 0, v38, vcc
	v_sub_u32_e32 v39, 0, v38
	v_ldexp_f32 v41, v41, v39
	v_ldexp_f32 v39, v42, v39
	v_add_f32_e32 v42, -1.0, v41
	v_add_f32_e32 v43, 1.0, v42
	v_sub_f32_e32 v43, v41, v43
	v_add_f32_e32 v43, v39, v43
	v_add_f32_e32 v44, v42, v43
	v_sub_f32_e32 v42, v44, v42
	v_sub_f32_e32 v42, v43, v42
	v_add_f32_e32 v43, 1.0, v41
	v_add_f32_e32 v45, -1.0, v43
	v_sub_f32_e32 v41, v41, v45
	v_add_f32_e32 v39, v39, v41
	v_add_f32_e32 v41, v43, v39
	v_sub_f32_e32 v43, v41, v43
	v_sub_f32_e32 v39, v39, v43
	v_rcp_f32_e32 v43, v41
	v_cvt_f32_i32_e32 v38, v38
	v_cmp_neq_f32_e32 vcc, s8, v35
	v_mul_f32_e32 v45, v44, v43
	v_mul_f32_e32 v46, v41, v45
	v_fma_f32 v47, v45, v41, -v46
	v_fmac_f32_e32 v47, v45, v39
	v_add_f32_e32 v48, v46, v47
	v_sub_f32_e32 v49, v44, v48
	v_sub_f32_e32 v44, v44, v49
	v_sub_f32_e32 v46, v48, v46
	v_sub_f32_e32 v44, v44, v48
	v_add_f32_e32 v42, v42, v44
	v_sub_f32_e32 v44, v46, v47
	v_add_f32_e32 v42, v44, v42
	v_add_f32_e32 v44, v49, v42
	v_mul_f32_e32 v46, v43, v44
	v_mul_f32_e32 v47, v41, v46
	v_fma_f32 v41, v46, v41, -v47
	v_fmac_f32_e32 v41, v46, v39
	v_sub_f32_e32 v39, v49, v44
	v_add_f32_e32 v39, v42, v39
	v_add_f32_e32 v42, v47, v41
	v_sub_f32_e32 v48, v44, v42
	v_sub_f32_e32 v44, v44, v48
	v_sub_f32_e32 v47, v42, v47
	v_sub_f32_e32 v42, v44, v42
	v_add_f32_e32 v39, v39, v42
	v_sub_f32_e32 v41, v47, v41
	v_add_f32_e32 v39, v41, v39
	v_add_f32_e32 v41, v45, v46
	v_add_f32_e32 v39, v48, v39
	v_sub_f32_e32 v42, v41, v45
	v_mul_f32_e32 v39, v43, v39
	v_sub_f32_e32 v42, v46, v42
	v_add_f32_e32 v39, v42, v39
	v_mul_f32_e32 v45, 0x3f317218, v38
	v_add_f32_e32 v42, v41, v39
	v_fma_f32 v46, v38, s7, -v45
	v_mul_f32_e32 v43, v42, v42
	v_fmac_f32_e32 v46, 0xb102e308, v38
	v_sub_f32_e32 v38, v42, v41
	v_fmamk_f32 v44, v43, 0x3e9b6dac, v214
	v_sub_f32_e32 v38, v39, v38
	v_add_f32_e32 v39, v45, v46
	v_fmaak_f32 v44, v43, v44, 0x3f2aaada
	v_sub_f32_e32 v41, v39, v45
	v_ldexp_f32 v45, v42, 1
	v_mul_f32_e32 v42, v42, v43
	v_mul_f32_e32 v42, v42, v44
	v_add_f32_e32 v43, v45, v42
	v_sub_f32_e32 v44, v43, v45
	v_ldexp_f32 v38, v38, 1
	v_sub_f32_e32 v42, v42, v44
	v_add_f32_e32 v38, v38, v42
	v_add_f32_e32 v42, v43, v38
	v_sub_f32_e32 v43, v42, v43
	v_sub_f32_e32 v38, v38, v43
	v_add_f32_e32 v43, v39, v42
	v_sub_f32_e32 v44, v43, v39
	v_sub_f32_e32 v45, v43, v44
	v_sub_f32_e32 v41, v46, v41
	v_sub_f32_e32 v39, v39, v45
	v_sub_f32_e32 v42, v42, v44
	v_add_f32_e32 v39, v42, v39
	v_add_f32_e32 v42, v41, v38
	v_sub_f32_e32 v44, v42, v41
	v_sub_f32_e32 v45, v42, v44
	v_sub_f32_e32 v41, v41, v45
	v_sub_f32_e32 v38, v38, v44
	v_add_f32_e32 v39, v42, v39
	v_add_f32_e32 v38, v38, v41
	v_add_f32_e32 v41, v43, v39
	v_sub_f32_e32 v42, v41, v43
	v_sub_f32_e32 v39, v39, v42
	v_add_f32_e32 v38, v38, v39
	v_add_f32_e32 v38, v41, v38
	v_cndmask_b32_e32 v38, v221, v38, vcc
	v_cmp_ngt_f32_e32 vcc, -1.0, v35
	s_nop 1
	v_cndmask_b32_e32 v38, v222, v38, vcc
	v_cmp_neq_f32_e32 vcc, -1.0, v35
	s_nop 1
	v_cndmask_b32_e32 v38, v219, v38, vcc
	v_cmp_lt_f32_e64 vcc, |v35|, s9
	s_nop 1
	v_cndmask_b32_e32 v35, v38, v35, vcc
	v_add_co_u32_e32 v38, vcc, s2, v36
	v_sub_f32_e32 v35, v40, v35
;     __device__ __forceinline__ void operator()(const AccT& acc, const pg8::Unit& u, int wr, int wc, int fr, int fq) const {
;     ...
;                     } else if (wc == 1 && fq == 0) {
; #pragma unroll
;                         for (int n = 0; n < 2; ++n)
; #pragma unroll
;                             for (int j = 0; j < 4; ++j) {
;                                 const float x = acc[ai][0][m][n][j] * rs + bfg[4 * n + j];
;                                 lf[(4 * n + j) * MROWS + row] = fminf(x, 0.f) - log1pf(__expf(-fabsf(x)));
;                             }
	s_nop 0
	v_addc_co_u32_e32 v39, vcc, 0, v37, vcc
	global_store_dword v[38:39], v35, off offset:1664
	s_mov_b32 s2, 0x31000
	v_add_f32_e32 v35, v28, v246
	v_min_f32_e32 v40, 0, v35
	v_mul_f32_e64 v35, |v35|, s3
	v_exp_f32_e32 v35, v35
	s_nop 0
	v_add_f32_e32 v41, 1.0, v35
	v_add_f32_e32 v38, -1.0, v41
	v_sub_f32_e32 v39, v38, v41
	v_add_f32_e32 v39, 1.0, v39
	v_sub_f32_e32 v38, v35, v38
	v_add_f32_e32 v42, v38, v39
	v_frexp_mant_f32_e32 v38, v41
	v_cmp_gt_f32_e32 vcc, s6, v38
	v_cvt_f64_f32_e32 v[38:39], v41
	v_frexp_exp_i32_f64_e32 v38, v[38:39]
	v_subbrev_co_u32_e32 v38, vcc, 0, v38, vcc
	v_sub_u32_e32 v39, 0, v38
	v_ldexp_f32 v41, v41, v39
	v_ldexp_f32 v39, v42, v39
	v_add_f32_e32 v42, -1.0, v41
	v_add_f32_e32 v43, 1.0, v42
	v_sub_f32_e32 v43, v41, v43
	v_add_f32_e32 v43, v39, v43
	v_add_f32_e32 v44, v42, v43
	v_sub_f32_e32 v42, v44, v42
	v_sub_f32_e32 v42, v43, v42
	v_add_f32_e32 v43, 1.0, v41
	v_add_f32_e32 v45, -1.0, v43
	v_sub_f32_e32 v41, v41, v45
	v_add_f32_e32 v39, v39, v41
	v_add_f32_e32 v41, v43, v39
	v_sub_f32_e32 v43, v41, v43
	v_sub_f32_e32 v39, v39, v43
	v_rcp_f32_e32 v43, v41
	v_cvt_f32_i32_e32 v38, v38
	v_cmp_neq_f32_e32 vcc, s8, v35
	v_mul_f32_e32 v45, v44, v43
	v_mul_f32_e32 v46, v41, v45
	v_fma_f32 v47, v45, v41, -v46
	v_fmac_f32_e32 v47, v45, v39
	v_add_f32_e32 v48, v46, v47
	v_sub_f32_e32 v49, v44, v48
	v_sub_f32_e32 v44, v44, v49
	v_sub_f32_e32 v46, v48, v46
	v_sub_f32_e32 v44, v44, v48
	v_add_f32_e32 v42, v42, v44
	v_sub_f32_e32 v44, v46, v47
	v_add_f32_e32 v42, v44, v42
	v_add_f32_e32 v44, v49, v42
	v_mul_f32_e32 v46, v43, v44
	v_mul_f32_e32 v47, v41, v46
	v_fma_f32 v41, v46, v41, -v47
	v_fmac_f32_e32 v41, v46, v39
	v_sub_f32_e32 v39, v49, v44
	v_add_f32_e32 v39, v42, v39
	v_add_f32_e32 v42, v47, v41
	v_sub_f32_e32 v48, v44, v42
	v_sub_f32_e32 v44, v44, v48
	v_sub_f32_e32 v47, v42, v47
	v_sub_f32_e32 v42, v44, v42
	v_add_f32_e32 v39, v39, v42
	v_sub_f32_e32 v41, v47, v41
	v_add_f32_e32 v39, v41, v39
	v_add_f32_e32 v41, v45, v46
	v_add_f32_e32 v39, v48, v39
	v_sub_f32_e32 v42, v41, v45
	v_mul_f32_e32 v39, v43, v39
	v_sub_f32_e32 v42, v46, v42
	v_add_f32_e32 v39, v42, v39
	v_mul_f32_e32 v45, 0x3f317218, v38
	v_add_f32_e32 v42, v41, v39
	v_fma_f32 v46, v38, s7, -v45
	v_mul_f32_e32 v43, v42, v42
	v_fmac_f32_e32 v46, 0xb102e308, v38
	v_sub_f32_e32 v38, v42, v41
	v_fmamk_f32 v44, v43, 0x3e9b6dac, v214
	v_sub_f32_e32 v38, v39, v38
	v_add_f32_e32 v39, v45, v46
	v_fmaak_f32 v44, v43, v44, 0x3f2aaada
	v_sub_f32_e32 v41, v39, v45
	v_ldexp_f32 v45, v42, 1
	v_mul_f32_e32 v42, v42, v43
	v_mul_f32_e32 v42, v42, v44
	v_add_f32_e32 v43, v45, v42
	v_sub_f32_e32 v44, v43, v45
	v_ldexp_f32 v38, v38, 1
	v_sub_f32_e32 v42, v42, v44
	v_add_f32_e32 v38, v38, v42
	v_add_f32_e32 v42, v43, v38
	v_sub_f32_e32 v43, v42, v43
	v_sub_f32_e32 v38, v38, v43
	v_add_f32_e32 v43, v39, v42
	v_sub_f32_e32 v44, v43, v39
	v_sub_f32_e32 v45, v43, v44
	v_sub_f32_e32 v41, v46, v41
	v_sub_f32_e32 v39, v39, v45
	v_sub_f32_e32 v42, v42, v44
	v_add_f32_e32 v39, v42, v39
	v_add_f32_e32 v42, v41, v38
	v_sub_f32_e32 v44, v42, v41
	v_sub_f32_e32 v45, v42, v44
	v_sub_f32_e32 v41, v41, v45
	v_sub_f32_e32 v38, v38, v44
	v_add_f32_e32 v39, v42, v39
	v_add_f32_e32 v38, v38, v41
	v_add_f32_e32 v41, v43, v39
	v_sub_f32_e32 v42, v41, v43
	v_sub_f32_e32 v39, v39, v42
	v_add_f32_e32 v38, v38, v39
	v_add_f32_e32 v38, v41, v38
	v_cndmask_b32_e32 v38, v221, v38, vcc
	v_cmp_ngt_f32_e32 vcc, -1.0, v35
	s_nop 1
	v_cndmask_b32_e32 v38, v222, v38, vcc
	v_cmp_neq_f32_e32 vcc, -1.0, v35
	s_nop 1
	v_cndmask_b32_e32 v38, v219, v38, vcc
	v_cmp_lt_f32_e64 vcc, |v35|, s9
	s_nop 1
	v_cndmask_b32_e32 v35, v38, v35, vcc
	v_add_co_u32_e32 v38, vcc, s2, v36
	v_sub_f32_e32 v35, v40, v35
	s_nop 0
	v_addc_co_u32_e32 v39, vcc, 0, v37, vcc
;     __device__ __forceinline__ void operator()(const AccT& acc, const pg8::Unit& u, int wr, int wc, int fr, int fq) const {
;     ...
;                     } else if (wc == 1 && fq == 0) {
; #pragma unroll
;                         for (int n = 0; n < 2; ++n)
; #pragma unroll
;                             for (int j = 0; j < 4; ++j) {
;                                 const float x = acc[ai][0][m][n][j] * rs + bfg[4 * n + j];
;                                 lf[(4 * n + j) * MROWS + row] = fminf(x, 0.f) - log1pf(__expf(-fabsf(x)));
;                             }
	global_store_dword v[38:39], v35, off offset:2688
	v_add_f32_e32 v35, v29, v247
	v_min_f32_e32 v40, 0, v35
	v_mul_f32_e64 v35, |v35|, s3
	v_exp_f32_e32 v35, v35
	s_nop 0
	v_add_f32_e32 v41, 1.0, v35
	v_add_f32_e32 v38, -1.0, v41
	v_sub_f32_e32 v39, v38, v41
	v_add_f32_e32 v39, 1.0, v39
	v_sub_f32_e32 v38, v35, v38
	v_add_f32_e32 v42, v38, v39
	v_frexp_mant_f32_e32 v38, v41
	v_cmp_gt_f32_e32 vcc, s6, v38
	v_cvt_f64_f32_e32 v[38:39], v41
	v_frexp_exp_i32_f64_e32 v38, v[38:39]
	v_subbrev_co_u32_e32 v38, vcc, 0, v38, vcc
	v_sub_u32_e32 v39, 0, v38
	v_ldexp_f32 v41, v41, v39
	v_ldexp_f32 v39, v42, v39
	v_add_f32_e32 v42, -1.0, v41
	v_add_f32_e32 v43, 1.0, v42
	v_sub_f32_e32 v43, v41, v43
	v_add_f32_e32 v43, v39, v43
	v_add_f32_e32 v44, v42, v43
	v_sub_f32_e32 v42, v44, v42
	v_sub_f32_e32 v42, v43, v42
	v_add_f32_e32 v43, 1.0, v41
	v_add_f32_e32 v45, -1.0, v43
	v_sub_f32_e32 v41, v41, v45
	v_add_f32_e32 v39, v39, v41
	v_add_f32_e32 v41, v43, v39
	v_sub_f32_e32 v43, v41, v43
	v_sub_f32_e32 v39, v39, v43
	v_rcp_f32_e32 v43, v41
	v_cvt_f32_i32_e32 v38, v38
	v_cmp_neq_f32_e32 vcc, s8, v35
	v_mul_f32_e32 v45, v44, v43
	v_mul_f32_e32 v46, v41, v45
	v_fma_f32 v47, v45, v41, -v46
	v_fmac_f32_e32 v47, v45, v39
	v_add_f32_e32 v48, v46, v47
	v_sub_f32_e32 v49, v44, v48
	v_sub_f32_e32 v44, v44, v49
	v_sub_f32_e32 v46, v48, v46
	v_sub_f32_e32 v44, v44, v48
	v_add_f32_e32 v42, v42, v44
	v_sub_f32_e32 v44, v46, v47
	v_add_f32_e32 v42, v44, v42
	v_add_f32_e32 v44, v49, v42
	v_mul_f32_e32 v46, v43, v44
	v_mul_f32_e32 v47, v41, v46
	v_fma_f32 v41, v46, v41, -v47
	v_fmac_f32_e32 v41, v46, v39
	v_sub_f32_e32 v39, v49, v44
	v_add_f32_e32 v39, v42, v39
	v_add_f32_e32 v42, v47, v41
	v_sub_f32_e32 v48, v44, v42
	v_sub_f32_e32 v44, v44, v48
	v_sub_f32_e32 v47, v42, v47
	v_sub_f32_e32 v42, v44, v42
	v_add_f32_e32 v39, v39, v42
	v_sub_f32_e32 v41, v47, v41
	v_add_f32_e32 v39, v41, v39
	v_add_f32_e32 v41, v45, v46
	v_add_f32_e32 v39, v48, v39
	v_sub_f32_e32 v42, v41, v45
	v_mul_f32_e32 v39, v43, v39
	v_sub_f32_e32 v42, v46, v42
	v_add_f32_e32 v39, v42, v39
	v_mul_f32_e32 v45, 0x3f317218, v38
	v_add_f32_e32 v42, v41, v39
	v_fma_f32 v46, v38, s7, -v45
	v_mul_f32_e32 v43, v42, v42
	v_fmac_f32_e32 v46, 0xb102e308, v38
	v_sub_f32_e32 v38, v42, v41
	v_fmamk_f32 v44, v43, 0x3e9b6dac, v214
	v_sub_f32_e32 v38, v39, v38
	v_add_f32_e32 v39, v45, v46
	v_fmaak_f32 v44, v43, v44, 0x3f2aaada
	v_sub_f32_e32 v41, v39, v45
	v_ldexp_f32 v45, v42, 1
	v_mul_f32_e32 v42, v42, v43
	v_mul_f32_e32 v42, v42, v44
	v_add_f32_e32 v43, v45, v42
	v_sub_f32_e32 v44, v43, v45
	v_ldexp_f32 v38, v38, 1
	v_sub_f32_e32 v42, v42, v44
	v_add_f32_e32 v38, v38, v42
	v_add_f32_e32 v42, v43, v38
	v_sub_f32_e32 v43, v42, v43
	v_sub_f32_e32 v38, v38, v43
	v_add_f32_e32 v43, v39, v42
	v_sub_f32_e32 v44, v43, v39
	v_sub_f32_e32 v45, v43, v44
	v_sub_f32_e32 v41, v46, v41
	v_sub_f32_e32 v39, v39, v45
	v_sub_f32_e32 v42, v42, v44
	v_add_f32_e32 v39, v42, v39
	v_add_f32_e32 v42, v41, v38
	v_sub_f32_e32 v44, v42, v41
	v_sub_f32_e32 v45, v42, v44
	v_sub_f32_e32 v41, v41, v45
	v_sub_f32_e32 v38, v38, v44
	v_add_f32_e32 v39, v42, v39
	v_add_f32_e32 v38, v38, v41
	v_add_f32_e32 v41, v43, v39
	v_sub_f32_e32 v42, v41, v43
	v_sub_f32_e32 v39, v39, v42
	v_add_f32_e32 v38, v38, v39
	v_add_f32_e32 v38, v41, v38
	v_cndmask_b32_e32 v38, v221, v38, vcc
	v_cmp_ngt_f32_e32 vcc, -1.0, v35
	s_nop 1
	v_cndmask_b32_e32 v38, v222, v38, vcc
	v_cmp_neq_f32_e32 vcc, -1.0, v35
	s_nop 1
	v_cndmask_b32_e32 v38, v219, v38, vcc
	v_cmp_lt_f32_e64 vcc, |v35|, s9
	s_nop 1
	v_cndmask_b32_e32 v35, v38, v35, vcc
	v_add_co_u32_e32 v36, vcc, 0x39000, v36
	v_sub_f32_e32 v35, v40, v35
	s_nop 0
	v_addc_co_u32_e32 v37, vcc, 0, v37, vcc
	global_store_dword v[36:37], v35, off offset:3712

;     __device__ __forceinline__ void operator()(const AccT& acc, const pg8::Unit& u, int wr, int wc, int fr, int fq) const {
;     ...
;                 const int row = row0 + ai * 128 + m * 16;
;                 const float rs = 1.0f;
;                 if (u.pn < 20) {
;                     float ss = 0.f;
; #pragma unroll
;                     for (int bj = 0; bj < 2; ++bj) {
;                         const f32x4 a = acc[ai][bj][m][0], b = acc[ai][bj][m][1];
;                         *(u32x4*)(Z + (size_t)row * ZLD + u.pn * 256 + bj * 128 + wc * 32 + 8 * fq) = pack8s(a, b, rs);
; #pragma unroll
;                         for (int j = 0; j < 4; ++j) ss += a[j] * a[j] + b[j] * b[j];
;                     }
;                     if (u.pn < 4) {
;                         ss *= rs * rs;
;                         ss += __shfl_xor(ss, 16); ss += __shfl_xor(ss, 32);
;                         if (fq == 0) ssqp[row * 16 + u.pn * 4 + wc] = ss;
;                     }
;                 } else {
;                     if (wc == 0) {
;                         const f32x4 c0 = *(const f32x4*)(cosT + row * 32 + 8 * fq), c1 = *(const f32x4*)(cosT + row * 32 + 8 * fq + 4);
;                         const f32x4 s0 = *(const f32x4*)(sinT + row * 32 + 8 * fq), s1 = *(const f32x4*)(sinT + row * 32 + 8 * fq + 4);
;                         const f32x4 x1a = acc[ai][0][m][0] * rs, x1b = acc[ai][0][m][1] * rs, x2a = acc[ai][1][m][0] * rs, x2b = acc[ai][1][m][1] * rs;
;                         const f32x4 y1a = x1a * c0 - x2a * s0, y1b = x1b * c1 - x2b * s1, y2a = x2a * c0 + x1a * s0, y2b = x2b * c1 + x1b * s1;
;                         *(u32x4*)(Kr + (size_t)row * 64 + 8 * fq) = pack8s(y1a, y1b, 1.0f);
;                         *(u32x4*)(Kr + (size_t)row * 64 + 32 + 8 * fq) = pack8s(y2a, y2b, 1.0f);
;                     } else if (wc == 1 && fq == 0) {
; #pragma unroll
;                         for (int n = 0; n < 2; ++n)
; #pragma unroll
;                             for (int j = 0; j < 4; ++j) {
;                                 const float x = acc[ai][0][m][n][j] * rs + bfg[4 * n + j];
;                                 lf[(4 * n + j) * MROWS + row] = fminf(x, 0.f) - log1pf(__expf(-fabsf(x)));
;                             }
.LBB0_1037:
	v_add_u32_e32 v18, 0xb0, v150
	s_and_b64 vcc, exec, s[44:45]
	s_mov_b64 s[8:9], -1
	s_cbranch_vccnz .LBB0_1045
	s_and_b64 vcc, exec, s[42:43]
	s_cbranch_vccnz .LBB0_1042
	s_and_saveexec_b64 s[42:43], s[58:59]
	s_cbranch_execz .LBB0_1041
	s_waitcnt lgkmcnt(0)
	s_mov_b32 s3, 0xbfb8aa3b
	s_mov_b32 s6, 0x3f2aaaab
	s_mov_b32 s7, 0x3f317218
	s_mov_b32 s8, 0x7f800000
	s_mov_b32 s9, 0x33800000
	v_ashrrev_i32_e32 v151, 31, v150
	s_mov_b32 s2, 0x8000
	v_add_f32_e32 v19, v14, v240
	v_min_f32_e32 v22, 0, v19
	v_mul_f32_e64 v19, |v19|, s3
	v_exp_f32_e32 v19, v19
	s_nop 0
	v_add_f32_e32 v23, 1.0, v19
	v_add_f32_e32 v20, -1.0, v23
	v_sub_f32_e32 v21, v20, v23
	v_add_f32_e32 v21, 1.0, v21
	v_sub_f32_e32 v20, v19, v20
	v_add_f32_e32 v24, v20, v21
	v_frexp_mant_f32_e32 v20, v23
	v_cmp_gt_f32_e32 vcc, s6, v20
	v_cvt_f64_f32_e32 v[20:21], v23
	v_frexp_exp_i32_f64_e32 v20, v[20:21]
	v_subbrev_co_u32_e32 v20, vcc, 0, v20, vcc
	v_sub_u32_e32 v21, 0, v20
	v_ldexp_f32 v23, v23, v21
	v_ldexp_f32 v21, v24, v21
	v_add_f32_e32 v24, -1.0, v23
	v_add_f32_e32 v25, 1.0, v24
	v_sub_f32_e32 v25, v23, v25
	v_add_f32_e32 v25, v21, v25
	v_add_f32_e32 v26, v24, v25
	v_sub_f32_e32 v24, v26, v24
	v_sub_f32_e32 v24, v25, v24
	v_add_f32_e32 v25, 1.0, v23
	v_add_f32_e32 v27, -1.0, v25
	v_sub_f32_e32 v23, v23, v27
	v_add_f32_e32 v21, v21, v23
	v_add_f32_e32 v23, v25, v21
	v_sub_f32_e32 v25, v23, v25
	v_sub_f32_e32 v21, v21, v25
	v_rcp_f32_e32 v25, v23
	v_cvt_f32_i32_e32 v20, v20
	v_cmp_neq_f32_e32 vcc, s8, v19
	v_mul_f32_e32 v27, v26, v25
	v_mul_f32_e32 v28, v23, v27
	v_fma_f32 v29, v27, v23, -v28
	v_fmac_f32_e32 v29, v27, v21
	v_add_f32_e32 v30, v28, v29
	v_sub_f32_e32 v31, v26, v30
	v_sub_f32_e32 v26, v26, v31
	v_sub_f32_e32 v28, v30, v28
	v_sub_f32_e32 v26, v26, v30
	v_add_f32_e32 v24, v24, v26
	v_sub_f32_e32 v26, v28, v29
	v_add_f32_e32 v24, v26, v24
	v_add_f32_e32 v26, v31, v24
	v_mul_f32_e32 v28, v25, v26
	v_mul_f32_e32 v29, v23, v28
	v_fma_f32 v23, v28, v23, -v29
	v_fmac_f32_e32 v23, v28, v21
	v_sub_f32_e32 v21, v31, v26
	v_add_f32_e32 v21, v24, v21
	v_add_f32_e32 v24, v29, v23
	v_sub_f32_e32 v30, v26, v24
	v_sub_f32_e32 v26, v26, v30
	v_sub_f32_e32 v29, v24, v29
	v_sub_f32_e32 v24, v26, v24
	v_add_f32_e32 v21, v21, v24
	v_sub_f32_e32 v23, v29, v23
	v_add_f32_e32 v21, v23, v21
	v_add_f32_e32 v23, v27, v28
	v_add_f32_e32 v21, v30, v21
	v_sub_f32_e32 v24, v23, v27
	v_mul_f32_e32 v21, v25, v21
	v_sub_f32_e32 v24, v28, v24
	v_add_f32_e32 v21, v24, v21
	v_mul_f32_e32 v27, 0x3f317218, v20
	v_add_f32_e32 v24, v23, v21
	v_fma_f32 v28, v20, s7, -v27
	v_mul_f32_e32 v25, v24, v24
	v_fmac_f32_e32 v28, 0xb102e308, v20
	v_sub_f32_e32 v20, v24, v23
	v_fmamk_f32 v26, v25, 0x3e9b6dac, v214
	v_sub_f32_e32 v20, v21, v20
	v_add_f32_e32 v21, v27, v28
	v_fmaak_f32 v26, v25, v26, 0x3f2aaada
	v_sub_f32_e32 v23, v21, v27
	v_ldexp_f32 v27, v24, 1
	v_mul_f32_e32 v24, v24, v25
	v_mul_f32_e32 v24, v24, v26
	v_add_f32_e32 v25, v27, v24
	v_sub_f32_e32 v26, v25, v27
	v_ldexp_f32 v20, v20, 1
	v_sub_f32_e32 v24, v24, v26
	v_add_f32_e32 v20, v20, v24
	v_add_f32_e32 v24, v25, v20
	v_sub_f32_e32 v25, v24, v25
	v_sub_f32_e32 v20, v20, v25
	v_add_f32_e32 v25, v21, v24
	v_sub_f32_e32 v26, v25, v21
	v_sub_f32_e32 v27, v25, v26
	v_sub_f32_e32 v23, v28, v23
	v_sub_f32_e32 v21, v21, v27
	v_sub_f32_e32 v24, v24, v26
	v_add_f32_e32 v21, v24, v21
	v_add_f32_e32 v24, v23, v20
	v_sub_f32_e32 v26, v24, v23
	v_sub_f32_e32 v27, v24, v26
	v_sub_f32_e32 v23, v23, v27
	v_sub_f32_e32 v20, v20, v26
	v_add_f32_e32 v21, v24, v21
	v_add_f32_e32 v20, v20, v23
	v_add_f32_e32 v23, v25, v21
	v_sub_f32_e32 v24, v23, v25
	v_sub_f32_e32 v21, v21, v24
	v_add_f32_e32 v20, v20, v21
	v_add_f32_e32 v20, v23, v20
	v_cndmask_b32_e32 v20, v221, v20, vcc
	v_cmp_ngt_f32_e32 vcc, -1.0, v19
	s_nop 1
	v_cndmask_b32_e32 v20, v222, v20, vcc
	v_cmp_neq_f32_e32 vcc, -1.0, v19
	s_nop 1
	v_cndmask_b32_e32 v20, v219, v20, vcc
	v_cmp_lt_f32_e64 vcc, |v19|, s9
	s_nop 1
	v_cndmask_b32_e32 v19, v20, v19, vcc
	v_sub_f32_e32 v22, v22, v19
	v_ashrrev_i32_e32 v19, 31, v18
	v_lshl_add_u64 v[20:21], v[18:19], 2, s[52:53]
	global_store_dword v[20:21], v22, off
	v_add_f32_e32 v19, v15, v241
	v_min_f32_e32 v22, 0, v19
	v_mul_f32_e64 v19, |v19|, s3
	v_exp_f32_e32 v19, v19
	s_nop 0
	v_add_f32_e32 v23, 1.0, v19
	v_add_f32_e32 v20, -1.0, v23
	v_sub_f32_e32 v21, v20, v23
	v_add_f32_e32 v21, 1.0, v21
	v_sub_f32_e32 v20, v19, v20
	v_add_f32_e32 v24, v20, v21
	v_frexp_mant_f32_e32 v20, v23
	v_cmp_gt_f32_e32 vcc, s6, v20
	v_cvt_f64_f32_e32 v[20:21], v23
	v_frexp_exp_i32_f64_e32 v20, v[20:21]
	v_subbrev_co_u32_e32 v20, vcc, 0, v20, vcc
	v_sub_u32_e32 v21, 0, v20
	v_ldexp_f32 v23, v23, v21
	v_ldexp_f32 v21, v24, v21
	v_add_f32_e32 v24, -1.0, v23
	v_add_f32_e32 v25, 1.0, v24
	v_sub_f32_e32 v25, v23, v25
	v_add_f32_e32 v25, v21, v25
	v_add_f32_e32 v26, v24, v25
	v_sub_f32_e32 v24, v26, v24
	v_sub_f32_e32 v24, v25, v24
	v_add_f32_e32 v25, 1.0, v23
	v_add_f32_e32 v27, -1.0, v25
	v_sub_f32_e32 v23, v23, v27
	v_add_f32_e32 v21, v21, v23
	v_add_f32_e32 v23, v25, v21
	v_sub_f32_e32 v25, v23, v25
	v_sub_f32_e32 v21, v21, v25
	v_rcp_f32_e32 v25, v23
	v_cvt_f32_i32_e32 v20, v20
	v_cmp_neq_f32_e32 vcc, s8, v19
	v_mul_f32_e32 v27, v26, v25
	v_mul_f32_e32 v28, v23, v27
	v_fma_f32 v29, v27, v23, -v28
	v_fmac_f32_e32 v29, v27, v21
	v_add_f32_e32 v30, v28, v29
	v_sub_f32_e32 v31, v26, v30
	v_sub_f32_e32 v26, v26, v31
	v_sub_f32_e32 v28, v30, v28
	v_sub_f32_e32 v26, v26, v30
	v_add_f32_e32 v24, v24, v26
	v_sub_f32_e32 v26, v28, v29
	v_add_f32_e32 v24, v26, v24
	v_add_f32_e32 v26, v31, v24
	v_mul_f32_e32 v28, v25, v26
	v_mul_f32_e32 v29, v23, v28
	v_fma_f32 v23, v28, v23, -v29
;     __device__ __forceinline__ void operator()(const AccT& acc, const pg8::Unit& u, int wr, int wc, int fr, int fq) const {
;     ...
;                     } else if (wc == 1 && fq == 0) {
; #pragma unroll
;                         for (int n = 0; n < 2; ++n)
; #pragma unroll
;                             for (int j = 0; j < 4; ++j) {
;                                 const float x = acc[ai][0][m][n][j] * rs + bfg[4 * n + j];
;                                 lf[(4 * n + j) * MROWS + row] = fminf(x, 0.f) - log1pf(__expf(-fabsf(x)));
;                             }
	v_fmac_f32_e32 v23, v28, v21
	v_sub_f32_e32 v21, v31, v26
	v_add_f32_e32 v21, v24, v21
	v_add_f32_e32 v24, v29, v23
	v_sub_f32_e32 v30, v26, v24
	v_sub_f32_e32 v26, v26, v30
	v_sub_f32_e32 v29, v24, v29
	v_sub_f32_e32 v24, v26, v24
	v_add_f32_e32 v21, v21, v24
	v_sub_f32_e32 v23, v29, v23
	v_add_f32_e32 v21, v23, v21
	v_add_f32_e32 v23, v27, v28
	v_add_f32_e32 v21, v30, v21
	v_sub_f32_e32 v24, v23, v27
	v_mul_f32_e32 v21, v25, v21
	v_sub_f32_e32 v24, v28, v24
	v_add_f32_e32 v21, v24, v21
	v_mul_f32_e32 v27, 0x3f317218, v20
	v_add_f32_e32 v24, v23, v21
	v_fma_f32 v28, v20, s7, -v27
	v_mul_f32_e32 v25, v24, v24
	v_fmac_f32_e32 v28, 0xb102e308, v20
	v_sub_f32_e32 v20, v24, v23
	v_fmamk_f32 v26, v25, 0x3e9b6dac, v214
	v_sub_f32_e32 v20, v21, v20
	v_add_f32_e32 v21, v27, v28
	v_fmaak_f32 v26, v25, v26, 0x3f2aaada
	v_sub_f32_e32 v23, v21, v27
	v_ldexp_f32 v27, v24, 1
	v_mul_f32_e32 v24, v24, v25
	v_mul_f32_e32 v24, v24, v26
	v_add_f32_e32 v25, v27, v24
	v_sub_f32_e32 v26, v25, v27
	v_ldexp_f32 v20, v20, 1
	v_sub_f32_e32 v24, v24, v26
	v_add_f32_e32 v20, v20, v24
	v_add_f32_e32 v24, v25, v20
	v_sub_f32_e32 v25, v24, v25
	v_sub_f32_e32 v20, v20, v25
	v_add_f32_e32 v25, v21, v24
	v_sub_f32_e32 v26, v25, v21
	v_sub_f32_e32 v27, v25, v26
	v_sub_f32_e32 v23, v28, v23
	v_sub_f32_e32 v21, v21, v27
	v_sub_f32_e32 v24, v24, v26
	v_add_f32_e32 v21, v24, v21
	v_add_f32_e32 v24, v23, v20
	v_sub_f32_e32 v26, v24, v23
	v_sub_f32_e32 v27, v24, v26
	v_sub_f32_e32 v23, v23, v27
	v_sub_f32_e32 v20, v20, v26
	v_add_f32_e32 v21, v24, v21
	v_add_f32_e32 v20, v20, v23
	v_add_f32_e32 v23, v25, v21
	v_sub_f32_e32 v24, v23, v25
	v_sub_f32_e32 v21, v21, v24
	v_add_f32_e32 v20, v20, v21
	v_add_f32_e32 v20, v23, v20
	v_cndmask_b32_e32 v20, v221, v20, vcc
	v_cmp_ngt_f32_e32 vcc, -1.0, v19
	s_nop 1
	v_cndmask_b32_e32 v20, v222, v20, vcc
	v_cmp_neq_f32_e32 vcc, -1.0, v19
	s_nop 1
	v_cndmask_b32_e32 v20, v219, v20, vcc
	v_cmp_lt_f32_e64 vcc, |v19|, s9
	s_nop 1
	v_cndmask_b32_e32 v19, v20, v19, vcc
	v_lshl_add_u64 v[20:21], v[150:151], 2, s[52:53]
	v_sub_f32_e32 v19, v22, v19
	v_add_co_u32_e32 v22, vcc, s2, v20
	s_mov_b32 s2, 0x10000
	s_nop 0
	v_addc_co_u32_e32 v23, vcc, 0, v21, vcc
	global_store_dword v[22:23], v19, off offset:1728
	v_add_f32_e32 v19, v16, v242
	v_min_f32_e32 v24, 0, v19
	v_mul_f32_e64 v19, |v19|, s3
	v_exp_f32_e32 v19, v19
	s_nop 0
	v_add_f32_e32 v25, 1.0, v19
	v_add_f32_e32 v22, -1.0, v25
	v_sub_f32_e32 v23, v22, v25
	v_add_f32_e32 v23, 1.0, v23
	v_sub_f32_e32 v22, v19, v22
	v_add_f32_e32 v26, v22, v23
	v_frexp_mant_f32_e32 v22, v25
	v_cmp_gt_f32_e32 vcc, s6, v22
	v_cvt_f64_f32_e32 v[22:23], v25
	v_frexp_exp_i32_f64_e32 v22, v[22:23]
	v_subbrev_co_u32_e32 v22, vcc, 0, v22, vcc
	v_sub_u32_e32 v23, 0, v22
	v_ldexp_f32 v25, v25, v23
	v_ldexp_f32 v23, v26, v23
	v_add_f32_e32 v26, -1.0, v25
	v_add_f32_e32 v27, 1.0, v26
	v_sub_f32_e32 v27, v25, v27
	v_add_f32_e32 v27, v23, v27
	v_add_f32_e32 v28, v26, v27
	v_sub_f32_e32 v26, v28, v26
	v_sub_f32_e32 v26, v27, v26
	v_add_f32_e32 v27, 1.0, v25
	v_add_f32_e32 v29, -1.0, v27
	v_sub_f32_e32 v25, v25, v29
	v_add_f32_e32 v23, v23, v25
	v_add_f32_e32 v25, v27, v23
	v_sub_f32_e32 v27, v25, v27
	v_sub_f32_e32 v23, v23, v27
	v_rcp_f32_e32 v27, v25
	v_cvt_f32_i32_e32 v22, v22
	v_cmp_neq_f32_e32 vcc, s8, v19
	v_mul_f32_e32 v29, v28, v27
	v_mul_f32_e32 v30, v25, v29
	v_fma_f32 v31, v29, v25, -v30
	v_fmac_f32_e32 v31, v29, v23
	v_add_f32_e32 v32, v30, v31
	v_sub_f32_e32 v33, v28, v32
	v_sub_f32_e32 v28, v28, v33
	v_sub_f32_e32 v30, v32, v30
	v_sub_f32_e32 v28, v28, v32
	v_add_f32_e32 v26, v26, v28
	v_sub_f32_e32 v28, v30, v31
	v_add_f32_e32 v26, v28, v26
	v_add_f32_e32 v28, v33, v26
	v_mul_f32_e32 v30, v27, v28
	v_mul_f32_e32 v31, v25, v30
	v_fma_f32 v25, v30, v25, -v31
	v_fmac_f32_e32 v25, v30, v23
	v_sub_f32_e32 v23, v33, v28
	v_add_f32_e32 v23, v26, v23
	v_add_f32_e32 v26, v31, v25
	v_sub_f32_e32 v32, v28, v26
	v_sub_f32_e32 v28, v28, v32
	v_sub_f32_e32 v31, v26, v31
	v_sub_f32_e32 v26, v28, v26
	v_add_f32_e32 v23, v23, v26
	v_sub_f32_e32 v25, v31, v25
	v_add_f32_e32 v23, v25, v23
	v_add_f32_e32 v25, v29, v30
	v_add_f32_e32 v23, v32, v23
	v_sub_f32_e32 v26, v25, v29
	v_mul_f32_e32 v23, v27, v23
	v_sub_f32_e32 v26, v30, v26
	v_add_f32_e32 v23, v26, v23
	v_mul_f32_e32 v29, 0x3f317218, v22
	v_add_f32_e32 v26, v25, v23
	v_fma_f32 v30, v22, s7, -v29
	v_mul_f32_e32 v27, v26, v26
	v_fmac_f32_e32 v30, 0xb102e308, v22
	v_sub_f32_e32 v22, v26, v25
	v_fmamk_f32 v28, v27, 0x3e9b6dac, v214
	v_sub_f32_e32 v22, v23, v22
	v_add_f32_e32 v23, v29, v30
	v_fmaak_f32 v28, v27, v28, 0x3f2aaada
	v_sub_f32_e32 v25, v23, v29
	v_ldexp_f32 v29, v26, 1
	v_mul_f32_e32 v26, v26, v27
	v_mul_f32_e32 v26, v26, v28
	v_add_f32_e32 v27, v29, v26
	v_sub_f32_e32 v28, v27, v29
	v_ldexp_f32 v22, v22, 1
	v_sub_f32_e32 v26, v26, v28
	v_add_f32_e32 v22, v22, v26
	v_add_f32_e32 v26, v27, v22
	v_sub_f32_e32 v27, v26, v27
	v_sub_f32_e32 v22, v22, v27
	v_add_f32_e32 v27, v23, v26
	v_sub_f32_e32 v28, v27, v23
	v_sub_f32_e32 v29, v27, v28
	v_sub_f32_e32 v25, v30, v25
	v_sub_f32_e32 v23, v23, v29
	v_sub_f32_e32 v26, v26, v28
	v_add_f32_e32 v23, v26, v23
	v_add_f32_e32 v26, v25, v22
	v_sub_f32_e32 v28, v26, v25
	v_sub_f32_e32 v29, v26, v28
	v_sub_f32_e32 v25, v25, v29
	v_sub_f32_e32 v22, v22, v28
	v_add_f32_e32 v23, v26, v23
	v_add_f32_e32 v22, v22, v25
	v_add_f32_e32 v25, v27, v23
	v_sub_f32_e32 v26, v25, v27
	v_sub_f32_e32 v23, v23, v26
	v_add_f32_e32 v22, v22, v23
	v_add_f32_e32 v22, v25, v22
	v_cndmask_b32_e32 v22, v221, v22, vcc
	v_cmp_ngt_f32_e32 vcc, -1.0, v19
	s_nop 1
	v_cndmask_b32_e32 v22, v222, v22, vcc
	v_cmp_neq_f32_e32 vcc, -1.0, v19
	s_nop 1
;     __device__ __forceinline__ void operator()(const AccT& acc, const pg8::Unit& u, int wr, int wc, int fr, int fq) const {
;     ...
;                     } else if (wc == 1 && fq == 0) {
; #pragma unroll
;                         for (int n = 0; n < 2; ++n)
; #pragma unroll
;                             for (int j = 0; j < 4; ++j) {
;                                 const float x = acc[ai][0][m][n][j] * rs + bfg[4 * n + j];
;                                 lf[(4 * n + j) * MROWS + row] = fminf(x, 0.f) - log1pf(__expf(-fabsf(x)));
;                             }
	v_cndmask_b32_e32 v22, v219, v22, vcc
	v_cmp_lt_f32_e64 vcc, |v19|, s9
	s_nop 1
	v_cndmask_b32_e32 v19, v22, v19, vcc
	v_add_co_u32_e32 v22, vcc, s2, v20
	v_sub_f32_e32 v19, v24, v19
	s_nop 0
	v_addc_co_u32_e32 v23, vcc, 0, v21, vcc
	global_store_dword v[22:23], v19, off offset:2752
	s_mov_b32 s2, 0x18000
	v_add_f32_e32 v19, v17, v243
	v_min_f32_e32 v24, 0, v19
	v_mul_f32_e64 v19, |v19|, s3
	v_exp_f32_e32 v19, v19
	s_nop 0
	v_add_f32_e32 v25, 1.0, v19
	v_add_f32_e32 v22, -1.0, v25
	v_sub_f32_e32 v23, v22, v25
	v_add_f32_e32 v23, 1.0, v23
	v_sub_f32_e32 v22, v19, v22
	v_add_f32_e32 v26, v22, v23
	v_frexp_mant_f32_e32 v22, v25
	v_cmp_gt_f32_e32 vcc, s6, v22
	v_cvt_f64_f32_e32 v[22:23], v25
	v_frexp_exp_i32_f64_e32 v22, v[22:23]
	v_subbrev_co_u32_e32 v22, vcc, 0, v22, vcc
	v_sub_u32_e32 v23, 0, v22
	v_ldexp_f32 v25, v25, v23
	v_ldexp_f32 v23, v26, v23
	v_add_f32_e32 v26, -1.0, v25
	v_add_f32_e32 v27, 1.0, v26
	v_sub_f32_e32 v27, v25, v27
	v_add_f32_e32 v27, v23, v27
	v_add_f32_e32 v28, v26, v27
	v_sub_f32_e32 v26, v28, v26
	v_sub_f32_e32 v26, v27, v26
	v_add_f32_e32 v27, 1.0, v25
	v_add_f32_e32 v29, -1.0, v27
	v_sub_f32_e32 v25, v25, v29
	v_add_f32_e32 v23, v23, v25
	v_add_f32_e32 v25, v27, v23
	v_sub_f32_e32 v27, v25, v27
	v_sub_f32_e32 v23, v23, v27
	v_rcp_f32_e32 v27, v25
	v_cvt_f32_i32_e32 v22, v22
	v_cmp_neq_f32_e32 vcc, s8, v19
	v_mul_f32_e32 v29, v28, v27
	v_mul_f32_e32 v30, v25, v29
	v_fma_f32 v31, v29, v25, -v30
	v_fmac_f32_e32 v31, v29, v23
	v_add_f32_e32 v32, v30, v31
	v_sub_f32_e32 v33, v28, v32
	v_sub_f32_e32 v28, v28, v33
	v_sub_f32_e32 v30, v32, v30
	v_sub_f32_e32 v28, v28, v32
	v_add_f32_e32 v26, v26, v28
	v_sub_f32_e32 v28, v30, v31
	v_add_f32_e32 v26, v28, v26
	v_add_f32_e32 v28, v33, v26
	v_mul_f32_e32 v30, v27, v28
	v_mul_f32_e32 v31, v25, v30
	v_fma_f32 v25, v30, v25, -v31
	v_fmac_f32_e32 v25, v30, v23
	v_sub_f32_e32 v23, v33, v28
	v_add_f32_e32 v23, v26, v23
	v_add_f32_e32 v26, v31, v25
	v_sub_f32_e32 v32, v28, v26
	v_sub_f32_e32 v28, v28, v32
	v_sub_f32_e32 v31, v26, v31
	v_sub_f32_e32 v26, v28, v26
	v_add_f32_e32 v23, v23, v26
	v_sub_f32_e32 v25, v31, v25
	v_add_f32_e32 v23, v25, v23
	v_add_f32_e32 v25, v29, v30
	v_add_f32_e32 v23, v32, v23
	v_sub_f32_e32 v26, v25, v29
	v_mul_f32_e32 v23, v27, v23
	v_sub_f32_e32 v26, v30, v26
	v_add_f32_e32 v23, v26, v23
	v_mul_f32_e32 v29, 0x3f317218, v22
	v_add_f32_e32 v26, v25, v23
	v_fma_f32 v30, v22, s7, -v29
	v_mul_f32_e32 v27, v26, v26
	v_fmac_f32_e32 v30, 0xb102e308, v22
	v_sub_f32_e32 v22, v26, v25
	v_fmamk_f32 v28, v27, 0x3e9b6dac, v214
	v_sub_f32_e32 v22, v23, v22
	v_add_f32_e32 v23, v29, v30
	v_fmaak_f32 v28, v27, v28, 0x3f2aaada
	v_sub_f32_e32 v25, v23, v29
	v_ldexp_f32 v29, v26, 1
	v_mul_f32_e32 v26, v26, v27
	v_mul_f32_e32 v26, v26, v28
	v_add_f32_e32 v27, v29, v26
	v_sub_f32_e32 v28, v27, v29
	v_ldexp_f32 v22, v22, 1
	v_sub_f32_e32 v26, v26, v28
	v_add_f32_e32 v22, v22, v26
	v_add_f32_e32 v26, v27, v22
	v_sub_f32_e32 v27, v26, v27
	v_sub_f32_e32 v22, v22, v27
	v_add_f32_e32 v27, v23, v26
	v_sub_f32_e32 v28, v27, v23
	v_sub_f32_e32 v29, v27, v28
	v_sub_f32_e32 v25, v30, v25
	v_sub_f32_e32 v23, v23, v29
	v_sub_f32_e32 v26, v26, v28
	v_add_f32_e32 v23, v26, v23
	v_add_f32_e32 v26, v25, v22
	v_sub_f32_e32 v28, v26, v25
	v_sub_f32_e32 v29, v26, v28
	v_sub_f32_e32 v25, v25, v29
	v_sub_f32_e32 v22, v22, v28
	v_add_f32_e32 v23, v26, v23
	v_add_f32_e32 v22, v22, v25
	v_add_f32_e32 v25, v27, v23
	v_sub_f32_e32 v26, v25, v27
	v_sub_f32_e32 v23, v23, v26
	v_add_f32_e32 v22, v22, v23
	v_add_f32_e32 v22, v25, v22
	v_cndmask_b32_e32 v22, v221, v22, vcc
	v_cmp_ngt_f32_e32 vcc, -1.0, v19
	s_nop 1
	v_cndmask_b32_e32 v22, v222, v22, vcc
	v_cmp_neq_f32_e32 vcc, -1.0, v19
	s_nop 1
	v_cndmask_b32_e32 v22, v219, v22, vcc
	v_cmp_lt_f32_e64 vcc, |v19|, s9
	s_nop 1
	v_cndmask_b32_e32 v19, v22, v19, vcc
	v_add_co_u32_e32 v22, vcc, s2, v20
	v_sub_f32_e32 v19, v24, v19
	s_nop 0
	v_addc_co_u32_e32 v23, vcc, 0, v21, vcc
	global_store_dword v[22:23], v19, off offset:3776
	s_mov_b32 s2, 0x21000
	v_add_f32_e32 v19, v10, v244
	v_min_f32_e32 v24, 0, v19
	v_mul_f32_e64 v19, |v19|, s3
	v_exp_f32_e32 v19, v19
	s_nop 0
	v_add_f32_e32 v25, 1.0, v19
	v_add_f32_e32 v22, -1.0, v25
	v_sub_f32_e32 v23, v22, v25
	v_add_f32_e32 v23, 1.0, v23
	v_sub_f32_e32 v22, v19, v22
	v_add_f32_e32 v26, v22, v23
	v_frexp_mant_f32_e32 v22, v25
	v_cmp_gt_f32_e32 vcc, s6, v22
	v_cvt_f64_f32_e32 v[22:23], v25
	v_frexp_exp_i32_f64_e32 v22, v[22:23]
	v_subbrev_co_u32_e32 v22, vcc, 0, v22, vcc
	v_sub_u32_e32 v23, 0, v22
	v_ldexp_f32 v25, v25, v23
	v_ldexp_f32 v23, v26, v23
	v_add_f32_e32 v26, -1.0, v25
	v_add_f32_e32 v27, 1.0, v26
	v_sub_f32_e32 v27, v25, v27
	v_add_f32_e32 v27, v23, v27
	v_add_f32_e32 v28, v26, v27
	v_sub_f32_e32 v26, v28, v26
	v_sub_f32_e32 v26, v27, v26
	v_add_f32_e32 v27, 1.0, v25
	v_add_f32_e32 v29, -1.0, v27
	v_sub_f32_e32 v25, v25, v29
	v_add_f32_e32 v23, v23, v25
	v_add_f32_e32 v25, v27, v23
	v_sub_f32_e32 v27, v25, v27
	v_sub_f32_e32 v23, v23, v27
	v_rcp_f32_e32 v27, v25
	v_cvt_f32_i32_e32 v22, v22
	v_cmp_neq_f32_e32 vcc, s8, v19
	v_mul_f32_e32 v29, v28, v27
	v_mul_f32_e32 v30, v25, v29
	v_fma_f32 v31, v29, v25, -v30
	v_fmac_f32_e32 v31, v29, v23
	v_add_f32_e32 v32, v30, v31
	v_sub_f32_e32 v33, v28, v32
	v_sub_f32_e32 v28, v28, v33
	v_sub_f32_e32 v30, v32, v30
	v_sub_f32_e32 v28, v28, v32
	v_add_f32_e32 v26, v26, v28
	v_sub_f32_e32 v28, v30, v31
	v_add_f32_e32 v26, v28, v26
	v_add_f32_e32 v28, v33, v26
	v_mul_f32_e32 v30, v27, v28
	v_mul_f32_e32 v31, v25, v30
	v_fma_f32 v25, v30, v25, -v31
	v_fmac_f32_e32 v25, v30, v23
	v_sub_f32_e32 v23, v33, v28
	v_add_f32_e32 v23, v26, v23
	v_add_f32_e32 v26, v31, v25
;     __device__ __forceinline__ void operator()(const AccT& acc, const pg8::Unit& u, int wr, int wc, int fr, int fq) const {
;     ...
;                     } else if (wc == 1 && fq == 0) {
; #pragma unroll
;                         for (int n = 0; n < 2; ++n)
; #pragma unroll
;                             for (int j = 0; j < 4; ++j) {
;                                 const float x = acc[ai][0][m][n][j] * rs + bfg[4 * n + j];
;                                 lf[(4 * n + j) * MROWS + row] = fminf(x, 0.f) - log1pf(__expf(-fabsf(x)));
;                             }
	v_sub_f32_e32 v32, v28, v26
	v_sub_f32_e32 v28, v28, v32
	v_sub_f32_e32 v31, v26, v31
	v_sub_f32_e32 v26, v28, v26
	v_add_f32_e32 v23, v23, v26
	v_sub_f32_e32 v25, v31, v25
	v_add_f32_e32 v23, v25, v23
	v_add_f32_e32 v25, v29, v30
	v_add_f32_e32 v23, v32, v23
	v_sub_f32_e32 v26, v25, v29
	v_mul_f32_e32 v23, v27, v23
	v_sub_f32_e32 v26, v30, v26
	v_add_f32_e32 v23, v26, v23
	v_mul_f32_e32 v29, 0x3f317218, v22
	v_add_f32_e32 v26, v25, v23
	v_fma_f32 v30, v22, s7, -v29
	v_mul_f32_e32 v27, v26, v26
	v_fmac_f32_e32 v30, 0xb102e308, v22
	v_sub_f32_e32 v22, v26, v25
	v_fmamk_f32 v28, v27, 0x3e9b6dac, v214
	v_sub_f32_e32 v22, v23, v22
	v_add_f32_e32 v23, v29, v30
	v_fmaak_f32 v28, v27, v28, 0x3f2aaada
	v_sub_f32_e32 v25, v23, v29
	v_ldexp_f32 v29, v26, 1
	v_mul_f32_e32 v26, v26, v27
	v_mul_f32_e32 v26, v26, v28
	v_add_f32_e32 v27, v29, v26
	v_sub_f32_e32 v28, v27, v29
	v_ldexp_f32 v22, v22, 1
	v_sub_f32_e32 v26, v26, v28
	v_add_f32_e32 v22, v22, v26
	v_add_f32_e32 v26, v27, v22
	v_sub_f32_e32 v27, v26, v27
	v_sub_f32_e32 v22, v22, v27
	v_add_f32_e32 v27, v23, v26
	v_sub_f32_e32 v28, v27, v23
	v_sub_f32_e32 v29, v27, v28
	v_sub_f32_e32 v25, v30, v25
	v_sub_f32_e32 v23, v23, v29
	v_sub_f32_e32 v26, v26, v28
	v_add_f32_e32 v23, v26, v23
	v_add_f32_e32 v26, v25, v22
	v_sub_f32_e32 v28, v26, v25
	v_sub_f32_e32 v29, v26, v28
	v_sub_f32_e32 v25, v25, v29
	v_sub_f32_e32 v22, v22, v28
	v_add_f32_e32 v23, v26, v23
	v_add_f32_e32 v22, v22, v25
	v_add_f32_e32 v25, v27, v23
	v_sub_f32_e32 v26, v25, v27
	v_sub_f32_e32 v23, v23, v26
	v_add_f32_e32 v22, v22, v23
	v_add_f32_e32 v22, v25, v22
	v_cndmask_b32_e32 v22, v221, v22, vcc
	v_cmp_ngt_f32_e32 vcc, -1.0, v19
	s_nop 1
	v_cndmask_b32_e32 v22, v222, v22, vcc
	v_cmp_neq_f32_e32 vcc, -1.0, v19
	s_nop 1
	v_cndmask_b32_e32 v22, v219, v22, vcc
	v_cmp_lt_f32_e64 vcc, |v19|, s9
	s_nop 1
	v_cndmask_b32_e32 v19, v22, v19, vcc
	v_add_co_u32_e32 v22, vcc, s2, v20
	v_sub_f32_e32 v19, v24, v19
	s_nop 0
	v_addc_co_u32_e32 v23, vcc, 0, v21, vcc
	global_store_dword v[22:23], v19, off offset:704
	s_mov_b32 s2, 0x29000
	v_add_f32_e32 v19, v11, v245
	v_min_f32_e32 v24, 0, v19
	v_mul_f32_e64 v19, |v19|, s3
	v_exp_f32_e32 v19, v19
	s_nop 0
	v_add_f32_e32 v25, 1.0, v19
	v_add_f32_e32 v22, -1.0, v25
	v_sub_f32_e32 v23, v22, v25
	v_add_f32_e32 v23, 1.0, v23
	v_sub_f32_e32 v22, v19, v22
	v_add_f32_e32 v26, v22, v23
	v_frexp_mant_f32_e32 v22, v25
	v_cmp_gt_f32_e32 vcc, s6, v22
	v_cvt_f64_f32_e32 v[22:23], v25
	v_frexp_exp_i32_f64_e32 v22, v[22:23]
	v_subbrev_co_u32_e32 v22, vcc, 0, v22, vcc
	v_sub_u32_e32 v23, 0, v22
	v_ldexp_f32 v25, v25, v23
	v_ldexp_f32 v23, v26, v23
	v_add_f32_e32 v26, -1.0, v25
	v_add_f32_e32 v27, 1.0, v26
	v_sub_f32_e32 v27, v25, v27
	v_add_f32_e32 v27, v23, v27
	v_add_f32_e32 v28, v26, v27
	v_sub_f32_e32 v26, v28, v26
	v_sub_f32_e32 v26, v27, v26
	v_add_f32_e32 v27, 1.0, v25
	v_add_f32_e32 v29, -1.0, v27
	v_sub_f32_e32 v25, v25, v29
	v_add_f32_e32 v23, v23, v25
	v_add_f32_e32 v25, v27, v23
	v_sub_f32_e32 v27, v25, v27
	v_sub_f32_e32 v23, v23, v27
	v_rcp_f32_e32 v27, v25
	v_cvt_f32_i32_e32 v22, v22
	v_cmp_neq_f32_e32 vcc, s8, v19
	v_mul_f32_e32 v29, v28, v27
	v_mul_f32_e32 v30, v25, v29
	v_fma_f32 v31, v29, v25, -v30
	v_fmac_f32_e32 v31, v29, v23
	v_add_f32_e32 v32, v30, v31
	v_sub_f32_e32 v33, v28, v32
	v_sub_f32_e32 v28, v28, v33
	v_sub_f32_e32 v30, v32, v30
	v_sub_f32_e32 v28, v28, v32
	v_add_f32_e32 v26, v26, v28
	v_sub_f32_e32 v28, v30, v31
	v_add_f32_e32 v26, v28, v26
	v_add_f32_e32 v28, v33, v26
	v_mul_f32_e32 v30, v27, v28
	v_mul_f32_e32 v31, v25, v30
	v_fma_f32 v25, v30, v25, -v31
	v_fmac_f32_e32 v25, v30, v23
	v_sub_f32_e32 v23, v33, v28
	v_add_f32_e32 v23, v26, v23
	v_add_f32_e32 v26, v31, v25
	v_sub_f32_e32 v32, v28, v26
	v_sub_f32_e32 v28, v28, v32
	v_sub_f32_e32 v31, v26, v31
	v_sub_f32_e32 v26, v28, v26
	v_add_f32_e32 v23, v23, v26
	v_sub_f32_e32 v25, v31, v25
	v_add_f32_e32 v23, v25, v23
	v_add_f32_e32 v25, v29, v30
	v_add_f32_e32 v23, v32, v23
	v_sub_f32_e32 v26, v25, v29
	v_mul_f32_e32 v23, v27, v23
	v_sub_f32_e32 v26, v30, v26
	v_add_f32_e32 v23, v26, v23
	v_mul_f32_e32 v29, 0x3f317218, v22
	v_add_f32_e32 v26, v25, v23
	v_fma_f32 v30, v22, s7, -v29
	v_mul_f32_e32 v27, v26, v26
	v_fmac_f32_e32 v30, 0xb102e308, v22
	v_sub_f32_e32 v22, v26, v25
	v_fmamk_f32 v28, v27, 0x3e9b6dac, v214
	v_sub_f32_e32 v22, v23, v22
	v_add_f32_e32 v23, v29, v30
	v_fmaak_f32 v28, v27, v28, 0x3f2aaada
	v_sub_f32_e32 v25, v23, v29
	v_ldexp_f32 v29, v26, 1
	v_mul_f32_e32 v26, v26, v27
	v_mul_f32_e32 v26, v26, v28
	v_add_f32_e32 v27, v29, v26
	v_sub_f32_e32 v28, v27, v29
	v_ldexp_f32 v22, v22, 1
	v_sub_f32_e32 v26, v26, v28
	v_add_f32_e32 v22, v22, v26
	v_add_f32_e32 v26, v27, v22
	v_sub_f32_e32 v27, v26, v27
	v_sub_f32_e32 v22, v22, v27
	v_add_f32_e32 v27, v23, v26
	v_sub_f32_e32 v28, v27, v23
	v_sub_f32_e32 v29, v27, v28
	v_sub_f32_e32 v25, v30, v25
	v_sub_f32_e32 v23, v23, v29
	v_sub_f32_e32 v26, v26, v28
	v_add_f32_e32 v23, v26, v23
	v_add_f32_e32 v26, v25, v22
	v_sub_f32_e32 v28, v26, v25
	v_sub_f32_e32 v29, v26, v28
	v_sub_f32_e32 v25, v25, v29
	v_sub_f32_e32 v22, v22, v28
	v_add_f32_e32 v23, v26, v23
	v_add_f32_e32 v22, v22, v25
	v_add_f32_e32 v25, v27, v23
	v_sub_f32_e32 v26, v25, v27
	v_sub_f32_e32 v23, v23, v26
	v_add_f32_e32 v22, v22, v23
	v_add_f32_e32 v22, v25, v22
	v_cndmask_b32_e32 v22, v221, v22, vcc
	v_cmp_ngt_f32_e32 vcc, -1.0, v19
	s_nop 1
	v_cndmask_b32_e32 v22, v222, v22, vcc
	v_cmp_neq_f32_e32 vcc, -1.0, v19
	s_nop 1
	v_cndmask_b32_e32 v22, v219, v22, vcc
	v_cmp_lt_f32_e64 vcc, |v19|, s9
	s_nop 1
	v_cndmask_b32_e32 v19, v22, v19, vcc
	v_add_co_u32_e32 v22, vcc, s2, v20
	v_sub_f32_e32 v19, v24, v19
;     __device__ __forceinline__ void operator()(const AccT& acc, const pg8::Unit& u, int wr, int wc, int fr, int fq) const {
;     ...
;                     } else if (wc == 1 && fq == 0) {
; #pragma unroll
;                         for (int n = 0; n < 2; ++n)
; #pragma unroll
;                             for (int j = 0; j < 4; ++j) {
;                                 const float x = acc[ai][0][m][n][j] * rs + bfg[4 * n + j];
;                                 lf[(4 * n + j) * MROWS + row] = fminf(x, 0.f) - log1pf(__expf(-fabsf(x)));
;                             }
	s_nop 0
	v_addc_co_u32_e32 v23, vcc, 0, v21, vcc
	global_store_dword v[22:23], v19, off offset:1728
	s_mov_b32 s2, 0x31000
	v_add_f32_e32 v19, v12, v246
	v_min_f32_e32 v24, 0, v19
	v_mul_f32_e64 v19, |v19|, s3
	v_exp_f32_e32 v19, v19
	s_nop 0
	v_add_f32_e32 v25, 1.0, v19
	v_add_f32_e32 v22, -1.0, v25
	v_sub_f32_e32 v23, v22, v25
	v_add_f32_e32 v23, 1.0, v23
	v_sub_f32_e32 v22, v19, v22
	v_add_f32_e32 v26, v22, v23
	v_frexp_mant_f32_e32 v22, v25
	v_cmp_gt_f32_e32 vcc, s6, v22
	v_cvt_f64_f32_e32 v[22:23], v25
	v_frexp_exp_i32_f64_e32 v22, v[22:23]
	v_subbrev_co_u32_e32 v22, vcc, 0, v22, vcc
	v_sub_u32_e32 v23, 0, v22
	v_ldexp_f32 v25, v25, v23
	v_ldexp_f32 v23, v26, v23
	v_add_f32_e32 v26, -1.0, v25
	v_add_f32_e32 v27, 1.0, v26
	v_sub_f32_e32 v27, v25, v27
	v_add_f32_e32 v27, v23, v27
	v_add_f32_e32 v28, v26, v27
	v_sub_f32_e32 v26, v28, v26
	v_sub_f32_e32 v26, v27, v26
	v_add_f32_e32 v27, 1.0, v25
	v_add_f32_e32 v29, -1.0, v27
	v_sub_f32_e32 v25, v25, v29
	v_add_f32_e32 v23, v23, v25
	v_add_f32_e32 v25, v27, v23
	v_sub_f32_e32 v27, v25, v27
	v_sub_f32_e32 v23, v23, v27
	v_rcp_f32_e32 v27, v25
	v_cvt_f32_i32_e32 v22, v22
	v_cmp_neq_f32_e32 vcc, s8, v19
	v_mul_f32_e32 v29, v28, v27
	v_mul_f32_e32 v30, v25, v29
	v_fma_f32 v31, v29, v25, -v30
	v_fmac_f32_e32 v31, v29, v23
	v_add_f32_e32 v32, v30, v31
	v_sub_f32_e32 v33, v28, v32
	v_sub_f32_e32 v28, v28, v33
	v_sub_f32_e32 v30, v32, v30
	v_sub_f32_e32 v28, v28, v32
	v_add_f32_e32 v26, v26, v28
	v_sub_f32_e32 v28, v30, v31
	v_add_f32_e32 v26, v28, v26
	v_add_f32_e32 v28, v33, v26
	v_mul_f32_e32 v30, v27, v28
	v_mul_f32_e32 v31, v25, v30
	v_fma_f32 v25, v30, v25, -v31
	v_fmac_f32_e32 v25, v30, v23
	v_sub_f32_e32 v23, v33, v28
	v_add_f32_e32 v23, v26, v23
	v_add_f32_e32 v26, v31, v25
	v_sub_f32_e32 v32, v28, v26
	v_sub_f32_e32 v28, v28, v32
	v_sub_f32_e32 v31, v26, v31
	v_sub_f32_e32 v26, v28, v26
	v_add_f32_e32 v23, v23, v26
	v_sub_f32_e32 v25, v31, v25
	v_add_f32_e32 v23, v25, v23
	v_add_f32_e32 v25, v29, v30
	v_add_f32_e32 v23, v32, v23
	v_sub_f32_e32 v26, v25, v29
	v_mul_f32_e32 v23, v27, v23
	v_sub_f32_e32 v26, v30, v26
	v_add_f32_e32 v23, v26, v23
	v_mul_f32_e32 v29, 0x3f317218, v22
	v_add_f32_e32 v26, v25, v23
	v_fma_f32 v30, v22, s7, -v29
	v_mul_f32_e32 v27, v26, v26
	v_fmac_f32_e32 v30, 0xb102e308, v22
	v_sub_f32_e32 v22, v26, v25
	v_fmamk_f32 v28, v27, 0x3e9b6dac, v214
	v_sub_f32_e32 v22, v23, v22
	v_add_f32_e32 v23, v29, v30
	v_fmaak_f32 v28, v27, v28, 0x3f2aaada
	v_sub_f32_e32 v25, v23, v29
	v_ldexp_f32 v29, v26, 1
	v_mul_f32_e32 v26, v26, v27
	v_mul_f32_e32 v26, v26, v28
	v_add_f32_e32 v27, v29, v26
	v_sub_f32_e32 v28, v27, v29
	v_ldexp_f32 v22, v22, 1
	v_sub_f32_e32 v26, v26, v28
	v_add_f32_e32 v22, v22, v26
	v_add_f32_e32 v26, v27, v22
	v_sub_f32_e32 v27, v26, v27
	v_sub_f32_e32 v22, v22, v27
	v_add_f32_e32 v27, v23, v26
	v_sub_f32_e32 v28, v27, v23
	v_sub_f32_e32 v29, v27, v28
	v_sub_f32_e32 v25, v30, v25
	v_sub_f32_e32 v23, v23, v29
	v_sub_f32_e32 v26, v26, v28
	v_add_f32_e32 v23, v26, v23
	v_add_f32_e32 v26, v25, v22
	v_sub_f32_e32 v28, v26, v25
	v_sub_f32_e32 v29, v26, v28
	v_sub_f32_e32 v25, v25, v29
	v_sub_f32_e32 v22, v22, v28
	v_add_f32_e32 v23, v26, v23
	v_add_f32_e32 v22, v22, v25
	v_add_f32_e32 v25, v27, v23
	v_sub_f32_e32 v26, v25, v27
	v_sub_f32_e32 v23, v23, v26
	v_add_f32_e32 v22, v22, v23
	v_add_f32_e32 v22, v25, v22
	v_cndmask_b32_e32 v22, v221, v22, vcc
	v_cmp_ngt_f32_e32 vcc, -1.0, v19
	s_nop 1
	v_cndmask_b32_e32 v22, v222, v22, vcc
	v_cmp_neq_f32_e32 vcc, -1.0, v19
	s_nop 1
	v_cndmask_b32_e32 v22, v219, v22, vcc
	v_cmp_lt_f32_e64 vcc, |v19|, s9
	s_nop 1
	v_cndmask_b32_e32 v19, v22, v19, vcc
	v_add_co_u32_e32 v22, vcc, s2, v20
	v_sub_f32_e32 v19, v24, v19
	s_nop 0
	v_addc_co_u32_e32 v23, vcc, 0, v21, vcc
;     __device__ __forceinline__ void operator()(const AccT& acc, const pg8::Unit& u, int wr, int wc, int fr, int fq) const {
;     ...
;                     } else if (wc == 1 && fq == 0) {
; #pragma unroll
;                         for (int n = 0; n < 2; ++n)
; #pragma unroll
;                             for (int j = 0; j < 4; ++j) {
;                                 const float x = acc[ai][0][m][n][j] * rs + bfg[4 * n + j];
;                                 lf[(4 * n + j) * MROWS + row] = fminf(x, 0.f) - log1pf(__expf(-fabsf(x)));
;                             }
	global_store_dword v[22:23], v19, off offset:2752
	v_add_f32_e32 v19, v13, v247
	v_min_f32_e32 v24, 0, v19
	v_mul_f32_e64 v19, |v19|, s3
	v_exp_f32_e32 v19, v19
	s_nop 0
	v_add_f32_e32 v25, 1.0, v19
	v_add_f32_e32 v22, -1.0, v25
	v_sub_f32_e32 v23, v22, v25
	v_add_f32_e32 v23, 1.0, v23
	v_sub_f32_e32 v22, v19, v22
	v_add_f32_e32 v26, v22, v23
	v_frexp_mant_f32_e32 v22, v25
	v_cmp_gt_f32_e32 vcc, s6, v22
	v_cvt_f64_f32_e32 v[22:23], v25
	v_frexp_exp_i32_f64_e32 v22, v[22:23]
	v_subbrev_co_u32_e32 v22, vcc, 0, v22, vcc
	v_sub_u32_e32 v23, 0, v22
	v_ldexp_f32 v25, v25, v23
	v_ldexp_f32 v23, v26, v23
	v_add_f32_e32 v26, -1.0, v25
	v_add_f32_e32 v27, 1.0, v26
	v_sub_f32_e32 v27, v25, v27
	v_add_f32_e32 v27, v23, v27
	v_add_f32_e32 v28, v26, v27
	v_sub_f32_e32 v26, v28, v26
	v_sub_f32_e32 v26, v27, v26
	v_add_f32_e32 v27, 1.0, v25
	v_add_f32_e32 v29, -1.0, v27
	v_sub_f32_e32 v25, v25, v29
	v_add_f32_e32 v23, v23, v25
	v_add_f32_e32 v25, v27, v23
	v_sub_f32_e32 v27, v25, v27
	v_sub_f32_e32 v23, v23, v27
	v_rcp_f32_e32 v27, v25
	v_cvt_f32_i32_e32 v22, v22
	v_cmp_neq_f32_e32 vcc, s8, v19
	v_mul_f32_e32 v29, v28, v27
	v_mul_f32_e32 v30, v25, v29
	v_fma_f32 v31, v29, v25, -v30
	v_fmac_f32_e32 v31, v29, v23
	v_add_f32_e32 v32, v30, v31
	v_sub_f32_e32 v33, v28, v32
	v_sub_f32_e32 v28, v28, v33
	v_sub_f32_e32 v30, v32, v30
	v_sub_f32_e32 v28, v28, v32
	v_add_f32_e32 v26, v26, v28
	v_sub_f32_e32 v28, v30, v31
	v_add_f32_e32 v26, v28, v26
	v_add_f32_e32 v28, v33, v26
	v_mul_f32_e32 v30, v27, v28
	v_mul_f32_e32 v31, v25, v30
	v_fma_f32 v25, v30, v25, -v31
	v_fmac_f32_e32 v25, v30, v23
	v_sub_f32_e32 v23, v33, v28
	v_add_f32_e32 v23, v26, v23
	v_add_f32_e32 v26, v31, v25
	v_sub_f32_e32 v32, v28, v26
	v_sub_f32_e32 v28, v28, v32
	v_sub_f32_e32 v31, v26, v31
	v_sub_f32_e32 v26, v28, v26
	v_add_f32_e32 v23, v23, v26
	v_sub_f32_e32 v25, v31, v25
	v_add_f32_e32 v23, v25, v23
	v_add_f32_e32 v25, v29, v30
	v_add_f32_e32 v23, v32, v23
	v_sub_f32_e32 v26, v25, v29
	v_mul_f32_e32 v23, v27, v23
	v_sub_f32_e32 v26, v30, v26
	v_add_f32_e32 v23, v26, v23
	v_mul_f32_e32 v29, 0x3f317218, v22
	v_add_f32_e32 v26, v25, v23
	v_fma_f32 v30, v22, s7, -v29
	v_mul_f32_e32 v27, v26, v26
	v_fmac_f32_e32 v30, 0xb102e308, v22
	v_sub_f32_e32 v22, v26, v25
	v_fmamk_f32 v28, v27, 0x3e9b6dac, v214
	v_sub_f32_e32 v22, v23, v22
	v_add_f32_e32 v23, v29, v30
	v_fmaak_f32 v28, v27, v28, 0x3f2aaada
	v_sub_f32_e32 v25, v23, v29
	v_ldexp_f32 v29, v26, 1
	v_mul_f32_e32 v26, v26, v27
	v_mul_f32_e32 v26, v26, v28
	v_add_f32_e32 v27, v29, v26
	v_sub_f32_e32 v28, v27, v29
	v_ldexp_f32 v22, v22, 1
	v_sub_f32_e32 v26, v26, v28
	v_add_f32_e32 v22, v22, v26
	v_add_f32_e32 v26, v27, v22
	v_sub_f32_e32 v27, v26, v27
	v_sub_f32_e32 v22, v22, v27
	v_add_f32_e32 v27, v23, v26
	v_sub_f32_e32 v28, v27, v23
	v_sub_f32_e32 v29, v27, v28
	v_sub_f32_e32 v25, v30, v25
	v_sub_f32_e32 v23, v23, v29
	v_sub_f32_e32 v26, v26, v28
	v_add_f32_e32 v23, v26, v23
	v_add_f32_e32 v26, v25, v22
	v_sub_f32_e32 v28, v26, v25
	v_sub_f32_e32 v29, v26, v28
	v_sub_f32_e32 v25, v25, v29
	v_sub_f32_e32 v22, v22, v28
	v_add_f32_e32 v23, v26, v23
	v_add_f32_e32 v22, v22, v25
	v_add_f32_e32 v25, v27, v23
	v_sub_f32_e32 v26, v25, v27
	v_sub_f32_e32 v23, v23, v26
	v_add_f32_e32 v22, v22, v23
	v_add_f32_e32 v22, v25, v22
	v_cndmask_b32_e32 v22, v221, v22, vcc
	v_cmp_ngt_f32_e32 vcc, -1.0, v19
	s_nop 1
	v_cndmask_b32_e32 v22, v222, v22, vcc
	v_cmp_neq_f32_e32 vcc, -1.0, v19
	s_nop 1
	v_cndmask_b32_e32 v22, v219, v22, vcc
	v_cmp_lt_f32_e64 vcc, |v19|, s9
	s_nop 1
	v_cndmask_b32_e32 v19, v22, v19, vcc
	v_add_co_u32_e32 v20, vcc, 0x39000, v20
	v_sub_f32_e32 v19, v24, v19
	s_nop 0
	v_addc_co_u32_e32 v21, vcc, 0, v21, vcc
	global_store_dword v[20:21], v19, off offset:3776
